# on top of v20: B-fragment LDS base constants folded into ds_read offset immediates (24 v_add_u32 removed, base register biased once per phase)
# speedup vs baseline: 1.0060x; 1.0034x over previous
; #define PG8_STAGE(bufoff, gbase) do { _Pragma("unroll") for (int _i = 0; _i < 2; ++_i) \
;         __builtin_amdgcn_global_load_lds((const unsigned*)((const char*)(gbase) + voff[_i]), (LAS unsigned*)(lds + (bufoff) + ldsw + _i * 8192), 16, 0, 0); } while (0)
; #define PG8_WAIT_V(n) asm volatile("s_waitcnt vmcnt(" #n ")" ::: "memory")
; #define PG8_BAR __builtin_amdgcn_s_barrier()
; template <class Epi>
; DI void gemm_phase(LAS unsigned char* lds, const Gemm g, const StaticOrder& S, const Epi& E) {
;     ...
;     for (int i = 0; i < 2; ++i) { int R, C; stage_rc(tid * 16 + i * 8192, R, C); voff[i] = (unsigned)(R * K + C) * 2u; }
;     const size_t kstep = (size_t)(BK * 2);
;     const size_t hstep = (size_t)HALF * K * 2;
;     const size_t tstep = 2 * hstep;
;     const unsigned ldsw = (unsigned)wid * 1024u;
;     const int aoff = lds_byte(wr * 64 + fr, fq * 8), boff = lds_byte(wc * 32 + fr, fq * 8);
;     ...
;     if (wr == 1) PG8_BAR;
;     PG8_WAIT_V(4); PG8_BAR;
;     PG8_STAGE(PG8_SB(1, 0), cB + kstep); PG8_STAGE(PG8_SA(1, 0), cA + kstep); PG8_STAGE(PG8_SB(1, 1), cB + hstep + kstep);
;     PG8_WAIT_V(6); PG8_BAR;
.LBB0_33:
	v_lshl_add_u64 v[8:9], s[20:21], 0, v[158:159]
	v_mov_b32_e32 v129, v159
	v_readlane_b32 s18, v254, 17
	s_lshl_b32 s3, s3, 5
	v_lshl_add_u64 v[10:11], s[20:21], 0, v[128:129]
	v_readlane_b32 s19, v254, 18
	s_and_b32 s3, s3, 0x60
	s_add_i32 m0, s28, 0x18000
	v_lshl_add_u64 v[8:9], v[8:9], 0, s[94:95]
	v_lshl_add_u64 v[12:13], s[18:19], 0, v[158:159]
	s_lshl_b32 s6, s2, 13
	s_lshl_b32 s7, s3, 7
	s_waitcnt vmcnt(4)
	s_barrier
	global_load_lds_dwordx4 v[8:9], off
	v_lshl_add_u64 v[8:9], v[10:11], 0, s[94:95]
	s_add_i32 m0, s28, 0x1a000
	s_add_i32 s34, s28, 0x8000
	s_add_i32 s35, s28, 0xa000
	v_lshl_add_u64 v[14:15], s[18:19], 0, v[128:129]
	global_load_lds_dwordx4 v[8:9], off
	v_lshl_add_u64 v[8:9], v[12:13], 0, s[94:95]
	s_mov_b32 m0, s34
	s_add_u32 s4, s20, 0x80080
	global_load_lds_dwordx4 v[8:9], off
	v_lshl_add_u64 v[8:9], v[14:15], 0, s[94:95]
	s_mov_b32 m0, s35
	s_addc_u32 s5, s21, 0
	global_load_lds_dwordx4 v[8:9], off
	s_add_i32 m0, s28, 0x1c000
	v_lshl_add_u64 v[8:9], s[4:5], 0, v[158:159]
	global_load_lds_dwordx4 v[8:9], off
	v_lshl_add_u64 v[8:9], s[4:5], 0, v[128:129]
	s_add_i32 m0, s28, 0x1e000
	v_and_b32_e32 v7, 15, v0
	global_load_lds_dwordx4 v[8:9], off
	v_lshrrev_b32_e32 v8, 1, v0
	v_and_b32_e32 v8, 24, v8
	v_lshlrev_b32_e32 v9, 1, v8
	v_lshlrev_b32_e32 v0, 2, v0
	v_lshl_or_b32 v134, s2, 6, v7
	v_lshl_or_b32 v7, v7, 6, v9
	v_and_b32_e32 v0, 32, v0
	v_bitop3_b32 v9, v7, s6, v0 bitop3:0xde
	v_bitop3_b32 v135, v7, s7, v0 bitop3:0xde
	v_add_u32_e32 v135, 0x10000, v135
	v_lshlrev_b32_e32 v0, 15, v4
	v_and_b32_e32 v0, 0xffff0000, v0
	v_lshl_add_u32 v0, v5, 12, v0
	v_and_b32_e32 v4, 1, v4
	v_lshl_or_b32 v0, v4, 6, v0
	v_lshl_add_u32 v130, v6, 1, v0
	v_lshlrev_b32_e32 v0, 15, v1
	v_and_b32_e32 v0, 0xffff0000, v0
	s_waitcnt vmcnt(6)
	v_lshl_add_u32 v0, v2, 12, v0
	v_and_b32_e32 v1, 1, v1
	v_lshl_or_b32 v0, v1, 6, v0
	v_readlane_b32 s4, v254, 15
	s_waitcnt vmcnt(0)
	v_or_b32_e32 v136, s3, v8
	v_mov_b32_e32 v131, v159
	v_lshl_add_u32 v132, v3, 1, v0
	v_mov_b32_e32 v133, v159
	s_mov_b32 s36, 0
	v_add_u32_e32 v137, 0, v9
	v_readlane_b32 s2, v254, 12
	s_mov_b32 s3, s4
	s_barrier
	v_readlane_b32 s5, v254, 16

; #define PG8_STAGE(bufoff, gbase) do { _Pragma("unroll") for (int _i = 0; _i < 2; ++_i) \
;         __builtin_amdgcn_global_load_lds((const unsigned*)((const char*)(gbase) + voff[_i]), (LAS unsigned*)(lds + (bufoff) + ldsw + _i * 8192), 16, 0, 0); } while (0)
; #define PG8_LDA(dst, b, h) do { _Pragma("unroll") for (int m = 0; m < 4; ++m) _Pragma("unroll") for (int k = 0; k < 2; ++k) dst[m][k] = *(const LAS bf16x8*)(lds + PG8_SA(b, h) + aoff + m * 2048 + k * 1024); } while (0)
; #define PG8_LDB(dst, b, h) do { _Pragma("unroll") for (int n = 0; n < 2; ++n) _Pragma("unroll") for (int k = 0; k < 2; ++k) dst[n][k] = *(const LAS bf16x8*)(lds + PG8_SB(b, h) + boff + n * 2048 + k * 1024); } while (0)
; #define PG8_MMA(ai, bj, At, Bt) do { __builtin_amdgcn_s_setprio(1); _Pragma("unroll") for (int m = 0; m < 4; ++m) _Pragma("unroll") for (int n = 0; n < 2; ++n) _Pragma("unroll") for (int k = 0; k < 2; ++k) \
;         acc[ai][bj][m][n] = __builtin_amdgcn_mfma_f32_16x16x32_bf16(Bt[n][k], At[m][k], acc[ai][bj][m][n], 0, 0, 0); __builtin_amdgcn_s_setprio(0); } while (0)
; #define PG8_WAIT_V(n) asm volatile("s_waitcnt vmcnt(" #n ")" ::: "memory")
; #define PG8_WAIT_L(n) asm volatile("s_waitcnt lgkmcnt(" #n ")" ::: "memory")
; #define PG8_BAR __builtin_amdgcn_s_barrier()
; #define PG8_SCHED __builtin_amdgcn_sched_barrier(0)
; template <class Epi>
; DI void gemm_phase(LAS unsigned char* lds, const Gemm g, const StaticOrder& S, const Epi& E) {
;     ...
;         for (int t = 0; t < nt; t += 2) {
;             const bool last = (t == nt - 2);
;             const char* a1 = cA + (size_t)(t + 1) * kstep;
;             const char* a2 = last ? nA : cA + (size_t)(t + 2) * kstep; const char* b2 = last ? nB : cB + (size_t)(t + 2) * kstep;
;             const char* a3 = a2 + kstep; const char* b3 = b2 + kstep;
;             PG8_LDB(B0, 0, 0); PG8_SCHED; PG8_LDA(At, 0, 0); PG8_STAGE(PG8_SA(1, 1), a1 + hstep);
;             PG8_WAIT_L(8); PG8_BAR; PG8_WAIT_L(0); PG8_MMA(0, 0, At, B0); PG8_BAR; PG8_SCHED;
;             PG8_LDB(B1, 0, 1); PG8_STAGE(PG8_SB(0, 0), b2);
;             PG8_BAR; PG8_WAIT_L(0); PG8_MMA(0, 1, At, B1); PG8_BAR;
;             PG8_LDA(At, 0, 1); PG8_STAGE(PG8_SA(0, 0), a2);
;             PG8_BAR; PG8_WAIT_L(0); PG8_MMA(1, 0, At, B0); PG8_BAR; PG8_SCHED;
;             PG8_STAGE(PG8_SB(0, 1), b2 + hstep);
;             PG8_WAIT_V(6); PG8_BAR; PG8_MMA(1, 1, At, B1); PG8_BAR;
.LBB0_37:
	s_add_u32 s20, s18, 0xfff80080
	s_addc_u32 s21, s19, -1
	s_add_i32 s39, 0, 0x10000
	ds_read_b128 v[138:141], v135
	ds_read_b128 v[142:145], v135 offset:1024
	ds_read_b128 v[146:149], v135 offset:2048
	ds_read_b128 v[150:153], v135 offset:3072
	s_cmp_eq_u32 s38, 28
	s_cselect_b32 s23, s4, s21
	s_cselect_b32 s22, s5, s20
	s_cselect_b32 s21, s9, s37
	s_cselect_b32 s20, s11, s33
	v_lshl_add_u64 v[154:155], s[18:19], 0, v[130:131]
	s_add_i32 m0, s28, 0xc000
	ds_read_b128 v[186:189], v137
	ds_read_b128 v[190:193], v137 offset:1024
	ds_read_b128 v[194:197], v137 offset:2048
	ds_read_b128 v[198:201], v137 offset:3072
	ds_read_b128 v[202:205], v137 offset:4096
	ds_read_b128 v[206:209], v137 offset:5120
	ds_read_b128 v[210:213], v137 offset:6144
	ds_read_b128 v[214:217], v137 offset:7168
	global_load_lds_dwordx4 v[154:155], off
	v_lshl_add_u64 v[154:155], s[18:19], 0, v[132:133]
	s_add_i32 m0, s28, 0xe000
	s_nop 0
	global_load_lds_dwordx4 v[154:155], off
	s_waitcnt lgkmcnt(8)
	s_setprio 1
	s_barrier
	s_waitcnt lgkmcnt(0)
	v_mfma_f32_16x16x32_bf16 v[124:127], v[138:141], v[186:189], v[124:127]
	v_mfma_f32_16x16x32_bf16 v[120:123], v[146:149], v[186:189], v[120:123]
	v_mfma_f32_16x16x32_bf16 v[108:111], v[138:141], v[194:197], v[108:111]
	v_mfma_f32_16x16x32_bf16 v[104:107], v[146:149], v[194:197], v[104:107]
	v_mfma_f32_16x16x32_bf16 v[92:95], v[138:141], v[202:205], v[92:95]
	v_mfma_f32_16x16x32_bf16 v[88:91], v[146:149], v[202:205], v[88:91]
	v_mfma_f32_16x16x32_bf16 v[76:79], v[138:141], v[210:213], v[76:79]
	v_mfma_f32_16x16x32_bf16 v[72:75], v[146:149], v[210:213], v[72:75]
	v_mfma_f32_16x16x32_bf16 v[124:127], v[142:145], v[190:193], v[124:127]
	v_mfma_f32_16x16x32_bf16 v[120:123], v[150:153], v[190:193], v[120:123]
	v_mfma_f32_16x16x32_bf16 v[108:111], v[142:145], v[198:201], v[108:111]
	v_mfma_f32_16x16x32_bf16 v[104:107], v[150:153], v[198:201], v[104:107]
	v_mfma_f32_16x16x32_bf16 v[92:95], v[142:145], v[206:209], v[92:95]
	v_mfma_f32_16x16x32_bf16 v[88:91], v[150:153], v[206:209], v[88:91]
	v_mfma_f32_16x16x32_bf16 v[76:79], v[142:145], v[214:217], v[76:79]
	v_mfma_f32_16x16x32_bf16 v[72:75], v[150:153], v[214:217], v[72:75]
	s_setprio 0
	s_barrier
	s_add_i32 s42, 0, 0x14000
	s_add_i32 s39, s39, s27
	ds_read_b128 v[226:229], v135 offset:16384
	ds_read_b128 v[230:233], v135 offset:17408
	ds_read_b128 v[234:237], v135 offset:18432
	ds_read_b128 v[238:241], v135 offset:19456
	v_lshl_add_u64 v[154:155], s[20:21], 0, v[158:159]
	s_mov_b32 m0, s39
	v_lshl_add_u64 v[218:219], s[20:21], 0, v[128:129]
	global_load_lds_dwordx4 v[154:155], off
	s_add_i32 m0, s39, 0x2000
	s_nop 0
	global_load_lds_dwordx4 v[218:219], off
	s_waitcnt lgkmcnt(0)
	s_setprio 1
	s_barrier
	v_mfma_f32_16x16x32_bf16 v[116:119], v[226:229], v[186:189], v[116:119]
	v_mfma_f32_16x16x32_bf16 v[112:115], v[234:237], v[186:189], v[112:115]
	v_mfma_f32_16x16x32_bf16 v[100:103], v[226:229], v[194:197], v[100:103]
	v_mfma_f32_16x16x32_bf16 v[96:99], v[234:237], v[194:197], v[96:99]
	v_mfma_f32_16x16x32_bf16 v[84:87], v[226:229], v[202:205], v[84:87]
	v_mfma_f32_16x16x32_bf16 v[80:83], v[234:237], v[202:205], v[80:83]
	v_mfma_f32_16x16x32_bf16 v[68:71], v[226:229], v[210:213], v[68:71]
	v_mfma_f32_16x16x32_bf16 v[64:67], v[234:237], v[210:213], v[64:67]
	v_mfma_f32_16x16x32_bf16 v[116:119], v[230:233], v[190:193], v[116:119]
	s_mov_b32 m0, s28
	v_mfma_f32_16x16x32_bf16 v[112:115], v[238:241], v[190:193], v[112:115]
	v_lshl_add_u64 v[220:221], s[22:23], 0, v[158:159]
	v_mfma_f32_16x16x32_bf16 v[100:103], v[230:233], v[198:201], v[100:103]
	v_mfma_f32_16x16x32_bf16 v[96:99], v[238:241], v[198:201], v[96:99]
	v_mfma_f32_16x16x32_bf16 v[84:87], v[230:233], v[206:209], v[84:87]
	v_mfma_f32_16x16x32_bf16 v[80:83], v[238:241], v[206:209], v[80:83]
	v_mfma_f32_16x16x32_bf16 v[68:71], v[230:233], v[214:217], v[68:71]
	v_mfma_f32_16x16x32_bf16 v[64:67], v[238:241], v[214:217], v[64:67]
	s_setprio 0
	s_barrier
	ds_read_b128 v[186:189], v137 offset:16384
	ds_read_b128 v[190:193], v137 offset:17408
	ds_read_b128 v[194:197], v137 offset:18432
	ds_read_b128 v[198:201], v137 offset:19456
	ds_read_b128 v[202:205], v137 offset:20480
	ds_read_b128 v[206:209], v137 offset:21504
	ds_read_b128 v[210:213], v137 offset:22528
	ds_read_b128 v[214:217], v137 offset:23552
	global_load_lds_dwordx4 v[220:221], off
	v_lshl_add_u64 v[242:243], s[22:23], 0, v[128:129]
	s_mov_b32 m0, s29
	s_nop 0
	global_load_lds_dwordx4 v[242:243], off
	s_waitcnt lgkmcnt(0)
	s_setprio 1
	s_barrier
	v_mfma_f32_16x16x32_bf16 v[60:63], v[138:141], v[186:189], v[60:63]
	v_mfma_f32_16x16x32_bf16 v[56:59], v[146:149], v[186:189], v[56:59]
	v_mfma_f32_16x16x32_bf16 v[44:47], v[138:141], v[194:197], v[44:47]
	v_mfma_f32_16x16x32_bf16 v[40:43], v[146:149], v[194:197], v[40:43]
	v_mfma_f32_16x16x32_bf16 v[28:31], v[138:141], v[202:205], v[28:31]
	v_mfma_f32_16x16x32_bf16 v[24:27], v[146:149], v[202:205], v[24:27]
	v_mfma_f32_16x16x32_bf16 v[12:15], v[138:141], v[210:213], v[12:15]
	v_mfma_f32_16x16x32_bf16 v[8:11], v[146:149], v[210:213], v[8:11]
	v_mfma_f32_16x16x32_bf16 v[60:63], v[142:145], v[190:193], v[60:63]
	v_mfma_f32_16x16x32_bf16 v[56:59], v[150:153], v[190:193], v[56:59]
	v_mfma_f32_16x16x32_bf16 v[44:47], v[142:145], v[198:201], v[44:47]
	v_mfma_f32_16x16x32_bf16 v[40:43], v[150:153], v[198:201], v[40:43]
	v_mfma_f32_16x16x32_bf16 v[28:31], v[142:145], v[206:209], v[28:31]
	v_mfma_f32_16x16x32_bf16 v[24:27], v[150:153], v[206:209], v[24:27]
	v_mfma_f32_16x16x32_bf16 v[12:15], v[142:145], v[214:217], v[12:15]
	v_mfma_f32_16x16x32_bf16 v[8:11], v[150:153], v[214:217], v[8:11]
	s_setprio 0
	s_barrier
; #define PG8_STAGE(bufoff, gbase) do { _Pragma("unroll") for (int _i = 0; _i < 2; ++_i) \
;         __builtin_amdgcn_global_load_lds((const unsigned*)((const char*)(gbase) + voff[_i]), (LAS unsigned*)(lds + (bufoff) + ldsw + _i * 8192), 16, 0, 0); } while (0)
; #define PG8_LDA(dst, b, h) do { _Pragma("unroll") for (int m = 0; m < 4; ++m) _Pragma("unroll") for (int k = 0; k < 2; ++k) dst[m][k] = *(const LAS bf16x8*)(lds + PG8_SA(b, h) + aoff + m * 2048 + k * 1024); } while (0)
; #define PG8_LDB(dst, b, h) do { _Pragma("unroll") for (int n = 0; n < 2; ++n) _Pragma("unroll") for (int k = 0; k < 2; ++k) dst[n][k] = *(const LAS bf16x8*)(lds + PG8_SB(b, h) + boff + n * 2048 + k * 1024); } while (0)
; #define PG8_MMA(ai, bj, At, Bt) do { __builtin_amdgcn_s_setprio(1); _Pragma("unroll") for (int m = 0; m < 4; ++m) _Pragma("unroll") for (int n = 0; n < 2; ++n) _Pragma("unroll") for (int k = 0; k < 2; ++k) \
;         acc[ai][bj][m][n] = __builtin_amdgcn_mfma_f32_16x16x32_bf16(Bt[n][k], At[m][k], acc[ai][bj][m][n], 0, 0, 0); __builtin_amdgcn_s_setprio(0); } while (0)
; #define PG8_WAIT_V(n) asm volatile("s_waitcnt vmcnt(" #n ")" ::: "memory")
; #define PG8_WAIT_L(n) asm volatile("s_waitcnt lgkmcnt(" #n ")" ::: "memory")
; #define PG8_BAR __builtin_amdgcn_s_barrier()
; #define PG8_SCHED __builtin_amdgcn_sched_barrier(0)
; template <class Epi>
; DI void gemm_phase(LAS unsigned char* lds, const Gemm g, const StaticOrder& S, const Epi& E) {
;     ...
;             PG8_LDA(At, 0, 1); PG8_STAGE(PG8_SA(0, 0), a2);
;             PG8_BAR; PG8_WAIT_L(0); PG8_MMA(1, 0, At, B0); PG8_BAR; PG8_SCHED;
;             PG8_STAGE(PG8_SB(0, 1), b2 + hstep);
;             PG8_WAIT_V(6); PG8_BAR; PG8_MMA(1, 1, At, B1); PG8_BAR;
;             PG8_LDB(B0, 1, 0); PG8_SCHED; PG8_LDA(At, 1, 0); PG8_STAGE(PG8_SA(0, 1), a2 + hstep);
;             PG8_WAIT_L(8); PG8_BAR; PG8_WAIT_L(0); PG8_MMA(0, 0, At, B0); PG8_BAR; PG8_SCHED;
;             PG8_LDB(B1, 1, 1); PG8_STAGE(PG8_SB(1, 0), b3);
;             PG8_BAR; PG8_WAIT_L(0); PG8_MMA(0, 1, At, B1); PG8_BAR;
;             PG8_LDA(At, 1, 1); PG8_STAGE(PG8_SA(1, 0), a3);
;             PG8_BAR; PG8_WAIT_L(0); PG8_MMA(1, 0, At, B0); PG8_BAR; PG8_SCHED;
	s_add_u32 s40, s20, 0x80000
	s_addc_u32 s41, s21, 0
	s_add_i32 s39, s42, s27
	v_lshl_add_u64 v[138:139], s[40:41], 0, v[158:159]
	s_mov_b32 m0, s39
	s_nop 0
	global_load_lds_dwordx4 v[138:139], off
	v_lshl_add_u64 v[138:139], s[40:41], 0, v[128:129]
	s_add_i32 m0, s39, 0x2000
	s_nop 0
	global_load_lds_dwordx4 v[138:139], off
	s_waitcnt vmcnt(6)
	s_setprio 1
	s_barrier
	v_mfma_f32_16x16x32_bf16 v[52:55], v[226:229], v[186:189], v[52:55]
	v_mfma_f32_16x16x32_bf16 v[48:51], v[234:237], v[186:189], v[48:51]
	v_mfma_f32_16x16x32_bf16 v[36:39], v[226:229], v[194:197], v[36:39]
	v_mfma_f32_16x16x32_bf16 v[32:35], v[234:237], v[194:197], v[32:35]
	v_mfma_f32_16x16x32_bf16 v[20:23], v[226:229], v[202:205], v[20:23]
	v_mfma_f32_16x16x32_bf16 v[16:19], v[234:237], v[202:205], v[16:19]
	v_mfma_f32_16x16x32_bf16 v[4:7], v[226:229], v[210:213], v[4:7]
	v_mfma_f32_16x16x32_bf16 v[0:3], v[234:237], v[210:213], v[0:3]
	v_mfma_f32_16x16x32_bf16 v[52:55], v[230:233], v[190:193], v[52:55]
	s_add_i32 s39, 0, 0x18000
	v_mfma_f32_16x16x32_bf16 v[48:51], v[238:241], v[190:193], v[48:51]
	v_mfma_f32_16x16x32_bf16 v[36:39], v[230:233], v[198:201], v[36:39]
	v_mfma_f32_16x16x32_bf16 v[32:35], v[238:241], v[198:201], v[32:35]
	v_mfma_f32_16x16x32_bf16 v[20:23], v[230:233], v[206:209], v[20:23]
	v_mfma_f32_16x16x32_bf16 v[16:19], v[238:241], v[206:209], v[16:19]
	v_mfma_f32_16x16x32_bf16 v[4:7], v[230:233], v[214:217], v[4:7]
	v_mfma_f32_16x16x32_bf16 v[0:3], v[238:241], v[214:217], v[0:3]
	s_setprio 0
	s_barrier
	ds_read_b128 v[138:141], v135 offset:32768
	ds_read_b128 v[142:145], v135 offset:33792
	ds_read_b128 v[146:149], v135 offset:34816
	ds_read_b128 v[150:153], v135 offset:35840
	s_add_u32 s22, s22, 0x80000
	s_addc_u32 s23, s23, 0
	s_mov_b32 m0, s30
	v_lshl_add_u64 v[226:227], s[22:23], 0, v[158:159]
	ds_read_b128 v[186:189], v137 offset:32768
	ds_read_b128 v[190:193], v137 offset:33792
	ds_read_b128 v[194:197], v137 offset:34816
	ds_read_b128 v[198:201], v137 offset:35840
	ds_read_b128 v[202:205], v137 offset:36864
	ds_read_b128 v[206:209], v137 offset:37888
	ds_read_b128 v[210:213], v137 offset:38912
	ds_read_b128 v[214:217], v137 offset:39936
	global_load_lds_dwordx4 v[226:227], off
	v_lshl_add_u64 v[226:227], s[22:23], 0, v[128:129]
	s_mov_b32 m0, s31
	s_nop 0
	global_load_lds_dwordx4 v[226:227], off
	s_waitcnt lgkmcnt(8)
	s_setprio 1
	s_barrier
	s_waitcnt lgkmcnt(0)
	v_mfma_f32_16x16x32_bf16 v[124:127], v[138:141], v[186:189], v[124:127]
	v_mfma_f32_16x16x32_bf16 v[120:123], v[146:149], v[186:189], v[120:123]
	v_mfma_f32_16x16x32_bf16 v[108:111], v[138:141], v[194:197], v[108:111]
	v_mfma_f32_16x16x32_bf16 v[104:107], v[146:149], v[194:197], v[104:107]
	v_mfma_f32_16x16x32_bf16 v[92:95], v[138:141], v[202:205], v[92:95]
	v_mfma_f32_16x16x32_bf16 v[88:91], v[146:149], v[202:205], v[88:91]
	v_mfma_f32_16x16x32_bf16 v[76:79], v[138:141], v[210:213], v[76:79]
	v_mfma_f32_16x16x32_bf16 v[72:75], v[146:149], v[210:213], v[72:75]
	v_mfma_f32_16x16x32_bf16 v[124:127], v[142:145], v[190:193], v[124:127]
	v_mfma_f32_16x16x32_bf16 v[120:123], v[150:153], v[190:193], v[120:123]
	v_mfma_f32_16x16x32_bf16 v[108:111], v[142:145], v[198:201], v[108:111]
	v_mfma_f32_16x16x32_bf16 v[104:107], v[150:153], v[198:201], v[104:107]
	v_mfma_f32_16x16x32_bf16 v[92:95], v[142:145], v[206:209], v[92:95]
	v_mfma_f32_16x16x32_bf16 v[88:91], v[150:153], v[206:209], v[88:91]
	v_mfma_f32_16x16x32_bf16 v[76:79], v[142:145], v[214:217], v[76:79]
	v_mfma_f32_16x16x32_bf16 v[72:75], v[150:153], v[214:217], v[72:75]
	s_setprio 0
	s_barrier
	s_add_i32 s22, 0, 0x1c000
	s_add_i32 s23, s39, s27
	v_lshl_add_u64 v[154:155], v[154:155], 0, s[94:95]
	s_mov_b32 m0, s23
	ds_read_b128 v[226:229], v135 offset:49152
	ds_read_b128 v[230:233], v135 offset:50176
	ds_read_b128 v[234:237], v135 offset:51200
	ds_read_b128 v[238:241], v135 offset:52224
	global_load_lds_dwordx4 v[154:155], off
	v_lshl_add_u64 v[154:155], v[218:219], 0, s[94:95]
	s_add_i32 m0, s23, 0x2000
	s_nop 0
	global_load_lds_dwordx4 v[154:155], off
	s_waitcnt lgkmcnt(0)
	s_setprio 1
	s_barrier
	v_mfma_f32_16x16x32_bf16 v[116:119], v[226:229], v[186:189], v[116:119]
	v_mfma_f32_16x16x32_bf16 v[112:115], v[234:237], v[186:189], v[112:115]
	v_mfma_f32_16x16x32_bf16 v[100:103], v[226:229], v[194:197], v[100:103]
	v_mfma_f32_16x16x32_bf16 v[96:99], v[234:237], v[194:197], v[96:99]
	v_mfma_f32_16x16x32_bf16 v[84:87], v[226:229], v[202:205], v[84:87]
	v_mfma_f32_16x16x32_bf16 v[80:83], v[234:237], v[202:205], v[80:83]
	v_mfma_f32_16x16x32_bf16 v[68:71], v[226:229], v[210:213], v[68:71]
	v_mfma_f32_16x16x32_bf16 v[64:67], v[234:237], v[210:213], v[64:67]
	v_mfma_f32_16x16x32_bf16 v[116:119], v[230:233], v[190:193], v[116:119]
	s_mov_b32 m0, s34
	v_mfma_f32_16x16x32_bf16 v[112:115], v[238:241], v[190:193], v[112:115]
	v_lshl_add_u64 v[154:155], v[220:221], 0, s[94:95]
	v_mfma_f32_16x16x32_bf16 v[100:103], v[230:233], v[198:201], v[100:103]
	v_mfma_f32_16x16x32_bf16 v[96:99], v[238:241], v[198:201], v[96:99]
	v_mfma_f32_16x16x32_bf16 v[84:87], v[230:233], v[206:209], v[84:87]
	v_mfma_f32_16x16x32_bf16 v[80:83], v[238:241], v[206:209], v[80:83]
	v_mfma_f32_16x16x32_bf16 v[68:71], v[230:233], v[214:217], v[68:71]
	v_mfma_f32_16x16x32_bf16 v[64:67], v[238:241], v[214:217], v[64:67]
	s_setprio 0
	s_barrier
	ds_read_b128 v[186:189], v137 offset:49152
	ds_read_b128 v[190:193], v137 offset:50176
	ds_read_b128 v[194:197], v137 offset:51200
	ds_read_b128 v[198:201], v137 offset:52224
	ds_read_b128 v[202:205], v137 offset:53248
	ds_read_b128 v[206:209], v137 offset:54272
	ds_read_b128 v[210:213], v137 offset:55296
	ds_read_b128 v[214:217], v137 offset:56320
	global_load_lds_dwordx4 v[154:155], off
	v_lshl_add_u64 v[154:155], v[242:243], 0, s[94:95]
	s_mov_b32 m0, s35
	s_nop 0
	global_load_lds_dwordx4 v[154:155], off
	s_waitcnt lgkmcnt(0)
	s_setprio 1
	s_barrier
; #define PG8_STAGE(bufoff, gbase) do { _Pragma("unroll") for (int _i = 0; _i < 2; ++_i) \
;         __builtin_amdgcn_global_load_lds((const unsigned*)((const char*)(gbase) + voff[_i]), (LAS unsigned*)(lds + (bufoff) + ldsw + _i * 8192), 16, 0, 0); } while (0)
; #define PG8_LDA(dst, b, h) do { _Pragma("unroll") for (int m = 0; m < 4; ++m) _Pragma("unroll") for (int k = 0; k < 2; ++k) dst[m][k] = *(const LAS bf16x8*)(lds + PG8_SA(b, h) + aoff + m * 2048 + k * 1024); } while (0)
; #define PG8_LDB(dst, b, h) do { _Pragma("unroll") for (int n = 0; n < 2; ++n) _Pragma("unroll") for (int k = 0; k < 2; ++k) dst[n][k] = *(const LAS bf16x8*)(lds + PG8_SB(b, h) + boff + n * 2048 + k * 1024); } while (0)
; #define PG8_MMA(ai, bj, At, Bt) do { __builtin_amdgcn_s_setprio(1); _Pragma("unroll") for (int m = 0; m < 4; ++m) _Pragma("unroll") for (int n = 0; n < 2; ++n) _Pragma("unroll") for (int k = 0; k < 2; ++k) \
;         acc[ai][bj][m][n] = __builtin_amdgcn_mfma_f32_16x16x32_bf16(Bt[n][k], At[m][k], acc[ai][bj][m][n], 0, 0, 0); __builtin_amdgcn_s_setprio(0); } while (0)
; #define PG8_WAIT_V(n) asm volatile("s_waitcnt vmcnt(" #n ")" ::: "memory")
; #define PG8_BAR __builtin_amdgcn_s_barrier()
; template <class Epi>
; DI void gemm_phase(LAS unsigned char* lds, const Gemm g, const StaticOrder& S, const Epi& E) {
;     ...
;             PG8_LDB(B1, 1, 1); PG8_STAGE(PG8_SB(1, 0), b3);
;             PG8_BAR; PG8_WAIT_L(0); PG8_MMA(0, 1, At, B1); PG8_BAR;
;             PG8_LDA(At, 1, 1); PG8_STAGE(PG8_SA(1, 0), a3);
;             PG8_BAR; PG8_WAIT_L(0); PG8_MMA(1, 0, At, B0); PG8_BAR; PG8_SCHED;
;             PG8_STAGE(PG8_SB(1, 1), b3 + hstep);
;             PG8_WAIT_V(6); PG8_BAR; PG8_MMA(1, 1, At, B1); PG8_BAR;
;     DI void operator()(const f32x4 (&acc)[2][2][4][2], const Unit& u, int wr, int wc, int fr, int fq) const {
;     ...
;             for (int m = 0; m < 4; ++m) { float hv[8];
; #pragma unroll
;                 for (int n = 0; n < 2; ++n)
; #pragma unroll
;                     for (int e = 0; e < 4; ++e) { const float gt = acc[ai][0][m][n][e], up = acc[ai][1][m][n][e];
;                         hv[n * 4 + e] = gt * __builtin_amdgcn_rcpf(1.f + __builtin_amdgcn_exp2f(-1.4426950408889634f * gt)) * up; }
;                 *(u32x4*)(H + (size_t)(row0 + ai * HALF + m * 16) * DFF + col0) = (u32x4){pk(hv[0], hv[1]), pk(hv[2], hv[3]), pk(hv[4], hv[5]), pk(hv[6], hv[7])}; }
	v_mfma_f32_16x16x32_bf16 v[60:63], v[138:141], v[186:189], v[60:63]
	v_mfma_f32_16x16x32_bf16 v[56:59], v[146:149], v[186:189], v[56:59]
	v_mfma_f32_16x16x32_bf16 v[44:47], v[138:141], v[194:197], v[44:47]
	v_mfma_f32_16x16x32_bf16 v[40:43], v[146:149], v[194:197], v[40:43]
	v_mfma_f32_16x16x32_bf16 v[28:31], v[138:141], v[202:205], v[28:31]
	v_mfma_f32_16x16x32_bf16 v[24:27], v[146:149], v[202:205], v[24:27]
	v_mfma_f32_16x16x32_bf16 v[12:15], v[138:141], v[210:213], v[12:15]
	v_mfma_f32_16x16x32_bf16 v[8:11], v[146:149], v[210:213], v[8:11]
	v_mfma_f32_16x16x32_bf16 v[60:63], v[142:145], v[190:193], v[60:63]
	v_mfma_f32_16x16x32_bf16 v[56:59], v[150:153], v[190:193], v[56:59]
	v_mfma_f32_16x16x32_bf16 v[44:47], v[142:145], v[198:201], v[44:47]
	v_mfma_f32_16x16x32_bf16 v[40:43], v[150:153], v[198:201], v[40:43]
	v_mfma_f32_16x16x32_bf16 v[28:31], v[142:145], v[206:209], v[28:31]
	v_mfma_f32_16x16x32_bf16 v[24:27], v[150:153], v[206:209], v[24:27]
	v_mfma_f32_16x16x32_bf16 v[12:15], v[142:145], v[214:217], v[12:15]
	v_mfma_f32_16x16x32_bf16 v[8:11], v[150:153], v[214:217], v[8:11]
	s_setprio 0
	s_barrier
	s_add_u32 s20, s20, 0x80080
	s_addc_u32 s21, s21, 0
	s_add_i32 s22, s22, s27
	v_lshl_add_u64 v[138:139], s[20:21], 0, v[158:159]
	s_mov_b32 m0, s22
	s_nop 0
	global_load_lds_dwordx4 v[138:139], off
	v_lshl_add_u64 v[138:139], s[20:21], 0, v[128:129]
	s_add_i32 m0, s22, 0x2000
	s_nop 0
	global_load_lds_dwordx4 v[138:139], off
	s_waitcnt vmcnt(6)
	s_setprio 1
	s_barrier
	v_mfma_f32_16x16x32_bf16 v[52:55], v[226:229], v[186:189], v[52:55]
	v_mfma_f32_16x16x32_bf16 v[48:51], v[234:237], v[186:189], v[48:51]
	v_mfma_f32_16x16x32_bf16 v[36:39], v[226:229], v[194:197], v[36:39]
	v_mfma_f32_16x16x32_bf16 v[32:35], v[234:237], v[194:197], v[32:35]
	v_mfma_f32_16x16x32_bf16 v[20:23], v[226:229], v[202:205], v[20:23]
	v_mfma_f32_16x16x32_bf16 v[16:19], v[234:237], v[202:205], v[16:19]
	v_mfma_f32_16x16x32_bf16 v[4:7], v[226:229], v[210:213], v[4:7]
	v_mfma_f32_16x16x32_bf16 v[0:3], v[234:237], v[210:213], v[0:3]
	v_mfma_f32_16x16x32_bf16 v[52:55], v[230:233], v[190:193], v[52:55]
	s_add_i32 s38, s38, 2
	v_mfma_f32_16x16x32_bf16 v[48:51], v[238:241], v[190:193], v[48:51]
	s_add_u32 s18, s18, 0x100
	v_mfma_f32_16x16x32_bf16 v[36:39], v[230:233], v[198:201], v[36:39]
	s_addc_u32 s19, s19, 0
	v_mfma_f32_16x16x32_bf16 v[32:35], v[238:241], v[198:201], v[32:35]
	s_add_u32 s33, s33, 0x100
	v_mfma_f32_16x16x32_bf16 v[20:23], v[230:233], v[206:209], v[20:23]
	s_addc_u32 s37, s37, 0
	v_mfma_f32_16x16x32_bf16 v[16:19], v[238:241], v[206:209], v[16:19]
	s_cmp_gt_u32 s38, 29
	v_mfma_f32_16x16x32_bf16 v[4:7], v[230:233], v[214:217], v[4:7]
	v_mfma_f32_16x16x32_bf16 v[0:3], v[238:241], v[214:217], v[0:3]
	s_setprio 0
	s_barrier
	s_cbranch_scc0 .LBB0_37
	v_mul_f32_e32 v139, 0xbfb8aa3b, v124
	v_exp_f32_e32 v139, v139
	v_lshl_or_b32 v140, s2, 7, v136
	v_lshl_add_u32 v138, s3, 8, v134
	v_ashrrev_i32_e32 v141, 31, v140
	v_add_f32_e32 v139, 1.0, v139
	v_rcp_f32_e32 v142, v139
	v_mul_f32_e32 v139, 0xbfb8aa3b, v125
	v_exp_f32_e32 v139, v139
	s_movk_i32 s4, 0x2c00
	s_and_b64 vcc, exec, s[6:7]
	s_mov_b64 s[20:21], s[16:17]
	v_add_f32_e32 v139, 1.0, v139
	v_rcp_f32_e32 v143, v139
	v_mul_f32_e32 v139, 0xbfb8aa3b, v126
	v_exp_f32_e32 v139, v139
	s_mov_b64 s[18:19], s[14:15]
	v_pk_mul_f32 v[124:125], v[124:125], v[142:143]
	v_add_f32_e32 v139, 1.0, v139
	v_rcp_f32_e32 v144, v139
	v_mul_f32_e32 v139, 0xbfb8aa3b, v127
	v_exp_f32_e32 v139, v139
	v_pk_mul_f32 v[116:117], v[124:125], v[116:117]
	v_add_f32_e32 v139, 1.0, v139
	v_rcp_f32_e32 v145, v139
	v_mul_f32_e32 v139, 0xbfb8aa3b, v120
	v_exp_f32_e32 v139, v139
	v_cvt_pk_bf16_f32 v116, v116, v117
	v_pk_mul_f32 v[124:125], v[126:127], v[144:145]
	v_add_f32_e32 v139, 1.0, v139
	v_rcp_f32_e32 v146, v139
	v_mul_f32_e32 v139, 0xbfb8aa3b, v121
	v_exp_f32_e32 v139, v139
	v_pk_mul_f32 v[118:119], v[124:125], v[118:119]
	v_add_f32_e32 v139, 1.0, v139
	v_rcp_f32_e32 v147, v139
	v_mul_f32_e32 v139, 0xbfb8aa3b, v122
	v_exp_f32_e32 v139, v139
	v_cvt_pk_bf16_f32 v117, v118, v119
	v_pk_mul_f32 v[118:119], v[120:121], v[146:147]
	v_add_f32_e32 v139, 1.0, v139
	v_rcp_f32_e32 v148, v139
	v_mul_f32_e32 v139, 0xbfb8aa3b, v123
	v_exp_f32_e32 v139, v139
	v_pk_mul_f32 v[112:113], v[118:119], v[112:113]
	v_add_f32_e32 v139, 1.0, v139
	v_rcp_f32_e32 v149, v139
	v_cvt_pk_bf16_f32 v118, v112, v113
	v_pk_mul_f32 v[112:113], v[122:123], v[148:149]
	s_nop 0
	v_pk_mul_f32 v[112:113], v[112:113], v[114:115]
	v_lshlrev_b64 v[114:115], 1, v[140:141]
	v_cvt_pk_bf16_f32 v119, v112, v113
	v_mov_b64_e32 v[112:113], s[54:55]
	v_mad_i64_i32 v[120:121], s[2:3], v138, s4, v[112:113]
	v_lshl_add_u64 v[120:121], v[120:121], 0, v[114:115]
	global_store_dwordx4 v[120:121], v[116:119], off
	v_mul_f32_e32 v120, 0xbfb8aa3b, v104
	v_mul_f32_e32 v121, 0xbfb8aa3b, v105
	v_mul_f32_e32 v116, 0xbfb8aa3b, v108
	v_mul_f32_e32 v117, 0xbfb8aa3b, v109
	v_exp_f32_e32 v116, v116
	v_exp_f32_e32 v117, v117
	v_mul_f32_e32 v118, 0xbfb8aa3b, v110
	v_mul_f32_e32 v119, 0xbfb8aa3b, v111
	v_exp_f32_e32 v118, v118
	v_exp_f32_e32 v119, v119
	v_exp_f32_e32 v120, v120
	v_exp_f32_e32 v121, v121
	v_add_f32_e32 v116, 1.0, v116
	v_add_f32_e32 v117, 1.0, v117
	v_mul_f32_e32 v122, 0xbfb8aa3b, v106
	v_mul_f32_e32 v123, 0xbfb8aa3b, v107
	v_rcp_f32_e32 v116, v116
	v_rcp_f32_e32 v117, v117
	v_add_f32_e32 v118, 1.0, v118
	v_add_f32_e32 v119, 1.0, v119
	v_exp_f32_e32 v122, v122
	v_exp_f32_e32 v123, v123
	v_rcp_f32_e32 v118, v118
	v_rcp_f32_e32 v119, v119
	v_add_f32_e32 v120, 1.0, v120
	v_add_f32_e32 v121, 1.0, v121
	v_rcp_f32_e32 v120, v120
	v_rcp_f32_e32 v121, v121
	v_add_f32_e32 v122, 1.0, v122
;     DI void operator()(const f32x4 (&acc)[2][2][4][2], const Unit& u, int wr, int wc, int fr, int fq) const {
;     ...
;         for (int ai = 0; ai < 2; ++ai)
; #pragma unroll
;             for (int m = 0; m < 4; ++m) { float hv[8];
; #pragma unroll
;                 for (int n = 0; n < 2; ++n)
; #pragma unroll
;                     for (int e = 0; e < 4; ++e) { const float gt = acc[ai][0][m][n][e], up = acc[ai][1][m][n][e];
;                         hv[n * 4 + e] = gt * __builtin_amdgcn_rcpf(1.f + __builtin_amdgcn_exp2f(-1.4426950408889634f * gt)) * up; }
;                 *(u32x4*)(H + (size_t)(row0 + ai * HALF + m * 16) * DFF + col0) = (u32x4){pk(hv[0], hv[1]), pk(hv[2], hv[3]), pk(hv[4], hv[5]), pk(hv[6], hv[7])}; }
	v_add_f32_e32 v123, 1.0, v123
	v_pk_mul_f32 v[108:109], v[108:109], v[116:117]
	v_rcp_f32_e32 v122, v122
	v_rcp_f32_e32 v123, v123
	v_pk_mul_f32 v[100:101], v[108:109], v[100:101]
	v_pk_mul_f32 v[108:109], v[110:111], v[118:119]
	v_cvt_pk_bf16_f32 v100, v100, v101
	v_pk_mul_f32 v[102:103], v[108:109], v[102:103]
	s_nop 0
	v_cvt_pk_bf16_f32 v101, v102, v103
	v_pk_mul_f32 v[102:103], v[104:105], v[120:121]
	s_nop 0
	v_pk_mul_f32 v[96:97], v[102:103], v[96:97]
	s_nop 0
	v_cvt_pk_bf16_f32 v102, v96, v97
	v_pk_mul_f32 v[96:97], v[106:107], v[122:123]
	s_nop 0
	v_pk_mul_f32 v[96:97], v[96:97], v[98:99]
	v_mul_f32_e32 v98, 0xbfb8aa3b, v94
	v_cvt_pk_bf16_f32 v103, v96, v97
	v_or_b32_e32 v96, 16, v138
	v_mad_i64_i32 v[96:97], s[2:3], v96, s4, v[112:113]
	v_lshl_add_u64 v[96:97], v[96:97], 0, v[114:115]
	global_store_dwordx4 v[96:97], v[100:103], off
	v_mul_f32_e32 v96, 0xbfb8aa3b, v92
	v_mul_f32_e32 v97, 0xbfb8aa3b, v93
	v_exp_f32_e32 v96, v96
	v_exp_f32_e32 v97, v97
	v_mul_f32_e32 v99, 0xbfb8aa3b, v95
	v_exp_f32_e32 v98, v98
	v_exp_f32_e32 v99, v99
	v_mul_f32_e32 v100, 0xbfb8aa3b, v88
	v_mul_f32_e32 v101, 0xbfb8aa3b, v89
	v_exp_f32_e32 v100, v100
	v_exp_f32_e32 v101, v101
	v_add_f32_e32 v96, 1.0, v96
	v_add_f32_e32 v97, 1.0, v97
	v_mul_f32_e32 v102, 0xbfb8aa3b, v90
	v_mul_f32_e32 v103, 0xbfb8aa3b, v91
	v_rcp_f32_e32 v96, v96
	v_rcp_f32_e32 v97, v97
	v_add_f32_e32 v98, 1.0, v98
	v_add_f32_e32 v99, 1.0, v99
	v_exp_f32_e32 v102, v102
	v_exp_f32_e32 v103, v103
	v_rcp_f32_e32 v98, v98
	v_rcp_f32_e32 v99, v99
	v_add_f32_e32 v100, 1.0, v100
	v_add_f32_e32 v101, 1.0, v101
	v_rcp_f32_e32 v100, v100
	v_rcp_f32_e32 v101, v101
	v_add_f32_e32 v102, 1.0, v102
	v_add_f32_e32 v103, 1.0, v103
	v_pk_mul_f32 v[92:93], v[92:93], v[96:97]
	v_rcp_f32_e32 v102, v102
	v_rcp_f32_e32 v103, v103
	v_pk_mul_f32 v[84:85], v[92:93], v[84:85]
	v_pk_mul_f32 v[92:93], v[94:95], v[98:99]
	v_cvt_pk_bf16_f32 v84, v84, v85
	v_pk_mul_f32 v[86:87], v[92:93], v[86:87]
	s_nop 0
	v_cvt_pk_bf16_f32 v85, v86, v87
	v_pk_mul_f32 v[86:87], v[88:89], v[100:101]
	s_nop 0
	v_pk_mul_f32 v[80:81], v[86:87], v[80:81]
	s_nop 0
	v_cvt_pk_bf16_f32 v86, v80, v81
	v_pk_mul_f32 v[80:81], v[90:91], v[102:103]
	s_nop 0
	v_pk_mul_f32 v[80:81], v[80:81], v[82:83]
	v_mul_f32_e32 v82, 0xbfb8aa3b, v78
	v_cvt_pk_bf16_f32 v87, v80, v81
	v_or_b32_e32 v80, 32, v138
	v_mad_i64_i32 v[80:81], s[2:3], v80, s4, v[112:113]
	v_lshl_add_u64 v[80:81], v[80:81], 0, v[114:115]
	global_store_dwordx4 v[80:81], v[84:87], off
	v_mul_f32_e32 v80, 0xbfb8aa3b, v76
	v_mul_f32_e32 v81, 0xbfb8aa3b, v77
	v_exp_f32_e32 v80, v80
	v_exp_f32_e32 v81, v81
	v_mul_f32_e32 v83, 0xbfb8aa3b, v79
	v_exp_f32_e32 v82, v82
	v_exp_f32_e32 v83, v83
	v_mul_f32_e32 v84, 0xbfb8aa3b, v72
	v_mul_f32_e32 v85, 0xbfb8aa3b, v73
	v_exp_f32_e32 v84, v84
	v_exp_f32_e32 v85, v85
	v_add_f32_e32 v80, 1.0, v80
	v_add_f32_e32 v81, 1.0, v81
	v_mul_f32_e32 v86, 0xbfb8aa3b, v74
	v_mul_f32_e32 v87, 0xbfb8aa3b, v75
	v_rcp_f32_e32 v80, v80
	v_rcp_f32_e32 v81, v81
	v_add_f32_e32 v82, 1.0, v82
	v_add_f32_e32 v83, 1.0, v83
	v_exp_f32_e32 v86, v86
	v_exp_f32_e32 v87, v87
	v_rcp_f32_e32 v82, v82
	v_rcp_f32_e32 v83, v83
	v_add_f32_e32 v84, 1.0, v84
	v_add_f32_e32 v85, 1.0, v85
	v_rcp_f32_e32 v84, v84
	v_rcp_f32_e32 v85, v85
	v_add_f32_e32 v86, 1.0, v86
	v_add_f32_e32 v87, 1.0, v87
	v_pk_mul_f32 v[76:77], v[76:77], v[80:81]
	v_rcp_f32_e32 v86, v86
	v_rcp_f32_e32 v87, v87
	v_pk_mul_f32 v[68:69], v[76:77], v[68:69]
	v_pk_mul_f32 v[76:77], v[78:79], v[82:83]
	v_cvt_pk_bf16_f32 v68, v68, v69
	v_pk_mul_f32 v[70:71], v[76:77], v[70:71]
	s_nop 0
	v_cvt_pk_bf16_f32 v69, v70, v71
	v_pk_mul_f32 v[70:71], v[72:73], v[84:85]
	v_add_u32_e32 v72, 0x80, v138
	v_pk_mul_f32 v[64:65], v[70:71], v[64:65]
	s_nop 0
	v_cvt_pk_bf16_f32 v70, v64, v65
	v_pk_mul_f32 v[64:65], v[74:75], v[86:87]
	s_nop 0
	v_pk_mul_f32 v[64:65], v[64:65], v[66:67]
	v_mul_f32_e32 v66, 0xbfb8aa3b, v62
	v_cvt_pk_bf16_f32 v71, v64, v65
	v_or_b32_e32 v64, 48, v138
	v_mad_i64_i32 v[64:65], s[2:3], v64, s4, v[112:113]
	v_lshl_add_u64 v[64:65], v[64:65], 0, v[114:115]
	global_store_dwordx4 v[64:65], v[68:71], off
	v_mul_f32_e32 v64, 0xbfb8aa3b, v60
	v_mul_f32_e32 v65, 0xbfb8aa3b, v61
	v_exp_f32_e32 v64, v64
	v_exp_f32_e32 v65, v65
	v_mul_f32_e32 v67, 0xbfb8aa3b, v63
	v_exp_f32_e32 v66, v66
	v_exp_f32_e32 v67, v67
	v_mul_f32_e32 v68, 0xbfb8aa3b, v56
	v_mul_f32_e32 v69, 0xbfb8aa3b, v57
	v_exp_f32_e32 v68, v68
	v_exp_f32_e32 v69, v69
	v_add_f32_e32 v64, 1.0, v64
	v_add_f32_e32 v65, 1.0, v65
	v_mul_f32_e32 v70, 0xbfb8aa3b, v58
	v_mul_f32_e32 v71, 0xbfb8aa3b, v59
	v_rcp_f32_e32 v64, v64
	v_rcp_f32_e32 v65, v65
	v_add_f32_e32 v66, 1.0, v66
	v_add_f32_e32 v67, 1.0, v67
	v_exp_f32_e32 v70, v70
	v_exp_f32_e32 v71, v71
	v_rcp_f32_e32 v66, v66
	v_rcp_f32_e32 v67, v67
	v_add_f32_e32 v68, 1.0, v68
	v_add_f32_e32 v69, 1.0, v69
	v_rcp_f32_e32 v68, v68
	v_rcp_f32_e32 v69, v69
	v_add_f32_e32 v70, 1.0, v70
	v_add_f32_e32 v71, 1.0, v71
	v_pk_mul_f32 v[60:61], v[60:61], v[64:65]
	v_rcp_f32_e32 v70, v70
	v_rcp_f32_e32 v71, v71
	v_pk_mul_f32 v[52:53], v[60:61], v[52:53]
	v_pk_mul_f32 v[60:61], v[62:63], v[66:67]
	v_cvt_pk_bf16_f32 v52, v52, v53
	v_pk_mul_f32 v[54:55], v[60:61], v[54:55]
	s_nop 0
	v_cvt_pk_bf16_f32 v53, v54, v55
	v_pk_mul_f32 v[54:55], v[56:57], v[68:69]
; #define PG8_WAIT_V(n) asm volatile("s_waitcnt vmcnt(" #n ")" ::: "memory")
; #define PG8_BAR __builtin_amdgcn_s_barrier()
; template <class Epi>
; DI void gemm_phase(LAS unsigned char* lds, const Gemm g, const StaticOrder& S, const Epi& E) {
;     ...
;         E(acc, cur, wr, wc, fr, fq);
;         if (!has_next) break;
; #pragma unroll
;         for (int a = 0; a < 2; ++a)
; #pragma unroll
;             for (int b = 0; b < 2; ++b)
; #pragma unroll
;                 for (int m = 0; m < 4; ++m)
; #pragma unroll
;                     for (int n = 0; n < 2; ++n) acc[a][b][m][n] = (f32x4){0.f, 0.f, 0.f, 0.f};
;         cur = nxt; cA = nA; cB = nB; ++ui;
;     }
;     PG8_WAIT_V(0);
;     if (wr == 0) PG8_BAR;
;     DI void operator()(const f32x4 (&acc)[2][2][4][2], const Unit& u, int wr, int wc, int fr, int fq) const {
;     ...
;             for (int m = 0; m < 4; ++m) { float hv[8];
; #pragma unroll
;                 for (int n = 0; n < 2; ++n)
; #pragma unroll
;                     for (int e = 0; e < 4; ++e) { const float gt = acc[ai][0][m][n][e], up = acc[ai][1][m][n][e];
;                         hv[n * 4 + e] = gt * __builtin_amdgcn_rcpf(1.f + __builtin_amdgcn_exp2f(-1.4426950408889634f * gt)) * up; }
;                 *(u32x4*)(H + (size_t)(row0 + ai * HALF + m * 16) * DFF + col0) = (u32x4){pk(hv[0], hv[1]), pk(hv[2], hv[3]), pk(hv[4], hv[5]), pk(hv[6], hv[7])}; }
	s_nop 0
	v_pk_mul_f32 v[48:49], v[54:55], v[48:49]
	s_nop 0
	v_cvt_pk_bf16_f32 v54, v48, v49
	v_pk_mul_f32 v[48:49], v[58:59], v[70:71]
	s_nop 0
	v_pk_mul_f32 v[48:49], v[48:49], v[50:51]
	v_mul_f32_e32 v50, 0xbfb8aa3b, v46
	v_cvt_pk_bf16_f32 v55, v48, v49
	v_mad_i64_i32 v[48:49], s[2:3], v72, s4, v[112:113]
	v_lshl_add_u64 v[48:49], v[48:49], 0, v[114:115]
	global_store_dwordx4 v[48:49], v[52:55], off
	v_mul_f32_e32 v48, 0xbfb8aa3b, v44
	v_mul_f32_e32 v49, 0xbfb8aa3b, v45
	v_exp_f32_e32 v48, v48
	v_exp_f32_e32 v49, v49
	v_mul_f32_e32 v51, 0xbfb8aa3b, v47
	v_exp_f32_e32 v50, v50
	v_exp_f32_e32 v51, v51
	v_mul_f32_e32 v52, 0xbfb8aa3b, v40
	v_mul_f32_e32 v53, 0xbfb8aa3b, v41
	v_exp_f32_e32 v52, v52
	v_exp_f32_e32 v53, v53
	v_add_f32_e32 v48, 1.0, v48
	v_add_f32_e32 v49, 1.0, v49
	v_mul_f32_e32 v54, 0xbfb8aa3b, v42
	v_mul_f32_e32 v55, 0xbfb8aa3b, v43
	v_rcp_f32_e32 v48, v48
	v_rcp_f32_e32 v49, v49
	v_add_f32_e32 v50, 1.0, v50
	v_add_f32_e32 v51, 1.0, v51
	v_exp_f32_e32 v54, v54
	v_exp_f32_e32 v55, v55
	v_rcp_f32_e32 v50, v50
	v_rcp_f32_e32 v51, v51
	v_add_f32_e32 v52, 1.0, v52
	v_add_f32_e32 v53, 1.0, v53
	v_rcp_f32_e32 v52, v52
	v_rcp_f32_e32 v53, v53
	v_add_f32_e32 v54, 1.0, v54
	v_add_f32_e32 v55, 1.0, v55
	v_pk_mul_f32 v[44:45], v[44:45], v[48:49]
	v_rcp_f32_e32 v54, v54
	v_rcp_f32_e32 v55, v55
	v_pk_mul_f32 v[36:37], v[44:45], v[36:37]
	v_pk_mul_f32 v[44:45], v[46:47], v[50:51]
	v_cvt_pk_bf16_f32 v36, v36, v37
	v_pk_mul_f32 v[38:39], v[44:45], v[38:39]
	s_nop 0
	v_cvt_pk_bf16_f32 v37, v38, v39
	v_pk_mul_f32 v[38:39], v[40:41], v[52:53]
	s_nop 0
	v_pk_mul_f32 v[32:33], v[38:39], v[32:33]
	s_nop 0
	v_cvt_pk_bf16_f32 v38, v32, v33
	v_pk_mul_f32 v[32:33], v[42:43], v[54:55]
	s_nop 0
	v_pk_mul_f32 v[32:33], v[32:33], v[34:35]
	v_mul_f32_e32 v34, 0xbfb8aa3b, v30
	v_cvt_pk_bf16_f32 v39, v32, v33
	v_add_u32_e32 v32, 0x90, v138
	v_mad_i64_i32 v[32:33], s[2:3], v32, s4, v[112:113]
	v_lshl_add_u64 v[32:33], v[32:33], 0, v[114:115]
	global_store_dwordx4 v[32:33], v[36:39], off
	v_mul_f32_e32 v32, 0xbfb8aa3b, v28
	v_mul_f32_e32 v33, 0xbfb8aa3b, v29
	v_exp_f32_e32 v32, v32
	v_exp_f32_e32 v33, v33
	v_mul_f32_e32 v35, 0xbfb8aa3b, v31
	v_exp_f32_e32 v34, v34
	v_exp_f32_e32 v35, v35
	v_mul_f32_e32 v36, 0xbfb8aa3b, v24
	v_mul_f32_e32 v37, 0xbfb8aa3b, v25
	v_exp_f32_e32 v36, v36
	v_exp_f32_e32 v37, v37
	v_add_f32_e32 v32, 1.0, v32
	v_add_f32_e32 v33, 1.0, v33
	v_mul_f32_e32 v38, 0xbfb8aa3b, v26
	v_mul_f32_e32 v39, 0xbfb8aa3b, v27
	v_rcp_f32_e32 v32, v32
	v_rcp_f32_e32 v33, v33
	v_add_f32_e32 v34, 1.0, v34
	v_add_f32_e32 v35, 1.0, v35
	v_exp_f32_e32 v38, v38
	v_exp_f32_e32 v39, v39
	v_rcp_f32_e32 v34, v34
	v_rcp_f32_e32 v35, v35
	v_add_f32_e32 v36, 1.0, v36
	v_add_f32_e32 v37, 1.0, v37
	v_rcp_f32_e32 v36, v36
	v_rcp_f32_e32 v37, v37
	v_add_f32_e32 v38, 1.0, v38
	v_add_f32_e32 v39, 1.0, v39
	v_pk_mul_f32 v[28:29], v[28:29], v[32:33]
	v_rcp_f32_e32 v38, v38
	v_rcp_f32_e32 v39, v39
	v_pk_mul_f32 v[20:21], v[28:29], v[20:21]
	v_pk_mul_f32 v[28:29], v[30:31], v[34:35]
	v_cvt_pk_bf16_f32 v20, v20, v21
	v_pk_mul_f32 v[22:23], v[28:29], v[22:23]
	s_nop 0
	v_cvt_pk_bf16_f32 v21, v22, v23
	v_pk_mul_f32 v[22:23], v[24:25], v[36:37]
	s_nop 0
	v_pk_mul_f32 v[16:17], v[22:23], v[16:17]
	s_nop 0
	v_cvt_pk_bf16_f32 v22, v16, v17
	v_pk_mul_f32 v[16:17], v[26:27], v[38:39]
	s_nop 0
	v_pk_mul_f32 v[16:17], v[16:17], v[18:19]
	v_mul_f32_e32 v18, 0xbfb8aa3b, v14
	v_cvt_pk_bf16_f32 v23, v16, v17
	v_add_u32_e32 v16, 0xa0, v138
	v_mad_i64_i32 v[16:17], s[2:3], v16, s4, v[112:113]
	v_lshl_add_u64 v[16:17], v[16:17], 0, v[114:115]
	global_store_dwordx4 v[16:17], v[20:23], off
	v_mul_f32_e32 v16, 0xbfb8aa3b, v12
	v_mul_f32_e32 v17, 0xbfb8aa3b, v13
	v_exp_f32_e32 v16, v16
	v_exp_f32_e32 v17, v17
	v_mul_f32_e32 v19, 0xbfb8aa3b, v15
	v_exp_f32_e32 v18, v18
	v_exp_f32_e32 v19, v19
	v_mul_f32_e32 v20, 0xbfb8aa3b, v8
	v_mul_f32_e32 v21, 0xbfb8aa3b, v9
	v_exp_f32_e32 v20, v20
	v_exp_f32_e32 v21, v21
	v_add_f32_e32 v16, 1.0, v16
	v_add_f32_e32 v17, 1.0, v17
	v_mul_f32_e32 v22, 0xbfb8aa3b, v10
	v_mul_f32_e32 v23, 0xbfb8aa3b, v11
	v_rcp_f32_e32 v16, v16
	v_rcp_f32_e32 v17, v17
	v_add_f32_e32 v18, 1.0, v18
	v_add_f32_e32 v19, 1.0, v19
	v_exp_f32_e32 v22, v22
	v_exp_f32_e32 v23, v23
	v_rcp_f32_e32 v18, v18
	v_rcp_f32_e32 v19, v19
	v_add_f32_e32 v20, 1.0, v20
	v_add_f32_e32 v21, 1.0, v21
	v_rcp_f32_e32 v20, v20
	v_rcp_f32_e32 v21, v21
	v_add_f32_e32 v22, 1.0, v22
	v_add_f32_e32 v23, 1.0, v23
	v_pk_mul_f32 v[12:13], v[12:13], v[16:17]
	v_rcp_f32_e32 v22, v22
	v_rcp_f32_e32 v23, v23
	v_pk_mul_f32 v[4:5], v[12:13], v[4:5]
	v_pk_mul_f32 v[12:13], v[14:15], v[18:19]
	v_cvt_pk_bf16_f32 v4, v4, v5
	v_pk_mul_f32 v[6:7], v[12:13], v[6:7]
	s_nop 0
	v_cvt_pk_bf16_f32 v5, v6, v7
	v_pk_mul_f32 v[6:7], v[8:9], v[20:21]
	s_nop 0
	v_pk_mul_f32 v[0:1], v[6:7], v[0:1]
	s_nop 0
	v_cvt_pk_bf16_f32 v6, v0, v1
	v_pk_mul_f32 v[0:1], v[10:11], v[22:23]
	s_nop 0
	v_pk_mul_f32 v[0:1], v[0:1], v[2:3]
	s_nop 0
	v_cvt_pk_bf16_f32 v7, v0, v1
	v_add_u32_e32 v0, 0xb0, v138
	v_mad_i64_i32 v[0:1], s[2:3], v0, s4, v[112:113]
	v_lshl_add_u64 v[0:1], v[0:1], 0, v[114:115]
	s_mov_b32 s2, s8
	s_mov_b32 s3, s10
	global_store_dwordx4 v[0:1], v[4:7], off
	s_cbranch_vccz .LBB0_34
	s_waitcnt vmcnt(0)
	s_cmpk_gt_u32 s24, 0xff
	s_cbranch_scc1 .LBB0_41
	s_barrier

; #define PG8_STAGE(bufoff, gbase) do { _Pragma("unroll") for (int _i = 0; _i < 2; ++_i) \
;         __builtin_amdgcn_global_load_lds((const unsigned*)((const char*)(gbase) + voff[_i]), (LAS unsigned*)(lds + (bufoff) + ldsw + _i * 8192), 16, 0, 0); } while (0)
; #define PG8_WAIT_V(n) asm volatile("s_waitcnt vmcnt(" #n ")" ::: "memory")
; #define PG8_BAR __builtin_amdgcn_s_barrier()
; template <class Epi>
; DI void gemm_phase(LAS unsigned char* lds, const Gemm g, const StaticOrder& S, const Epi& E) {
;     ...
;     for (int i = 0; i < 2; ++i) { int R, C; stage_rc(tid * 16 + i * 8192, R, C); voff[i] = (unsigned)(R * K + C) * 2u; }
;     const size_t kstep = (size_t)(BK * 2);
;     const size_t hstep = (size_t)HALF * K * 2;
;     const size_t tstep = 2 * hstep;
;     const unsigned ldsw = (unsigned)wid * 1024u;
;     const int aoff = lds_byte(wr * 64 + fr, fq * 8), boff = lds_byte(wc * 32 + fr, fq * 8);
;     ...
;     if (wr == 1) PG8_BAR;
;     PG8_WAIT_V(4); PG8_BAR;
;     PG8_STAGE(PG8_SB(1, 0), cB + kstep); PG8_STAGE(PG8_SA(1, 0), cA + kstep); PG8_STAGE(PG8_SB(1, 1), cB + hstep + kstep);
;     PG8_WAIT_V(6); PG8_BAR;
.LBB0_64:
	v_mov_b32_e32 v189, v159
	v_lshl_add_u64 v[10:11], s[22:23], 0, v[188:189]
	v_mov_b32_e32 v187, v159
	v_readlane_b32 s20, v254, 21
	s_lshl_b32 s3, s3, 5
	v_lshl_add_u64 v[12:13], s[22:23], 0, v[186:187]
	v_readlane_b32 s21, v254, 22
	s_and_b32 s3, s3, 0x60
	s_add_i32 m0, s34, 0x18000
	v_lshl_add_u64 v[10:11], v[10:11], 0, s[94:95]
	v_lshl_add_u64 v[14:15], s[20:21], 0, v[188:189]
	s_lshl_b32 s6, s2, 13
	s_lshl_b32 s7, s3, 7
	s_waitcnt vmcnt(4)
	s_barrier
	global_load_lds_dwordx4 v[10:11], off
	v_lshl_add_u64 v[10:11], v[12:13], 0, s[94:95]
	s_add_i32 m0, s34, 0x1a000
	s_add_i32 s38, s34, 0x8000
	s_add_i32 s39, s34, 0xa000
	v_lshl_add_u64 v[16:17], s[20:21], 0, v[186:187]
	global_load_lds_dwordx4 v[10:11], off
	v_lshl_add_u64 v[10:11], v[14:15], 0, s[94:95]
	s_mov_b32 m0, s38
	s_add_u32 s4, s22, 0x90080
	global_load_lds_dwordx4 v[10:11], off
	v_lshl_add_u64 v[10:11], v[16:17], 0, s[94:95]
	s_mov_b32 m0, s39
	s_addc_u32 s5, s23, 0
	global_load_lds_dwordx4 v[10:11], off
	s_add_i32 m0, s34, 0x1c000
	v_lshl_add_u64 v[10:11], s[4:5], 0, v[188:189]
	global_load_lds_dwordx4 v[10:11], off
	v_lshl_add_u64 v[10:11], s[4:5], 0, v[186:187]
	s_add_i32 m0, s34, 0x1e000
	v_bfe_u32 v9, v0, 4, 2
	global_load_lds_dwordx4 v[10:11], off
	v_and_b32_e32 v10, 15, v0
	v_lshlrev_b32_e32 v11, 4, v9
	v_lshlrev_b32_e32 v0, 2, v0
	v_lshl_or_b32 v225, s2, 6, v10
	v_lshl_or_b32 v10, v10, 6, v11
	v_and_b32_e32 v0, 32, v0
	s_movk_i32 s4, 0x900
	v_bitop3_b32 v12, v10, s6, v0 bitop3:0xde
	v_bitop3_b32 v226, v10, s7, v0 bitop3:0xde
	v_add_u32_e32 v226, 0x10000, v226
	v_lshrrev_b32_e32 v6, 1, v6
	v_mul_lo_u32 v0, v5, s4
	s_mov_b32 s5, 0x9000
	v_lshl_or_b32 v227, v9, 2, s3
	v_mad_u64_u32 v[10:11], s[2:3], v6, s5, v[0:1]
	v_or_b32_e32 v0, v10, v7
	v_add_lshl_u32 v158, v0, v8, 1
	v_lshrrev_b32_e32 v1, 1, v1
	v_mul_lo_u32 v0, v2, s4
	v_mad_u64_u32 v[0:1], s[2:3], v1, s5, v[0:1]
	s_waitcnt vmcnt(6)
	s_mov_b64 s[6:7], 0x90080
	v_or_b32_e32 v0, v0, v3
	v_lshl_add_u64 v[190:191], v[158:159], 0, s[6:7]
	v_add_lshl_u32 v158, v0, v4, 1
	v_readlane_b32 s4, v254, 50
	v_lshl_add_u64 v[192:193], v[158:159], 0, s[6:7]
	s_mov_b32 s40, 0
	v_add_u32_e32 v228, 0, v12
	v_readlane_b32 s2, v254, 31
	s_mov_b32 s3, s4
	s_barrier
	v_readlane_b32 s5, v254, 51
	s_branch .LBB0_66

; #define PG8_STAGE(bufoff, gbase) do { _Pragma("unroll") for (int _i = 0; _i < 2; ++_i) \
;         __builtin_amdgcn_global_load_lds((const unsigned*)((const char*)(gbase) + voff[_i]), (LAS unsigned*)(lds + (bufoff) + ldsw + _i * 8192), 16, 0, 0); } while (0)
; #define PG8_LDA(dst, b, h) do { _Pragma("unroll") for (int m = 0; m < 4; ++m) _Pragma("unroll") for (int k = 0; k < 2; ++k) dst[m][k] = *(const LAS bf16x8*)(lds + PG8_SA(b, h) + aoff + m * 2048 + k * 1024); } while (0)
; #define PG8_LDB(dst, b, h) do { _Pragma("unroll") for (int n = 0; n < 2; ++n) _Pragma("unroll") for (int k = 0; k < 2; ++k) dst[n][k] = *(const LAS bf16x8*)(lds + PG8_SB(b, h) + boff + n * 2048 + k * 1024); } while (0)
; #define PG8_MMA(ai, bj, At, Bt) do { __builtin_amdgcn_s_setprio(1); _Pragma("unroll") for (int m = 0; m < 4; ++m) _Pragma("unroll") for (int n = 0; n < 2; ++n) _Pragma("unroll") for (int k = 0; k < 2; ++k) \
;         acc[ai][bj][m][n] = __builtin_amdgcn_mfma_f32_16x16x32_bf16(Bt[n][k], At[m][k], acc[ai][bj][m][n], 0, 0, 0); __builtin_amdgcn_s_setprio(0); } while (0)
; #define PG8_WAIT_V(n) asm volatile("s_waitcnt vmcnt(" #n ")" ::: "memory")
; #define PG8_WAIT_L(n) asm volatile("s_waitcnt lgkmcnt(" #n ")" ::: "memory")
; #define PG8_BAR __builtin_amdgcn_s_barrier()
; #define PG8_SCHED __builtin_amdgcn_sched_barrier(0)
; template <class Epi>
; DI void gemm_phase(LAS unsigned char* lds, const Gemm g, const StaticOrder& S, const Epi& E) {
;     ...
;         for (int t = 0; t < nt; t += 2) {
;             const bool last = (t == nt - 2);
;             const char* a1 = cA + (size_t)(t + 1) * kstep;
;             const char* a2 = last ? nA : cA + (size_t)(t + 2) * kstep; const char* b2 = last ? nB : cB + (size_t)(t + 2) * kstep;
;             const char* a3 = a2 + kstep; const char* b3 = b2 + kstep;
;             PG8_LDB(B0, 0, 0); PG8_SCHED; PG8_LDA(At, 0, 0); PG8_STAGE(PG8_SA(1, 1), a1 + hstep);
;             PG8_WAIT_L(8); PG8_BAR; PG8_WAIT_L(0); PG8_MMA(0, 0, At, B0); PG8_BAR; PG8_SCHED;
;             PG8_LDB(B1, 0, 1); PG8_STAGE(PG8_SB(0, 0), b2);
;             PG8_BAR; PG8_WAIT_L(0); PG8_MMA(0, 1, At, B1); PG8_BAR;
;             PG8_LDA(At, 0, 1); PG8_STAGE(PG8_SA(0, 0), a2);
;             PG8_BAR; PG8_WAIT_L(0); PG8_MMA(1, 0, At, B0); PG8_BAR; PG8_SCHED;
;             PG8_STAGE(PG8_SB(0, 1), b2 + hstep);
;             PG8_WAIT_V(6); PG8_BAR; PG8_MMA(1, 1, At, B1); PG8_BAR;
.LBB0_77:
	s_add_u32 s22, s20, 0x100
	s_addc_u32 s23, s21, 0
	s_add_i32 s43, 0, 0x10000
	ds_read_b128 v[128:131], v226
	ds_read_b128 v[132:135], v226 offset:1024
	ds_read_b128 v[136:139], v226 offset:2048
	ds_read_b128 v[140:143], v226 offset:3072
	s_cmp_eq_u32 s33, 32
	s_cselect_b32 s27, s9, s23
	s_cselect_b32 s26, s8, s22
	s_cselect_b32 s25, s11, s5
	s_cselect_b32 s24, s10, s4
	v_lshl_add_u64 v[214:215], s[20:21], 0, v[190:191]
	s_add_i32 m0, s34, 0xc000
	ds_read_b128 v[144:147], v228
	ds_read_b128 v[148:151], v228 offset:1024
	ds_read_b128 v[152:155], v228 offset:2048
	ds_read_b128 v[194:197], v228 offset:3072
	ds_read_b128 v[198:201], v228 offset:4096
	ds_read_b128 v[202:205], v228 offset:5120
	ds_read_b128 v[206:209], v228 offset:6144
	ds_read_b128 v[210:213], v228 offset:7168
	global_load_lds_dwordx4 v[214:215], off
	v_lshl_add_u64 v[214:215], s[20:21], 0, v[192:193]
	s_add_i32 m0, s34, 0xe000
	s_nop 0
	global_load_lds_dwordx4 v[214:215], off
	s_waitcnt lgkmcnt(8)
	s_setprio 1
	s_barrier
	s_waitcnt lgkmcnt(0)
	v_mfma_f32_16x16x32_bf16 v[124:127], v[128:131], v[144:147], v[124:127]
	v_mfma_f32_16x16x32_bf16 v[120:123], v[136:139], v[144:147], v[120:123]
	v_mfma_f32_16x16x32_bf16 v[116:119], v[128:131], v[152:155], v[116:119]
	v_mfma_f32_16x16x32_bf16 v[112:115], v[136:139], v[152:155], v[112:115]
	v_mfma_f32_16x16x32_bf16 v[108:111], v[128:131], v[198:201], v[108:111]
	v_mfma_f32_16x16x32_bf16 v[104:107], v[136:139], v[198:201], v[104:107]
	v_mfma_f32_16x16x32_bf16 v[100:103], v[128:131], v[206:209], v[100:103]
	v_mfma_f32_16x16x32_bf16 v[96:99], v[136:139], v[206:209], v[96:99]
	v_mfma_f32_16x16x32_bf16 v[124:127], v[132:135], v[148:151], v[124:127]
	v_mfma_f32_16x16x32_bf16 v[120:123], v[140:143], v[148:151], v[120:123]
	v_mfma_f32_16x16x32_bf16 v[116:119], v[132:135], v[194:197], v[116:119]
	v_mfma_f32_16x16x32_bf16 v[112:115], v[140:143], v[194:197], v[112:115]
	v_mfma_f32_16x16x32_bf16 v[108:111], v[132:135], v[202:205], v[108:111]
	v_mfma_f32_16x16x32_bf16 v[104:107], v[140:143], v[202:205], v[104:107]
	v_mfma_f32_16x16x32_bf16 v[100:103], v[132:135], v[210:213], v[100:103]
	v_mfma_f32_16x16x32_bf16 v[96:99], v[140:143], v[210:213], v[96:99]
	s_setprio 0
	s_barrier
	s_add_i32 s44, 0, 0x14000
	s_add_i32 s20, s43, s31
	v_lshl_add_u64 v[218:219], s[24:25], 0, v[188:189]
	s_mov_b32 m0, s20
	ds_read_b128 v[214:217], v226 offset:16384
	ds_read_b128 v[230:233], v226 offset:17408
	ds_read_b128 v[234:237], v226 offset:18432
	ds_read_b128 v[238:241], v226 offset:19456
	global_load_lds_dwordx4 v[218:219], off
	v_lshl_add_u64 v[220:221], s[24:25], 0, v[186:187]
	s_add_i32 m0, s20, 0x2000
	s_nop 0
	global_load_lds_dwordx4 v[220:221], off
	s_waitcnt lgkmcnt(0)
	s_setprio 1
	s_barrier
	v_mfma_f32_16x16x32_bf16 v[60:63], v[214:217], v[144:147], v[60:63]
	v_mfma_f32_16x16x32_bf16 v[56:59], v[234:237], v[144:147], v[56:59]
	v_mfma_f32_16x16x32_bf16 v[52:55], v[214:217], v[152:155], v[52:55]
	v_mfma_f32_16x16x32_bf16 v[48:51], v[234:237], v[152:155], v[48:51]
	v_mfma_f32_16x16x32_bf16 v[44:47], v[214:217], v[198:201], v[44:47]
	v_mfma_f32_16x16x32_bf16 v[40:43], v[234:237], v[198:201], v[40:43]
	v_mfma_f32_16x16x32_bf16 v[36:39], v[214:217], v[206:209], v[36:39]
	v_mfma_f32_16x16x32_bf16 v[32:35], v[234:237], v[206:209], v[32:35]
	v_mfma_f32_16x16x32_bf16 v[60:63], v[230:233], v[148:151], v[60:63]
	s_mov_b32 m0, s34
	v_mfma_f32_16x16x32_bf16 v[56:59], v[238:241], v[148:151], v[56:59]
	v_lshl_add_u64 v[242:243], s[26:27], 0, v[188:189]
	v_mfma_f32_16x16x32_bf16 v[52:55], v[230:233], v[194:197], v[52:55]
	v_mfma_f32_16x16x32_bf16 v[48:51], v[238:241], v[194:197], v[48:51]
	v_mfma_f32_16x16x32_bf16 v[44:47], v[230:233], v[202:205], v[44:47]
	v_mfma_f32_16x16x32_bf16 v[40:43], v[238:241], v[202:205], v[40:43]
	v_mfma_f32_16x16x32_bf16 v[36:39], v[230:233], v[210:213], v[36:39]
	v_mfma_f32_16x16x32_bf16 v[32:35], v[238:241], v[210:213], v[32:35]
	s_setprio 0
	s_barrier
	ds_read_b128 v[144:147], v228 offset:16384
	ds_read_b128 v[148:151], v228 offset:17408
	ds_read_b128 v[152:155], v228 offset:18432
	ds_read_b128 v[194:197], v228 offset:19456
	ds_read_b128 v[198:201], v228 offset:20480
	ds_read_b128 v[202:205], v228 offset:21504
	ds_read_b128 v[206:209], v228 offset:22528
	ds_read_b128 v[210:213], v228 offset:23552
	global_load_lds_dwordx4 v[242:243], off
	v_lshl_add_u64 v[244:245], s[26:27], 0, v[186:187]
	s_mov_b32 m0, s35
	s_nop 0
	global_load_lds_dwordx4 v[244:245], off
	s_waitcnt lgkmcnt(0)
	s_setprio 1
	s_barrier
	v_mfma_f32_16x16x32_bf16 v[92:95], v[128:131], v[144:147], v[92:95]
	v_mfma_f32_16x16x32_bf16 v[88:91], v[136:139], v[144:147], v[88:91]
	v_mfma_f32_16x16x32_bf16 v[84:87], v[128:131], v[152:155], v[84:87]
	v_mfma_f32_16x16x32_bf16 v[80:83], v[136:139], v[152:155], v[80:83]
	v_mfma_f32_16x16x32_bf16 v[76:79], v[128:131], v[198:201], v[76:79]
	v_mfma_f32_16x16x32_bf16 v[72:75], v[136:139], v[198:201], v[72:75]
	v_mfma_f32_16x16x32_bf16 v[68:71], v[128:131], v[206:209], v[68:71]
	v_mfma_f32_16x16x32_bf16 v[64:67], v[136:139], v[206:209], v[64:67]
	v_mfma_f32_16x16x32_bf16 v[92:95], v[132:135], v[148:151], v[92:95]
	v_mfma_f32_16x16x32_bf16 v[88:91], v[140:143], v[148:151], v[88:91]
	v_mfma_f32_16x16x32_bf16 v[84:87], v[132:135], v[194:197], v[84:87]
	v_mfma_f32_16x16x32_bf16 v[80:83], v[140:143], v[194:197], v[80:83]
	v_mfma_f32_16x16x32_bf16 v[76:79], v[132:135], v[202:205], v[76:79]
	v_mfma_f32_16x16x32_bf16 v[72:75], v[140:143], v[202:205], v[72:75]
	v_mfma_f32_16x16x32_bf16 v[68:71], v[132:135], v[210:213], v[68:71]
	v_mfma_f32_16x16x32_bf16 v[64:67], v[140:143], v[210:213], v[64:67]
	s_setprio 0
	s_barrier
; #define PG8_STAGE(bufoff, gbase) do { _Pragma("unroll") for (int _i = 0; _i < 2; ++_i) \
;         __builtin_amdgcn_global_load_lds((const unsigned*)((const char*)(gbase) + voff[_i]), (LAS unsigned*)(lds + (bufoff) + ldsw + _i * 8192), 16, 0, 0); } while (0)
; #define PG8_LDA(dst, b, h) do { _Pragma("unroll") for (int m = 0; m < 4; ++m) _Pragma("unroll") for (int k = 0; k < 2; ++k) dst[m][k] = *(const LAS bf16x8*)(lds + PG8_SA(b, h) + aoff + m * 2048 + k * 1024); } while (0)
; #define PG8_LDB(dst, b, h) do { _Pragma("unroll") for (int n = 0; n < 2; ++n) _Pragma("unroll") for (int k = 0; k < 2; ++k) dst[n][k] = *(const LAS bf16x8*)(lds + PG8_SB(b, h) + boff + n * 2048 + k * 1024); } while (0)
; #define PG8_MMA(ai, bj, At, Bt) do { __builtin_amdgcn_s_setprio(1); _Pragma("unroll") for (int m = 0; m < 4; ++m) _Pragma("unroll") for (int n = 0; n < 2; ++n) _Pragma("unroll") for (int k = 0; k < 2; ++k) \
;         acc[ai][bj][m][n] = __builtin_amdgcn_mfma_f32_16x16x32_bf16(Bt[n][k], At[m][k], acc[ai][bj][m][n], 0, 0, 0); __builtin_amdgcn_s_setprio(0); } while (0)
; #define PG8_WAIT_V(n) asm volatile("s_waitcnt vmcnt(" #n ")" ::: "memory")
; #define PG8_WAIT_L(n) asm volatile("s_waitcnt lgkmcnt(" #n ")" ::: "memory")
; #define PG8_BAR __builtin_amdgcn_s_barrier()
; #define PG8_SCHED __builtin_amdgcn_sched_barrier(0)
; template <class Epi>
; DI void gemm_phase(LAS unsigned char* lds, const Gemm g, const StaticOrder& S, const Epi& E) {
;     ...
;             PG8_LDA(At, 0, 1); PG8_STAGE(PG8_SA(0, 0), a2);
;             PG8_BAR; PG8_WAIT_L(0); PG8_MMA(1, 0, At, B0); PG8_BAR; PG8_SCHED;
;             PG8_STAGE(PG8_SB(0, 1), b2 + hstep);
;             PG8_WAIT_V(6); PG8_BAR; PG8_MMA(1, 1, At, B1); PG8_BAR;
;             PG8_LDB(B0, 1, 0); PG8_SCHED; PG8_LDA(At, 1, 0); PG8_STAGE(PG8_SA(0, 1), a2 + hstep);
;             PG8_WAIT_L(8); PG8_BAR; PG8_WAIT_L(0); PG8_MMA(0, 0, At, B0); PG8_BAR; PG8_SCHED;
;             PG8_LDB(B1, 1, 1); PG8_STAGE(PG8_SB(1, 0), b3);
;             PG8_BAR; PG8_WAIT_L(0); PG8_MMA(0, 1, At, B1); PG8_BAR;
;             PG8_LDA(At, 1, 1); PG8_STAGE(PG8_SA(1, 0), a3);
;             PG8_BAR; PG8_WAIT_L(0); PG8_MMA(1, 0, At, B0); PG8_BAR; PG8_SCHED;
	s_add_u32 s20, s24, 0x90000
	s_addc_u32 s21, s25, 0
	s_add_i32 s43, s44, s31
	v_lshl_add_u64 v[128:129], s[20:21], 0, v[188:189]
	s_mov_b32 m0, s43
	s_nop 0
	global_load_lds_dwordx4 v[128:129], off
	v_lshl_add_u64 v[128:129], s[20:21], 0, v[186:187]
	s_add_i32 m0, s43, 0x2000
	s_nop 0
	global_load_lds_dwordx4 v[128:129], off
	s_waitcnt vmcnt(6)
	s_setprio 1
	s_barrier
	v_mfma_f32_16x16x32_bf16 v[28:31], v[214:217], v[144:147], v[28:31]
	v_mfma_f32_16x16x32_bf16 v[24:27], v[234:237], v[144:147], v[24:27]
	v_mfma_f32_16x16x32_bf16 v[20:23], v[214:217], v[152:155], v[20:23]
	v_mfma_f32_16x16x32_bf16 v[16:19], v[234:237], v[152:155], v[16:19]
	v_mfma_f32_16x16x32_bf16 v[12:15], v[214:217], v[198:201], v[12:15]
	v_mfma_f32_16x16x32_bf16 v[8:11], v[234:237], v[198:201], v[8:11]
	v_mfma_f32_16x16x32_bf16 v[4:7], v[214:217], v[206:209], v[4:7]
	v_mfma_f32_16x16x32_bf16 v[0:3], v[234:237], v[206:209], v[0:3]
	v_mfma_f32_16x16x32_bf16 v[28:31], v[230:233], v[148:151], v[28:31]
	s_add_i32 s43, 0, 0x18000
	v_mfma_f32_16x16x32_bf16 v[24:27], v[238:241], v[148:151], v[24:27]
	v_mfma_f32_16x16x32_bf16 v[20:23], v[230:233], v[194:197], v[20:23]
	v_mfma_f32_16x16x32_bf16 v[16:19], v[238:241], v[194:197], v[16:19]
	v_mfma_f32_16x16x32_bf16 v[12:15], v[230:233], v[202:205], v[12:15]
	v_mfma_f32_16x16x32_bf16 v[8:11], v[238:241], v[202:205], v[8:11]
	v_mfma_f32_16x16x32_bf16 v[4:7], v[230:233], v[210:213], v[4:7]
	v_mfma_f32_16x16x32_bf16 v[0:3], v[238:241], v[210:213], v[0:3]
	s_setprio 0
	s_barrier
	ds_read_b128 v[128:131], v226 offset:32768
	ds_read_b128 v[132:135], v226 offset:33792
	ds_read_b128 v[136:139], v226 offset:34816
	ds_read_b128 v[140:143], v226 offset:35840
	s_add_u32 s20, s26, 0x90000
	s_addc_u32 s21, s27, 0
	s_mov_b32 m0, s36
	v_lshl_add_u64 v[214:215], s[20:21], 0, v[188:189]
	ds_read_b128 v[144:147], v228 offset:32768
	ds_read_b128 v[148:151], v228 offset:33792
	ds_read_b128 v[152:155], v228 offset:34816
	ds_read_b128 v[194:197], v228 offset:35840
	ds_read_b128 v[198:201], v228 offset:36864
	ds_read_b128 v[202:205], v228 offset:37888
	ds_read_b128 v[206:209], v228 offset:38912
	ds_read_b128 v[210:213], v228 offset:39936
	global_load_lds_dwordx4 v[214:215], off
	v_lshl_add_u64 v[214:215], s[20:21], 0, v[186:187]
	s_mov_b32 m0, s37
	s_nop 0
	global_load_lds_dwordx4 v[214:215], off
	s_waitcnt lgkmcnt(8)
	s_setprio 1
	s_barrier
	s_waitcnt lgkmcnt(0)
	v_mfma_f32_16x16x32_bf16 v[124:127], v[128:131], v[144:147], v[124:127]
	v_mfma_f32_16x16x32_bf16 v[120:123], v[136:139], v[144:147], v[120:123]
	v_mfma_f32_16x16x32_bf16 v[116:119], v[128:131], v[152:155], v[116:119]
	v_mfma_f32_16x16x32_bf16 v[112:115], v[136:139], v[152:155], v[112:115]
	v_mfma_f32_16x16x32_bf16 v[108:111], v[128:131], v[198:201], v[108:111]
	v_mfma_f32_16x16x32_bf16 v[104:107], v[136:139], v[198:201], v[104:107]
	v_mfma_f32_16x16x32_bf16 v[100:103], v[128:131], v[206:209], v[100:103]
	v_mfma_f32_16x16x32_bf16 v[96:99], v[136:139], v[206:209], v[96:99]
	v_mfma_f32_16x16x32_bf16 v[124:127], v[132:135], v[148:151], v[124:127]
	v_mfma_f32_16x16x32_bf16 v[120:123], v[140:143], v[148:151], v[120:123]
	v_mfma_f32_16x16x32_bf16 v[116:119], v[132:135], v[194:197], v[116:119]
	v_mfma_f32_16x16x32_bf16 v[112:115], v[140:143], v[194:197], v[112:115]
	v_mfma_f32_16x16x32_bf16 v[108:111], v[132:135], v[202:205], v[108:111]
	v_mfma_f32_16x16x32_bf16 v[104:107], v[140:143], v[202:205], v[104:107]
	v_mfma_f32_16x16x32_bf16 v[100:103], v[132:135], v[210:213], v[100:103]
	v_mfma_f32_16x16x32_bf16 v[96:99], v[140:143], v[210:213], v[96:99]
	s_setprio 0
	s_barrier
	s_add_i32 s26, 0, 0x1c000
	s_add_i32 s20, s43, s31
	v_lshl_add_u64 v[218:219], v[218:219], 0, s[94:95]
	s_mov_b32 m0, s20
	ds_read_b128 v[214:217], v226 offset:49152
	ds_read_b128 v[230:233], v226 offset:50176
	ds_read_b128 v[234:237], v226 offset:51200
	ds_read_b128 v[238:241], v226 offset:52224
	global_load_lds_dwordx4 v[218:219], off
	v_lshl_add_u64 v[218:219], v[220:221], 0, s[94:95]
	s_add_i32 m0, s20, 0x2000
	s_nop 0
	global_load_lds_dwordx4 v[218:219], off
	s_waitcnt lgkmcnt(0)
	s_setprio 1
	s_barrier
	v_mfma_f32_16x16x32_bf16 v[60:63], v[214:217], v[144:147], v[60:63]
	v_mfma_f32_16x16x32_bf16 v[56:59], v[234:237], v[144:147], v[56:59]
	v_mfma_f32_16x16x32_bf16 v[52:55], v[214:217], v[152:155], v[52:55]
	v_mfma_f32_16x16x32_bf16 v[48:51], v[234:237], v[152:155], v[48:51]
	v_mfma_f32_16x16x32_bf16 v[44:47], v[214:217], v[198:201], v[44:47]
	v_mfma_f32_16x16x32_bf16 v[40:43], v[234:237], v[198:201], v[40:43]
	v_mfma_f32_16x16x32_bf16 v[36:39], v[214:217], v[206:209], v[36:39]
	v_mfma_f32_16x16x32_bf16 v[32:35], v[234:237], v[206:209], v[32:35]
	v_mfma_f32_16x16x32_bf16 v[60:63], v[230:233], v[148:151], v[60:63]
	s_mov_b32 m0, s38
	v_mfma_f32_16x16x32_bf16 v[56:59], v[238:241], v[148:151], v[56:59]
	v_lshl_add_u64 v[218:219], v[242:243], 0, s[94:95]
	v_mfma_f32_16x16x32_bf16 v[52:55], v[230:233], v[194:197], v[52:55]
	v_mfma_f32_16x16x32_bf16 v[48:51], v[238:241], v[194:197], v[48:51]
	v_mfma_f32_16x16x32_bf16 v[44:47], v[230:233], v[202:205], v[44:47]
	v_mfma_f32_16x16x32_bf16 v[40:43], v[238:241], v[202:205], v[40:43]
	v_mfma_f32_16x16x32_bf16 v[36:39], v[230:233], v[210:213], v[36:39]
	v_mfma_f32_16x16x32_bf16 v[32:35], v[238:241], v[210:213], v[32:35]
	s_setprio 0
	s_barrier
	ds_read_b128 v[144:147], v228 offset:49152
	ds_read_b128 v[148:151], v228 offset:50176
	ds_read_b128 v[152:155], v228 offset:51200
	ds_read_b128 v[194:197], v228 offset:52224
	ds_read_b128 v[198:201], v228 offset:53248
	ds_read_b128 v[202:205], v228 offset:54272
	ds_read_b128 v[206:209], v228 offset:55296
	ds_read_b128 v[210:213], v228 offset:56320
	global_load_lds_dwordx4 v[218:219], off
	v_lshl_add_u64 v[218:219], v[244:245], 0, s[94:95]
	s_mov_b32 m0, s39
	s_nop 0
	global_load_lds_dwordx4 v[218:219], off
	s_waitcnt lgkmcnt(0)
	s_setprio 1
	s_barrier
; template <class Epi>
; DI void gemm_phase(LAS unsigned char* lds, const Gemm g, const StaticOrder& S, const Epi& E) {
;     ...
;             PG8_LDB(B1, 1, 1); PG8_STAGE(PG8_SB(1, 0), b3);
;             PG8_BAR; PG8_WAIT_L(0); PG8_MMA(0, 1, At, B1); PG8_BAR;
;             PG8_LDA(At, 1, 1); PG8_STAGE(PG8_SA(1, 0), a3);
;             PG8_BAR; PG8_WAIT_L(0); PG8_MMA(1, 0, At, B0); PG8_BAR; PG8_SCHED;
;             PG8_STAGE(PG8_SB(1, 1), b3 + hstep);
;             PG8_WAIT_V(6); PG8_BAR; PG8_MMA(1, 1, At, B1); PG8_BAR;
;     template <bool LN, int BJ, int LO, int HI> DI void batch(const f32x4 (&acc)[2][2][4][2], unsigned row0, unsigned col0, const f32x4 (&gv)[2], const f32x4 (&bv)[2]) const {
;         f32x4 r[HI - LO]; float mean[(HI - LO) / 2], rstd[(HI - LO) / 2];
; #pragma unroll
;         for (int i = LO; i < HI; ++i) { const int ai = i >> 3, m = (i >> 1) & 3, n = i & 1; const unsigned row = row0 + ai * HALF + m * 16;
;             if (n == 0) { mean[(i - LO) >> 1] = 0.f; rstd[(i - LO) >> 1] = 1.f;
;                 if (LN) { const float2 st = *(const float2*)(stats + row * 2u); mean[(i - LO) >> 1] = st.x; rstd[(i - LO) >> 1] = st.y; } }
;             r[i - LO] = *(const f32x4*)(src + (row * (unsigned)DM + col0 + BJ * HALF + n * 16)); }
; #pragma unroll
;         for (int i = LO; i < HI; ++i) { const int ai = i >> 3, m = (i >> 1) & 3, n = i & 1; const unsigned row = row0 + ai * HALF + m * 16;
;             *(f32x4*)(Y + (row * (unsigned)DM + col0 + BJ * HALF + n * 16)) = acc[ai][BJ][m][n] + ((r[i - LO] - mean[(i - LO) >> 1]) * rstd[(i - LO) >> 1]) * gv[n] + bv[n]; }
;         __builtin_amdgcn_sched_barrier(0);
;     }
;     template <bool LN, int BJ> DI void load_gb(unsigned col0, f32x4 (&gv)[2], f32x4 (&bv)[2]) const {
; #pragma unroll
;         for (int n = 0; n < 2; ++n) {
;             if (LN) { gv[n] = *(const f32x4*)(gam + col0 + BJ * HALF + n * 16) * ALPHA; bv[n] = *(const f32x4*)(bet + col0 + BJ * HALF + n * 16) * ALPHA; }
;             else { gv[n] = (f32x4){ALPHA, ALPHA, ALPHA, ALPHA}; bv[n] = (f32x4){0.f, 0.f, 0.f, 0.f}; }
;         }
;     }
;     template <bool LN> DI void run(const f32x4 (&acc)[2][2][4][2], const Unit& u, int wr, int wc, int fr, int fq) const {
;         const unsigned row0 = u.pm * BM + wr * 64 + fr, col0 = u.pn * BM + wc * 32 + 4 * fq;
;         f32x4 gv[2], bv[2];
;         load_gb<LN, 0>(col0, gv, bv);
	v_mfma_f32_16x16x32_bf16 v[92:95], v[128:131], v[144:147], v[92:95]
	v_mfma_f32_16x16x32_bf16 v[88:91], v[136:139], v[144:147], v[88:91]
	v_mfma_f32_16x16x32_bf16 v[84:87], v[128:131], v[152:155], v[84:87]
	v_mfma_f32_16x16x32_bf16 v[80:83], v[136:139], v[152:155], v[80:83]
	v_mfma_f32_16x16x32_bf16 v[76:79], v[128:131], v[198:201], v[76:79]
	v_mfma_f32_16x16x32_bf16 v[72:75], v[136:139], v[198:201], v[72:75]
	v_mfma_f32_16x16x32_bf16 v[68:71], v[128:131], v[206:209], v[68:71]
	v_mfma_f32_16x16x32_bf16 v[64:67], v[136:139], v[206:209], v[64:67]
	v_mfma_f32_16x16x32_bf16 v[92:95], v[132:135], v[148:151], v[92:95]
	v_mfma_f32_16x16x32_bf16 v[88:91], v[140:143], v[148:151], v[88:91]
	v_mfma_f32_16x16x32_bf16 v[84:87], v[132:135], v[194:197], v[84:87]
	v_mfma_f32_16x16x32_bf16 v[80:83], v[140:143], v[194:197], v[80:83]
	v_mfma_f32_16x16x32_bf16 v[76:79], v[132:135], v[202:205], v[76:79]
	v_mfma_f32_16x16x32_bf16 v[72:75], v[140:143], v[202:205], v[72:75]
	v_mfma_f32_16x16x32_bf16 v[68:71], v[132:135], v[210:213], v[68:71]
	v_mfma_f32_16x16x32_bf16 v[64:67], v[140:143], v[210:213], v[64:67]
	s_setprio 0
	s_barrier
	s_add_u32 s20, s24, 0x90080
	s_addc_u32 s21, s25, 0
	s_add_i32 s24, s26, s31
	v_lshl_add_u64 v[128:129], s[20:21], 0, v[188:189]
	s_mov_b32 m0, s24
	s_nop 0
	global_load_lds_dwordx4 v[128:129], off
	v_lshl_add_u64 v[128:129], s[20:21], 0, v[186:187]
	s_add_i32 m0, s24, 0x2000
	s_nop 0
	global_load_lds_dwordx4 v[128:129], off
	s_waitcnt vmcnt(6)
	s_setprio 1
	s_barrier
	v_mfma_f32_16x16x32_bf16 v[28:31], v[214:217], v[144:147], v[28:31]
	v_mfma_f32_16x16x32_bf16 v[24:27], v[234:237], v[144:147], v[24:27]
	v_mfma_f32_16x16x32_bf16 v[20:23], v[214:217], v[152:155], v[20:23]
	v_mfma_f32_16x16x32_bf16 v[16:19], v[234:237], v[152:155], v[16:19]
	v_mfma_f32_16x16x32_bf16 v[12:15], v[214:217], v[198:201], v[12:15]
	v_mfma_f32_16x16x32_bf16 v[8:11], v[234:237], v[198:201], v[8:11]
	v_mfma_f32_16x16x32_bf16 v[4:7], v[214:217], v[206:209], v[4:7]
	v_mfma_f32_16x16x32_bf16 v[0:3], v[234:237], v[206:209], v[0:3]
	v_mfma_f32_16x16x32_bf16 v[28:31], v[230:233], v[148:151], v[28:31]
	s_add_i32 s33, s33, 2
	v_mfma_f32_16x16x32_bf16 v[24:27], v[238:241], v[148:151], v[24:27]
	s_add_u32 s4, s4, 0x100
	v_mfma_f32_16x16x32_bf16 v[20:23], v[230:233], v[194:197], v[20:23]
	s_addc_u32 s5, s5, 0
	v_mfma_f32_16x16x32_bf16 v[16:19], v[238:241], v[194:197], v[16:19]
	s_cmp_gt_u32 s33, 33
	v_mfma_f32_16x16x32_bf16 v[12:15], v[230:233], v[202:205], v[12:15]
	s_mov_b64 s[20:21], s[22:23]
	v_mfma_f32_16x16x32_bf16 v[8:11], v[238:241], v[202:205], v[8:11]
	v_mfma_f32_16x16x32_bf16 v[4:7], v[230:233], v[210:213], v[4:7]
	v_mfma_f32_16x16x32_bf16 v[0:3], v[238:241], v[210:213], v[0:3]
	s_setprio 0
	s_barrier
	s_cbranch_scc0 .LBB0_77
	v_lshl_add_u32 v206, s3, 8, v225
	v_lshl_or_b32 v158, s2, 8, v227
	v_lshlrev_b32_e32 v232, 11, v206
	s_andn2_b64 vcc, exec, s[14:15]
	v_or_b32_e32 v231, 16, v158
	v_add_u32_e32 v194, v232, v158
	v_or_b32_e32 v230, 0x80, v158
	v_or_b32_e32 v229, 0x90, v158
	s_cbranch_vccnz .LBB0_80
	v_lshlrev_b64 v[132:133], 2, v[158:159]
	v_lshl_add_u64 v[140:141], s[16:17], 0, v[132:133]
	global_load_dwordx4 v[128:131], v[140:141], off
	v_lshl_add_u64 v[142:143], s[18:19], 0, v[132:133]
	v_readlane_b32 s2, v253, 8
	v_mov_b32_e32 v195, v159
	v_lshlrev_b32_e32 v136, 1, v206
	v_mov_b32_e32 v137, v159
	v_readlane_b32 s3, v253, 9
	v_lshlrev_b64 v[212:213], 2, v[194:195]
	v_add_u32_e32 v146, v232, v231
	v_lshl_add_u64 v[144:145], v[136:137], 2, s[2:3]
	v_lshl_add_u64 v[136:137], s[88:89], 0, v[212:213]
	v_mov_b32_e32 v147, v159
	v_lshl_add_u64 v[146:147], v[146:147], 2, s[88:89]
	v_or_b32_e32 v195, 16, v206
	v_mov_b32_e32 v201, v159
	v_mov_b32_e32 v209, v159
	v_lshl_add_u64 v[212:213], s[90:91], 0, v[212:213]
	s_waitcnt vmcnt(0)
	v_pk_mul_f32 v[152:153], v[130:131], s[78:79] op_sel_hi:[1,0]
	v_pk_mul_f32 v[154:155], v[128:129], s[78:79] op_sel_hi:[1,0]
	global_load_dwordx4 v[132:135], v[142:143], off
	global_load_dwordx4 v[128:131], v[140:141], off offset:64
	global_load_dwordx2 v[204:205], v[144:145], off
	global_load_dwordx4 v[196:199], v[146:147], off
	v_lshlrev_b32_e32 v146, 1, v195
	global_load_dwordx4 v[136:139], v[136:137], off
	v_lshlrev_b32_e32 v195, 11, v195
	v_mov_b32_e32 v147, v159
	v_add_u32_e32 v200, v195, v158
	v_lshl_add_u64 v[146:147], v[146:147], 2, s[2:3]
	v_lshl_add_u64 v[200:201], v[200:201], 2, s[88:89]
	global_load_dwordx2 v[214:215], v[146:147], off
	v_add_u32_e32 v208, v195, v231
	global_load_dwordx4 v[200:203], v[200:201], off
	v_lshl_add_u64 v[208:209], v[208:209], 2, s[88:89]
	global_load_dwordx4 v[208:211], v[208:209], off
	s_waitcnt vmcnt(0)
	v_pk_mul_f32 v[148:149], v[130:131], s[78:79] op_sel_hi:[1,0]
	v_pk_mul_f32 v[150:151], v[128:129], s[78:79] op_sel_hi:[1,0]
	global_load_dwordx4 v[128:131], v[142:143], off offset:64
	v_sub_f32_e32 v137, v137, v204
	v_sub_f32_e32 v136, v136, v204
	v_sub_f32_e32 v139, v139, v204
	v_sub_f32_e32 v138, v138, v204
	v_pk_mul_f32 v[138:139], v[204:205], v[138:139] op_sel:[1,0]
	v_pk_mul_f32 v[136:137], v[204:205], v[136:137] op_sel:[1,0]
	v_pk_fma_f32 v[138:139], v[152:153], v[138:139], v[126:127]
	v_pk_fma_f32 v[136:137], v[154:155], v[136:137], v[124:125]
	v_pk_fma_f32 v[138:139], v[134:135], s[78:79], v[138:139] op_sel_hi:[1,0,1]
	v_pk_fma_f32 v[136:137], v[132:133], s[78:79], v[136:137] op_sel_hi:[1,0,1]
	global_store_dwordx4 v[212:213], v[136:139], off
	s_nop 1
	v_sub_f32_e32 v137, v197, v204
	v_sub_f32_e32 v136, v196, v204
	v_sub_f32_e32 v139, v199, v204
	v_sub_f32_e32 v138, v198, v204
	v_pk_mul_f32 v[138:139], v[204:205], v[138:139] op_sel:[1,0]
	v_pk_mul_f32 v[136:137], v[204:205], v[136:137] op_sel:[1,0]
	v_pk_fma_f32 v[138:139], v[148:149], v[138:139], v[122:123]
	v_pk_fma_f32 v[136:137], v[150:151], v[136:137], v[120:121]
	v_or_b32_e32 v196, 16, v194
	v_mov_b32_e32 v197, v159
	v_lshl_add_u64 v[196:197], v[196:197], 2, s[90:91]
	s_waitcnt vmcnt(0)
;     template <bool LN, int BJ, int LO, int HI> DI void batch(const f32x4 (&acc)[2][2][4][2], unsigned row0, unsigned col0, const f32x4 (&gv)[2], const f32x4 (&bv)[2]) const {
;         f32x4 r[HI - LO]; float mean[(HI - LO) / 2], rstd[(HI - LO) / 2];
; #pragma unroll
;         for (int i = LO; i < HI; ++i) { const int ai = i >> 3, m = (i >> 1) & 3, n = i & 1; const unsigned row = row0 + ai * HALF + m * 16;
;             if (n == 0) { mean[(i - LO) >> 1] = 0.f; rstd[(i - LO) >> 1] = 1.f;
;                 if (LN) { const float2 st = *(const float2*)(stats + row * 2u); mean[(i - LO) >> 1] = st.x; rstd[(i - LO) >> 1] = st.y; } }
;             r[i - LO] = *(const f32x4*)(src + (row * (unsigned)DM + col0 + BJ * HALF + n * 16)); }
; #pragma unroll
;         for (int i = LO; i < HI; ++i) { const int ai = i >> 3, m = (i >> 1) & 3, n = i & 1; const unsigned row = row0 + ai * HALF + m * 16;
;             *(f32x4*)(Y + (row * (unsigned)DM + col0 + BJ * HALF + n * 16)) = acc[ai][BJ][m][n] + ((r[i - LO] - mean[(i - LO) >> 1]) * rstd[(i - LO) >> 1]) * gv[n] + bv[n]; }
;         __builtin_amdgcn_sched_barrier(0);
;     }
;     template <bool LN, int BJ> DI void load_gb(unsigned col0, f32x4 (&gv)[2], f32x4 (&bv)[2]) const {
; #pragma unroll
;         for (int n = 0; n < 2; ++n) {
;             if (LN) { gv[n] = *(const f32x4*)(gam + col0 + BJ * HALF + n * 16) * ALPHA; bv[n] = *(const f32x4*)(bet + col0 + BJ * HALF + n * 16) * ALPHA; }
;             else { gv[n] = (f32x4){ALPHA, ALPHA, ALPHA, ALPHA}; bv[n] = (f32x4){0.f, 0.f, 0.f, 0.f}; }
;         }
;     }
;     template <bool LN> DI void run(const f32x4 (&acc)[2][2][4][2], const Unit& u, int wr, int wc, int fr, int fq) const {
;         const unsigned row0 = u.pm * BM + wr * 64 + fr, col0 = u.pn * BM + wc * 32 + 4 * fq;
;         f32x4 gv[2], bv[2];
;         load_gb<LN, 0>(col0, gv, bv);
;         batch<LN, 0, 0, 4>(acc, row0, col0, gv, bv);
;         batch<LN, 0, 4, 8>(acc, row0, col0, gv, bv);
;         batch<LN, 0, 8, 12>(acc, row0, col0, gv, bv);
;         batch<LN, 0, 12, 16>(acc, row0, col0, gv, bv);
	v_pk_fma_f32 v[138:139], v[130:131], s[78:79], v[138:139] op_sel_hi:[1,0,1]
	v_pk_fma_f32 v[136:137], v[128:129], s[78:79], v[136:137] op_sel_hi:[1,0,1]
	global_store_dwordx4 v[196:197], v[136:139], off
	v_add_u32_e32 v196, 0x8000, v194
	v_mov_b32_e32 v197, v159
	v_sub_f32_e32 v137, v201, v214
	v_sub_f32_e32 v136, v200, v214
	v_sub_f32_e32 v139, v203, v214
	v_sub_f32_e32 v138, v202, v214
	v_pk_mul_f32 v[138:139], v[214:215], v[138:139] op_sel:[1,0]
	v_pk_mul_f32 v[136:137], v[214:215], v[136:137] op_sel:[1,0]
	v_pk_fma_f32 v[138:139], v[152:153], v[138:139], v[118:119]
	v_pk_fma_f32 v[136:137], v[154:155], v[136:137], v[116:117]
	v_pk_fma_f32 v[138:139], v[134:135], s[78:79], v[138:139] op_sel_hi:[1,0,1]
	v_pk_fma_f32 v[136:137], v[132:133], s[78:79], v[136:137] op_sel_hi:[1,0,1]
	v_lshl_add_u64 v[196:197], v[196:197], 2, s[90:91]
	global_store_dwordx4 v[196:197], v[136:139], off
	v_add_u32_e32 v196, 0x8010, v194
	v_mov_b32_e32 v197, v159
	v_sub_f32_e32 v137, v209, v214
	v_sub_f32_e32 v136, v208, v214
	v_sub_f32_e32 v139, v211, v214
	v_sub_f32_e32 v138, v210, v214
	v_pk_mul_f32 v[138:139], v[214:215], v[138:139] op_sel:[1,0]
	v_pk_mul_f32 v[136:137], v[214:215], v[136:137] op_sel:[1,0]
	v_pk_fma_f32 v[138:139], v[148:149], v[138:139], v[114:115]
	v_pk_fma_f32 v[136:137], v[150:151], v[136:137], v[112:113]
	v_pk_fma_f32 v[138:139], v[130:131], s[78:79], v[138:139] op_sel_hi:[1,0,1]
	v_pk_fma_f32 v[136:137], v[128:129], s[78:79], v[136:137] op_sel_hi:[1,0,1]
	v_lshl_add_u64 v[196:197], v[196:197], 2, s[90:91]
	global_store_dwordx4 v[196:197], v[136:139], off
	s_nop 1
	v_or_b32_e32 v138, 32, v206
	v_lshlrev_b32_e32 v136, 1, v138
	v_mov_b32_e32 v137, v159
	v_lshlrev_b32_e32 v236, 11, v138
	v_lshl_add_u64 v[200:201], v[136:137], 2, s[2:3]
	v_add_u32_e32 v136, v236, v158
	v_lshl_add_u64 v[136:137], v[136:137], 2, s[88:89]
	global_load_dwordx2 v[204:205], v[200:201], off
	v_add_u32_e32 v196, v236, v231
	global_load_dwordx4 v[136:139], v[136:137], off
	v_mov_b32_e32 v197, v159
	v_lshl_add_u64 v[196:197], v[196:197], 2, s[88:89]
	global_load_dwordx4 v[196:199], v[196:197], off
	v_or_b32_e32 v207, 48, v206
	v_lshlrev_b32_e32 v235, 11, v207
	v_lshlrev_b32_e32 v202, 1, v207
	v_mov_b32_e32 v203, v159
	v_add_u32_e32 v208, v235, v158
	v_mov_b32_e32 v209, v159
	v_lshl_add_u64 v[202:203], v[202:203], 2, s[2:3]
	v_lshl_add_u64 v[208:209], v[208:209], 2, s[88:89]
	global_load_dwordx2 v[216:217], v[202:203], off
	v_add_u32_e32 v212, v235, v231
	global_load_dwordx4 v[208:211], v[208:209], off
	v_mov_b32_e32 v213, v159
	v_lshl_add_u64 v[212:213], v[212:213], 2, s[88:89]
	global_load_dwordx4 v[212:215], v[212:213], off
	v_add_u32_e32 v218, 0x10000, v194
	v_mov_b32_e32 v219, v159
	v_lshl_add_u64 v[218:219], v[218:219], 2, s[90:91]
	s_waitcnt vmcnt(0)
	v_sub_f32_e32 v137, v137, v204
	v_sub_f32_e32 v136, v136, v204
	v_sub_f32_e32 v139, v139, v204
	v_sub_f32_e32 v138, v138, v204
	v_pk_mul_f32 v[138:139], v[204:205], v[138:139] op_sel:[1,0]
	v_pk_mul_f32 v[136:137], v[204:205], v[136:137] op_sel:[1,0]
	v_pk_fma_f32 v[138:139], v[152:153], v[138:139], v[110:111]
	v_pk_fma_f32 v[136:137], v[154:155], v[136:137], v[108:109]
	v_pk_fma_f32 v[138:139], v[134:135], s[78:79], v[138:139] op_sel_hi:[1,0,1]
	v_pk_fma_f32 v[136:137], v[132:133], s[78:79], v[136:137] op_sel_hi:[1,0,1]
	global_store_dwordx4 v[218:219], v[136:139], off
	s_nop 1
	v_sub_f32_e32 v137, v197, v204
	v_sub_f32_e32 v136, v196, v204
	v_sub_f32_e32 v139, v199, v204
	v_sub_f32_e32 v138, v198, v204
	v_pk_mul_f32 v[138:139], v[204:205], v[138:139] op_sel:[1,0]
	v_pk_mul_f32 v[136:137], v[204:205], v[136:137] op_sel:[1,0]
	v_pk_fma_f32 v[138:139], v[148:149], v[138:139], v[106:107]
	v_pk_fma_f32 v[136:137], v[150:151], v[136:137], v[104:105]
	v_add_u32_e32 v196, 0x10010, v194
	v_mov_b32_e32 v197, v159
	v_pk_fma_f32 v[138:139], v[130:131], s[78:79], v[138:139] op_sel_hi:[1,0,1]
	v_pk_fma_f32 v[136:137], v[128:129], s[78:79], v[136:137] op_sel_hi:[1,0,1]
	v_lshl_add_u64 v[196:197], v[196:197], 2, s[90:91]
	global_store_dwordx4 v[196:197], v[136:139], off
	v_add_u32_e32 v196, 0x18000, v194
	v_mov_b32_e32 v197, v159
	v_sub_f32_e32 v137, v209, v216
	v_sub_f32_e32 v136, v208, v216
	v_sub_f32_e32 v139, v211, v216
	v_sub_f32_e32 v138, v210, v216
	v_pk_mul_f32 v[138:139], v[216:217], v[138:139] op_sel:[1,0]
	v_pk_mul_f32 v[136:137], v[216:217], v[136:137] op_sel:[1,0]
	v_pk_fma_f32 v[138:139], v[152:153], v[138:139], v[102:103]
	v_pk_fma_f32 v[136:137], v[154:155], v[136:137], v[100:101]
	v_pk_fma_f32 v[138:139], v[134:135], s[78:79], v[138:139] op_sel_hi:[1,0,1]
	v_pk_fma_f32 v[136:137], v[132:133], s[78:79], v[136:137] op_sel_hi:[1,0,1]
	v_lshl_add_u64 v[196:197], v[196:197], 2, s[90:91]
	global_store_dwordx4 v[196:197], v[136:139], off
	v_add_u32_e32 v196, 0x18010, v194
	v_mov_b32_e32 v197, v159
	v_sub_f32_e32 v137, v213, v216
	v_sub_f32_e32 v136, v212, v216
	v_sub_f32_e32 v139, v215, v216
	v_sub_f32_e32 v138, v214, v216
	v_pk_mul_f32 v[138:139], v[216:217], v[138:139] op_sel:[1,0]
	v_pk_mul_f32 v[136:137], v[216:217], v[136:137] op_sel:[1,0]
	v_pk_fma_f32 v[138:139], v[148:149], v[138:139], v[98:99]
	v_pk_fma_f32 v[136:137], v[150:151], v[136:137], v[96:97]
	v_pk_fma_f32 v[138:139], v[130:131], s[78:79], v[138:139] op_sel_hi:[1,0,1]
	v_pk_fma_f32 v[136:137], v[128:129], s[78:79], v[136:137] op_sel_hi:[1,0,1]
	v_lshl_add_u64 v[196:197], v[196:197], 2, s[90:91]
	global_store_dwordx4 v[196:197], v[136:139], off
	s_nop 1
	v_add_u32_e32 v138, 0x80, v206
	v_lshlrev_b32_e32 v136, 1, v138
	v_mov_b32_e32 v137, v159
	v_lshlrev_b32_e32 v233, 11, v138
	v_lshl_add_u64 v[196:197], v[136:137], 2, s[2:3]
	v_add_u32_e32 v136, v233, v158
	v_lshl_add_u64 v[136:137], v[136:137], 2, s[88:89]
	global_load_dwordx2 v[204:205], v[196:197], off
	v_add_u32_e32 v198, v233, v231
	global_load_dwordx4 v[136:139], v[136:137], off
	v_mov_b32_e32 v199, v159
	v_add_u32_e32 v207, 0x90, v206
	v_lshl_add_u64 v[198:199], v[198:199], 2, s[88:89]
	v_lshlrev_b32_e32 v234, 11, v207
	global_load_dwordx4 v[208:211], v[198:199], off
	v_add_u32_e32 v212, v234, v158
	v_mov_b32_e32 v213, v159
	v_lshl_add_u64 v[212:213], v[212:213], 2, s[88:89]
	global_load_dwordx4 v[212:215], v[212:213], off
	v_lshlrev_b32_e32 v198, 1, v207
	v_mov_b32_e32 v199, v159
	v_lshl_add_u64 v[198:199], v[198:199], 2, s[2:3]
	global_load_dwordx2 v[220:221], v[198:199], off
	v_add_u32_e32 v216, v234, v231
	v_mov_b32_e32 v217, v159
	v_lshl_add_u64 v[216:217], v[216:217], 2, s[88:89]
	global_load_dwordx4 v[216:219], v[216:217], off
	v_add_u32_e32 v238, 0x40000, v194
	v_mov_b32_e32 v239, v159
	v_lshl_add_u64 v[238:239], v[238:239], 2, s[90:91]
	s_waitcnt vmcnt(0)
;     template <bool LN, int BJ, int LO, int HI> DI void batch(const f32x4 (&acc)[2][2][4][2], unsigned row0, unsigned col0, const f32x4 (&gv)[2], const f32x4 (&bv)[2]) const {
;         f32x4 r[HI - LO]; float mean[(HI - LO) / 2], rstd[(HI - LO) / 2];
; #pragma unroll
;         for (int i = LO; i < HI; ++i) { const int ai = i >> 3, m = (i >> 1) & 3, n = i & 1; const unsigned row = row0 + ai * HALF + m * 16;
;             if (n == 0) { mean[(i - LO) >> 1] = 0.f; rstd[(i - LO) >> 1] = 1.f;
;                 if (LN) { const float2 st = *(const float2*)(stats + row * 2u); mean[(i - LO) >> 1] = st.x; rstd[(i - LO) >> 1] = st.y; } }
;             r[i - LO] = *(const f32x4*)(src + (row * (unsigned)DM + col0 + BJ * HALF + n * 16)); }
; #pragma unroll
;         for (int i = LO; i < HI; ++i) { const int ai = i >> 3, m = (i >> 1) & 3, n = i & 1; const unsigned row = row0 + ai * HALF + m * 16;
;             *(f32x4*)(Y + (row * (unsigned)DM + col0 + BJ * HALF + n * 16)) = acc[ai][BJ][m][n] + ((r[i - LO] - mean[(i - LO) >> 1]) * rstd[(i - LO) >> 1]) * gv[n] + bv[n]; }
;         __builtin_amdgcn_sched_barrier(0);
;     }
;     template <bool LN, int BJ> DI void load_gb(unsigned col0, f32x4 (&gv)[2], f32x4 (&bv)[2]) const {
; #pragma unroll
;         for (int n = 0; n < 2; ++n) {
;             if (LN) { gv[n] = *(const f32x4*)(gam + col0 + BJ * HALF + n * 16) * ALPHA; bv[n] = *(const f32x4*)(bet + col0 + BJ * HALF + n * 16) * ALPHA; }
;             else { gv[n] = (f32x4){ALPHA, ALPHA, ALPHA, ALPHA}; bv[n] = (f32x4){0.f, 0.f, 0.f, 0.f}; }
;         }
;     }
;     template <bool LN> DI void run(const f32x4 (&acc)[2][2][4][2], const Unit& u, int wr, int wc, int fr, int fq) const {
;         const unsigned row0 = u.pm * BM + wr * 64 + fr, col0 = u.pn * BM + wc * 32 + 4 * fq;
;         f32x4 gv[2], bv[2];
;         load_gb<LN, 0>(col0, gv, bv);
;         batch<LN, 0, 0, 4>(acc, row0, col0, gv, bv);
;         batch<LN, 0, 4, 8>(acc, row0, col0, gv, bv);
;         batch<LN, 0, 8, 12>(acc, row0, col0, gv, bv);
;         batch<LN, 0, 12, 16>(acc, row0, col0, gv, bv);
;         load_gb<LN, 1>(col0, gv, bv);
;         batch<LN, 1, 0, 8>(acc, row0, col0, gv, bv);
	v_sub_f32_e32 v137, v137, v204
	v_sub_f32_e32 v136, v136, v204
	v_sub_f32_e32 v139, v139, v204
	v_sub_f32_e32 v138, v138, v204
	v_pk_mul_f32 v[138:139], v[204:205], v[138:139] op_sel:[1,0]
	v_pk_mul_f32 v[136:137], v[204:205], v[136:137] op_sel:[1,0]
	v_pk_fma_f32 v[138:139], v[152:153], v[138:139], v[94:95]
	v_pk_fma_f32 v[136:137], v[154:155], v[136:137], v[92:93]
	v_pk_fma_f32 v[138:139], v[134:135], s[78:79], v[138:139] op_sel_hi:[1,0,1]
	v_pk_fma_f32 v[136:137], v[132:133], s[78:79], v[136:137] op_sel_hi:[1,0,1]
	global_store_dwordx4 v[238:239], v[136:139], off
	s_nop 1
	v_sub_f32_e32 v137, v209, v204
	v_sub_f32_e32 v136, v208, v204
	v_sub_f32_e32 v139, v211, v204
	v_sub_f32_e32 v138, v210, v204
	v_pk_mul_f32 v[138:139], v[204:205], v[138:139] op_sel:[1,0]
	v_pk_mul_f32 v[136:137], v[204:205], v[136:137] op_sel:[1,0]
	v_pk_fma_f32 v[138:139], v[148:149], v[138:139], v[90:91]
	v_pk_fma_f32 v[136:137], v[150:151], v[136:137], v[88:89]
	v_add_u32_e32 v204, 0x40010, v194
	v_mov_b32_e32 v205, v159
	v_pk_fma_f32 v[138:139], v[130:131], s[78:79], v[138:139] op_sel_hi:[1,0,1]
	v_pk_fma_f32 v[136:137], v[128:129], s[78:79], v[136:137] op_sel_hi:[1,0,1]
	v_lshl_add_u64 v[204:205], v[204:205], 2, s[90:91]
	global_store_dwordx4 v[204:205], v[136:139], off
	v_add_u32_e32 v204, 0x48000, v194
	v_mov_b32_e32 v205, v159
	v_sub_f32_e32 v137, v213, v220
	v_sub_f32_e32 v136, v212, v220
	v_sub_f32_e32 v139, v215, v220
	v_sub_f32_e32 v138, v214, v220
	v_pk_mul_f32 v[138:139], v[220:221], v[138:139] op_sel:[1,0]
	v_pk_mul_f32 v[136:137], v[220:221], v[136:137] op_sel:[1,0]
	v_pk_fma_f32 v[138:139], v[152:153], v[138:139], v[86:87]
	v_pk_fma_f32 v[136:137], v[154:155], v[136:137], v[84:85]
	v_pk_fma_f32 v[138:139], v[134:135], s[78:79], v[138:139] op_sel_hi:[1,0,1]
	v_pk_fma_f32 v[136:137], v[132:133], s[78:79], v[136:137] op_sel_hi:[1,0,1]
	v_lshl_add_u64 v[204:205], v[204:205], 2, s[90:91]
	global_store_dwordx4 v[204:205], v[136:139], off
	v_add_u32_e32 v204, 0x48010, v194
	v_mov_b32_e32 v205, v159
	v_sub_f32_e32 v137, v217, v220
	v_sub_f32_e32 v136, v216, v220
	v_sub_f32_e32 v139, v219, v220
	v_sub_f32_e32 v138, v218, v220
	v_pk_mul_f32 v[138:139], v[220:221], v[138:139] op_sel:[1,0]
	v_pk_mul_f32 v[136:137], v[220:221], v[136:137] op_sel:[1,0]
	v_pk_fma_f32 v[138:139], v[148:149], v[138:139], v[82:83]
	v_pk_fma_f32 v[136:137], v[150:151], v[136:137], v[80:81]
	v_pk_fma_f32 v[138:139], v[130:131], s[78:79], v[138:139] op_sel_hi:[1,0,1]
	v_pk_fma_f32 v[136:137], v[128:129], s[78:79], v[136:137] op_sel_hi:[1,0,1]
	v_lshl_add_u64 v[204:205], v[204:205], 2, s[90:91]
	global_store_dwordx4 v[204:205], v[136:139], off
	s_nop 1
	v_add_u32_e32 v138, 0xa0, v206
	v_lshlrev_b32_e32 v136, 1, v138
	v_mov_b32_e32 v137, v159
	v_lshlrev_b32_e32 v237, 11, v138
	v_lshl_add_u64 v[204:205], v[136:137], 2, s[2:3]
	v_add_u32_e32 v136, v237, v158
	v_lshl_add_u64 v[136:137], v[136:137], 2, s[88:89]
	global_load_dwordx2 v[220:221], v[204:205], off
	v_add_u32_e32 v208, v237, v231
	global_load_dwordx4 v[136:139], v[136:137], off
	v_mov_b32_e32 v209, v159
	v_lshl_add_u64 v[208:209], v[208:209], 2, s[88:89]
	global_load_dwordx4 v[212:215], v[208:209], off
	v_add_u32_e32 v208, 0xb0, v206
	v_lshlrev_b32_e32 v206, 1, v208
	v_mov_b32_e32 v207, v159
	v_lshlrev_b32_e32 v238, 11, v208
	v_lshl_add_u64 v[210:211], v[206:207], 2, s[2:3]
	v_add_u32_e32 v206, v238, v158
	v_lshl_add_u64 v[206:207], v[206:207], 2, s[88:89]
	global_load_dwordx2 v[240:241], v[210:211], off
	v_add_u32_e32 v216, v238, v231
	global_load_dwordx4 v[206:209], v[206:207], off
	v_mov_b32_e32 v217, v159
	v_lshl_add_u64 v[216:217], v[216:217], 2, s[88:89]
	global_load_dwordx4 v[216:219], v[216:217], off
	v_add_u32_e32 v242, 0x50000, v194
	v_mov_b32_e32 v243, v159
	v_lshl_add_u64 v[242:243], v[242:243], 2, s[90:91]
	s_waitcnt vmcnt(0)
	v_sub_f32_e32 v137, v137, v220
	v_sub_f32_e32 v136, v136, v220
	v_sub_f32_e32 v139, v139, v220
	v_sub_f32_e32 v138, v138, v220
	v_pk_mul_f32 v[138:139], v[220:221], v[138:139] op_sel:[1,0]
	v_pk_mul_f32 v[136:137], v[220:221], v[136:137] op_sel:[1,0]
	v_pk_fma_f32 v[138:139], v[152:153], v[138:139], v[78:79]
	v_pk_fma_f32 v[136:137], v[154:155], v[136:137], v[76:77]
	v_pk_fma_f32 v[138:139], v[134:135], s[78:79], v[138:139] op_sel_hi:[1,0,1]
	v_pk_fma_f32 v[136:137], v[132:133], s[78:79], v[136:137] op_sel_hi:[1,0,1]
	global_store_dwordx4 v[242:243], v[136:139], off
	s_nop 1
	v_sub_f32_e32 v137, v213, v220
	v_sub_f32_e32 v136, v212, v220
	v_sub_f32_e32 v139, v215, v220
	v_sub_f32_e32 v138, v214, v220
	v_pk_mul_f32 v[138:139], v[220:221], v[138:139] op_sel:[1,0]
	v_pk_mul_f32 v[136:137], v[220:221], v[136:137] op_sel:[1,0]
	v_pk_fma_f32 v[138:139], v[148:149], v[138:139], v[74:75]
	v_pk_fma_f32 v[136:137], v[150:151], v[136:137], v[72:73]
	v_add_u32_e32 v212, 0x50010, v194
	v_mov_b32_e32 v213, v159
	v_pk_fma_f32 v[138:139], v[130:131], s[78:79], v[138:139] op_sel_hi:[1,0,1]
	v_pk_fma_f32 v[136:137], v[128:129], s[78:79], v[136:137] op_sel_hi:[1,0,1]
	v_lshl_add_u64 v[212:213], v[212:213], 2, s[90:91]
	global_store_dwordx4 v[212:213], v[136:139], off
	s_nop 1
	v_sub_f32_e32 v137, v207, v240
	v_sub_f32_e32 v136, v206, v240
	v_sub_f32_e32 v139, v209, v240
	v_sub_f32_e32 v138, v208, v240
	v_pk_mul_f32 v[136:137], v[240:241], v[136:137] op_sel:[1,0]
	v_pk_mul_f32 v[138:139], v[240:241], v[138:139] op_sel:[1,0]
	v_pk_fma_f32 v[136:137], v[154:155], v[136:137], v[68:69]
	v_pk_fma_f32 v[138:139], v[152:153], v[138:139], v[70:71]
	v_pk_fma_f32 v[132:133], v[132:133], s[78:79], v[136:137] op_sel_hi:[1,0,1]
	v_add_u32_e32 v136, 0x58000, v194
	v_mov_b32_e32 v137, v159
	v_pk_fma_f32 v[134:135], v[134:135], s[78:79], v[138:139] op_sel_hi:[1,0,1]
	v_lshl_add_u64 v[136:137], v[136:137], 2, s[90:91]
	global_store_dwordx4 v[136:137], v[132:135], off
	s_nop 1
	v_sub_f32_e32 v133, v217, v240
	v_sub_f32_e32 v132, v216, v240
	v_sub_f32_e32 v135, v219, v240
	v_sub_f32_e32 v134, v218, v240
	v_pk_mul_f32 v[132:133], v[240:241], v[132:133] op_sel:[1,0]
	v_pk_mul_f32 v[134:135], v[240:241], v[134:135] op_sel:[1,0]
	v_pk_fma_f32 v[132:133], v[150:151], v[132:133], v[64:65]
	v_pk_fma_f32 v[134:135], v[148:149], v[134:135], v[66:67]
	v_pk_fma_f32 v[128:129], v[128:129], s[78:79], v[132:133] op_sel_hi:[1,0,1]
	v_add_u32_e32 v132, 0x58010, v194
	v_mov_b32_e32 v133, v159
	v_pk_fma_f32 v[130:131], v[130:131], s[78:79], v[134:135] op_sel_hi:[1,0,1]
	v_lshl_add_u64 v[132:133], v[132:133], 2, s[90:91]
	global_store_dwordx4 v[132:133], v[128:131], off
	global_load_dwordx4 v[128:131], v[140:141], off offset:512
	v_add_u32_e32 v136, v232, v230
	v_mov_b32_e32 v137, v159
	v_lshl_add_u64 v[136:137], v[136:137], 2, s[88:89]
	s_waitcnt vmcnt(0)
;     template <bool LN, int BJ, int LO, int HI> DI void batch(const f32x4 (&acc)[2][2][4][2], unsigned row0, unsigned col0, const f32x4 (&gv)[2], const f32x4 (&bv)[2]) const {
;         f32x4 r[HI - LO]; float mean[(HI - LO) / 2], rstd[(HI - LO) / 2];
; #pragma unroll
;         for (int i = LO; i < HI; ++i) { const int ai = i >> 3, m = (i >> 1) & 3, n = i & 1; const unsigned row = row0 + ai * HALF + m * 16;
;             if (n == 0) { mean[(i - LO) >> 1] = 0.f; rstd[(i - LO) >> 1] = 1.f;
;                 if (LN) { const float2 st = *(const float2*)(stats + row * 2u); mean[(i - LO) >> 1] = st.x; rstd[(i - LO) >> 1] = st.y; } }
;             r[i - LO] = *(const f32x4*)(src + (row * (unsigned)DM + col0 + BJ * HALF + n * 16)); }
; #pragma unroll
;         for (int i = LO; i < HI; ++i) { const int ai = i >> 3, m = (i >> 1) & 3, n = i & 1; const unsigned row = row0 + ai * HALF + m * 16;
;             *(f32x4*)(Y + (row * (unsigned)DM + col0 + BJ * HALF + n * 16)) = acc[ai][BJ][m][n] + ((r[i - LO] - mean[(i - LO) >> 1]) * rstd[(i - LO) >> 1]) * gv[n] + bv[n]; }
;         __builtin_amdgcn_sched_barrier(0);
;     }
;     template <bool LN, int BJ> DI void load_gb(unsigned col0, f32x4 (&gv)[2], f32x4 (&bv)[2]) const {
; #pragma unroll
;         for (int n = 0; n < 2; ++n) {
;             if (LN) { gv[n] = *(const f32x4*)(gam + col0 + BJ * HALF + n * 16) * ALPHA; bv[n] = *(const f32x4*)(bet + col0 + BJ * HALF + n * 16) * ALPHA; }
;             else { gv[n] = (f32x4){ALPHA, ALPHA, ALPHA, ALPHA}; bv[n] = (f32x4){0.f, 0.f, 0.f, 0.f}; }
;         }
;     }
;     template <bool LN> DI void run(const f32x4 (&acc)[2][2][4][2], const Unit& u, int wr, int wc, int fr, int fq) const {
;         const unsigned row0 = u.pm * BM + wr * 64 + fr, col0 = u.pn * BM + wc * 32 + 4 * fq;
;         f32x4 gv[2], bv[2];
;         load_gb<LN, 0>(col0, gv, bv);
;         batch<LN, 0, 0, 4>(acc, row0, col0, gv, bv);
;         batch<LN, 0, 4, 8>(acc, row0, col0, gv, bv);
;         batch<LN, 0, 8, 12>(acc, row0, col0, gv, bv);
;         batch<LN, 0, 12, 16>(acc, row0, col0, gv, bv);
;         load_gb<LN, 1>(col0, gv, bv);
;         batch<LN, 1, 0, 8>(acc, row0, col0, gv, bv);
;         batch<LN, 1, 8, 16>(acc, row0, col0, gv, bv);
	v_pk_mul_f32 v[212:213], v[130:131], s[78:79] op_sel_hi:[1,0]
	v_pk_mul_f32 v[214:215], v[128:129], s[78:79] op_sel_hi:[1,0]
	global_load_dwordx4 v[132:135], v[142:143], off offset:512
	global_load_dwordx4 v[128:131], v[140:141], off offset:576
	s_waitcnt vmcnt(0)
	v_pk_mul_f32 v[206:207], v[130:131], s[78:79] op_sel_hi:[1,0]
	v_pk_mul_f32 v[208:209], v[128:129], s[78:79] op_sel_hi:[1,0]
	global_load_dwordx4 v[128:131], v[142:143], off offset:576
	global_load_dwordx2 v[220:221], v[144:145], off
	global_load_dwordx4 v[240:243], v[136:137], off
	v_add_u32_e32 v136, v232, v229
	v_mov_b32_e32 v137, v159
	v_lshl_add_u64 v[136:137], v[136:137], 2, s[88:89]
	global_load_dwordx4 v[244:247], v[136:137], off
	global_load_dwordx2 v[218:219], v[146:147], off
	v_add_u32_e32 v136, v195, v230
	v_mov_b32_e32 v137, v159
	v_lshl_add_u64 v[136:137], v[136:137], 2, s[88:89]
	global_load_dwordx4 v[248:251], v[136:137], off
	v_add_u32_e32 v136, v195, v229
	v_mov_b32_e32 v137, v159
	v_lshl_add_u64 v[136:137], v[136:137], 2, s[88:89]
	global_load_dwordx4 v[152:155], v[136:137], off
	global_load_dwordx2 v[216:217], v[200:201], off
	v_add_u32_e32 v136, v236, v230
	v_mov_b32_e32 v137, v159
	v_lshl_add_u64 v[136:137], v[136:137], 2, s[88:89]
	global_load_dwordx4 v[148:151], v[136:137], off
	v_add_u32_e32 v136, v236, v229
	v_mov_b32_e32 v137, v159
	v_lshl_add_u64 v[136:137], v[136:137], 2, s[88:89]
	global_load_dwordx4 v[144:147], v[136:137], off
	global_load_dwordx2 v[200:201], v[202:203], off
	v_add_u32_e32 v136, v235, v230
	v_mov_b32_e32 v137, v159
	v_lshl_add_u64 v[136:137], v[136:137], 2, s[88:89]
	global_load_dwordx4 v[140:143], v[136:137], off
	v_add_u32_e32 v136, v235, v229
	v_mov_b32_e32 v137, v159
	v_lshl_add_u64 v[136:137], v[136:137], 2, s[88:89]
	global_load_dwordx4 v[136:139], v[136:137], off
	v_add_u32_e32 v202, 0x80, v194
	v_mov_b32_e32 v203, v159
	v_lshl_add_u64 v[202:203], v[202:203], 2, s[90:91]
	s_waitcnt vmcnt(0)
	v_sub_f32_e32 v241, v241, v220
	v_sub_f32_e32 v240, v240, v220
	v_sub_f32_e32 v243, v243, v220
	v_sub_f32_e32 v242, v242, v220
	v_pk_mul_f32 v[242:243], v[220:221], v[242:243] op_sel:[1,0]
	v_pk_mul_f32 v[240:241], v[220:221], v[240:241] op_sel:[1,0]
	v_pk_fma_f32 v[242:243], v[212:213], v[242:243], v[62:63]
	v_pk_fma_f32 v[240:241], v[214:215], v[240:241], v[60:61]
	v_pk_fma_f32 v[242:243], v[134:135], s[78:79], v[242:243] op_sel_hi:[1,0,1]
	v_pk_fma_f32 v[240:241], v[132:133], s[78:79], v[240:241] op_sel_hi:[1,0,1]
	global_store_dwordx4 v[202:203], v[240:243], off
	v_sub_f32_e32 v203, v245, v220
	v_sub_f32_e32 v202, v244, v220
	v_sub_f32_e32 v241, v247, v220
	v_sub_f32_e32 v240, v246, v220
	v_pk_mul_f32 v[202:203], v[220:221], v[202:203] op_sel:[1,0]
	v_pk_mul_f32 v[240:241], v[220:221], v[240:241] op_sel:[1,0]
	v_pk_fma_f32 v[202:203], v[208:209], v[202:203], v[56:57]
	v_pk_fma_f32 v[220:221], v[206:207], v[240:241], v[58:59]
	v_pk_fma_f32 v[240:241], v[128:129], s[78:79], v[202:203] op_sel_hi:[1,0,1]
	v_add_u32_e32 v202, 0x90, v194
	v_mov_b32_e32 v203, v159
	v_pk_fma_f32 v[242:243], v[130:131], s[78:79], v[220:221] op_sel_hi:[1,0,1]
	v_lshl_add_u64 v[202:203], v[202:203], 2, s[90:91]
	global_store_dwordx4 v[202:203], v[240:243], off
	v_sub_f32_e32 v203, v249, v218
	v_sub_f32_e32 v202, v248, v218
	v_sub_f32_e32 v221, v251, v218
	v_sub_f32_e32 v220, v250, v218
	v_pk_mul_f32 v[202:203], v[218:219], v[202:203] op_sel:[1,0]
	v_pk_mul_f32 v[220:221], v[218:219], v[220:221] op_sel:[1,0]
	v_pk_fma_f32 v[202:203], v[214:215], v[202:203], v[52:53]
	v_pk_fma_f32 v[220:221], v[212:213], v[220:221], v[54:55]
	v_pk_fma_f32 v[240:241], v[132:133], s[78:79], v[202:203] op_sel_hi:[1,0,1]
	v_add_u32_e32 v202, 0x8080, v194
	v_mov_b32_e32 v203, v159
	v_sub_f32_e32 v153, v153, v218
	v_sub_f32_e32 v152, v152, v218
	v_sub_f32_e32 v155, v155, v218
	v_sub_f32_e32 v154, v154, v218
	v_pk_fma_f32 v[242:243], v[134:135], s[78:79], v[220:221] op_sel_hi:[1,0,1]
	v_lshl_add_u64 v[202:203], v[202:203], 2, s[90:91]
	v_pk_mul_f32 v[154:155], v[218:219], v[154:155] op_sel:[1,0]
	v_pk_mul_f32 v[152:153], v[218:219], v[152:153] op_sel:[1,0]
	global_store_dwordx4 v[202:203], v[240:243], off
	v_pk_fma_f32 v[152:153], v[208:209], v[152:153], v[48:49]
	v_pk_fma_f32 v[154:155], v[206:207], v[154:155], v[50:51]
	v_add_u32_e32 v202, 0x8090, v194
	v_mov_b32_e32 v203, v159
	v_sub_f32_e32 v149, v149, v216
	v_sub_f32_e32 v148, v148, v216
	v_sub_f32_e32 v151, v151, v216
	v_sub_f32_e32 v150, v150, v216
	v_pk_fma_f32 v[154:155], v[130:131], s[78:79], v[154:155] op_sel_hi:[1,0,1]
	v_pk_fma_f32 v[152:153], v[128:129], s[78:79], v[152:153] op_sel_hi:[1,0,1]
	v_lshl_add_u64 v[202:203], v[202:203], 2, s[90:91]
	v_pk_mul_f32 v[150:151], v[216:217], v[150:151] op_sel:[1,0]
	v_pk_mul_f32 v[148:149], v[216:217], v[148:149] op_sel:[1,0]
	global_store_dwordx4 v[202:203], v[152:155], off
	v_pk_fma_f32 v[148:149], v[214:215], v[148:149], v[44:45]
	v_pk_fma_f32 v[150:151], v[212:213], v[150:151], v[46:47]
	v_add_u32_e32 v152, 0x10080, v194
	v_mov_b32_e32 v153, v159
	v_sub_f32_e32 v145, v145, v216
	v_sub_f32_e32 v144, v144, v216
	v_sub_f32_e32 v147, v147, v216
	v_sub_f32_e32 v146, v146, v216
	v_pk_fma_f32 v[150:151], v[134:135], s[78:79], v[150:151] op_sel_hi:[1,0,1]
	v_pk_fma_f32 v[148:149], v[132:133], s[78:79], v[148:149] op_sel_hi:[1,0,1]
	v_lshl_add_u64 v[152:153], v[152:153], 2, s[90:91]
	v_pk_mul_f32 v[146:147], v[216:217], v[146:147] op_sel:[1,0]
	v_pk_mul_f32 v[144:145], v[216:217], v[144:145] op_sel:[1,0]
	global_store_dwordx4 v[152:153], v[148:151], off
	v_pk_fma_f32 v[144:145], v[208:209], v[144:145], v[40:41]
	v_pk_fma_f32 v[146:147], v[206:207], v[146:147], v[42:43]
;     template <bool LN, int BJ, int LO, int HI> DI void batch(const f32x4 (&acc)[2][2][4][2], unsigned row0, unsigned col0, const f32x4 (&gv)[2], const f32x4 (&bv)[2]) const {
;         f32x4 r[HI - LO]; float mean[(HI - LO) / 2], rstd[(HI - LO) / 2];
; #pragma unroll
;         for (int i = LO; i < HI; ++i) { const int ai = i >> 3, m = (i >> 1) & 3, n = i & 1; const unsigned row = row0 + ai * HALF + m * 16;
;             if (n == 0) { mean[(i - LO) >> 1] = 0.f; rstd[(i - LO) >> 1] = 1.f;
;                 if (LN) { const float2 st = *(const float2*)(stats + row * 2u); mean[(i - LO) >> 1] = st.x; rstd[(i - LO) >> 1] = st.y; } }
;             r[i - LO] = *(const f32x4*)(src + (row * (unsigned)DM + col0 + BJ * HALF + n * 16)); }
; #pragma unroll
;         for (int i = LO; i < HI; ++i) { const int ai = i >> 3, m = (i >> 1) & 3, n = i & 1; const unsigned row = row0 + ai * HALF + m * 16;
;             *(f32x4*)(Y + (row * (unsigned)DM + col0 + BJ * HALF + n * 16)) = acc[ai][BJ][m][n] + ((r[i - LO] - mean[(i - LO) >> 1]) * rstd[(i - LO) >> 1]) * gv[n] + bv[n]; }
	v_add_u32_e32 v148, 0x10090, v194
	v_mov_b32_e32 v149, v159
	v_sub_f32_e32 v141, v141, v200
	v_sub_f32_e32 v140, v140, v200
	v_sub_f32_e32 v143, v143, v200
	v_sub_f32_e32 v142, v142, v200
	v_pk_fma_f32 v[146:147], v[130:131], s[78:79], v[146:147] op_sel_hi:[1,0,1]
	v_pk_fma_f32 v[144:145], v[128:129], s[78:79], v[144:145] op_sel_hi:[1,0,1]
	v_lshl_add_u64 v[148:149], v[148:149], 2, s[90:91]
	v_pk_mul_f32 v[142:143], v[200:201], v[142:143] op_sel:[1,0]
	v_pk_mul_f32 v[140:141], v[200:201], v[140:141] op_sel:[1,0]
	global_store_dwordx4 v[148:149], v[144:147], off
	v_pk_fma_f32 v[140:141], v[214:215], v[140:141], v[36:37]
	v_pk_fma_f32 v[142:143], v[212:213], v[142:143], v[38:39]
	v_add_u32_e32 v144, 0x18080, v194
	v_mov_b32_e32 v145, v159
	v_sub_f32_e32 v137, v137, v200
	v_sub_f32_e32 v136, v136, v200
	v_sub_f32_e32 v139, v139, v200
	v_sub_f32_e32 v138, v138, v200
	v_pk_fma_f32 v[142:143], v[134:135], s[78:79], v[142:143] op_sel_hi:[1,0,1]
	v_pk_fma_f32 v[140:141], v[132:133], s[78:79], v[140:141] op_sel_hi:[1,0,1]
	v_lshl_add_u64 v[144:145], v[144:145], 2, s[90:91]
	v_pk_mul_f32 v[138:139], v[200:201], v[138:139] op_sel:[1,0]
	v_pk_mul_f32 v[136:137], v[200:201], v[136:137] op_sel:[1,0]
	global_store_dwordx4 v[144:145], v[140:143], off
	v_pk_fma_f32 v[136:137], v[208:209], v[136:137], v[32:33]
	v_pk_fma_f32 v[138:139], v[206:207], v[138:139], v[34:35]
	v_add_u32_e32 v140, 0x18090, v194
	v_mov_b32_e32 v141, v159
	v_pk_fma_f32 v[138:139], v[130:131], s[78:79], v[138:139] op_sel_hi:[1,0,1]
	v_pk_fma_f32 v[136:137], v[128:129], s[78:79], v[136:137] op_sel_hi:[1,0,1]
	v_lshl_add_u64 v[140:141], v[140:141], 2, s[90:91]
	global_store_dwordx4 v[140:141], v[136:139], off
	s_nop 1
	v_add_u32_e32 v136, v233, v230
	v_mov_b32_e32 v137, v159
	v_lshl_add_u64 v[136:137], v[136:137], 2, s[88:89]
	global_load_dwordx2 v[220:221], v[196:197], off
	global_load_dwordx4 v[216:219], v[136:137], off
	v_add_u32_e32 v136, v233, v229
	v_mov_b32_e32 v137, v159
	v_lshl_add_u64 v[136:137], v[136:137], 2, s[88:89]
	global_load_dwordx4 v[240:243], v[136:137], off
	global_load_dwordx2 v[200:201], v[198:199], off
	v_add_u32_e32 v136, v234, v230
	v_mov_b32_e32 v137, v159
	v_lshl_add_u64 v[136:137], v[136:137], 2, s[88:89]
	global_load_dwordx4 v[244:247], v[136:137], off
	v_add_u32_e32 v136, v234, v229
	v_mov_b32_e32 v137, v159
	v_lshl_add_u64 v[136:137], v[136:137], 2, s[88:89]
	global_load_dwordx4 v[152:155], v[136:137], off
	global_load_dwordx2 v[198:199], v[204:205], off
	v_add_u32_e32 v136, v237, v230
	v_mov_b32_e32 v137, v159
	v_lshl_add_u64 v[136:137], v[136:137], 2, s[88:89]
	global_load_dwordx4 v[148:151], v[136:137], off
	v_add_u32_e32 v136, v237, v229
	v_mov_b32_e32 v137, v159
	v_lshl_add_u64 v[136:137], v[136:137], 2, s[88:89]
	global_load_dwordx4 v[144:147], v[136:137], off
	global_load_dwordx2 v[196:197], v[210:211], off
	v_add_u32_e32 v136, v238, v230
	v_mov_b32_e32 v137, v159
	v_lshl_add_u64 v[136:137], v[136:137], 2, s[88:89]
	global_load_dwordx4 v[140:143], v[136:137], off
	v_add_u32_e32 v136, v238, v229
	v_mov_b32_e32 v137, v159
	v_lshl_add_u64 v[136:137], v[136:137], 2, s[88:89]
	global_load_dwordx4 v[136:139], v[136:137], off
	v_add_u32_e32 v210, 0x40080, v194
	v_mov_b32_e32 v211, v159
	v_lshl_add_u64 v[210:211], v[210:211], 2, s[90:91]
	s_waitcnt vmcnt(0)
;     template <bool LN, int BJ, int LO, int HI> DI void batch(const f32x4 (&acc)[2][2][4][2], unsigned row0, unsigned col0, const f32x4 (&gv)[2], const f32x4 (&bv)[2]) const {
;         f32x4 r[HI - LO]; float mean[(HI - LO) / 2], rstd[(HI - LO) / 2];
; #pragma unroll
;         for (int i = LO; i < HI; ++i) { const int ai = i >> 3, m = (i >> 1) & 3, n = i & 1; const unsigned row = row0 + ai * HALF + m * 16;
;             if (n == 0) { mean[(i - LO) >> 1] = 0.f; rstd[(i - LO) >> 1] = 1.f;
;                 if (LN) { const float2 st = *(const float2*)(stats + row * 2u); mean[(i - LO) >> 1] = st.x; rstd[(i - LO) >> 1] = st.y; } }
;             r[i - LO] = *(const f32x4*)(src + (row * (unsigned)DM + col0 + BJ * HALF + n * 16)); }
; #pragma unroll
;         for (int i = LO; i < HI; ++i) { const int ai = i >> 3, m = (i >> 1) & 3, n = i & 1; const unsigned row = row0 + ai * HALF + m * 16;
;             *(f32x4*)(Y + (row * (unsigned)DM + col0 + BJ * HALF + n * 16)) = acc[ai][BJ][m][n] + ((r[i - LO] - mean[(i - LO) >> 1]) * rstd[(i - LO) >> 1]) * gv[n] + bv[n]; }
	v_sub_f32_e32 v203, v217, v220
	v_sub_f32_e32 v202, v216, v220
	v_sub_f32_e32 v205, v219, v220
	v_sub_f32_e32 v204, v218, v220
	v_pk_mul_f32 v[204:205], v[220:221], v[204:205] op_sel:[1,0]
	v_pk_mul_f32 v[202:203], v[220:221], v[202:203] op_sel:[1,0]
	v_pk_fma_f32 v[204:205], v[212:213], v[204:205], v[30:31]
	v_pk_fma_f32 v[202:203], v[214:215], v[202:203], v[28:29]
	v_pk_fma_f32 v[204:205], v[134:135], s[78:79], v[204:205] op_sel_hi:[1,0,1]
	v_pk_fma_f32 v[202:203], v[132:133], s[78:79], v[202:203] op_sel_hi:[1,0,1]
	global_store_dwordx4 v[210:211], v[202:205], off
	v_add_u32_e32 v210, 0x40090, v194
	v_mov_b32_e32 v211, v159
	v_sub_f32_e32 v203, v241, v220
	v_sub_f32_e32 v202, v240, v220
	v_sub_f32_e32 v205, v243, v220
	v_sub_f32_e32 v204, v242, v220
	v_pk_mul_f32 v[204:205], v[220:221], v[204:205] op_sel:[1,0]
	v_pk_mul_f32 v[202:203], v[220:221], v[202:203] op_sel:[1,0]
	v_pk_fma_f32 v[204:205], v[206:207], v[204:205], v[26:27]
	v_pk_fma_f32 v[202:203], v[208:209], v[202:203], v[24:25]
	v_pk_fma_f32 v[204:205], v[130:131], s[78:79], v[204:205] op_sel_hi:[1,0,1]
	v_pk_fma_f32 v[202:203], v[128:129], s[78:79], v[202:203] op_sel_hi:[1,0,1]
	v_lshl_add_u64 v[210:211], v[210:211], 2, s[90:91]
	global_store_dwordx4 v[210:211], v[202:205], off
	v_sub_f32_e32 v149, v149, v198
	v_sub_f32_e32 v148, v148, v198
	v_sub_f32_e32 v203, v245, v200
	v_sub_f32_e32 v202, v244, v200
	v_sub_f32_e32 v141, v141, v196
	v_sub_f32_e32 v140, v140, v196
	v_sub_f32_e32 v205, v247, v200
	v_sub_f32_e32 v204, v246, v200
	v_pk_mul_f32 v[202:203], v[200:201], v[202:203] op_sel:[1,0]
	v_sub_f32_e32 v151, v151, v198
	v_sub_f32_e32 v150, v150, v198
	v_pk_mul_f32 v[148:149], v[198:199], v[148:149] op_sel:[1,0]
	v_sub_f32_e32 v143, v143, v196
	v_sub_f32_e32 v142, v142, v196
	v_pk_mul_f32 v[140:141], v[196:197], v[140:141] op_sel:[1,0]
	v_pk_mul_f32 v[204:205], v[200:201], v[204:205] op_sel:[1,0]
	v_pk_fma_f32 v[202:203], v[214:215], v[202:203], v[20:21]
	v_sub_f32_e32 v153, v153, v200
	v_sub_f32_e32 v152, v152, v200
	v_sub_f32_e32 v155, v155, v200
	v_sub_f32_e32 v154, v154, v200
	v_pk_mul_f32 v[150:151], v[198:199], v[150:151] op_sel:[1,0]
	v_pk_fma_f32 v[148:149], v[214:215], v[148:149], v[12:13]
	v_pk_mul_f32 v[142:143], v[196:197], v[142:143] op_sel:[1,0]
	v_pk_fma_f32 v[140:141], v[214:215], v[140:141], v[4:5]
	v_pk_fma_f32 v[204:205], v[212:213], v[204:205], v[22:23]
	v_pk_fma_f32 v[202:203], v[132:133], s[78:79], v[202:203] op_sel_hi:[1,0,1]
	v_pk_mul_f32 v[154:155], v[200:201], v[154:155] op_sel:[1,0]
	v_pk_mul_f32 v[152:153], v[200:201], v[152:153] op_sel:[1,0]
	v_pk_fma_f32 v[150:151], v[212:213], v[150:151], v[14:15]
	v_pk_fma_f32 v[148:149], v[132:133], s[78:79], v[148:149] op_sel_hi:[1,0,1]
	v_pk_fma_f32 v[142:143], v[212:213], v[142:143], v[6:7]
	v_pk_fma_f32 v[132:133], v[132:133], s[78:79], v[140:141] op_sel_hi:[1,0,1]
	v_add_u32_e32 v140, 0x58080, v194
	v_mov_b32_e32 v141, v159
	v_pk_fma_f32 v[204:205], v[134:135], s[78:79], v[204:205] op_sel_hi:[1,0,1]
	v_pk_fma_f32 v[152:153], v[208:209], v[152:153], v[16:17]
	v_pk_fma_f32 v[154:155], v[206:207], v[154:155], v[18:19]
	v_add_u32_e32 v200, 0x48090, v194
	v_mov_b32_e32 v201, v159
	v_pk_fma_f32 v[150:151], v[134:135], s[78:79], v[150:151] op_sel_hi:[1,0,1]
	v_pk_fma_f32 v[134:135], v[134:135], s[78:79], v[142:143] op_sel_hi:[1,0,1]
	v_lshl_add_u64 v[140:141], v[140:141], 2, s[90:91]
	v_pk_fma_f32 v[154:155], v[130:131], s[78:79], v[154:155] op_sel_hi:[1,0,1]
	v_pk_fma_f32 v[152:153], v[128:129], s[78:79], v[152:153] op_sel_hi:[1,0,1]
	v_lshl_add_u64 v[200:201], v[200:201], 2, s[90:91]
	v_sub_f32_e32 v145, v145, v198
	v_sub_f32_e32 v144, v144, v198
	global_store_dwordx4 v[140:141], v[132:135], off
	global_store_dwordx4 v[200:201], v[152:155], off
	v_sub_f32_e32 v147, v147, v198
	v_sub_f32_e32 v133, v137, v196
	v_sub_f32_e32 v132, v136, v196
	v_add_u32_e32 v152, 0x50080, v194
	v_mov_b32_e32 v153, v159
	v_sub_f32_e32 v146, v146, v198
	v_pk_mul_f32 v[144:145], v[198:199], v[144:145] op_sel:[1,0]
	v_sub_f32_e32 v135, v139, v196
	v_sub_f32_e32 v134, v138, v196
	v_pk_mul_f32 v[132:133], v[196:197], v[132:133] op_sel:[1,0]
	v_lshl_add_u64 v[152:153], v[152:153], 2, s[90:91]
	v_pk_mul_f32 v[146:147], v[198:199], v[146:147] op_sel:[1,0]
	v_pk_fma_f32 v[144:145], v[208:209], v[144:145], v[8:9]
	v_pk_mul_f32 v[134:135], v[196:197], v[134:135] op_sel:[1,0]
	v_pk_fma_f32 v[132:133], v[208:209], v[132:133], v[0:1]
	v_add_u32_e32 v210, 0x48080, v194
	v_mov_b32_e32 v211, v159
	global_store_dwordx4 v[152:153], v[148:151], off
	v_pk_fma_f32 v[146:147], v[206:207], v[146:147], v[10:11]
	v_pk_fma_f32 v[144:145], v[128:129], s[78:79], v[144:145] op_sel_hi:[1,0,1]
	v_add_u32_e32 v148, 0x50090, v194
	v_mov_b32_e32 v149, v159
	v_pk_fma_f32 v[134:135], v[206:207], v[134:135], v[2:3]
	v_pk_fma_f32 v[128:129], v[128:129], s[78:79], v[132:133] op_sel_hi:[1,0,1]
	v_add_u32_e32 v132, 0x58090, v194
	v_mov_b32_e32 v133, v159
	v_lshl_add_u64 v[210:211], v[210:211], 2, s[90:91]
	v_pk_fma_f32 v[146:147], v[130:131], s[78:79], v[146:147] op_sel_hi:[1,0,1]
	v_lshl_add_u64 v[148:149], v[148:149], 2, s[90:91]
	v_pk_fma_f32 v[130:131], v[130:131], s[78:79], v[134:135] op_sel_hi:[1,0,1]
	v_lshl_add_u64 v[132:133], v[132:133], 2, s[90:91]
	global_store_dwordx4 v[210:211], v[202:205], off
	global_store_dwordx4 v[148:149], v[144:147], off
	global_store_dwordx4 v[132:133], v[128:131], off
	s_mov_b64 s[20:21], 0
	s_branch .LBB0_81

; #define PG8_STAGE(bufoff, gbase) do { _Pragma("unroll") for (int _i = 0; _i < 2; ++_i) \
;         __builtin_amdgcn_global_load_lds((const unsigned*)((const char*)(gbase) + voff[_i]), (LAS unsigned*)(lds + (bufoff) + ldsw + _i * 8192), 16, 0, 0); } while (0)
; #define PG8_WAIT_V(n) asm volatile("s_waitcnt vmcnt(" #n ")" ::: "memory")
; #define PG8_BAR __builtin_amdgcn_s_barrier()
; template <class Epi>
; DI void gemm_phase(LAS unsigned char* lds, const Gemm g, const StaticOrder& S, const Epi& E) {
;     ...
;     for (int i = 0; i < 2; ++i) { int R, C; stage_rc(tid * 16 + i * 8192, R, C); voff[i] = (unsigned)(R * K + C) * 2u; }
;     const size_t kstep = (size_t)(BK * 2);
;     const size_t hstep = (size_t)HALF * K * 2;
;     const size_t tstep = 2 * hstep;
;     const unsigned ldsw = (unsigned)wid * 1024u;
;     const int aoff = lds_byte(wr * 64 + fr, fq * 8), boff = lds_byte(wc * 32 + fr, fq * 8);
;     ...
;     if (wr == 1) PG8_BAR;
;     PG8_WAIT_V(4); PG8_BAR;
;     PG8_STAGE(PG8_SB(1, 0), cB + kstep); PG8_STAGE(PG8_SA(1, 0), cA + kstep); PG8_STAGE(PG8_SB(1, 1), cB + hstep + kstep);
;     PG8_WAIT_V(6); PG8_BAR;
.LBB0_122:
	s_load_dwordx8 s[8:15], s[0:1], 0x0
	s_lshl_b64 s[4:5], s[76:77], 2
	v_readlane_b32 s16, v254, 42
	v_readlane_b32 s17, v254, 43
	v_lshl_add_u64 v[0:1], v[0:1], 0, s[94:95]
	s_waitcnt lgkmcnt(0)
	s_mov_b64 s[42:43], s[14:15]
	s_mov_b64 s[38:39], s[10:11]
	s_mov_b64 s[40:41], s[12:13]
	s_mov_b64 s[36:37], s[8:9]
	s_add_u32 s12, s38, s4
	s_addc_u32 s13, s39, s5
	s_add_u32 s14, s40, s4
	s_addc_u32 s15, s41, s5
	s_lshl_b32 s3, s3, 5
	s_and_b32 s3, s3, 0x60
	s_add_i32 m0, s28, 0x18000
	v_lshl_add_u64 v[14:15], s[16:17], 0, v[142:143]
	s_lshl_b32 s6, s2, 13
	s_lshl_b32 s7, s3, 7
	s_waitcnt vmcnt(4)
	s_barrier
	global_load_lds_dwordx4 v[0:1], off
	v_lshl_add_u64 v[0:1], v[2:3], 0, s[94:95]
	s_add_i32 m0, s28, 0x1a000
	s_add_i32 s34, s28, 0x8000
	s_add_i32 s35, s28, 0xa000
	v_lshl_add_u64 v[16:17], s[16:17], 0, v[140:141]
	global_load_lds_dwordx4 v[0:1], off
	v_lshl_add_u64 v[0:1], v[14:15], 0, s[94:95]
	s_mov_b32 m0, s34
	s_add_u32 s4, s18, 0x160080
	global_load_lds_dwordx4 v[0:1], off
	v_lshl_add_u64 v[0:1], v[16:17], 0, s[94:95]
	s_mov_b32 m0, s35
	s_addc_u32 s5, s19, 0
	global_load_lds_dwordx4 v[0:1], off
	s_add_i32 m0, s28, 0x1c000
	v_lshl_add_u64 v[0:1], s[4:5], 0, v[142:143]
	global_load_lds_dwordx4 v[0:1], off
	v_lshl_add_u64 v[0:1], s[4:5], 0, v[140:141]
	s_add_i32 m0, s28, 0x1e000
	s_movk_i32 s5, 0x1600
	global_load_lds_dwordx4 v[0:1], off
	v_bfe_u32 v0, v4, 4, 2
	v_and_b32_e32 v1, 15, v4
	v_lshlrev_b32_e32 v2, 4, v0
	v_lshl_or_b32 v198, s2, 6, v1
	v_lshl_or_b32 v1, v1, 6, v2
	v_lshlrev_b32_e32 v2, 2, v4
	v_and_b32_e32 v2, 32, v2
	v_bitop3_b32 v3, v1, s6, v2 bitop3:0xde
	v_bitop3_b32 v199, v1, s7, v2 bitop3:0xde
	v_add_u32_e32 v199, 0x10000, v199
	v_lshl_or_b32 v200, v0, 2, s3
	v_lshrrev_b32_e32 v1, 1, v10
	v_mul_lo_u32 v0, v9, s5
	s_mov_b32 s4, 0x16000
	v_mad_u64_u32 v[0:1], s[2:3], v1, s4, v[0:1]
	v_or_b32_e32 v0, v0, v11
	v_add_lshl_u32 v158, v0, v12, 1
	v_lshrrev_b32_e32 v1, 1, v5
	v_mul_lo_u32 v0, v6, s5
	v_mad_u64_u32 v[0:1], s[2:3], v1, s4, v[0:1]
	s_waitcnt vmcnt(6)
	s_mov_b64 s[6:7], 0x160080
	v_or_b32_e32 v0, v0, v7
	v_lshl_add_u64 v[144:145], v[158:159], 0, s[6:7]
	v_add_lshl_u32 v158, v0, v8, 1
	v_readlane_b32 s4, v254, 50
	v_lshl_add_u64 v[146:147], v[158:159], 0, s[6:7]
	s_mov_b32 s36, 0
	v_add_u32_e32 v201, 0, v3
	v_readlane_b32 s2, v254, 31
	s_mov_b32 s3, s4
	s_barrier
	v_readlane_b32 s5, v254, 51

; #define PG8_STAGE(bufoff, gbase) do { _Pragma("unroll") for (int _i = 0; _i < 2; ++_i) \
;         __builtin_amdgcn_global_load_lds((const unsigned*)((const char*)(gbase) + voff[_i]), (LAS unsigned*)(lds + (bufoff) + ldsw + _i * 8192), 16, 0, 0); } while (0)
; #define PG8_LDA(dst, b, h) do { _Pragma("unroll") for (int m = 0; m < 4; ++m) _Pragma("unroll") for (int k = 0; k < 2; ++k) dst[m][k] = *(const LAS bf16x8*)(lds + PG8_SA(b, h) + aoff + m * 2048 + k * 1024); } while (0)
; #define PG8_LDB(dst, b, h) do { _Pragma("unroll") for (int n = 0; n < 2; ++n) _Pragma("unroll") for (int k = 0; k < 2; ++k) dst[n][k] = *(const LAS bf16x8*)(lds + PG8_SB(b, h) + boff + n * 2048 + k * 1024); } while (0)
; #define PG8_MMA(ai, bj, At, Bt) do { __builtin_amdgcn_s_setprio(1); _Pragma("unroll") for (int m = 0; m < 4; ++m) _Pragma("unroll") for (int n = 0; n < 2; ++n) _Pragma("unroll") for (int k = 0; k < 2; ++k) \
;         acc[ai][bj][m][n] = __builtin_amdgcn_mfma_f32_16x16x32_bf16(Bt[n][k], At[m][k], acc[ai][bj][m][n], 0, 0, 0); __builtin_amdgcn_s_setprio(0); } while (0)
; #define PG8_WAIT_V(n) asm volatile("s_waitcnt vmcnt(" #n ")" ::: "memory")
; #define PG8_WAIT_L(n) asm volatile("s_waitcnt lgkmcnt(" #n ")" ::: "memory")
; #define PG8_BAR __builtin_amdgcn_s_barrier()
; #define PG8_SCHED __builtin_amdgcn_sched_barrier(0)
; template <class Epi>
; DI void gemm_phase(LAS unsigned char* lds, const Gemm g, const StaticOrder& S, const Epi& E) {
;     ...
;         for (int t = 0; t < nt; t += 2) {
;             const bool last = (t == nt - 2);
;             const char* a1 = cA + (size_t)(t + 1) * kstep;
;             const char* a2 = last ? nA : cA + (size_t)(t + 2) * kstep; const char* b2 = last ? nB : cB + (size_t)(t + 2) * kstep;
;             const char* a3 = a2 + kstep; const char* b3 = b2 + kstep;
;             PG8_LDB(B0, 0, 0); PG8_SCHED; PG8_LDA(At, 0, 0); PG8_STAGE(PG8_SA(1, 1), a1 + hstep);
;             PG8_WAIT_L(8); PG8_BAR; PG8_WAIT_L(0); PG8_MMA(0, 0, At, B0); PG8_BAR; PG8_SCHED;
;             PG8_LDB(B1, 0, 1); PG8_STAGE(PG8_SB(0, 0), b2);
;             PG8_BAR; PG8_WAIT_L(0); PG8_MMA(0, 1, At, B1); PG8_BAR;
;             PG8_LDA(At, 0, 1); PG8_STAGE(PG8_SA(0, 0), a2);
;             PG8_BAR; PG8_WAIT_L(0); PG8_MMA(1, 0, At, B0); PG8_BAR; PG8_SCHED;
;             PG8_STAGE(PG8_SB(0, 1), b2 + hstep);
;             PG8_WAIT_V(6); PG8_BAR; PG8_MMA(1, 1, At, B1); PG8_BAR;
.LBB0_134:
	s_add_u32 s18, s16, 0x100
	s_addc_u32 s19, s17, 0
	s_add_i32 s39, 0, 0x10000
	ds_read_b128 v[96:99], v199
	ds_read_b128 v[100:103], v199 offset:1024
	ds_read_b128 v[136:139], v199 offset:2048
	ds_read_b128 v[148:151], v199 offset:3072
	s_cmpk_eq_i32 s33, 0x54
	s_cselect_b32 s23, s9, s19
	s_cselect_b32 s22, s8, s18
	s_cselect_b32 s21, s11, s5
	s_cselect_b32 s20, s10, s4
	v_lshl_add_u64 v[218:219], s[16:17], 0, v[144:145]
	s_add_i32 m0, s28, 0xc000
	ds_read_b128 v[152:155], v201
	ds_read_b128 v[186:189], v201 offset:1024
	ds_read_b128 v[190:193], v201 offset:2048
	ds_read_b128 v[194:197], v201 offset:3072
	ds_read_b128 v[202:205], v201 offset:4096
	ds_read_b128 v[206:209], v201 offset:5120
	ds_read_b128 v[210:213], v201 offset:6144
	ds_read_b128 v[214:217], v201 offset:7168
	global_load_lds_dwordx4 v[218:219], off
	v_lshl_add_u64 v[218:219], s[16:17], 0, v[146:147]
	s_add_i32 m0, s28, 0xe000
	s_nop 0
	global_load_lds_dwordx4 v[218:219], off
	s_waitcnt lgkmcnt(8)
	s_setprio 1
	s_barrier
	s_waitcnt lgkmcnt(0)
	v_mfma_f32_16x16x32_bf16 v[132:135], v[96:99], v[152:155], v[132:135]
	v_mfma_f32_16x16x32_bf16 v[128:131], v[136:139], v[152:155], v[128:131]
	v_mfma_f32_16x16x32_bf16 v[124:127], v[96:99], v[190:193], v[124:127]
	v_mfma_f32_16x16x32_bf16 v[120:123], v[136:139], v[190:193], v[120:123]
	v_mfma_f32_16x16x32_bf16 v[116:119], v[96:99], v[202:205], v[116:119]
	v_mfma_f32_16x16x32_bf16 v[112:115], v[136:139], v[202:205], v[112:115]
	v_mfma_f32_16x16x32_bf16 v[108:111], v[96:99], v[210:213], v[108:111]
	v_mfma_f32_16x16x32_bf16 v[104:107], v[136:139], v[210:213], v[104:107]
	v_mfma_f32_16x16x32_bf16 v[132:135], v[100:103], v[186:189], v[132:135]
	v_mfma_f32_16x16x32_bf16 v[128:131], v[148:151], v[186:189], v[128:131]
	v_mfma_f32_16x16x32_bf16 v[124:127], v[100:103], v[194:197], v[124:127]
	v_mfma_f32_16x16x32_bf16 v[120:123], v[148:151], v[194:197], v[120:123]
	v_mfma_f32_16x16x32_bf16 v[116:119], v[100:103], v[206:209], v[116:119]
	v_mfma_f32_16x16x32_bf16 v[112:115], v[148:151], v[206:209], v[112:115]
	v_mfma_f32_16x16x32_bf16 v[108:111], v[100:103], v[214:217], v[108:111]
	v_mfma_f32_16x16x32_bf16 v[104:107], v[148:151], v[214:217], v[104:107]
	s_setprio 0
	s_barrier
	s_add_i32 s40, 0, 0x14000
	s_add_i32 s16, s39, s27
	v_lshl_add_u64 v[218:219], s[20:21], 0, v[142:143]
	s_mov_b32 m0, s16
	ds_read_b128 v[226:229], v199 offset:16384
	ds_read_b128 v[230:233], v199 offset:17408
	ds_read_b128 v[234:237], v199 offset:18432
	ds_read_b128 v[238:241], v199 offset:19456
	global_load_lds_dwordx4 v[218:219], off
	v_lshl_add_u64 v[220:221], s[20:21], 0, v[140:141]
	s_add_i32 m0, s16, 0x2000
	s_nop 0
	global_load_lds_dwordx4 v[220:221], off
	s_waitcnt lgkmcnt(0)
	s_setprio 1
	s_barrier
	v_mfma_f32_16x16x32_bf16 v[60:63], v[226:229], v[152:155], v[60:63]
	v_mfma_f32_16x16x32_bf16 v[56:59], v[234:237], v[152:155], v[56:59]
	v_mfma_f32_16x16x32_bf16 v[52:55], v[226:229], v[190:193], v[52:55]
	v_mfma_f32_16x16x32_bf16 v[48:51], v[234:237], v[190:193], v[48:51]
	v_mfma_f32_16x16x32_bf16 v[44:47], v[226:229], v[202:205], v[44:47]
	v_mfma_f32_16x16x32_bf16 v[40:43], v[234:237], v[202:205], v[40:43]
	v_mfma_f32_16x16x32_bf16 v[36:39], v[226:229], v[210:213], v[36:39]
	v_mfma_f32_16x16x32_bf16 v[32:35], v[234:237], v[210:213], v[32:35]
	v_mfma_f32_16x16x32_bf16 v[60:63], v[230:233], v[186:189], v[60:63]
	s_mov_b32 m0, s28
	v_mfma_f32_16x16x32_bf16 v[56:59], v[238:241], v[186:189], v[56:59]
	v_lshl_add_u64 v[242:243], s[22:23], 0, v[142:143]
	v_mfma_f32_16x16x32_bf16 v[52:55], v[230:233], v[194:197], v[52:55]
	v_mfma_f32_16x16x32_bf16 v[48:51], v[238:241], v[194:197], v[48:51]
	v_mfma_f32_16x16x32_bf16 v[44:47], v[230:233], v[206:209], v[44:47]
	v_mfma_f32_16x16x32_bf16 v[40:43], v[238:241], v[206:209], v[40:43]
	v_mfma_f32_16x16x32_bf16 v[36:39], v[230:233], v[214:217], v[36:39]
	v_mfma_f32_16x16x32_bf16 v[32:35], v[238:241], v[214:217], v[32:35]
	s_setprio 0
	s_barrier
	ds_read_b128 v[152:155], v201 offset:16384
	ds_read_b128 v[186:189], v201 offset:17408
	ds_read_b128 v[190:193], v201 offset:18432
	ds_read_b128 v[194:197], v201 offset:19456
	ds_read_b128 v[202:205], v201 offset:20480
	ds_read_b128 v[206:209], v201 offset:21504
	ds_read_b128 v[210:213], v201 offset:22528
	ds_read_b128 v[214:217], v201 offset:23552
	global_load_lds_dwordx4 v[242:243], off
	v_lshl_add_u64 v[244:245], s[22:23], 0, v[140:141]
	s_mov_b32 m0, s29
	s_nop 0
	global_load_lds_dwordx4 v[244:245], off
	s_waitcnt lgkmcnt(0)
	s_setprio 1
	s_barrier
	v_mfma_f32_16x16x32_bf16 v[92:95], v[96:99], v[152:155], v[92:95]
	v_mfma_f32_16x16x32_bf16 v[88:91], v[136:139], v[152:155], v[88:91]
	v_mfma_f32_16x16x32_bf16 v[84:87], v[96:99], v[190:193], v[84:87]
	v_mfma_f32_16x16x32_bf16 v[80:83], v[136:139], v[190:193], v[80:83]
	v_mfma_f32_16x16x32_bf16 v[76:79], v[96:99], v[202:205], v[76:79]
	v_mfma_f32_16x16x32_bf16 v[72:75], v[136:139], v[202:205], v[72:75]
	v_mfma_f32_16x16x32_bf16 v[68:71], v[96:99], v[210:213], v[68:71]
	v_mfma_f32_16x16x32_bf16 v[64:67], v[136:139], v[210:213], v[64:67]
	v_mfma_f32_16x16x32_bf16 v[92:95], v[100:103], v[186:189], v[92:95]
	v_mfma_f32_16x16x32_bf16 v[88:91], v[148:151], v[186:189], v[88:91]
	v_mfma_f32_16x16x32_bf16 v[84:87], v[100:103], v[194:197], v[84:87]
	v_mfma_f32_16x16x32_bf16 v[80:83], v[148:151], v[194:197], v[80:83]
	v_mfma_f32_16x16x32_bf16 v[76:79], v[100:103], v[206:209], v[76:79]
	v_mfma_f32_16x16x32_bf16 v[72:75], v[148:151], v[206:209], v[72:75]
	v_mfma_f32_16x16x32_bf16 v[68:71], v[100:103], v[214:217], v[68:71]
	v_mfma_f32_16x16x32_bf16 v[64:67], v[148:151], v[214:217], v[64:67]
	s_setprio 0
	s_barrier
; #define PG8_STAGE(bufoff, gbase) do { _Pragma("unroll") for (int _i = 0; _i < 2; ++_i) \
;         __builtin_amdgcn_global_load_lds((const unsigned*)((const char*)(gbase) + voff[_i]), (LAS unsigned*)(lds + (bufoff) + ldsw + _i * 8192), 16, 0, 0); } while (0)
; #define PG8_LDA(dst, b, h) do { _Pragma("unroll") for (int m = 0; m < 4; ++m) _Pragma("unroll") for (int k = 0; k < 2; ++k) dst[m][k] = *(const LAS bf16x8*)(lds + PG8_SA(b, h) + aoff + m * 2048 + k * 1024); } while (0)
; #define PG8_LDB(dst, b, h) do { _Pragma("unroll") for (int n = 0; n < 2; ++n) _Pragma("unroll") for (int k = 0; k < 2; ++k) dst[n][k] = *(const LAS bf16x8*)(lds + PG8_SB(b, h) + boff + n * 2048 + k * 1024); } while (0)
; #define PG8_MMA(ai, bj, At, Bt) do { __builtin_amdgcn_s_setprio(1); _Pragma("unroll") for (int m = 0; m < 4; ++m) _Pragma("unroll") for (int n = 0; n < 2; ++n) _Pragma("unroll") for (int k = 0; k < 2; ++k) \
;         acc[ai][bj][m][n] = __builtin_amdgcn_mfma_f32_16x16x32_bf16(Bt[n][k], At[m][k], acc[ai][bj][m][n], 0, 0, 0); __builtin_amdgcn_s_setprio(0); } while (0)
; #define PG8_WAIT_V(n) asm volatile("s_waitcnt vmcnt(" #n ")" ::: "memory")
; #define PG8_WAIT_L(n) asm volatile("s_waitcnt lgkmcnt(" #n ")" ::: "memory")
; #define PG8_BAR __builtin_amdgcn_s_barrier()
; #define PG8_SCHED __builtin_amdgcn_sched_barrier(0)
; template <class Epi>
; DI void gemm_phase(LAS unsigned char* lds, const Gemm g, const StaticOrder& S, const Epi& E) {
;     ...
;             PG8_LDA(At, 0, 1); PG8_STAGE(PG8_SA(0, 0), a2);
;             PG8_BAR; PG8_WAIT_L(0); PG8_MMA(1, 0, At, B0); PG8_BAR; PG8_SCHED;
;             PG8_STAGE(PG8_SB(0, 1), b2 + hstep);
;             PG8_WAIT_V(6); PG8_BAR; PG8_MMA(1, 1, At, B1); PG8_BAR;
;             PG8_LDB(B0, 1, 0); PG8_SCHED; PG8_LDA(At, 1, 0); PG8_STAGE(PG8_SA(0, 1), a2 + hstep);
;             PG8_WAIT_L(8); PG8_BAR; PG8_WAIT_L(0); PG8_MMA(0, 0, At, B0); PG8_BAR; PG8_SCHED;
;             PG8_LDB(B1, 1, 1); PG8_STAGE(PG8_SB(1, 0), b3);
;             PG8_BAR; PG8_WAIT_L(0); PG8_MMA(0, 1, At, B1); PG8_BAR;
;             PG8_LDA(At, 1, 1); PG8_STAGE(PG8_SA(1, 0), a3);
;             PG8_BAR; PG8_WAIT_L(0); PG8_MMA(1, 0, At, B0); PG8_BAR; PG8_SCHED;
	s_add_u32 s16, s20, 0x160000
	s_addc_u32 s17, s21, 0
	s_add_i32 s39, s40, s27
	v_lshl_add_u64 v[96:97], s[16:17], 0, v[142:143]
	s_mov_b32 m0, s39
	s_nop 0
	global_load_lds_dwordx4 v[96:97], off
	v_lshl_add_u64 v[96:97], s[16:17], 0, v[140:141]
	s_add_i32 m0, s39, 0x2000
	s_nop 0
	global_load_lds_dwordx4 v[96:97], off
	s_waitcnt vmcnt(6)
	s_setprio 1
	s_barrier
	v_mfma_f32_16x16x32_bf16 v[28:31], v[226:229], v[152:155], v[28:31]
	v_mfma_f32_16x16x32_bf16 v[24:27], v[234:237], v[152:155], v[24:27]
	v_mfma_f32_16x16x32_bf16 v[20:23], v[226:229], v[190:193], v[20:23]
	v_mfma_f32_16x16x32_bf16 v[16:19], v[234:237], v[190:193], v[16:19]
	v_mfma_f32_16x16x32_bf16 v[12:15], v[226:229], v[202:205], v[12:15]
	v_mfma_f32_16x16x32_bf16 v[8:11], v[234:237], v[202:205], v[8:11]
	v_mfma_f32_16x16x32_bf16 v[4:7], v[226:229], v[210:213], v[4:7]
	v_mfma_f32_16x16x32_bf16 v[0:3], v[234:237], v[210:213], v[0:3]
	v_mfma_f32_16x16x32_bf16 v[28:31], v[230:233], v[186:189], v[28:31]
	s_add_i32 s39, 0, 0x18000
	v_mfma_f32_16x16x32_bf16 v[24:27], v[238:241], v[186:189], v[24:27]
	v_mfma_f32_16x16x32_bf16 v[20:23], v[230:233], v[194:197], v[20:23]
	v_mfma_f32_16x16x32_bf16 v[16:19], v[238:241], v[194:197], v[16:19]
	v_mfma_f32_16x16x32_bf16 v[12:15], v[230:233], v[206:209], v[12:15]
	v_mfma_f32_16x16x32_bf16 v[8:11], v[238:241], v[206:209], v[8:11]
	v_mfma_f32_16x16x32_bf16 v[4:7], v[230:233], v[214:217], v[4:7]
	v_mfma_f32_16x16x32_bf16 v[0:3], v[238:241], v[214:217], v[0:3]
	s_setprio 0
	s_barrier
	ds_read_b128 v[96:99], v199 offset:32768
	ds_read_b128 v[100:103], v199 offset:33792
	ds_read_b128 v[136:139], v199 offset:34816
	ds_read_b128 v[148:151], v199 offset:35840
	s_add_u32 s16, s22, 0x160000
	s_addc_u32 s17, s23, 0
	s_mov_b32 m0, s30
	v_lshl_add_u64 v[226:227], s[16:17], 0, v[142:143]
	ds_read_b128 v[152:155], v201 offset:32768
	ds_read_b128 v[186:189], v201 offset:33792
	ds_read_b128 v[190:193], v201 offset:34816
	ds_read_b128 v[194:197], v201 offset:35840
	ds_read_b128 v[202:205], v201 offset:36864
	ds_read_b128 v[206:209], v201 offset:37888
	ds_read_b128 v[210:213], v201 offset:38912
	ds_read_b128 v[214:217], v201 offset:39936
	global_load_lds_dwordx4 v[226:227], off
	v_lshl_add_u64 v[226:227], s[16:17], 0, v[140:141]
	s_mov_b32 m0, s31
	s_nop 0
	global_load_lds_dwordx4 v[226:227], off
	s_waitcnt lgkmcnt(8)
	s_setprio 1
	s_barrier
	s_waitcnt lgkmcnt(0)
	v_mfma_f32_16x16x32_bf16 v[132:135], v[96:99], v[152:155], v[132:135]
	v_mfma_f32_16x16x32_bf16 v[128:131], v[136:139], v[152:155], v[128:131]
	v_mfma_f32_16x16x32_bf16 v[124:127], v[96:99], v[190:193], v[124:127]
	v_mfma_f32_16x16x32_bf16 v[120:123], v[136:139], v[190:193], v[120:123]
	v_mfma_f32_16x16x32_bf16 v[116:119], v[96:99], v[202:205], v[116:119]
	v_mfma_f32_16x16x32_bf16 v[112:115], v[136:139], v[202:205], v[112:115]
	v_mfma_f32_16x16x32_bf16 v[108:111], v[96:99], v[210:213], v[108:111]
	v_mfma_f32_16x16x32_bf16 v[104:107], v[136:139], v[210:213], v[104:107]
	v_mfma_f32_16x16x32_bf16 v[132:135], v[100:103], v[186:189], v[132:135]
	v_mfma_f32_16x16x32_bf16 v[128:131], v[148:151], v[186:189], v[128:131]
	v_mfma_f32_16x16x32_bf16 v[124:127], v[100:103], v[194:197], v[124:127]
	v_mfma_f32_16x16x32_bf16 v[120:123], v[148:151], v[194:197], v[120:123]
	v_mfma_f32_16x16x32_bf16 v[116:119], v[100:103], v[206:209], v[116:119]
	v_mfma_f32_16x16x32_bf16 v[112:115], v[148:151], v[206:209], v[112:115]
	v_mfma_f32_16x16x32_bf16 v[108:111], v[100:103], v[214:217], v[108:111]
	v_mfma_f32_16x16x32_bf16 v[104:107], v[148:151], v[214:217], v[104:107]
	s_setprio 0
	s_barrier
	s_add_i32 s22, 0, 0x1c000
	s_add_i32 s16, s39, s27
	v_lshl_add_u64 v[218:219], v[218:219], 0, s[94:95]
	s_mov_b32 m0, s16
	ds_read_b128 v[226:229], v199 offset:49152
	ds_read_b128 v[230:233], v199 offset:50176
	ds_read_b128 v[234:237], v199 offset:51200
	ds_read_b128 v[238:241], v199 offset:52224
	global_load_lds_dwordx4 v[218:219], off
	v_lshl_add_u64 v[218:219], v[220:221], 0, s[94:95]
	s_add_i32 m0, s16, 0x2000
	s_nop 0
	global_load_lds_dwordx4 v[218:219], off
	s_waitcnt lgkmcnt(0)
	s_setprio 1
	s_barrier
	v_mfma_f32_16x16x32_bf16 v[60:63], v[226:229], v[152:155], v[60:63]
	v_mfma_f32_16x16x32_bf16 v[56:59], v[234:237], v[152:155], v[56:59]
	v_mfma_f32_16x16x32_bf16 v[52:55], v[226:229], v[190:193], v[52:55]
	v_mfma_f32_16x16x32_bf16 v[48:51], v[234:237], v[190:193], v[48:51]
	v_mfma_f32_16x16x32_bf16 v[44:47], v[226:229], v[202:205], v[44:47]
	v_mfma_f32_16x16x32_bf16 v[40:43], v[234:237], v[202:205], v[40:43]
	v_mfma_f32_16x16x32_bf16 v[36:39], v[226:229], v[210:213], v[36:39]
	v_mfma_f32_16x16x32_bf16 v[32:35], v[234:237], v[210:213], v[32:35]
	v_mfma_f32_16x16x32_bf16 v[60:63], v[230:233], v[186:189], v[60:63]
	s_mov_b32 m0, s34
	v_mfma_f32_16x16x32_bf16 v[56:59], v[238:241], v[186:189], v[56:59]
	v_lshl_add_u64 v[218:219], v[242:243], 0, s[94:95]
	v_mfma_f32_16x16x32_bf16 v[52:55], v[230:233], v[194:197], v[52:55]
	v_mfma_f32_16x16x32_bf16 v[48:51], v[238:241], v[194:197], v[48:51]
	v_mfma_f32_16x16x32_bf16 v[44:47], v[230:233], v[206:209], v[44:47]
	v_mfma_f32_16x16x32_bf16 v[40:43], v[238:241], v[206:209], v[40:43]
	v_mfma_f32_16x16x32_bf16 v[36:39], v[230:233], v[214:217], v[36:39]
	v_mfma_f32_16x16x32_bf16 v[32:35], v[238:241], v[214:217], v[32:35]
	s_setprio 0
	s_barrier
	ds_read_b128 v[152:155], v201 offset:49152
	ds_read_b128 v[186:189], v201 offset:50176
	ds_read_b128 v[190:193], v201 offset:51200
	ds_read_b128 v[194:197], v201 offset:52224
	ds_read_b128 v[202:205], v201 offset:53248
	ds_read_b128 v[206:209], v201 offset:54272
	ds_read_b128 v[210:213], v201 offset:55296
	ds_read_b128 v[214:217], v201 offset:56320
	global_load_lds_dwordx4 v[218:219], off
	v_lshl_add_u64 v[218:219], v[244:245], 0, s[94:95]
	s_mov_b32 m0, s35
	s_nop 0
	global_load_lds_dwordx4 v[218:219], off
	s_waitcnt lgkmcnt(0)
	s_setprio 1
	s_barrier
; template <class Epi>
; DI void gemm_phase(LAS unsigned char* lds, const Gemm g, const StaticOrder& S, const Epi& E) {
;     ...
;             PG8_LDB(B1, 1, 1); PG8_STAGE(PG8_SB(1, 0), b3);
;             PG8_BAR; PG8_WAIT_L(0); PG8_MMA(0, 1, At, B1); PG8_BAR;
;             PG8_LDA(At, 1, 1); PG8_STAGE(PG8_SA(1, 0), a3);
;             PG8_BAR; PG8_WAIT_L(0); PG8_MMA(1, 0, At, B0); PG8_BAR; PG8_SCHED;
;             PG8_STAGE(PG8_SB(1, 1), b3 + hstep);
;             PG8_WAIT_V(6); PG8_BAR; PG8_MMA(1, 1, At, B1); PG8_BAR;
;     template <bool LN, int BJ, int LO, int HI> DI void batch(const f32x4 (&acc)[2][2][4][2], unsigned row0, unsigned col0, const f32x4 (&gv)[2], const f32x4 (&bv)[2]) const {
;         f32x4 r[HI - LO]; float mean[(HI - LO) / 2], rstd[(HI - LO) / 2];
; #pragma unroll
;         for (int i = LO; i < HI; ++i) { const int ai = i >> 3, m = (i >> 1) & 3, n = i & 1; const unsigned row = row0 + ai * HALF + m * 16;
;             if (n == 0) { mean[(i - LO) >> 1] = 0.f; rstd[(i - LO) >> 1] = 1.f;
;                 if (LN) { const float2 st = *(const float2*)(stats + row * 2u); mean[(i - LO) >> 1] = st.x; rstd[(i - LO) >> 1] = st.y; } }
;             r[i - LO] = *(const f32x4*)(src + (row * (unsigned)DM + col0 + BJ * HALF + n * 16)); }
; #pragma unroll
;         for (int i = LO; i < HI; ++i) { const int ai = i >> 3, m = (i >> 1) & 3, n = i & 1; const unsigned row = row0 + ai * HALF + m * 16;
;             *(f32x4*)(Y + (row * (unsigned)DM + col0 + BJ * HALF + n * 16)) = acc[ai][BJ][m][n] + ((r[i - LO] - mean[(i - LO) >> 1]) * rstd[(i - LO) >> 1]) * gv[n] + bv[n]; }
;         __builtin_amdgcn_sched_barrier(0);
;     }
;     template <bool LN, int BJ> DI void load_gb(unsigned col0, f32x4 (&gv)[2], f32x4 (&bv)[2]) const {
; #pragma unroll
;         for (int n = 0; n < 2; ++n) {
;             if (LN) { gv[n] = *(const f32x4*)(gam + col0 + BJ * HALF + n * 16) * ALPHA; bv[n] = *(const f32x4*)(bet + col0 + BJ * HALF + n * 16) * ALPHA; }
;             else { gv[n] = (f32x4){ALPHA, ALPHA, ALPHA, ALPHA}; bv[n] = (f32x4){0.f, 0.f, 0.f, 0.f}; }
;         }
;     }
;     template <bool LN> DI void run(const f32x4 (&acc)[2][2][4][2], const Unit& u, int wr, int wc, int fr, int fq) const {
;         const unsigned row0 = u.pm * BM + wr * 64 + fr, col0 = u.pn * BM + wc * 32 + 4 * fq;
;         f32x4 gv[2], bv[2];
;         load_gb<LN, 0>(col0, gv, bv);
	v_mfma_f32_16x16x32_bf16 v[92:95], v[96:99], v[152:155], v[92:95]
	v_mfma_f32_16x16x32_bf16 v[88:91], v[136:139], v[152:155], v[88:91]
	v_mfma_f32_16x16x32_bf16 v[84:87], v[96:99], v[190:193], v[84:87]
	v_mfma_f32_16x16x32_bf16 v[80:83], v[136:139], v[190:193], v[80:83]
	v_mfma_f32_16x16x32_bf16 v[76:79], v[96:99], v[202:205], v[76:79]
	v_mfma_f32_16x16x32_bf16 v[72:75], v[136:139], v[202:205], v[72:75]
	v_mfma_f32_16x16x32_bf16 v[68:71], v[96:99], v[210:213], v[68:71]
	v_mfma_f32_16x16x32_bf16 v[64:67], v[136:139], v[210:213], v[64:67]
	v_mfma_f32_16x16x32_bf16 v[92:95], v[100:103], v[186:189], v[92:95]
	v_mfma_f32_16x16x32_bf16 v[88:91], v[148:151], v[186:189], v[88:91]
	v_mfma_f32_16x16x32_bf16 v[84:87], v[100:103], v[194:197], v[84:87]
	v_mfma_f32_16x16x32_bf16 v[80:83], v[148:151], v[194:197], v[80:83]
	v_mfma_f32_16x16x32_bf16 v[76:79], v[100:103], v[206:209], v[76:79]
	v_mfma_f32_16x16x32_bf16 v[72:75], v[148:151], v[206:209], v[72:75]
	v_mfma_f32_16x16x32_bf16 v[68:71], v[100:103], v[214:217], v[68:71]
	v_mfma_f32_16x16x32_bf16 v[64:67], v[148:151], v[214:217], v[64:67]
	s_setprio 0
	s_barrier
	s_add_u32 s16, s20, 0x160080
	s_addc_u32 s17, s21, 0
	s_add_i32 s20, s22, s27
	v_lshl_add_u64 v[96:97], s[16:17], 0, v[142:143]
	s_mov_b32 m0, s20
	s_nop 0
	global_load_lds_dwordx4 v[96:97], off
	v_lshl_add_u64 v[96:97], s[16:17], 0, v[140:141]
	s_add_i32 m0, s20, 0x2000
	s_nop 0
	global_load_lds_dwordx4 v[96:97], off
	s_waitcnt vmcnt(6)
	s_setprio 1
	s_barrier
	v_mfma_f32_16x16x32_bf16 v[28:31], v[226:229], v[152:155], v[28:31]
	v_mfma_f32_16x16x32_bf16 v[24:27], v[234:237], v[152:155], v[24:27]
	v_mfma_f32_16x16x32_bf16 v[20:23], v[226:229], v[190:193], v[20:23]
	v_mfma_f32_16x16x32_bf16 v[16:19], v[234:237], v[190:193], v[16:19]
	v_mfma_f32_16x16x32_bf16 v[12:15], v[226:229], v[202:205], v[12:15]
	v_mfma_f32_16x16x32_bf16 v[8:11], v[234:237], v[202:205], v[8:11]
	v_mfma_f32_16x16x32_bf16 v[4:7], v[226:229], v[210:213], v[4:7]
	v_mfma_f32_16x16x32_bf16 v[0:3], v[234:237], v[210:213], v[0:3]
	v_mfma_f32_16x16x32_bf16 v[28:31], v[230:233], v[186:189], v[28:31]
	s_add_i32 s33, s33, 2
	v_mfma_f32_16x16x32_bf16 v[24:27], v[238:241], v[186:189], v[24:27]
	s_add_u32 s4, s4, 0x100
	v_mfma_f32_16x16x32_bf16 v[20:23], v[230:233], v[194:197], v[20:23]
	s_addc_u32 s5, s5, 0
	v_mfma_f32_16x16x32_bf16 v[16:19], v[238:241], v[194:197], v[16:19]
	s_cmpk_gt_u32 s33, 0x55
	v_mfma_f32_16x16x32_bf16 v[12:15], v[230:233], v[206:209], v[12:15]
	s_mov_b64 s[16:17], s[18:19]
	v_mfma_f32_16x16x32_bf16 v[8:11], v[238:241], v[206:209], v[8:11]
	v_mfma_f32_16x16x32_bf16 v[4:7], v[230:233], v[214:217], v[4:7]
	v_mfma_f32_16x16x32_bf16 v[0:3], v[238:241], v[214:217], v[0:3]
	s_setprio 0
	s_barrier
	s_cbranch_scc0 .LBB0_134
	v_lshl_or_b32 v158, s2, 8, v200
	v_lshlrev_b64 v[100:101], 2, v[158:159]
	v_lshl_add_u64 v[150:151], s[12:13], 0, v[100:101]
	global_load_dwordx4 v[96:99], v[150:151], off
	v_lshl_add_u64 v[152:153], s[14:15], 0, v[100:101]
	v_lshl_add_u32 v203, s3, 8, v198
	v_lshlrev_b32_e32 v202, 11, v203
	v_add_u32_e32 v148, v202, v158
	v_mov_b32_e32 v149, v159
	v_lshlrev_b32_e32 v136, 1, v203
	v_mov_b32_e32 v137, v159
	v_lshlrev_b64 v[220:221], 2, v[148:149]
	v_lshl_add_u64 v[154:155], v[136:137], 2, s[96:97]
	v_lshl_add_u64 v[136:137], s[90:91], 0, v[220:221]
	v_or_b32_e32 v204, 16, v158
	v_or_b32_e32 v138, 16, v203
	v_lshlrev_b32_e32 v149, 11, v138
	s_waitcnt vmcnt(0)
	v_pk_mul_f32 v[192:193], v[98:99], s[78:79] op_sel_hi:[1,0]
	v_pk_mul_f32 v[194:195], v[96:97], s[78:79] op_sel_hi:[1,0]
	global_load_dwordx4 v[100:103], v[152:153], off
	global_load_dwordx4 v[96:99], v[150:151], off offset:64
	global_load_dwordx2 v[218:219], v[154:155], off
	global_load_dwordx4 v[206:209], v[136:137], off
	v_add_u32_e32 v136, v202, v204
	v_mov_b32_e32 v137, v159
	v_lshl_add_u64 v[136:137], v[136:137], 2, s[90:91]
	global_load_dwordx4 v[210:213], v[136:137], off
	v_lshlrev_b32_e32 v136, 1, v138
	v_mov_b32_e32 v137, v159
	v_lshl_add_u64 v[186:187], v[136:137], 2, s[96:97]
	v_add_u32_e32 v136, v149, v158
	v_lshl_add_u64 v[136:137], v[136:137], 2, s[90:91]
	global_load_dwordx2 v[196:197], v[186:187], off
	global_load_dwordx4 v[214:217], v[136:137], off
	v_add_u32_e32 v136, v149, v204
	v_mov_b32_e32 v137, v159
	v_lshl_add_u64 v[136:137], v[136:137], 2, s[90:91]
	global_load_dwordx4 v[136:139], v[136:137], off
	s_waitcnt vmcnt(0)
	v_pk_mul_f32 v[188:189], v[98:99], s[78:79] op_sel_hi:[1,0]
	v_pk_mul_f32 v[190:191], v[96:97], s[78:79] op_sel_hi:[1,0]
	global_load_dwordx4 v[96:99], v[152:153], off offset:64
	v_sub_f32_e32 v207, v207, v218
	v_sub_f32_e32 v206, v206, v218
	v_sub_f32_e32 v209, v209, v218
	v_sub_f32_e32 v208, v208, v218
	v_pk_mul_f32 v[208:209], v[218:219], v[208:209] op_sel:[1,0]
	v_pk_mul_f32 v[206:207], v[218:219], v[206:207] op_sel:[1,0]
	v_pk_fma_f32 v[134:135], v[192:193], v[208:209], v[134:135]
	v_pk_fma_f32 v[132:133], v[194:195], v[206:207], v[132:133]
	v_pk_fma_f32 v[134:135], v[102:103], s[78:79], v[134:135] op_sel_hi:[1,0,1]
	v_pk_fma_f32 v[132:133], v[100:101], s[78:79], v[132:133] op_sel_hi:[1,0,1]
	v_lshl_add_u64 v[206:207], s[88:89], 0, v[220:221]
	global_store_dwordx4 v[206:207], v[132:135], off
	s_nop 1
	v_sub_f32_e32 v133, v211, v218
	v_sub_f32_e32 v132, v210, v218
	v_sub_f32_e32 v135, v213, v218
	v_sub_f32_e32 v134, v212, v218
	v_pk_mul_f32 v[134:135], v[218:219], v[134:135] op_sel:[1,0]
	v_pk_mul_f32 v[132:133], v[218:219], v[132:133] op_sel:[1,0]
	v_pk_fma_f32 v[130:131], v[188:189], v[134:135], v[130:131]
	v_pk_fma_f32 v[128:129], v[190:191], v[132:133], v[128:129]
	v_or_b32_e32 v132, 16, v148
	v_mov_b32_e32 v133, v159
	v_lshl_add_u64 v[132:133], v[132:133], 2, s[88:89]
	s_waitcnt vmcnt(0)
;     template <bool LN, int BJ, int LO, int HI> DI void batch(const f32x4 (&acc)[2][2][4][2], unsigned row0, unsigned col0, const f32x4 (&gv)[2], const f32x4 (&bv)[2]) const {
;         f32x4 r[HI - LO]; float mean[(HI - LO) / 2], rstd[(HI - LO) / 2];
; #pragma unroll
;         for (int i = LO; i < HI; ++i) { const int ai = i >> 3, m = (i >> 1) & 3, n = i & 1; const unsigned row = row0 + ai * HALF + m * 16;
;             if (n == 0) { mean[(i - LO) >> 1] = 0.f; rstd[(i - LO) >> 1] = 1.f;
;                 if (LN) { const float2 st = *(const float2*)(stats + row * 2u); mean[(i - LO) >> 1] = st.x; rstd[(i - LO) >> 1] = st.y; } }
;             r[i - LO] = *(const f32x4*)(src + (row * (unsigned)DM + col0 + BJ * HALF + n * 16)); }
; #pragma unroll
;         for (int i = LO; i < HI; ++i) { const int ai = i >> 3, m = (i >> 1) & 3, n = i & 1; const unsigned row = row0 + ai * HALF + m * 16;
;             *(f32x4*)(Y + (row * (unsigned)DM + col0 + BJ * HALF + n * 16)) = acc[ai][BJ][m][n] + ((r[i - LO] - mean[(i - LO) >> 1]) * rstd[(i - LO) >> 1]) * gv[n] + bv[n]; }
;         __builtin_amdgcn_sched_barrier(0);
;     }
;     template <bool LN, int BJ> DI void load_gb(unsigned col0, f32x4 (&gv)[2], f32x4 (&bv)[2]) const {
; #pragma unroll
;         for (int n = 0; n < 2; ++n) {
;             if (LN) { gv[n] = *(const f32x4*)(gam + col0 + BJ * HALF + n * 16) * ALPHA; bv[n] = *(const f32x4*)(bet + col0 + BJ * HALF + n * 16) * ALPHA; }
;             else { gv[n] = (f32x4){ALPHA, ALPHA, ALPHA, ALPHA}; bv[n] = (f32x4){0.f, 0.f, 0.f, 0.f}; }
;         }
;     }
;     template <bool LN> DI void run(const f32x4 (&acc)[2][2][4][2], const Unit& u, int wr, int wc, int fr, int fq) const {
;         const unsigned row0 = u.pm * BM + wr * 64 + fr, col0 = u.pn * BM + wc * 32 + 4 * fq;
;         f32x4 gv[2], bv[2];
;         load_gb<LN, 0>(col0, gv, bv);
;         batch<LN, 0, 0, 4>(acc, row0, col0, gv, bv);
;         batch<LN, 0, 4, 8>(acc, row0, col0, gv, bv);
;         batch<LN, 0, 8, 12>(acc, row0, col0, gv, bv);
;         batch<LN, 0, 12, 16>(acc, row0, col0, gv, bv);
	v_pk_fma_f32 v[130:131], v[98:99], s[78:79], v[130:131] op_sel_hi:[1,0,1]
	v_pk_fma_f32 v[128:129], v[96:97], s[78:79], v[128:129] op_sel_hi:[1,0,1]
	global_store_dwordx4 v[132:133], v[128:131], off
	s_nop 1
	v_sub_f32_e32 v129, v215, v196
	v_sub_f32_e32 v128, v214, v196
	v_sub_f32_e32 v131, v217, v196
	v_sub_f32_e32 v130, v216, v196
	v_pk_mul_f32 v[130:131], v[196:197], v[130:131] op_sel:[1,0]
	v_pk_mul_f32 v[128:129], v[196:197], v[128:129] op_sel:[1,0]
	v_pk_fma_f32 v[126:127], v[192:193], v[130:131], v[126:127]
	v_pk_fma_f32 v[124:125], v[194:195], v[128:129], v[124:125]
	v_add_u32_e32 v128, 0x8000, v148
	v_mov_b32_e32 v129, v159
	v_pk_fma_f32 v[126:127], v[102:103], s[78:79], v[126:127] op_sel_hi:[1,0,1]
	v_pk_fma_f32 v[124:125], v[100:101], s[78:79], v[124:125] op_sel_hi:[1,0,1]
	v_lshl_add_u64 v[128:129], v[128:129], 2, s[88:89]
	global_store_dwordx4 v[128:129], v[124:127], off
	s_nop 1
	v_sub_f32_e32 v125, v137, v196
	v_sub_f32_e32 v124, v136, v196
	v_sub_f32_e32 v127, v139, v196
	v_sub_f32_e32 v126, v138, v196
	v_pk_mul_f32 v[126:127], v[196:197], v[126:127] op_sel:[1,0]
	v_pk_mul_f32 v[124:125], v[196:197], v[124:125] op_sel:[1,0]
	v_pk_fma_f32 v[122:123], v[188:189], v[126:127], v[122:123]
	v_pk_fma_f32 v[120:121], v[190:191], v[124:125], v[120:121]
	v_add_u32_e32 v124, 0x8010, v148
	v_mov_b32_e32 v125, v159
	v_pk_fma_f32 v[122:123], v[98:99], s[78:79], v[122:123] op_sel_hi:[1,0,1]
	v_pk_fma_f32 v[120:121], v[96:97], s[78:79], v[120:121] op_sel_hi:[1,0,1]
	v_lshl_add_u64 v[124:125], v[124:125], 2, s[88:89]
	global_store_dwordx4 v[124:125], v[120:123], off
	s_nop 1
	v_or_b32_e32 v122, 32, v203
	v_lshlrev_b32_e32 v124, 11, v122
	v_lshlrev_b32_e32 v120, 1, v122
	v_mov_b32_e32 v121, v159
	v_add_u32_e32 v122, v124, v158
	v_mov_b32_e32 v123, v159
	v_lshl_add_u64 v[120:121], v[120:121], 2, s[96:97]
	v_lshl_add_u64 v[122:123], v[122:123], 2, s[90:91]
	global_load_dwordx2 v[138:139], v[120:121], off
	global_load_dwordx4 v[126:129], v[122:123], off
	v_add_u32_e32 v122, v124, v204
	v_mov_b32_e32 v123, v159
	v_lshl_add_u64 v[122:123], v[122:123], 2, s[90:91]
	global_load_dwordx4 v[130:133], v[122:123], off
	v_or_b32_e32 v125, 48, v203
	v_lshlrev_b32_e32 v122, 1, v125
	v_lshlrev_b32_e32 v125, 11, v125
	v_mov_b32_e32 v123, v159
	v_add_u32_e32 v134, v125, v158
	v_mov_b32_e32 v135, v159
	v_lshl_add_u64 v[122:123], v[122:123], 2, s[96:97]
	v_lshl_add_u64 v[134:135], v[134:135], 2, s[90:91]
	global_load_dwordx2 v[196:197], v[122:123], off
	v_add_u32_e32 v206, v125, v204
	global_load_dwordx4 v[134:137], v[134:135], off
	v_mov_b32_e32 v207, v159
	v_lshl_add_u64 v[206:207], v[206:207], 2, s[90:91]
	global_load_dwordx4 v[206:209], v[206:207], off
	s_waitcnt vmcnt(0)
	v_sub_f32_e32 v127, v127, v138
	v_sub_f32_e32 v126, v126, v138
	v_sub_f32_e32 v129, v129, v138
	v_sub_f32_e32 v128, v128, v138
	v_pk_mul_f32 v[128:129], v[138:139], v[128:129] op_sel:[1,0]
	v_pk_mul_f32 v[126:127], v[138:139], v[126:127] op_sel:[1,0]
	v_pk_fma_f32 v[118:119], v[192:193], v[128:129], v[118:119]
	v_pk_fma_f32 v[116:117], v[194:195], v[126:127], v[116:117]
	v_add_u32_e32 v126, 0x10000, v148
	v_mov_b32_e32 v127, v159
	v_pk_fma_f32 v[118:119], v[102:103], s[78:79], v[118:119] op_sel_hi:[1,0,1]
	v_pk_fma_f32 v[116:117], v[100:101], s[78:79], v[116:117] op_sel_hi:[1,0,1]
	v_lshl_add_u64 v[126:127], v[126:127], 2, s[88:89]
	global_store_dwordx4 v[126:127], v[116:119], off
	s_nop 1
	v_sub_f32_e32 v117, v131, v138
	v_sub_f32_e32 v116, v130, v138
	v_sub_f32_e32 v119, v133, v138
	v_sub_f32_e32 v118, v132, v138
	v_pk_mul_f32 v[118:119], v[138:139], v[118:119] op_sel:[1,0]
	v_pk_mul_f32 v[116:117], v[138:139], v[116:117] op_sel:[1,0]
	v_pk_fma_f32 v[114:115], v[188:189], v[118:119], v[114:115]
	v_pk_fma_f32 v[112:113], v[190:191], v[116:117], v[112:113]
	v_add_u32_e32 v116, 0x10010, v148
	v_mov_b32_e32 v117, v159
	v_pk_fma_f32 v[114:115], v[98:99], s[78:79], v[114:115] op_sel_hi:[1,0,1]
	v_pk_fma_f32 v[112:113], v[96:97], s[78:79], v[112:113] op_sel_hi:[1,0,1]
	v_lshl_add_u64 v[116:117], v[116:117], 2, s[88:89]
	global_store_dwordx4 v[116:117], v[112:115], off
	s_nop 1
	v_sub_f32_e32 v113, v135, v196
	v_sub_f32_e32 v112, v134, v196
	v_sub_f32_e32 v115, v137, v196
	v_sub_f32_e32 v114, v136, v196
	v_pk_mul_f32 v[114:115], v[196:197], v[114:115] op_sel:[1,0]
	v_pk_mul_f32 v[112:113], v[196:197], v[112:113] op_sel:[1,0]
	v_pk_fma_f32 v[110:111], v[192:193], v[114:115], v[110:111]
	v_pk_fma_f32 v[108:109], v[194:195], v[112:113], v[108:109]
	v_add_u32_e32 v112, 0x18000, v148
	v_mov_b32_e32 v113, v159
	v_pk_fma_f32 v[110:111], v[102:103], s[78:79], v[110:111] op_sel_hi:[1,0,1]
	v_pk_fma_f32 v[108:109], v[100:101], s[78:79], v[108:109] op_sel_hi:[1,0,1]
	v_lshl_add_u64 v[112:113], v[112:113], 2, s[88:89]
	global_store_dwordx4 v[112:113], v[108:111], off
	s_nop 1
	v_sub_f32_e32 v109, v207, v196
	v_sub_f32_e32 v108, v206, v196
	v_sub_f32_e32 v111, v209, v196
	v_sub_f32_e32 v110, v208, v196
	v_pk_mul_f32 v[110:111], v[196:197], v[110:111] op_sel:[1,0]
	v_pk_mul_f32 v[108:109], v[196:197], v[108:109] op_sel:[1,0]
	v_pk_fma_f32 v[106:107], v[188:189], v[110:111], v[106:107]
	v_pk_fma_f32 v[104:105], v[190:191], v[108:109], v[104:105]
	v_add_u32_e32 v108, 0x18010, v148
	v_mov_b32_e32 v109, v159
	v_pk_fma_f32 v[106:107], v[98:99], s[78:79], v[106:107] op_sel_hi:[1,0,1]
	v_pk_fma_f32 v[104:105], v[96:97], s[78:79], v[104:105] op_sel_hi:[1,0,1]
	v_lshl_add_u64 v[108:109], v[108:109], 2, s[88:89]
	global_store_dwordx4 v[108:109], v[104:107], off
	s_nop 1
	v_add_u32_e32 v106, 0x80, v203
	v_lshlrev_b32_e32 v114, 11, v106
	v_lshlrev_b32_e32 v104, 1, v106
	v_mov_b32_e32 v105, v159
	v_add_u32_e32 v106, v114, v158
	v_mov_b32_e32 v107, v159
	v_lshl_add_u64 v[104:105], v[104:105], 2, s[96:97]
	v_lshl_add_u64 v[106:107], v[106:107], 2, s[90:91]
	global_load_dwordx2 v[112:113], v[104:105], off
	global_load_dwordx4 v[108:111], v[106:107], off
	v_add_u32_e32 v106, v114, v204
	v_mov_b32_e32 v107, v159
	v_lshl_add_u64 v[106:107], v[106:107], 2, s[90:91]
	global_load_dwordx4 v[116:119], v[106:107], off
	v_add_u32_e32 v115, 0x90, v203
	v_lshlrev_b32_e32 v106, 1, v115
	v_lshlrev_b32_e32 v115, 11, v115
	v_mov_b32_e32 v107, v159
	v_add_u32_e32 v126, v115, v158
	v_mov_b32_e32 v127, v159
	v_lshl_add_u64 v[106:107], v[106:107], 2, s[96:97]
	v_lshl_add_u64 v[126:127], v[126:127], 2, s[90:91]
	global_load_dwordx2 v[134:135], v[106:107], off
	v_add_u32_e32 v130, v115, v204
	global_load_dwordx4 v[126:129], v[126:127], off
	v_mov_b32_e32 v131, v159
	v_lshl_add_u64 v[130:131], v[130:131], 2, s[90:91]
	global_load_dwordx4 v[130:133], v[130:131], off
	s_waitcnt vmcnt(0)
;     template <bool LN, int BJ, int LO, int HI> DI void batch(const f32x4 (&acc)[2][2][4][2], unsigned row0, unsigned col0, const f32x4 (&gv)[2], const f32x4 (&bv)[2]) const {
;         f32x4 r[HI - LO]; float mean[(HI - LO) / 2], rstd[(HI - LO) / 2];
; #pragma unroll
;         for (int i = LO; i < HI; ++i) { const int ai = i >> 3, m = (i >> 1) & 3, n = i & 1; const unsigned row = row0 + ai * HALF + m * 16;
;             if (n == 0) { mean[(i - LO) >> 1] = 0.f; rstd[(i - LO) >> 1] = 1.f;
;                 if (LN) { const float2 st = *(const float2*)(stats + row * 2u); mean[(i - LO) >> 1] = st.x; rstd[(i - LO) >> 1] = st.y; } }
;             r[i - LO] = *(const f32x4*)(src + (row * (unsigned)DM + col0 + BJ * HALF + n * 16)); }
; #pragma unroll
;         for (int i = LO; i < HI; ++i) { const int ai = i >> 3, m = (i >> 1) & 3, n = i & 1; const unsigned row = row0 + ai * HALF + m * 16;
;             *(f32x4*)(Y + (row * (unsigned)DM + col0 + BJ * HALF + n * 16)) = acc[ai][BJ][m][n] + ((r[i - LO] - mean[(i - LO) >> 1]) * rstd[(i - LO) >> 1]) * gv[n] + bv[n]; }
;         __builtin_amdgcn_sched_barrier(0);
;     }
;     template <bool LN, int BJ> DI void load_gb(unsigned col0, f32x4 (&gv)[2], f32x4 (&bv)[2]) const {
; #pragma unroll
;         for (int n = 0; n < 2; ++n) {
;             if (LN) { gv[n] = *(const f32x4*)(gam + col0 + BJ * HALF + n * 16) * ALPHA; bv[n] = *(const f32x4*)(bet + col0 + BJ * HALF + n * 16) * ALPHA; }
;             else { gv[n] = (f32x4){ALPHA, ALPHA, ALPHA, ALPHA}; bv[n] = (f32x4){0.f, 0.f, 0.f, 0.f}; }
;         }
;     }
;     template <bool LN> DI void run(const f32x4 (&acc)[2][2][4][2], const Unit& u, int wr, int wc, int fr, int fq) const {
;         const unsigned row0 = u.pm * BM + wr * 64 + fr, col0 = u.pn * BM + wc * 32 + 4 * fq;
;         f32x4 gv[2], bv[2];
;         load_gb<LN, 0>(col0, gv, bv);
;         batch<LN, 0, 0, 4>(acc, row0, col0, gv, bv);
;         batch<LN, 0, 4, 8>(acc, row0, col0, gv, bv);
;         batch<LN, 0, 8, 12>(acc, row0, col0, gv, bv);
;         batch<LN, 0, 12, 16>(acc, row0, col0, gv, bv);
;         load_gb<LN, 1>(col0, gv, bv);
;         batch<LN, 1, 0, 8>(acc, row0, col0, gv, bv);
;         batch<LN, 1, 8, 16>(acc, row0, col0, gv, bv);
	v_sub_f32_e32 v109, v109, v112
	v_sub_f32_e32 v108, v108, v112
	v_sub_f32_e32 v111, v111, v112
	v_sub_f32_e32 v110, v110, v112
	v_pk_mul_f32 v[110:111], v[112:113], v[110:111] op_sel:[1,0]
	v_pk_mul_f32 v[108:109], v[112:113], v[108:109] op_sel:[1,0]
	v_pk_fma_f32 v[94:95], v[192:193], v[110:111], v[94:95]
	v_pk_fma_f32 v[92:93], v[194:195], v[108:109], v[92:93]
	v_add_u32_e32 v108, 0x40000, v148
	v_mov_b32_e32 v109, v159
	v_pk_fma_f32 v[94:95], v[102:103], s[78:79], v[94:95] op_sel_hi:[1,0,1]
	v_pk_fma_f32 v[92:93], v[100:101], s[78:79], v[92:93] op_sel_hi:[1,0,1]
	v_lshl_add_u64 v[108:109], v[108:109], 2, s[88:89]
	global_store_dwordx4 v[108:109], v[92:95], off
	s_nop 1
	v_sub_f32_e32 v93, v117, v112
	v_sub_f32_e32 v92, v116, v112
	v_sub_f32_e32 v95, v119, v112
	v_sub_f32_e32 v94, v118, v112
	v_pk_mul_f32 v[94:95], v[112:113], v[94:95] op_sel:[1,0]
	v_pk_mul_f32 v[92:93], v[112:113], v[92:93] op_sel:[1,0]
	v_pk_fma_f32 v[90:91], v[188:189], v[94:95], v[90:91]
	v_pk_fma_f32 v[88:89], v[190:191], v[92:93], v[88:89]
	v_add_u32_e32 v92, 0x40010, v148
	v_mov_b32_e32 v93, v159
	v_pk_fma_f32 v[90:91], v[98:99], s[78:79], v[90:91] op_sel_hi:[1,0,1]
	v_pk_fma_f32 v[88:89], v[96:97], s[78:79], v[88:89] op_sel_hi:[1,0,1]
	v_lshl_add_u64 v[92:93], v[92:93], 2, s[88:89]
	global_store_dwordx4 v[92:93], v[88:91], off
	s_nop 1
	v_sub_f32_e32 v89, v127, v134
	v_sub_f32_e32 v88, v126, v134
	v_sub_f32_e32 v91, v129, v134
	v_sub_f32_e32 v90, v128, v134
	v_pk_mul_f32 v[90:91], v[134:135], v[90:91] op_sel:[1,0]
	v_pk_mul_f32 v[88:89], v[134:135], v[88:89] op_sel:[1,0]
	v_pk_fma_f32 v[86:87], v[192:193], v[90:91], v[86:87]
	v_pk_fma_f32 v[84:85], v[194:195], v[88:89], v[84:85]
	v_add_u32_e32 v88, 0x48000, v148
	v_mov_b32_e32 v89, v159
	v_pk_fma_f32 v[86:87], v[102:103], s[78:79], v[86:87] op_sel_hi:[1,0,1]
	v_pk_fma_f32 v[84:85], v[100:101], s[78:79], v[84:85] op_sel_hi:[1,0,1]
	v_lshl_add_u64 v[88:89], v[88:89], 2, s[88:89]
	global_store_dwordx4 v[88:89], v[84:87], off
	s_nop 1
	v_sub_f32_e32 v85, v131, v134
	v_sub_f32_e32 v84, v130, v134
	v_sub_f32_e32 v87, v133, v134
	v_sub_f32_e32 v86, v132, v134
	v_pk_mul_f32 v[86:87], v[134:135], v[86:87] op_sel:[1,0]
	v_pk_mul_f32 v[84:85], v[134:135], v[84:85] op_sel:[1,0]
	v_pk_fma_f32 v[82:83], v[188:189], v[86:87], v[82:83]
	v_pk_fma_f32 v[80:81], v[190:191], v[84:85], v[80:81]
	v_add_u32_e32 v84, 0x48010, v148
	v_mov_b32_e32 v85, v159
	v_pk_fma_f32 v[82:83], v[98:99], s[78:79], v[82:83] op_sel_hi:[1,0,1]
	v_pk_fma_f32 v[80:81], v[96:97], s[78:79], v[80:81] op_sel_hi:[1,0,1]
	v_lshl_add_u64 v[84:85], v[84:85], 2, s[88:89]
	global_store_dwordx4 v[84:85], v[80:83], off
	s_nop 1
	v_add_u32_e32 v82, 0xa0, v203
	v_lshlrev_b32_e32 v80, 1, v82
	v_mov_b32_e32 v81, v159
	v_lshlrev_b32_e32 v116, 11, v82
	v_lshl_add_u64 v[108:109], v[80:81], 2, s[96:97]
	v_add_u32_e32 v80, v116, v158
	v_lshl_add_u64 v[80:81], v[80:81], 2, s[90:91]
	global_load_dwordx2 v[112:113], v[108:109], off
	v_add_u32_e32 v84, v116, v204
	global_load_dwordx4 v[80:83], v[80:81], off
	v_mov_b32_e32 v85, v159
	v_lshl_add_u64 v[84:85], v[84:85], 2, s[90:91]
	global_load_dwordx4 v[84:87], v[84:85], off
	v_add_u32_e32 v90, 0xb0, v203
	v_lshlrev_b32_e32 v88, 1, v90
	v_mov_b32_e32 v89, v159
	v_lshlrev_b32_e32 v117, 11, v90
	v_lshl_add_u64 v[110:111], v[88:89], 2, s[96:97]
	v_add_u32_e32 v88, v117, v158
	v_lshl_add_u64 v[88:89], v[88:89], 2, s[90:91]
	global_load_dwordx2 v[118:119], v[110:111], off
	v_add_u32_e32 v92, v117, v204
	global_load_dwordx4 v[88:91], v[88:89], off
	v_mov_b32_e32 v93, v159
	v_lshl_add_u64 v[92:93], v[92:93], 2, s[90:91]
	global_load_dwordx4 v[92:95], v[92:93], off
	s_waitcnt vmcnt(0)
	v_sub_f32_e32 v81, v81, v112
	v_sub_f32_e32 v80, v80, v112
	v_sub_f32_e32 v83, v83, v112
	v_sub_f32_e32 v82, v82, v112
	v_pk_mul_f32 v[82:83], v[112:113], v[82:83] op_sel:[1,0]
	v_pk_mul_f32 v[80:81], v[112:113], v[80:81] op_sel:[1,0]
	v_pk_fma_f32 v[78:79], v[192:193], v[82:83], v[78:79]
	v_pk_fma_f32 v[76:77], v[194:195], v[80:81], v[76:77]
	v_add_u32_e32 v80, 0x50000, v148
	v_mov_b32_e32 v81, v159
	v_pk_fma_f32 v[78:79], v[102:103], s[78:79], v[78:79] op_sel_hi:[1,0,1]
	v_pk_fma_f32 v[76:77], v[100:101], s[78:79], v[76:77] op_sel_hi:[1,0,1]
	v_lshl_add_u64 v[80:81], v[80:81], 2, s[88:89]
	global_store_dwordx4 v[80:81], v[76:79], off
	s_nop 1
	v_sub_f32_e32 v77, v85, v112
	v_sub_f32_e32 v76, v84, v112
	v_sub_f32_e32 v79, v87, v112
	v_sub_f32_e32 v78, v86, v112
	v_pk_mul_f32 v[78:79], v[112:113], v[78:79] op_sel:[1,0]
	v_pk_mul_f32 v[76:77], v[112:113], v[76:77] op_sel:[1,0]
	v_pk_fma_f32 v[74:75], v[188:189], v[78:79], v[74:75]
	v_pk_fma_f32 v[72:73], v[190:191], v[76:77], v[72:73]
	v_add_u32_e32 v76, 0x50010, v148
	v_mov_b32_e32 v77, v159
	v_pk_fma_f32 v[74:75], v[98:99], s[78:79], v[74:75] op_sel_hi:[1,0,1]
	v_pk_fma_f32 v[72:73], v[96:97], s[78:79], v[72:73] op_sel_hi:[1,0,1]
	v_lshl_add_u64 v[76:77], v[76:77], 2, s[88:89]
	global_store_dwordx4 v[76:77], v[72:75], off
	s_nop 1
	v_sub_f32_e32 v73, v89, v118
	v_sub_f32_e32 v72, v88, v118
	v_sub_f32_e32 v75, v91, v118
	v_sub_f32_e32 v74, v90, v118
	v_pk_mul_f32 v[74:75], v[118:119], v[74:75] op_sel:[1,0]
	v_pk_mul_f32 v[72:73], v[118:119], v[72:73] op_sel:[1,0]
	v_pk_fma_f32 v[70:71], v[192:193], v[74:75], v[70:71]
	v_pk_fma_f32 v[68:69], v[194:195], v[72:73], v[68:69]
	v_add_u32_e32 v72, 0x58000, v148
	v_mov_b32_e32 v73, v159
	v_pk_fma_f32 v[70:71], v[102:103], s[78:79], v[70:71] op_sel_hi:[1,0,1]
	v_pk_fma_f32 v[68:69], v[100:101], s[78:79], v[68:69] op_sel_hi:[1,0,1]
	v_lshl_add_u64 v[72:73], v[72:73], 2, s[88:89]
	global_store_dwordx4 v[72:73], v[68:71], off
	s_nop 1
	v_sub_f32_e32 v69, v93, v118
	v_sub_f32_e32 v68, v92, v118
	v_sub_f32_e32 v71, v95, v118
	v_sub_f32_e32 v70, v94, v118
	v_pk_mul_f32 v[70:71], v[118:119], v[70:71] op_sel:[1,0]
	v_pk_mul_f32 v[68:69], v[118:119], v[68:69] op_sel:[1,0]
	v_pk_fma_f32 v[66:67], v[188:189], v[70:71], v[66:67]
	v_pk_fma_f32 v[64:65], v[190:191], v[68:69], v[64:65]
	v_add_u32_e32 v68, 0x58010, v148
	v_mov_b32_e32 v69, v159
	v_pk_fma_f32 v[66:67], v[98:99], s[78:79], v[66:67] op_sel_hi:[1,0,1]
	v_pk_fma_f32 v[64:65], v[96:97], s[78:79], v[64:65] op_sel_hi:[1,0,1]
	v_lshl_add_u64 v[68:69], v[68:69], 2, s[88:89]
	global_store_dwordx4 v[68:69], v[64:67], off
	global_load_dwordx4 v[64:67], v[150:151], off offset:512
	v_or_b32_e32 v119, 0x80, v158
	v_add_u32_e32 v72, v202, v119
	v_mov_b32_e32 v73, v159
	v_lshl_add_u64 v[72:73], v[72:73], 2, s[90:91]
	v_or_b32_e32 v118, 0x90, v158
	v_add_u32_e32 v158, v202, v118
	s_waitcnt vmcnt(0)
;     template <bool LN, int BJ, int LO, int HI> DI void batch(const f32x4 (&acc)[2][2][4][2], unsigned row0, unsigned col0, const f32x4 (&gv)[2], const f32x4 (&bv)[2]) const {
;         f32x4 r[HI - LO]; float mean[(HI - LO) / 2], rstd[(HI - LO) / 2];
; #pragma unroll
;         for (int i = LO; i < HI; ++i) { const int ai = i >> 3, m = (i >> 1) & 3, n = i & 1; const unsigned row = row0 + ai * HALF + m * 16;
;             if (n == 0) { mean[(i - LO) >> 1] = 0.f; rstd[(i - LO) >> 1] = 1.f;
;                 if (LN) { const float2 st = *(const float2*)(stats + row * 2u); mean[(i - LO) >> 1] = st.x; rstd[(i - LO) >> 1] = st.y; } }
;             r[i - LO] = *(const f32x4*)(src + (row * (unsigned)DM + col0 + BJ * HALF + n * 16)); }
; #pragma unroll
;         for (int i = LO; i < HI; ++i) { const int ai = i >> 3, m = (i >> 1) & 3, n = i & 1; const unsigned row = row0 + ai * HALF + m * 16;
;             *(f32x4*)(Y + (row * (unsigned)DM + col0 + BJ * HALF + n * 16)) = acc[ai][BJ][m][n] + ((r[i - LO] - mean[(i - LO) >> 1]) * rstd[(i - LO) >> 1]) * gv[n] + bv[n]; }
;         __builtin_amdgcn_sched_barrier(0);
;     }
;     template <bool LN, int BJ> DI void load_gb(unsigned col0, f32x4 (&gv)[2], f32x4 (&bv)[2]) const {
; #pragma unroll
;         for (int n = 0; n < 2; ++n) {
;             if (LN) { gv[n] = *(const f32x4*)(gam + col0 + BJ * HALF + n * 16) * ALPHA; bv[n] = *(const f32x4*)(bet + col0 + BJ * HALF + n * 16) * ALPHA; }
;             else { gv[n] = (f32x4){ALPHA, ALPHA, ALPHA, ALPHA}; bv[n] = (f32x4){0.f, 0.f, 0.f, 0.f}; }
;         }
;     }
;     template <bool LN> DI void run(const f32x4 (&acc)[2][2][4][2], const Unit& u, int wr, int wc, int fr, int fq) const {
;         const unsigned row0 = u.pm * BM + wr * 64 + fr, col0 = u.pn * BM + wc * 32 + 4 * fq;
;         f32x4 gv[2], bv[2];
;         load_gb<LN, 0>(col0, gv, bv);
;         batch<LN, 0, 0, 4>(acc, row0, col0, gv, bv);
;         batch<LN, 0, 4, 8>(acc, row0, col0, gv, bv);
;         batch<LN, 0, 8, 12>(acc, row0, col0, gv, bv);
;         batch<LN, 0, 12, 16>(acc, row0, col0, gv, bv);
;         load_gb<LN, 1>(col0, gv, bv);
;         batch<LN, 1, 0, 8>(acc, row0, col0, gv, bv);
	v_pk_mul_f32 v[96:97], v[66:67], s[78:79] op_sel_hi:[1,0]
	v_pk_mul_f32 v[98:99], v[64:65], s[78:79] op_sel_hi:[1,0]
	global_load_dwordx4 v[68:71], v[152:153], off offset:512
	global_load_dwordx4 v[64:67], v[150:151], off offset:576
	global_load_dwordx2 v[138:139], v[154:155], off
	global_load_dwordx4 v[126:129], v[72:73], off
	v_lshl_add_u64 v[72:73], v[158:159], 2, s[90:91]
	v_add_u32_e32 v158, v149, v119
	s_waitcnt vmcnt(0)
	v_pk_mul_f32 v[92:93], v[66:67], s[78:79] op_sel_hi:[1,0]
	v_pk_mul_f32 v[94:95], v[64:65], s[78:79] op_sel_hi:[1,0]
	global_load_dwordx4 v[64:67], v[152:153], off offset:576
	global_load_dwordx4 v[130:133], v[72:73], off
	global_load_dwordx2 v[112:113], v[186:187], off
	v_lshl_add_u64 v[72:73], v[158:159], 2, s[90:91]
	global_load_dwordx4 v[134:137], v[72:73], off
	v_add_u32_e32 v158, v149, v118
	v_lshl_add_u64 v[72:73], v[158:159], 2, s[90:91]
	global_load_dwordx4 v[88:91], v[72:73], off
	global_load_dwordx2 v[102:103], v[120:121], off
	v_add_u32_e32 v158, v124, v119
	v_lshl_add_u64 v[72:73], v[158:159], 2, s[90:91]
	global_load_dwordx4 v[84:87], v[72:73], off
	v_add_u32_e32 v158, v124, v118
	v_lshl_add_u64 v[72:73], v[158:159], 2, s[90:91]
	global_load_dwordx4 v[80:83], v[72:73], off
	global_load_dwordx2 v[100:101], v[122:123], off
	v_add_u32_e32 v158, v125, v119
	v_lshl_add_u64 v[72:73], v[158:159], 2, s[90:91]
	global_load_dwordx4 v[76:79], v[72:73], off
	v_add_u32_e32 v158, v125, v118
	v_lshl_add_u64 v[72:73], v[158:159], 2, s[90:91]
	global_load_dwordx4 v[72:75], v[72:73], off
	v_sub_f32_e32 v121, v127, v138
	v_sub_f32_e32 v120, v126, v138
	v_sub_f32_e32 v123, v129, v138
	v_sub_f32_e32 v122, v128, v138
	v_pk_mul_f32 v[122:123], v[138:139], v[122:123] op_sel:[1,0]
	v_pk_mul_f32 v[120:121], v[138:139], v[120:121] op_sel:[1,0]
	v_or_b32_e32 v158, 0x80, v148
	v_pk_fma_f32 v[60:61], v[98:99], v[120:121], v[60:61]
	v_pk_fma_f32 v[62:63], v[96:97], v[122:123], v[62:63]
	v_pk_fma_f32 v[60:61], v[68:69], s[78:79], v[60:61] op_sel_hi:[1,0,1]
	v_pk_fma_f32 v[62:63], v[70:71], s[78:79], v[62:63] op_sel_hi:[1,0,1]
	v_lshl_add_u64 v[120:121], v[158:159], 2, s[88:89]
	global_store_dwordx4 v[120:121], v[60:63], off
	v_or_b32_e32 v158, 0x90, v148
	s_waitcnt vmcnt(0)
	v_sub_f32_e32 v61, v131, v138
	v_sub_f32_e32 v60, v130, v138
	v_sub_f32_e32 v63, v133, v138
	v_sub_f32_e32 v62, v132, v138
	v_pk_mul_f32 v[62:63], v[138:139], v[62:63] op_sel:[1,0]
	v_pk_mul_f32 v[60:61], v[138:139], v[60:61] op_sel:[1,0]
	v_pk_fma_f32 v[58:59], v[92:93], v[62:63], v[58:59]
	v_pk_fma_f32 v[56:57], v[94:95], v[60:61], v[56:57]
	v_pk_fma_f32 v[58:59], v[66:67], s[78:79], v[58:59] op_sel_hi:[1,0,1]
	v_pk_fma_f32 v[56:57], v[64:65], s[78:79], v[56:57] op_sel_hi:[1,0,1]
	v_lshl_add_u64 v[60:61], v[158:159], 2, s[88:89]
	global_store_dwordx4 v[60:61], v[56:59], off
	v_add_u32_e32 v158, 0x8080, v148
	s_nop 0
	v_sub_f32_e32 v57, v135, v112
	v_sub_f32_e32 v56, v134, v112
	v_sub_f32_e32 v59, v137, v112
	v_sub_f32_e32 v58, v136, v112
	v_pk_mul_f32 v[58:59], v[112:113], v[58:59] op_sel:[1,0]
	v_pk_mul_f32 v[56:57], v[112:113], v[56:57] op_sel:[1,0]
	v_pk_fma_f32 v[54:55], v[96:97], v[58:59], v[54:55]
	v_pk_fma_f32 v[52:53], v[98:99], v[56:57], v[52:53]
	v_pk_fma_f32 v[54:55], v[70:71], s[78:79], v[54:55] op_sel_hi:[1,0,1]
	v_pk_fma_f32 v[52:53], v[68:69], s[78:79], v[52:53] op_sel_hi:[1,0,1]
	v_lshl_add_u64 v[56:57], v[158:159], 2, s[88:89]
	global_store_dwordx4 v[56:57], v[52:55], off
	v_add_u32_e32 v158, 0x8090, v148
	s_nop 0
	v_sub_f32_e32 v53, v89, v112
	v_sub_f32_e32 v52, v88, v112
	v_sub_f32_e32 v55, v91, v112
	v_sub_f32_e32 v54, v90, v112
	v_pk_mul_f32 v[54:55], v[112:113], v[54:55] op_sel:[1,0]
	v_pk_mul_f32 v[52:53], v[112:113], v[52:53] op_sel:[1,0]
	v_pk_fma_f32 v[50:51], v[92:93], v[54:55], v[50:51]
	v_pk_fma_f32 v[48:49], v[94:95], v[52:53], v[48:49]
	v_pk_fma_f32 v[50:51], v[66:67], s[78:79], v[50:51] op_sel_hi:[1,0,1]
	v_pk_fma_f32 v[48:49], v[64:65], s[78:79], v[48:49] op_sel_hi:[1,0,1]
	v_lshl_add_u64 v[52:53], v[158:159], 2, s[88:89]
	global_store_dwordx4 v[52:53], v[48:51], off
	v_add_u32_e32 v158, 0x10080, v148
	s_nop 0
	v_sub_f32_e32 v49, v85, v102
	v_sub_f32_e32 v48, v84, v102
	v_sub_f32_e32 v51, v87, v102
	v_sub_f32_e32 v50, v86, v102
	v_pk_mul_f32 v[50:51], v[102:103], v[50:51] op_sel:[1,0]
	v_pk_mul_f32 v[48:49], v[102:103], v[48:49] op_sel:[1,0]
	v_pk_fma_f32 v[46:47], v[96:97], v[50:51], v[46:47]
	v_pk_fma_f32 v[44:45], v[98:99], v[48:49], v[44:45]
	v_pk_fma_f32 v[46:47], v[70:71], s[78:79], v[46:47] op_sel_hi:[1,0,1]
	v_pk_fma_f32 v[44:45], v[68:69], s[78:79], v[44:45] op_sel_hi:[1,0,1]
	v_lshl_add_u64 v[48:49], v[158:159], 2, s[88:89]
	global_store_dwordx4 v[48:49], v[44:47], off
	v_add_u32_e32 v158, 0x10090, v148
	s_nop 0
	v_sub_f32_e32 v45, v81, v102
	v_sub_f32_e32 v44, v80, v102
	v_sub_f32_e32 v47, v83, v102
	v_sub_f32_e32 v46, v82, v102
	v_pk_mul_f32 v[46:47], v[102:103], v[46:47] op_sel:[1,0]
	v_pk_mul_f32 v[44:45], v[102:103], v[44:45] op_sel:[1,0]
	v_pk_fma_f32 v[42:43], v[92:93], v[46:47], v[42:43]
	v_pk_fma_f32 v[40:41], v[94:95], v[44:45], v[40:41]
	v_pk_fma_f32 v[42:43], v[66:67], s[78:79], v[42:43] op_sel_hi:[1,0,1]
	v_pk_fma_f32 v[40:41], v[64:65], s[78:79], v[40:41] op_sel_hi:[1,0,1]
	v_lshl_add_u64 v[44:45], v[158:159], 2, s[88:89]
	global_store_dwordx4 v[44:45], v[40:43], off
	v_add_u32_e32 v158, 0x18080, v148
	s_nop 0
	v_sub_f32_e32 v41, v77, v100
	v_sub_f32_e32 v40, v76, v100
	v_sub_f32_e32 v43, v79, v100
	v_sub_f32_e32 v42, v78, v100
	v_pk_mul_f32 v[42:43], v[100:101], v[42:43] op_sel:[1,0]
	v_pk_mul_f32 v[40:41], v[100:101], v[40:41] op_sel:[1,0]
	v_pk_fma_f32 v[38:39], v[96:97], v[42:43], v[38:39]
;     template <bool LN, int BJ, int LO, int HI> DI void batch(const f32x4 (&acc)[2][2][4][2], unsigned row0, unsigned col0, const f32x4 (&gv)[2], const f32x4 (&bv)[2]) const {
;         f32x4 r[HI - LO]; float mean[(HI - LO) / 2], rstd[(HI - LO) / 2];
; #pragma unroll
;         for (int i = LO; i < HI; ++i) { const int ai = i >> 3, m = (i >> 1) & 3, n = i & 1; const unsigned row = row0 + ai * HALF + m * 16;
;             if (n == 0) { mean[(i - LO) >> 1] = 0.f; rstd[(i - LO) >> 1] = 1.f;
;                 if (LN) { const float2 st = *(const float2*)(stats + row * 2u); mean[(i - LO) >> 1] = st.x; rstd[(i - LO) >> 1] = st.y; } }
;             r[i - LO] = *(const f32x4*)(src + (row * (unsigned)DM + col0 + BJ * HALF + n * 16)); }
; #pragma unroll
;         for (int i = LO; i < HI; ++i) { const int ai = i >> 3, m = (i >> 1) & 3, n = i & 1; const unsigned row = row0 + ai * HALF + m * 16;
;             *(f32x4*)(Y + (row * (unsigned)DM + col0 + BJ * HALF + n * 16)) = acc[ai][BJ][m][n] + ((r[i - LO] - mean[(i - LO) >> 1]) * rstd[(i - LO) >> 1]) * gv[n] + bv[n]; }
	v_pk_fma_f32 v[36:37], v[98:99], v[40:41], v[36:37]
	v_pk_fma_f32 v[38:39], v[70:71], s[78:79], v[38:39] op_sel_hi:[1,0,1]
	v_pk_fma_f32 v[36:37], v[68:69], s[78:79], v[36:37] op_sel_hi:[1,0,1]
	v_lshl_add_u64 v[40:41], v[158:159], 2, s[88:89]
	global_store_dwordx4 v[40:41], v[36:39], off
	v_add_u32_e32 v158, 0x18090, v148
	s_nop 0
	v_sub_f32_e32 v37, v73, v100
	v_sub_f32_e32 v36, v72, v100
	v_sub_f32_e32 v39, v75, v100
	v_sub_f32_e32 v38, v74, v100
	v_pk_mul_f32 v[38:39], v[100:101], v[38:39] op_sel:[1,0]
	v_pk_mul_f32 v[36:37], v[100:101], v[36:37] op_sel:[1,0]
	v_pk_fma_f32 v[34:35], v[92:93], v[38:39], v[34:35]
	v_pk_fma_f32 v[32:33], v[94:95], v[36:37], v[32:33]
	v_pk_fma_f32 v[34:35], v[66:67], s[78:79], v[34:35] op_sel_hi:[1,0,1]
	v_pk_fma_f32 v[32:33], v[64:65], s[78:79], v[32:33] op_sel_hi:[1,0,1]
	v_lshl_add_u64 v[36:37], v[158:159], 2, s[88:89]
	global_store_dwordx4 v[36:37], v[32:35], off
	v_add_u32_e32 v158, v114, v119
	s_nop 0
	v_lshl_add_u64 v[32:33], v[158:159], 2, s[90:91]
	global_load_dwordx2 v[62:63], v[104:105], off
	global_load_dwordx4 v[54:57], v[32:33], off
	v_add_u32_e32 v158, v114, v118
	v_lshl_add_u64 v[32:33], v[158:159], 2, s[90:91]
	global_load_dwordx4 v[58:61], v[32:33], off
	global_load_dwordx2 v[52:53], v[106:107], off
	v_add_u32_e32 v158, v115, v119
	v_lshl_add_u64 v[32:33], v[158:159], 2, s[90:91]
	global_load_dwordx4 v[72:75], v[32:33], off
	v_add_u32_e32 v158, v115, v118
	v_lshl_add_u64 v[32:33], v[158:159], 2, s[90:91]
	global_load_dwordx4 v[76:79], v[32:33], off
	global_load_dwordx2 v[50:51], v[108:109], off
	v_add_u32_e32 v158, v116, v119
	v_lshl_add_u64 v[32:33], v[158:159], 2, s[90:91]
	global_load_dwordx4 v[44:47], v[32:33], off
	v_add_u32_e32 v158, v116, v118
	v_lshl_add_u64 v[32:33], v[158:159], 2, s[90:91]
	global_load_dwordx4 v[40:43], v[32:33], off
	global_load_dwordx2 v[48:49], v[110:111], off
	v_add_u32_e32 v158, v117, v119
	v_lshl_add_u64 v[32:33], v[158:159], 2, s[90:91]
	global_load_dwordx4 v[36:39], v[32:33], off
	v_add_u32_e32 v158, v117, v118
	v_lshl_add_u64 v[32:33], v[158:159], 2, s[90:91]
	global_load_dwordx4 v[32:35], v[32:33], off
	v_add_u32_e32 v158, 0x40080, v148
	s_waitcnt vmcnt(0)
; #define PG8_WAIT_V(n) asm volatile("s_waitcnt vmcnt(" #n ")" ::: "memory")
; #define PG8_BAR __builtin_amdgcn_s_barrier()
; template <class Epi>
; DI void gemm_phase(LAS unsigned char* lds, const Gemm g, const StaticOrder& S, const Epi& E) {
;     ...
;         E(acc, cur, wr, wc, fr, fq);
;         if (!has_next) break;
; #pragma unroll
;         for (int a = 0; a < 2; ++a)
; #pragma unroll
;             for (int b = 0; b < 2; ++b)
; #pragma unroll
;                 for (int m = 0; m < 4; ++m)
; #pragma unroll
;                     for (int n = 0; n < 2; ++n) acc[a][b][m][n] = (f32x4){0.f, 0.f, 0.f, 0.f};
;         cur = nxt; cA = nA; cB = nB; ++ui;
;     }
;     PG8_WAIT_V(0);
;     if (wr == 0) PG8_BAR;
;     PG8_BAR;
;     template <bool LN, int BJ, int LO, int HI> DI void batch(const f32x4 (&acc)[2][2][4][2], unsigned row0, unsigned col0, const f32x4 (&gv)[2], const f32x4 (&bv)[2]) const {
;     ...
;         for (int i = LO; i < HI; ++i) { const int ai = i >> 3, m = (i >> 1) & 3, n = i & 1; const unsigned row = row0 + ai * HALF + m * 16;
;             if (n == 0) { mean[(i - LO) >> 1] = 0.f; rstd[(i - LO) >> 1] = 1.f;
;                 if (LN) { const float2 st = *(const float2*)(stats + row * 2u); mean[(i - LO) >> 1] = st.x; rstd[(i - LO) >> 1] = st.y; } }
;             r[i - LO] = *(const f32x4*)(src + (row * (unsigned)DM + col0 + BJ * HALF + n * 16)); }
; #pragma unroll
;         for (int i = LO; i < HI; ++i) { const int ai = i >> 3, m = (i >> 1) & 3, n = i & 1; const unsigned row = row0 + ai * HALF + m * 16;
;             *(f32x4*)(Y + (row * (unsigned)DM + col0 + BJ * HALF + n * 16)) = acc[ai][BJ][m][n] + ((r[i - LO] - mean[(i - LO) >> 1]) * rstd[(i - LO) >> 1]) * gv[n] + bv[n]; }
	v_sub_f32_e32 v55, v55, v62
	v_sub_f32_e32 v54, v54, v62
	v_sub_f32_e32 v57, v57, v62
	v_sub_f32_e32 v56, v56, v62
	v_pk_mul_f32 v[56:57], v[62:63], v[56:57] op_sel:[1,0]
	v_pk_mul_f32 v[54:55], v[62:63], v[54:55] op_sel:[1,0]
	v_pk_fma_f32 v[30:31], v[96:97], v[56:57], v[30:31]
	v_pk_fma_f32 v[28:29], v[98:99], v[54:55], v[28:29]
	v_pk_fma_f32 v[30:31], v[70:71], s[78:79], v[30:31] op_sel_hi:[1,0,1]
	v_pk_fma_f32 v[28:29], v[68:69], s[78:79], v[28:29] op_sel_hi:[1,0,1]
	v_lshl_add_u64 v[54:55], v[158:159], 2, s[88:89]
	global_store_dwordx4 v[54:55], v[28:31], off
	v_add_u32_e32 v158, 0x40090, v148
	s_nop 0
	v_sub_f32_e32 v29, v59, v62
	v_sub_f32_e32 v28, v58, v62
	v_sub_f32_e32 v31, v61, v62
	v_sub_f32_e32 v30, v60, v62
	v_pk_mul_f32 v[30:31], v[62:63], v[30:31] op_sel:[1,0]
	v_pk_mul_f32 v[28:29], v[62:63], v[28:29] op_sel:[1,0]
	v_pk_fma_f32 v[26:27], v[92:93], v[30:31], v[26:27]
	v_pk_fma_f32 v[24:25], v[94:95], v[28:29], v[24:25]
	v_pk_fma_f32 v[26:27], v[66:67], s[78:79], v[26:27] op_sel_hi:[1,0,1]
	v_pk_fma_f32 v[24:25], v[64:65], s[78:79], v[24:25] op_sel_hi:[1,0,1]
	v_lshl_add_u64 v[28:29], v[158:159], 2, s[88:89]
	global_store_dwordx4 v[28:29], v[24:27], off
	v_add_u32_e32 v158, 0x48080, v148
	s_nop 0
	v_sub_f32_e32 v25, v73, v52
	v_sub_f32_e32 v24, v72, v52
	v_sub_f32_e32 v27, v75, v52
	v_sub_f32_e32 v26, v74, v52
	v_pk_mul_f32 v[26:27], v[52:53], v[26:27] op_sel:[1,0]
	v_pk_mul_f32 v[24:25], v[52:53], v[24:25] op_sel:[1,0]
	v_pk_fma_f32 v[22:23], v[96:97], v[26:27], v[22:23]
	v_pk_fma_f32 v[20:21], v[98:99], v[24:25], v[20:21]
	v_pk_fma_f32 v[22:23], v[70:71], s[78:79], v[22:23] op_sel_hi:[1,0,1]
	v_pk_fma_f32 v[20:21], v[68:69], s[78:79], v[20:21] op_sel_hi:[1,0,1]
	v_lshl_add_u64 v[24:25], v[158:159], 2, s[88:89]
	global_store_dwordx4 v[24:25], v[20:23], off
	v_add_u32_e32 v158, 0x48090, v148
	s_nop 0
	v_sub_f32_e32 v21, v77, v52
	v_sub_f32_e32 v20, v76, v52
	v_sub_f32_e32 v23, v79, v52
	v_sub_f32_e32 v22, v78, v52
	v_pk_mul_f32 v[22:23], v[52:53], v[22:23] op_sel:[1,0]
	v_pk_mul_f32 v[20:21], v[52:53], v[20:21] op_sel:[1,0]
	v_pk_fma_f32 v[18:19], v[92:93], v[22:23], v[18:19]
	v_pk_fma_f32 v[16:17], v[94:95], v[20:21], v[16:17]
	v_pk_fma_f32 v[18:19], v[66:67], s[78:79], v[18:19] op_sel_hi:[1,0,1]
	v_pk_fma_f32 v[16:17], v[64:65], s[78:79], v[16:17] op_sel_hi:[1,0,1]
	v_lshl_add_u64 v[20:21], v[158:159], 2, s[88:89]
	global_store_dwordx4 v[20:21], v[16:19], off
	v_add_u32_e32 v158, 0x50080, v148
	s_nop 0
	v_sub_f32_e32 v17, v45, v50
	v_sub_f32_e32 v16, v44, v50
	v_sub_f32_e32 v19, v47, v50
	v_sub_f32_e32 v18, v46, v50
	v_pk_mul_f32 v[18:19], v[50:51], v[18:19] op_sel:[1,0]
	v_pk_mul_f32 v[16:17], v[50:51], v[16:17] op_sel:[1,0]
	v_pk_fma_f32 v[14:15], v[96:97], v[18:19], v[14:15]
	v_pk_fma_f32 v[12:13], v[98:99], v[16:17], v[12:13]
	v_pk_fma_f32 v[14:15], v[70:71], s[78:79], v[14:15] op_sel_hi:[1,0,1]
	v_pk_fma_f32 v[12:13], v[68:69], s[78:79], v[12:13] op_sel_hi:[1,0,1]
	v_lshl_add_u64 v[16:17], v[158:159], 2, s[88:89]
	global_store_dwordx4 v[16:17], v[12:15], off
	v_add_u32_e32 v158, 0x50090, v148
	s_nop 0
	v_sub_f32_e32 v13, v41, v50
	v_sub_f32_e32 v12, v40, v50
	v_sub_f32_e32 v15, v43, v50
	v_sub_f32_e32 v14, v42, v50
	v_pk_mul_f32 v[14:15], v[50:51], v[14:15] op_sel:[1,0]
	v_pk_mul_f32 v[12:13], v[50:51], v[12:13] op_sel:[1,0]
	v_pk_fma_f32 v[10:11], v[92:93], v[14:15], v[10:11]
	v_pk_fma_f32 v[8:9], v[94:95], v[12:13], v[8:9]
	v_pk_fma_f32 v[10:11], v[66:67], s[78:79], v[10:11] op_sel_hi:[1,0,1]
	v_pk_fma_f32 v[8:9], v[64:65], s[78:79], v[8:9] op_sel_hi:[1,0,1]
	v_lshl_add_u64 v[12:13], v[158:159], 2, s[88:89]
	global_store_dwordx4 v[12:13], v[8:11], off
	v_add_u32_e32 v158, 0x58080, v148
	s_nop 0
	v_sub_f32_e32 v9, v37, v48
	v_sub_f32_e32 v8, v36, v48
	v_sub_f32_e32 v11, v39, v48
	v_sub_f32_e32 v10, v38, v48
	v_pk_mul_f32 v[10:11], v[48:49], v[10:11] op_sel:[1,0]
	v_pk_mul_f32 v[8:9], v[48:49], v[8:9] op_sel:[1,0]
	v_pk_fma_f32 v[6:7], v[96:97], v[10:11], v[6:7]
	v_pk_fma_f32 v[4:5], v[98:99], v[8:9], v[4:5]
	v_pk_fma_f32 v[6:7], v[70:71], s[78:79], v[6:7] op_sel_hi:[1,0,1]
	v_pk_fma_f32 v[4:5], v[68:69], s[78:79], v[4:5] op_sel_hi:[1,0,1]
	v_lshl_add_u64 v[8:9], v[158:159], 2, s[88:89]
	global_store_dwordx4 v[8:9], v[4:7], off
	v_add_u32_e32 v158, 0x58090, v148
	s_nop 0
	v_sub_f32_e32 v5, v33, v48
	v_sub_f32_e32 v4, v32, v48
	v_sub_f32_e32 v7, v35, v48
	v_sub_f32_e32 v6, v34, v48
	v_pk_mul_f32 v[6:7], v[48:49], v[6:7] op_sel:[1,0]
	v_pk_mul_f32 v[4:5], v[48:49], v[4:5] op_sel:[1,0]
	v_pk_fma_f32 v[2:3], v[92:93], v[6:7], v[2:3]
	v_pk_fma_f32 v[0:1], v[94:95], v[4:5], v[0:1]
	v_pk_fma_f32 v[2:3], v[66:67], s[78:79], v[2:3] op_sel_hi:[1,0,1]
	v_pk_fma_f32 v[0:1], v[64:65], s[78:79], v[0:1] op_sel_hi:[1,0,1]
	v_lshl_add_u64 v[4:5], v[158:159], 2, s[88:89]
	global_store_dwordx4 v[4:5], v[0:3], off
	s_and_b64 vcc, exec, s[6:7]
	s_mov_b32 s2, s37
	s_mov_b32 s3, s38
	s_mov_b64 s[18:19], s[10:11]
	s_mov_b64 s[16:17], s[8:9]
	v_readlane_b32 s33, v255, 39
	s_cbranch_vccz .LBB0_123
	s_waitcnt vmcnt(0)
	s_cmpk_gt_u32 s24, 0xff
	s_cbranch_scc1 .LBB0_138
	s_barrier

; __device__ __forceinline__ int opaque_tid() { int t = threadIdx.x; asm volatile("" : "+v"(t)); return t; }
; #define PG8_STAGE(bufoff, gbase) do { _Pragma("unroll") for (int _i = 0; _i < 2; ++_i) \
;         __builtin_amdgcn_global_load_lds((const unsigned*)((const char*)(gbase) + voff[_i]), (LAS unsigned*)(lds + (bufoff) + ldsw + _i * 8192), 16, 0, 0); } while (0)
; #define PG8_WAIT_V(n) asm volatile("s_waitcnt vmcnt(" #n ")" ::: "memory")
; #define PG8_BAR __builtin_amdgcn_s_barrier()
; template <class Epi>
; DI void gemm_phase(LAS unsigned char* lds, const Gemm g, const StaticOrder& S, const Epi& E) {
;     const int tid = opaque_tid(), wid = __builtin_amdgcn_readfirstlane(tid >> 6), lane = tid & 63, wr = wid >> 2, wc = wid & 3, fr = lane & 15, fq = lane >> 4;
;     const int K = g.K, nt = K / BK;
;     unsigned voff[2];
; #pragma unroll
;     for (int i = 0; i < 2; ++i) { int R, C; stage_rc(tid * 16 + i * 8192, R, C); voff[i] = (unsigned)(R * K + C) * 2u; }
;     const size_t kstep = (size_t)(BK * 2);
;     const size_t hstep = (size_t)HALF * K * 2;
;     const size_t tstep = 2 * hstep;
;     const unsigned ldsw = (unsigned)wid * 1024u;
;     const int aoff = lds_byte(wr * 64 + fr, fq * 8), boff = lds_byte(wc * 32 + fr, fq * 8);
;     ...
;     PG8_STAGE(PG8_SB(0, 0), cB); PG8_STAGE(PG8_SA(0, 0), cA); PG8_STAGE(PG8_SB(0, 1), cB + hstep); PG8_STAGE(PG8_SA(0, 1), cA + hstep);
;     if (wr == 1) PG8_BAR;
;     PG8_WAIT_V(4); PG8_BAR;
;     PG8_STAGE(PG8_SB(1, 0), cB + kstep); PG8_STAGE(PG8_SA(1, 0), cA + kstep); PG8_STAGE(PG8_SB(1, 1), cB + hstep + kstep);
;     PG8_WAIT_V(6); PG8_BAR;
.LBB0_197:
	v_mov_b32_e32 v145, v159
	v_lshl_add_u64 v[8:9], s[18:19], 0, v[144:145]
	v_mov_b32_e32 v143, v159
	v_readlane_b32 s8, v254, 57
	v_lshl_add_u64 v[10:11], s[18:19], 0, v[142:143]
	v_readlane_b32 s9, v254, 58
	s_and_b32 s6, s3, 3
	s_add_i32 m0, s26, 0x18000
	v_lshl_add_u64 v[8:9], v[8:9], 0, s[94:95]
	v_lshl_add_u64 v[12:13], s[8:9], 0, v[144:145]
	s_lshl_b32 s3, s2, 13
	s_lshl_b32 s7, s6, 12
	s_waitcnt vmcnt(4)
	s_barrier
	global_load_lds_dwordx4 v[8:9], off
	v_lshl_add_u64 v[8:9], v[10:11], 0, s[94:95]
	s_add_i32 m0, s26, 0x1a000
	s_add_i32 s30, s26, 0x8000
	s_add_i32 s31, s26, 0xa000
	v_lshl_add_u64 v[14:15], s[8:9], 0, v[142:143]
	global_load_lds_dwordx4 v[8:9], off
	v_lshl_add_u64 v[8:9], v[12:13], 0, s[94:95]
	s_mov_b32 m0, s30
	s_add_u32 s4, s18, 0x80080
	global_load_lds_dwordx4 v[8:9], off
	v_lshl_add_u64 v[8:9], v[14:15], 0, s[94:95]
	s_mov_b32 m0, s31
	s_addc_u32 s5, s19, 0
	global_load_lds_dwordx4 v[8:9], off
	s_add_i32 m0, s26, 0x1c000
	v_lshl_add_u64 v[8:9], s[4:5], 0, v[144:145]
	global_load_lds_dwordx4 v[8:9], off
	v_lshl_add_u64 v[8:9], s[4:5], 0, v[142:143]
	s_add_i32 m0, s26, 0x1e000
	v_and_b32_e32 v7, 15, v0
	global_load_lds_dwordx4 v[8:9], off
	v_bfe_u32 v8, v0, 4, 2
	v_lshlrev_b32_e32 v158, 4, v8
	v_lshlrev_b32_e32 v0, 2, v0
	v_lshl_or_b32 v186, s2, 6, v7
	v_lshl_or_b32 v7, v7, 6, v158
	v_and_b32_e32 v0, 32, v0
	v_bitop3_b32 v9, v7, s3, v0 bitop3:0xde
	v_bitop3_b32 v187, v7, s7, v0 bitop3:0xde
	v_add_u32_e32 v187, 0x10000, v187
	v_lshlrev_b32_e32 v0, 2, v8
	v_lshl_or_b32 v188, s6, 4, v0
	v_lshlrev_b32_e32 v0, 15, v4
	v_and_b32_e32 v0, 0xffff0000, v0
	v_lshl_add_u32 v0, v5, 12, v0
	v_and_b32_e32 v4, 1, v4
	s_lshl_b32 s4, s6, 6
	v_lshl_or_b32 v0, v4, 6, v0
	s_add_u32 s2, s58, s4
	v_lshl_add_u32 v150, v6, 1, v0
	v_lshlrev_b32_e32 v0, 15, v1
	s_addc_u32 s3, s59, 0
	v_and_b32_e32 v0, 0xffff0000, v0
	s_waitcnt vmcnt(6)
	v_lshl_add_u64 v[146:147], s[2:3], 0, v[158:159]
	s_add_u32 s2, s60, s4
	v_lshl_add_u32 v0, v2, 12, v0
	v_and_b32_e32 v1, 1, v1
	s_addc_u32 s3, s61, 0
	v_lshl_or_b32 v0, v1, 6, v0
	v_readlane_b32 s4, v254, 55
	v_lshl_add_u64 v[148:149], s[2:3], 0, v[158:159]
	v_mov_b32_e32 v151, v159
	v_lshl_add_u32 v152, v3, 1, v0
	v_mov_b32_e32 v153, v159
	s_mov_b32 s34, 0
	v_add_u32_e32 v189, 0, v9
	v_readlane_b32 s2, v254, 35
	s_mov_b32 s3, s4
	s_barrier
	v_readlane_b32 s5, v254, 56
	s_branch .LBB0_199

; #define PG8_STAGE(bufoff, gbase) do { _Pragma("unroll") for (int _i = 0; _i < 2; ++_i) \
;         __builtin_amdgcn_global_load_lds((const unsigned*)((const char*)(gbase) + voff[_i]), (LAS unsigned*)(lds + (bufoff) + ldsw + _i * 8192), 16, 0, 0); } while (0)
; #define PG8_LDA(dst, b, h) do { _Pragma("unroll") for (int m = 0; m < 4; ++m) _Pragma("unroll") for (int k = 0; k < 2; ++k) dst[m][k] = *(const LAS bf16x8*)(lds + PG8_SA(b, h) + aoff + m * 2048 + k * 1024); } while (0)
; #define PG8_LDB(dst, b, h) do { _Pragma("unroll") for (int n = 0; n < 2; ++n) _Pragma("unroll") for (int k = 0; k < 2; ++k) dst[n][k] = *(const LAS bf16x8*)(lds + PG8_SB(b, h) + boff + n * 2048 + k * 1024); } while (0)
; #define PG8_MMA(ai, bj, At, Bt) do { __builtin_amdgcn_s_setprio(1); _Pragma("unroll") for (int m = 0; m < 4; ++m) _Pragma("unroll") for (int n = 0; n < 2; ++n) _Pragma("unroll") for (int k = 0; k < 2; ++k) \
;         acc[ai][bj][m][n] = __builtin_amdgcn_mfma_f32_16x16x32_bf16(Bt[n][k], At[m][k], acc[ai][bj][m][n], 0, 0, 0); __builtin_amdgcn_s_setprio(0); } while (0)
; #define PG8_WAIT_L(n) asm volatile("s_waitcnt lgkmcnt(" #n ")" ::: "memory")
; #define PG8_BAR __builtin_amdgcn_s_barrier()
; #define PG8_SCHED __builtin_amdgcn_sched_barrier(0)
; template <class Epi>
; DI void gemm_phase(LAS unsigned char* lds, const Gemm g, const StaticOrder& S, const Epi& E) {
;     ...
;         for (int t = 0; t < nt; t += 2) {
;             const bool last = (t == nt - 2);
;             const char* a1 = cA + (size_t)(t + 1) * kstep;
;             const char* a2 = last ? nA : cA + (size_t)(t + 2) * kstep; const char* b2 = last ? nB : cB + (size_t)(t + 2) * kstep;
;             const char* a3 = a2 + kstep; const char* b3 = b2 + kstep;
;             PG8_LDB(B0, 0, 0); PG8_SCHED; PG8_LDA(At, 0, 0); PG8_STAGE(PG8_SA(1, 1), a1 + hstep);
;             PG8_WAIT_L(8); PG8_BAR; PG8_WAIT_L(0); PG8_MMA(0, 0, At, B0); PG8_BAR; PG8_SCHED;
;             PG8_LDB(B1, 0, 1); PG8_STAGE(PG8_SB(0, 0), b2);
;             PG8_BAR; PG8_WAIT_L(0); PG8_MMA(0, 1, At, B1); PG8_BAR;
;             PG8_LDA(At, 0, 1); PG8_STAGE(PG8_SA(0, 0), a2);
;             PG8_BAR; PG8_WAIT_L(0); PG8_MMA(1, 0, At, B0); PG8_BAR; PG8_SCHED;
.LBB0_202:
	s_add_u32 s18, s8, 0xfff80080
	s_addc_u32 s19, s9, -1
	s_add_i32 s37, 0, 0x10000
	s_waitcnt lgkmcnt(0)
	ds_read_b128 v[128:131], v187
	ds_read_b128 v[132:135], v187 offset:1024
	ds_read_b128 v[136:139], v187 offset:2048
	ds_read_b128 v[190:193], v187 offset:3072
	s_cmp_eq_u32 s36, 28
	s_cselect_b32 s21, s4, s19
	s_cselect_b32 s20, s5, s18
	s_cselect_b32 s19, s11, s35
	s_cselect_b32 s18, s13, s33
	v_lshl_add_u64 v[140:141], s[8:9], 0, v[150:151]
	s_add_i32 m0, s26, 0xc000
	ds_read_b128 v[194:197], v189
	ds_read_b128 v[198:201], v189 offset:1024
	ds_read_b128 v[202:205], v189 offset:2048
	ds_read_b128 v[206:209], v189 offset:3072
	ds_read_b128 v[210:213], v189 offset:4096
	ds_read_b128 v[214:217], v189 offset:5120
	ds_read_b128 v[226:229], v189 offset:6144
	ds_read_b128 v[230:233], v189 offset:7168
	global_load_lds_dwordx4 v[140:141], off
	v_lshl_add_u64 v[140:141], s[8:9], 0, v[152:153]
	s_add_i32 m0, s26, 0xe000
	s_nop 0
	global_load_lds_dwordx4 v[140:141], off
	s_waitcnt lgkmcnt(8)
	s_setprio 1
	s_barrier
	s_waitcnt lgkmcnt(0)
	v_mfma_f32_16x16x32_bf16 v[124:127], v[128:131], v[194:197], v[124:127]
	v_mfma_f32_16x16x32_bf16 v[120:123], v[136:139], v[194:197], v[120:123]
	v_mfma_f32_16x16x32_bf16 v[108:111], v[128:131], v[202:205], v[108:111]
	v_mfma_f32_16x16x32_bf16 v[104:107], v[136:139], v[202:205], v[104:107]
	v_mfma_f32_16x16x32_bf16 v[92:95], v[128:131], v[210:213], v[92:95]
	v_mfma_f32_16x16x32_bf16 v[88:91], v[136:139], v[210:213], v[88:91]
	v_mfma_f32_16x16x32_bf16 v[76:79], v[128:131], v[226:229], v[76:79]
	v_mfma_f32_16x16x32_bf16 v[72:75], v[136:139], v[226:229], v[72:75]
	v_mfma_f32_16x16x32_bf16 v[124:127], v[132:135], v[198:201], v[124:127]
	v_mfma_f32_16x16x32_bf16 v[120:123], v[190:193], v[198:201], v[120:123]
	v_mfma_f32_16x16x32_bf16 v[108:111], v[132:135], v[206:209], v[108:111]
	v_mfma_f32_16x16x32_bf16 v[104:107], v[190:193], v[206:209], v[104:107]
	v_mfma_f32_16x16x32_bf16 v[92:95], v[132:135], v[214:217], v[92:95]
	v_mfma_f32_16x16x32_bf16 v[88:91], v[190:193], v[214:217], v[88:91]
	v_mfma_f32_16x16x32_bf16 v[76:79], v[132:135], v[230:233], v[76:79]
	v_mfma_f32_16x16x32_bf16 v[72:75], v[190:193], v[230:233], v[72:75]
	s_setprio 0
	s_barrier
	s_add_i32 s40, 0, 0x14000
	s_add_i32 s37, s37, s25
	ds_read_b128 v[234:237], v187 offset:16384
	ds_read_b128 v[238:241], v187 offset:17408
	ds_read_b128 v[242:245], v187 offset:18432
	ds_read_b128 v[246:249], v187 offset:19456
	v_lshl_add_u64 v[140:141], s[18:19], 0, v[144:145]
	s_mov_b32 m0, s37
	v_lshl_add_u64 v[154:155], s[18:19], 0, v[142:143]
	global_load_lds_dwordx4 v[140:141], off
	s_add_i32 m0, s37, 0x2000
	s_nop 0
	global_load_lds_dwordx4 v[154:155], off
	s_waitcnt lgkmcnt(0)
	s_setprio 1
	s_barrier
	v_mfma_f32_16x16x32_bf16 v[116:119], v[234:237], v[194:197], v[116:119]
	v_mfma_f32_16x16x32_bf16 v[112:115], v[242:245], v[194:197], v[112:115]
	v_mfma_f32_16x16x32_bf16 v[100:103], v[234:237], v[202:205], v[100:103]
	v_mfma_f32_16x16x32_bf16 v[96:99], v[242:245], v[202:205], v[96:99]
	v_mfma_f32_16x16x32_bf16 v[84:87], v[234:237], v[210:213], v[84:87]
	v_mfma_f32_16x16x32_bf16 v[80:83], v[242:245], v[210:213], v[80:83]
	v_mfma_f32_16x16x32_bf16 v[68:71], v[234:237], v[226:229], v[68:71]
	v_mfma_f32_16x16x32_bf16 v[64:67], v[242:245], v[226:229], v[64:67]
	v_mfma_f32_16x16x32_bf16 v[116:119], v[238:241], v[198:201], v[116:119]
	s_mov_b32 m0, s26
	v_mfma_f32_16x16x32_bf16 v[112:115], v[246:249], v[198:201], v[112:115]
	v_lshl_add_u64 v[218:219], s[20:21], 0, v[144:145]
	v_mfma_f32_16x16x32_bf16 v[100:103], v[238:241], v[206:209], v[100:103]
	v_mfma_f32_16x16x32_bf16 v[96:99], v[246:249], v[206:209], v[96:99]
	v_mfma_f32_16x16x32_bf16 v[84:87], v[238:241], v[214:217], v[84:87]
	v_mfma_f32_16x16x32_bf16 v[80:83], v[246:249], v[214:217], v[80:83]
	v_mfma_f32_16x16x32_bf16 v[68:71], v[238:241], v[230:233], v[68:71]
	v_mfma_f32_16x16x32_bf16 v[64:67], v[246:249], v[230:233], v[64:67]
	s_setprio 0
	s_barrier
	ds_read_b128 v[194:197], v189 offset:16384
	ds_read_b128 v[198:201], v189 offset:17408
	ds_read_b128 v[202:205], v189 offset:18432
	ds_read_b128 v[206:209], v189 offset:19456
	ds_read_b128 v[210:213], v189 offset:20480
	ds_read_b128 v[214:217], v189 offset:21504
	ds_read_b128 v[226:229], v189 offset:22528
	ds_read_b128 v[230:233], v189 offset:23552
	global_load_lds_dwordx4 v[218:219], off
	v_lshl_add_u64 v[250:251], s[20:21], 0, v[142:143]
	s_mov_b32 m0, s27
	s_nop 0
	global_load_lds_dwordx4 v[250:251], off
	s_waitcnt lgkmcnt(0)
	s_setprio 1
	s_barrier
	v_mfma_f32_16x16x32_bf16 v[60:63], v[128:131], v[194:197], v[60:63]
	v_mfma_f32_16x16x32_bf16 v[56:59], v[136:139], v[194:197], v[56:59]
	v_mfma_f32_16x16x32_bf16 v[44:47], v[128:131], v[202:205], v[44:47]
	v_mfma_f32_16x16x32_bf16 v[40:43], v[136:139], v[202:205], v[40:43]
	v_mfma_f32_16x16x32_bf16 v[28:31], v[128:131], v[210:213], v[28:31]
	v_mfma_f32_16x16x32_bf16 v[24:27], v[136:139], v[210:213], v[24:27]
	v_mfma_f32_16x16x32_bf16 v[12:15], v[128:131], v[226:229], v[12:15]
	v_mfma_f32_16x16x32_bf16 v[8:11], v[136:139], v[226:229], v[8:11]
	v_mfma_f32_16x16x32_bf16 v[60:63], v[132:135], v[198:201], v[60:63]
	v_mfma_f32_16x16x32_bf16 v[56:59], v[190:193], v[198:201], v[56:59]
	v_mfma_f32_16x16x32_bf16 v[44:47], v[132:135], v[206:209], v[44:47]
	v_mfma_f32_16x16x32_bf16 v[40:43], v[190:193], v[206:209], v[40:43]
	v_mfma_f32_16x16x32_bf16 v[28:31], v[132:135], v[214:217], v[28:31]
	v_mfma_f32_16x16x32_bf16 v[24:27], v[190:193], v[214:217], v[24:27]
	v_mfma_f32_16x16x32_bf16 v[12:15], v[132:135], v[230:233], v[12:15]
	v_mfma_f32_16x16x32_bf16 v[8:11], v[190:193], v[230:233], v[8:11]
	s_setprio 0
	s_barrier
; #define PG8_STAGE(bufoff, gbase) do { _Pragma("unroll") for (int _i = 0; _i < 2; ++_i) \
;         __builtin_amdgcn_global_load_lds((const unsigned*)((const char*)(gbase) + voff[_i]), (LAS unsigned*)(lds + (bufoff) + ldsw + _i * 8192), 16, 0, 0); } while (0)
; #define PG8_LDA(dst, b, h) do { _Pragma("unroll") for (int m = 0; m < 4; ++m) _Pragma("unroll") for (int k = 0; k < 2; ++k) dst[m][k] = *(const LAS bf16x8*)(lds + PG8_SA(b, h) + aoff + m * 2048 + k * 1024); } while (0)
; #define PG8_LDB(dst, b, h) do { _Pragma("unroll") for (int n = 0; n < 2; ++n) _Pragma("unroll") for (int k = 0; k < 2; ++k) dst[n][k] = *(const LAS bf16x8*)(lds + PG8_SB(b, h) + boff + n * 2048 + k * 1024); } while (0)
; #define PG8_MMA(ai, bj, At, Bt) do { __builtin_amdgcn_s_setprio(1); _Pragma("unroll") for (int m = 0; m < 4; ++m) _Pragma("unroll") for (int n = 0; n < 2; ++n) _Pragma("unroll") for (int k = 0; k < 2; ++k) \
;         acc[ai][bj][m][n] = __builtin_amdgcn_mfma_f32_16x16x32_bf16(Bt[n][k], At[m][k], acc[ai][bj][m][n], 0, 0, 0); __builtin_amdgcn_s_setprio(0); } while (0)
; #define PG8_WAIT_V(n) asm volatile("s_waitcnt vmcnt(" #n ")" ::: "memory")
; #define PG8_WAIT_L(n) asm volatile("s_waitcnt lgkmcnt(" #n ")" ::: "memory")
; #define PG8_BAR __builtin_amdgcn_s_barrier()
; #define PG8_SCHED __builtin_amdgcn_sched_barrier(0)
; template <class Epi>
; DI void gemm_phase(LAS unsigned char* lds, const Gemm g, const StaticOrder& S, const Epi& E) {
;     ...
;             PG8_STAGE(PG8_SB(0, 1), b2 + hstep);
;             PG8_WAIT_V(6); PG8_BAR; PG8_MMA(1, 1, At, B1); PG8_BAR;
;             PG8_LDB(B0, 1, 0); PG8_SCHED; PG8_LDA(At, 1, 0); PG8_STAGE(PG8_SA(0, 1), a2 + hstep);
;             PG8_WAIT_L(8); PG8_BAR; PG8_WAIT_L(0); PG8_MMA(0, 0, At, B0); PG8_BAR; PG8_SCHED;
;             PG8_LDB(B1, 1, 1); PG8_STAGE(PG8_SB(1, 0), b3);
	s_add_u32 s38, s18, 0x80000
	s_addc_u32 s39, s19, 0
	s_add_i32 s37, s40, s25
	v_lshl_add_u64 v[128:129], s[38:39], 0, v[144:145]
	s_mov_b32 m0, s37
	s_nop 0
	global_load_lds_dwordx4 v[128:129], off
	v_lshl_add_u64 v[128:129], s[38:39], 0, v[142:143]
	s_add_i32 m0, s37, 0x2000
	s_nop 0
	global_load_lds_dwordx4 v[128:129], off
	s_waitcnt vmcnt(6)
	s_setprio 1
	s_barrier
	v_mfma_f32_16x16x32_bf16 v[52:55], v[234:237], v[194:197], v[52:55]
	v_mfma_f32_16x16x32_bf16 v[48:51], v[242:245], v[194:197], v[48:51]
	v_mfma_f32_16x16x32_bf16 v[36:39], v[234:237], v[202:205], v[36:39]
	v_mfma_f32_16x16x32_bf16 v[32:35], v[242:245], v[202:205], v[32:35]
	v_mfma_f32_16x16x32_bf16 v[20:23], v[234:237], v[210:213], v[20:23]
	v_mfma_f32_16x16x32_bf16 v[16:19], v[242:245], v[210:213], v[16:19]
	v_mfma_f32_16x16x32_bf16 v[4:7], v[234:237], v[226:229], v[4:7]
	v_mfma_f32_16x16x32_bf16 v[0:3], v[242:245], v[226:229], v[0:3]
	v_mfma_f32_16x16x32_bf16 v[52:55], v[238:241], v[198:201], v[52:55]
	s_add_i32 s37, 0, 0x18000
	v_mfma_f32_16x16x32_bf16 v[48:51], v[246:249], v[198:201], v[48:51]
	v_mfma_f32_16x16x32_bf16 v[36:39], v[238:241], v[206:209], v[36:39]
	v_mfma_f32_16x16x32_bf16 v[32:35], v[246:249], v[206:209], v[32:35]
	v_mfma_f32_16x16x32_bf16 v[20:23], v[238:241], v[214:217], v[20:23]
	v_mfma_f32_16x16x32_bf16 v[16:19], v[246:249], v[214:217], v[16:19]
	v_mfma_f32_16x16x32_bf16 v[4:7], v[238:241], v[230:233], v[4:7]
	v_mfma_f32_16x16x32_bf16 v[0:3], v[246:249], v[230:233], v[0:3]
	s_setprio 0
	s_barrier
	ds_read_b128 v[128:131], v187 offset:32768
	ds_read_b128 v[132:135], v187 offset:33792
	ds_read_b128 v[136:139], v187 offset:34816
	ds_read_b128 v[190:193], v187 offset:35840
	s_add_u32 s20, s20, 0x80000
	s_addc_u32 s21, s21, 0
	s_mov_b32 m0, s28
	v_lshl_add_u64 v[234:235], s[20:21], 0, v[144:145]
	ds_read_b128 v[194:197], v189 offset:32768
	ds_read_b128 v[198:201], v189 offset:33792
	ds_read_b128 v[202:205], v189 offset:34816
	ds_read_b128 v[206:209], v189 offset:35840
	ds_read_b128 v[210:213], v189 offset:36864
	ds_read_b128 v[214:217], v189 offset:37888
	ds_read_b128 v[226:229], v189 offset:38912
	ds_read_b128 v[230:233], v189 offset:39936
	global_load_lds_dwordx4 v[234:235], off
	v_lshl_add_u64 v[234:235], s[20:21], 0, v[142:143]
	s_mov_b32 m0, s29
	s_nop 0
	global_load_lds_dwordx4 v[234:235], off
	s_waitcnt lgkmcnt(8)
	s_setprio 1
	s_barrier
	s_waitcnt lgkmcnt(0)
	v_mfma_f32_16x16x32_bf16 v[124:127], v[128:131], v[194:197], v[124:127]
	v_mfma_f32_16x16x32_bf16 v[120:123], v[136:139], v[194:197], v[120:123]
	v_mfma_f32_16x16x32_bf16 v[108:111], v[128:131], v[202:205], v[108:111]
	v_mfma_f32_16x16x32_bf16 v[104:107], v[136:139], v[202:205], v[104:107]
	v_mfma_f32_16x16x32_bf16 v[92:95], v[128:131], v[210:213], v[92:95]
	v_mfma_f32_16x16x32_bf16 v[88:91], v[136:139], v[210:213], v[88:91]
	v_mfma_f32_16x16x32_bf16 v[76:79], v[128:131], v[226:229], v[76:79]
	v_mfma_f32_16x16x32_bf16 v[72:75], v[136:139], v[226:229], v[72:75]
	v_mfma_f32_16x16x32_bf16 v[124:127], v[132:135], v[198:201], v[124:127]
	v_mfma_f32_16x16x32_bf16 v[120:123], v[190:193], v[198:201], v[120:123]
	v_mfma_f32_16x16x32_bf16 v[108:111], v[132:135], v[206:209], v[108:111]
	v_mfma_f32_16x16x32_bf16 v[104:107], v[190:193], v[206:209], v[104:107]
	v_mfma_f32_16x16x32_bf16 v[92:95], v[132:135], v[214:217], v[92:95]
	v_mfma_f32_16x16x32_bf16 v[88:91], v[190:193], v[214:217], v[88:91]
	v_mfma_f32_16x16x32_bf16 v[76:79], v[132:135], v[230:233], v[76:79]
	v_mfma_f32_16x16x32_bf16 v[72:75], v[190:193], v[230:233], v[72:75]
	s_setprio 0
	s_barrier
	s_add_i32 s20, 0, 0x1c000
	s_add_i32 s21, s37, s25
	v_lshl_add_u64 v[140:141], v[140:141], 0, s[94:95]
	s_mov_b32 m0, s21
	ds_read_b128 v[234:237], v187 offset:49152
	ds_read_b128 v[238:241], v187 offset:50176
	ds_read_b128 v[242:245], v187 offset:51200
	ds_read_b128 v[246:249], v187 offset:52224
	global_load_lds_dwordx4 v[140:141], off
	v_lshl_add_u64 v[140:141], v[154:155], 0, s[94:95]
	s_add_i32 m0, s21, 0x2000
	s_nop 0
	global_load_lds_dwordx4 v[140:141], off
	s_waitcnt lgkmcnt(0)
	s_setprio 1
	s_barrier
; #define PG8_STAGE(bufoff, gbase) do { _Pragma("unroll") for (int _i = 0; _i < 2; ++_i) \
;         __builtin_amdgcn_global_load_lds((const unsigned*)((const char*)(gbase) + voff[_i]), (LAS unsigned*)(lds + (bufoff) + ldsw + _i * 8192), 16, 0, 0); } while (0)
; #define PG8_LDA(dst, b, h) do { _Pragma("unroll") for (int m = 0; m < 4; ++m) _Pragma("unroll") for (int k = 0; k < 2; ++k) dst[m][k] = *(const LAS bf16x8*)(lds + PG8_SA(b, h) + aoff + m * 2048 + k * 1024); } while (0)
; #define PG8_MMA(ai, bj, At, Bt) do { __builtin_amdgcn_s_setprio(1); _Pragma("unroll") for (int m = 0; m < 4; ++m) _Pragma("unroll") for (int n = 0; n < 2; ++n) _Pragma("unroll") for (int k = 0; k < 2; ++k) \
;         acc[ai][bj][m][n] = __builtin_amdgcn_mfma_f32_16x16x32_bf16(Bt[n][k], At[m][k], acc[ai][bj][m][n], 0, 0, 0); __builtin_amdgcn_s_setprio(0); } while (0)
; #define PG8_WAIT_V(n) asm volatile("s_waitcnt vmcnt(" #n ")" ::: "memory")
; #define PG8_WAIT_L(n) asm volatile("s_waitcnt lgkmcnt(" #n ")" ::: "memory")
; #define PG8_BAR __builtin_amdgcn_s_barrier()
; #define PG8_SCHED __builtin_amdgcn_sched_barrier(0)
; template <class Epi>
; DI void gemm_phase(LAS unsigned char* lds, const Gemm g, const StaticOrder& S, const Epi& E) {
;     ...
;             PG8_BAR; PG8_WAIT_L(0); PG8_MMA(0, 1, At, B1); PG8_BAR;
;             PG8_LDA(At, 1, 1); PG8_STAGE(PG8_SA(1, 0), a3);
;             PG8_BAR; PG8_WAIT_L(0); PG8_MMA(1, 0, At, B0); PG8_BAR; PG8_SCHED;
;             PG8_STAGE(PG8_SB(1, 1), b3 + hstep);
;             PG8_WAIT_V(6); PG8_BAR; PG8_MMA(1, 1, At, B1); PG8_BAR;
;     DI void operator()(const f32x4 (&acc)[2][2][4][2], const Unit& u, int wr, int wc, int fr, int fq) const {
;         const int row0 = u.pm * BM + wr * 64 + fr, col0 = u.pn * BM + wc * 16 + 4 * fq;
;         const bool rot = u.pn < 18;
; #pragma unroll
;         for (int ai = 0; ai < 2; ++ai)
; #pragma unroll
;             for (int m = 0; m < 4; ++m) { const int row = row0 + ai * HALF + m * 16; u16* rowp = O + (size_t)row * NQKV_DIL + col0;
;                 f32x4 c4 = (f32x4){1.f, 1.f, 1.f, 1.f}, s4 = (f32x4){0.f, 0.f, 0.f, 0.f};
;                 if (rot) { const int pos = row & (SEQ - 1); c4 = *(const f32x4*)(cs + pos * 64 + wc * 16 + 4 * fq); s4 = *(const f32x4*)(sn + pos * 64 + wc * 16 + 4 * fq); }
	v_mfma_f32_16x16x32_bf16 v[116:119], v[234:237], v[194:197], v[116:119]
	v_mfma_f32_16x16x32_bf16 v[112:115], v[242:245], v[194:197], v[112:115]
	v_mfma_f32_16x16x32_bf16 v[100:103], v[234:237], v[202:205], v[100:103]
	v_mfma_f32_16x16x32_bf16 v[96:99], v[242:245], v[202:205], v[96:99]
	v_mfma_f32_16x16x32_bf16 v[84:87], v[234:237], v[210:213], v[84:87]
	v_mfma_f32_16x16x32_bf16 v[80:83], v[242:245], v[210:213], v[80:83]
	v_mfma_f32_16x16x32_bf16 v[68:71], v[234:237], v[226:229], v[68:71]
	v_mfma_f32_16x16x32_bf16 v[64:67], v[242:245], v[226:229], v[64:67]
	v_mfma_f32_16x16x32_bf16 v[116:119], v[238:241], v[198:201], v[116:119]
	s_mov_b32 m0, s30
	v_mfma_f32_16x16x32_bf16 v[112:115], v[246:249], v[198:201], v[112:115]
	v_lshl_add_u64 v[140:141], v[218:219], 0, s[94:95]
	v_mfma_f32_16x16x32_bf16 v[100:103], v[238:241], v[206:209], v[100:103]
	v_mfma_f32_16x16x32_bf16 v[96:99], v[246:249], v[206:209], v[96:99]
	v_mfma_f32_16x16x32_bf16 v[84:87], v[238:241], v[214:217], v[84:87]
	v_mfma_f32_16x16x32_bf16 v[80:83], v[246:249], v[214:217], v[80:83]
	v_mfma_f32_16x16x32_bf16 v[68:71], v[238:241], v[230:233], v[68:71]
	v_mfma_f32_16x16x32_bf16 v[64:67], v[246:249], v[230:233], v[64:67]
	s_setprio 0
	s_barrier
	ds_read_b128 v[194:197], v189 offset:49152
	ds_read_b128 v[198:201], v189 offset:50176
	ds_read_b128 v[202:205], v189 offset:51200
	ds_read_b128 v[206:209], v189 offset:52224
	ds_read_b128 v[210:213], v189 offset:53248
	ds_read_b128 v[214:217], v189 offset:54272
	ds_read_b128 v[226:229], v189 offset:55296
	ds_read_b128 v[230:233], v189 offset:56320
	global_load_lds_dwordx4 v[140:141], off
	v_lshl_add_u64 v[140:141], v[250:251], 0, s[94:95]
	s_mov_b32 m0, s31
	s_nop 0
	global_load_lds_dwordx4 v[140:141], off
	s_waitcnt lgkmcnt(0)
	s_setprio 1
	s_barrier
	v_mfma_f32_16x16x32_bf16 v[60:63], v[128:131], v[194:197], v[60:63]
	v_mfma_f32_16x16x32_bf16 v[56:59], v[136:139], v[194:197], v[56:59]
	v_mfma_f32_16x16x32_bf16 v[44:47], v[128:131], v[202:205], v[44:47]
	v_mfma_f32_16x16x32_bf16 v[40:43], v[136:139], v[202:205], v[40:43]
	v_mfma_f32_16x16x32_bf16 v[28:31], v[128:131], v[210:213], v[28:31]
	v_mfma_f32_16x16x32_bf16 v[24:27], v[136:139], v[210:213], v[24:27]
	v_mfma_f32_16x16x32_bf16 v[12:15], v[128:131], v[226:229], v[12:15]
	v_mfma_f32_16x16x32_bf16 v[8:11], v[136:139], v[226:229], v[8:11]
	v_mfma_f32_16x16x32_bf16 v[60:63], v[132:135], v[198:201], v[60:63]
	v_mfma_f32_16x16x32_bf16 v[56:59], v[190:193], v[198:201], v[56:59]
	v_mfma_f32_16x16x32_bf16 v[44:47], v[132:135], v[206:209], v[44:47]
	v_mfma_f32_16x16x32_bf16 v[40:43], v[190:193], v[206:209], v[40:43]
	v_mfma_f32_16x16x32_bf16 v[28:31], v[132:135], v[214:217], v[28:31]
	v_mfma_f32_16x16x32_bf16 v[24:27], v[190:193], v[214:217], v[24:27]
	v_mfma_f32_16x16x32_bf16 v[12:15], v[132:135], v[230:233], v[12:15]
	v_mfma_f32_16x16x32_bf16 v[8:11], v[190:193], v[230:233], v[8:11]
	s_setprio 0
	s_barrier
	s_add_u32 s18, s18, 0x80080
	s_addc_u32 s19, s19, 0
	s_add_i32 s20, s20, s25
	v_lshl_add_u64 v[128:129], s[18:19], 0, v[144:145]
	s_mov_b32 m0, s20
	s_nop 0
	global_load_lds_dwordx4 v[128:129], off
	v_lshl_add_u64 v[128:129], s[18:19], 0, v[142:143]
	s_add_i32 m0, s20, 0x2000
	s_nop 0
	global_load_lds_dwordx4 v[128:129], off
	s_waitcnt vmcnt(6)
	s_setprio 1
	s_barrier
	v_mfma_f32_16x16x32_bf16 v[52:55], v[234:237], v[194:197], v[52:55]
	v_mfma_f32_16x16x32_bf16 v[48:51], v[242:245], v[194:197], v[48:51]
	v_mfma_f32_16x16x32_bf16 v[36:39], v[234:237], v[202:205], v[36:39]
	v_mfma_f32_16x16x32_bf16 v[32:35], v[242:245], v[202:205], v[32:35]
	v_mfma_f32_16x16x32_bf16 v[20:23], v[234:237], v[210:213], v[20:23]
	v_mfma_f32_16x16x32_bf16 v[16:19], v[242:245], v[210:213], v[16:19]
	v_mfma_f32_16x16x32_bf16 v[4:7], v[234:237], v[226:229], v[4:7]
	v_mfma_f32_16x16x32_bf16 v[0:3], v[242:245], v[226:229], v[0:3]
	v_mfma_f32_16x16x32_bf16 v[52:55], v[238:241], v[198:201], v[52:55]
	s_add_i32 s36, s36, 2
	v_mfma_f32_16x16x32_bf16 v[48:51], v[246:249], v[198:201], v[48:51]
	s_add_u32 s8, s8, 0x100
	v_mfma_f32_16x16x32_bf16 v[36:39], v[238:241], v[206:209], v[36:39]
	s_addc_u32 s9, s9, 0
	v_mfma_f32_16x16x32_bf16 v[32:35], v[246:249], v[206:209], v[32:35]
	s_add_u32 s33, s33, 0x100
	v_mfma_f32_16x16x32_bf16 v[20:23], v[238:241], v[214:217], v[20:23]
	s_addc_u32 s35, s35, 0
	v_mfma_f32_16x16x32_bf16 v[16:19], v[246:249], v[214:217], v[16:19]
	s_cmp_gt_u32 s36, 29
	v_mfma_f32_16x16x32_bf16 v[4:7], v[238:241], v[230:233], v[4:7]
	v_mfma_f32_16x16x32_bf16 v[0:3], v[246:249], v[230:233], v[0:3]
	s_setprio 0
	s_barrier
	s_cbranch_scc0 .LBB0_202
	s_cmp_lt_i32 s2, 18
	v_lshl_add_u32 v190, s3, 8, v186
	v_mov_b32_e32 v128, 1.0
	v_mov_b32_e32 v132, 0
	s_cselect_b64 s[18:19], -1, 0
	s_cmp_gt_i32 s2, 17
	v_mov_b32_e32 v134, 0
	v_mov_b32_e32 v135, 0
	v_mov_b32_e32 v136, 0
	v_mov_b32_e32 v137, 0
	v_mov_b32_e32 v138, 1.0
	v_mov_b32_e32 v139, 1.0
	v_mov_b32_e32 v140, 1.0
	v_mov_b32_e32 v141, 1.0
	s_cbranch_scc1 .LBB0_205
	v_lshlrev_b32_e32 v129, 8, v190
	v_and_b32_e32 v158, 0xfcf00, v129
	v_lshl_add_u64 v[130:131], v[146:147], 0, v[158:159]
	v_lshl_add_u64 v[134:135], v[148:149], 0, v[158:159]
	global_load_dwordx4 v[138:141], v[130:131], off
	s_nop 0
	global_load_dwordx4 v[134:137], v[134:135], off

; __device__ __forceinline__ int opaque_tid() { int t = threadIdx.x; asm volatile("" : "+v"(t)); return t; }
; #define PG8_STAGE(bufoff, gbase) do { _Pragma("unroll") for (int _i = 0; _i < 2; ++_i) \
;         __builtin_amdgcn_global_load_lds((const unsigned*)((const char*)(gbase) + voff[_i]), (LAS unsigned*)(lds + (bufoff) + ldsw + _i * 8192), 16, 0, 0); } while (0)
; #define PG8_WAIT_V(n) asm volatile("s_waitcnt vmcnt(" #n ")" ::: "memory")
; #define PG8_BAR __builtin_amdgcn_s_barrier()
; template <class Epi>
; DI void gemm_phase(LAS unsigned char* lds, const Gemm g, const StaticOrder& S, const Epi& E) {
;     const int tid = opaque_tid(), wid = __builtin_amdgcn_readfirstlane(tid >> 6), lane = tid & 63, wr = wid >> 2, wc = wid & 3, fr = lane & 15, fq = lane >> 4;
;     const int K = g.K, nt = K / BK;
;     unsigned voff[2];
; #pragma unroll
;     for (int i = 0; i < 2; ++i) { int R, C; stage_rc(tid * 16 + i * 8192, R, C); voff[i] = (unsigned)(R * K + C) * 2u; }
;     const size_t kstep = (size_t)(BK * 2);
;     const size_t hstep = (size_t)HALF * K * 2;
;     const size_t tstep = 2 * hstep;
;     const unsigned ldsw = (unsigned)wid * 1024u;
;     const int aoff = lds_byte(wr * 64 + fr, fq * 8), boff = lds_byte(wc * 32 + fr, fq * 8);
;     ...
;     PG8_STAGE(PG8_SB(1, 0), cB + kstep); PG8_STAGE(PG8_SA(1, 0), cA + kstep); PG8_STAGE(PG8_SB(1, 1), cB + hstep + kstep);
;     PG8_WAIT_V(6); PG8_BAR;
.LBB0_227:
	v_lshl_add_u64 v[8:9], s[18:19], 0, v[158:159]
	v_mov_b32_e32 v129, v159
	v_readlane_b32 s16, v254, 38
	s_lshl_b32 s5, s5, 5
	v_lshl_add_u64 v[10:11], s[18:19], 0, v[128:129]
	v_readlane_b32 s17, v254, 39
	s_and_b32 s5, s5, 0x60
	s_add_i32 m0, s24, 0x18000
	v_lshl_add_u64 v[8:9], v[8:9], 0, s[94:95]
	v_lshl_add_u64 v[12:13], s[16:17], 0, v[158:159]
	s_lshl_b32 s8, s4, 13
	s_lshl_b32 s9, s5, 7
	s_waitcnt vmcnt(4)
	s_barrier
	global_load_lds_dwordx4 v[8:9], off
	v_lshl_add_u64 v[8:9], v[10:11], 0, s[94:95]
	s_add_i32 m0, s24, 0x1a000
	s_add_i32 s28, s24, 0x8000
	s_add_i32 s29, s24, 0xa000
	v_lshl_add_u64 v[14:15], s[16:17], 0, v[128:129]
	global_load_lds_dwordx4 v[8:9], off
	v_lshl_add_u64 v[8:9], v[12:13], 0, s[94:95]
	s_mov_b32 m0, s28
	s_add_u32 s6, s18, 0x80080
	global_load_lds_dwordx4 v[8:9], off
	v_lshl_add_u64 v[8:9], v[14:15], 0, s[94:95]
	s_mov_b32 m0, s29
	s_addc_u32 s7, s19, 0
	global_load_lds_dwordx4 v[8:9], off
	s_add_i32 m0, s24, 0x1c000
	v_lshl_add_u64 v[8:9], s[6:7], 0, v[158:159]
	global_load_lds_dwordx4 v[8:9], off
	v_lshl_add_u64 v[8:9], s[6:7], 0, v[128:129]
	s_add_i32 m0, s24, 0x1e000
	v_and_b32_e32 v7, 15, v0
	global_load_lds_dwordx4 v[8:9], off
	v_lshrrev_b32_e32 v8, 1, v0
	v_and_b32_e32 v8, 24, v8
	v_lshlrev_b32_e32 v9, 1, v8
	v_lshlrev_b32_e32 v0, 2, v0
	v_lshl_or_b32 v134, s4, 6, v7
	v_lshl_or_b32 v7, v7, 6, v9
	v_and_b32_e32 v0, 32, v0
	v_bitop3_b32 v9, v7, s8, v0 bitop3:0xde
	v_bitop3_b32 v135, v7, s9, v0 bitop3:0xde
	v_add_u32_e32 v135, 0x10000, v135
	v_lshlrev_b32_e32 v0, 15, v4
	v_and_b32_e32 v0, 0xffff0000, v0
	v_lshl_add_u32 v0, v5, 12, v0
	v_and_b32_e32 v4, 1, v4
	v_lshl_or_b32 v0, v4, 6, v0
	v_lshl_add_u32 v130, v6, 1, v0
	v_lshlrev_b32_e32 v0, 15, v1
	v_and_b32_e32 v0, 0xffff0000, v0
	s_waitcnt vmcnt(6)
	v_lshl_add_u32 v0, v2, 12, v0
	v_and_b32_e32 v1, 1, v1
	s_waitcnt vmcnt(0)
	v_or_b32_e32 v136, s5, v8
	v_lshl_or_b32 v0, v1, 6, v0
	v_readlane_b32 s4, v254, 36
	s_waitcnt lgkmcnt(0)
	v_mov_b32_e32 v131, v159
	v_lshl_add_u32 v132, v3, 1, v0
	v_mov_b32_e32 v133, v159
	s_mov_b32 s30, 0
	v_add_u32_e32 v137, 0, v9
	v_readlane_b32 s31, v254, 32
	s_mov_b32 s33, s4
	s_barrier
	v_readlane_b32 s5, v254, 37

; #define PG8_STAGE(bufoff, gbase) do { _Pragma("unroll") for (int _i = 0; _i < 2; ++_i) \
;         __builtin_amdgcn_global_load_lds((const unsigned*)((const char*)(gbase) + voff[_i]), (LAS unsigned*)(lds + (bufoff) + ldsw + _i * 8192), 16, 0, 0); } while (0)
; #define PG8_LDA(dst, b, h) do { _Pragma("unroll") for (int m = 0; m < 4; ++m) _Pragma("unroll") for (int k = 0; k < 2; ++k) dst[m][k] = *(const LAS bf16x8*)(lds + PG8_SA(b, h) + aoff + m * 2048 + k * 1024); } while (0)
; #define PG8_LDB(dst, b, h) do { _Pragma("unroll") for (int n = 0; n < 2; ++n) _Pragma("unroll") for (int k = 0; k < 2; ++k) dst[n][k] = *(const LAS bf16x8*)(lds + PG8_SB(b, h) + boff + n * 2048 + k * 1024); } while (0)
; #define PG8_MMA(ai, bj, At, Bt) do { __builtin_amdgcn_s_setprio(1); _Pragma("unroll") for (int m = 0; m < 4; ++m) _Pragma("unroll") for (int n = 0; n < 2; ++n) _Pragma("unroll") for (int k = 0; k < 2; ++k) \
;         acc[ai][bj][m][n] = __builtin_amdgcn_mfma_f32_16x16x32_bf16(Bt[n][k], At[m][k], acc[ai][bj][m][n], 0, 0, 0); __builtin_amdgcn_s_setprio(0); } while (0)
; #define PG8_WAIT_L(n) asm volatile("s_waitcnt lgkmcnt(" #n ")" ::: "memory")
; #define PG8_BAR __builtin_amdgcn_s_barrier()
; #define PG8_SCHED __builtin_amdgcn_sched_barrier(0)
; template <class Epi>
; DI void gemm_phase(LAS unsigned char* lds, const Gemm g, const StaticOrder& S, const Epi& E) {
;     ...
;         for (int t = 0; t < nt; t += 2) {
;             const bool last = (t == nt - 2);
;             const char* a1 = cA + (size_t)(t + 1) * kstep;
;             const char* a2 = last ? nA : cA + (size_t)(t + 2) * kstep; const char* b2 = last ? nB : cB + (size_t)(t + 2) * kstep;
;             const char* a3 = a2 + kstep; const char* b3 = b2 + kstep;
;             PG8_LDB(B0, 0, 0); PG8_SCHED; PG8_LDA(At, 0, 0); PG8_STAGE(PG8_SA(1, 1), a1 + hstep);
;             PG8_WAIT_L(8); PG8_BAR; PG8_WAIT_L(0); PG8_MMA(0, 0, At, B0); PG8_BAR; PG8_SCHED;
;             PG8_LDB(B1, 0, 1); PG8_STAGE(PG8_SB(0, 0), b2);
;             PG8_BAR; PG8_WAIT_L(0); PG8_MMA(0, 1, At, B1); PG8_BAR;
;             PG8_LDA(At, 0, 1); PG8_STAGE(PG8_SA(0, 0), a2);
;             PG8_BAR; PG8_WAIT_L(0); PG8_MMA(1, 0, At, B0); PG8_BAR; PG8_SCHED;
.LBB0_231:
	s_add_u32 s18, s16, 0xfff80080
	s_addc_u32 s19, s17, -1
	s_add_i32 s37, 0, 0x10000
	ds_read_b128 v[138:141], v135
	ds_read_b128 v[142:145], v135 offset:1024
	ds_read_b128 v[146:149], v135 offset:2048
	ds_read_b128 v[150:153], v135 offset:3072
	s_cmp_eq_u32 s36, 28
	s_cselect_b32 s21, s4, s19
	s_cselect_b32 s20, s5, s18
	s_cselect_b32 s19, s9, s35
	s_cselect_b32 s18, s11, s34
	v_lshl_add_u64 v[154:155], s[16:17], 0, v[130:131]
	s_add_i32 m0, s24, 0xc000
	ds_read_b128 v[186:189], v137
	ds_read_b128 v[190:193], v137 offset:1024
	ds_read_b128 v[194:197], v137 offset:2048
	ds_read_b128 v[198:201], v137 offset:3072
	ds_read_b128 v[202:205], v137 offset:4096
	ds_read_b128 v[206:209], v137 offset:5120
	ds_read_b128 v[210:213], v137 offset:6144
	ds_read_b128 v[214:217], v137 offset:7168
	global_load_lds_dwordx4 v[154:155], off
	v_lshl_add_u64 v[154:155], s[16:17], 0, v[132:133]
	s_add_i32 m0, s24, 0xe000
	s_nop 0
	global_load_lds_dwordx4 v[154:155], off
	s_waitcnt lgkmcnt(8)
	s_setprio 1
	s_barrier
	s_waitcnt lgkmcnt(0)
	v_mfma_f32_16x16x32_bf16 v[124:127], v[138:141], v[186:189], v[124:127]
	v_mfma_f32_16x16x32_bf16 v[120:123], v[146:149], v[186:189], v[120:123]
	v_mfma_f32_16x16x32_bf16 v[116:119], v[138:141], v[194:197], v[116:119]
	v_mfma_f32_16x16x32_bf16 v[112:115], v[146:149], v[194:197], v[112:115]
	v_mfma_f32_16x16x32_bf16 v[100:103], v[138:141], v[202:205], v[100:103]
	v_mfma_f32_16x16x32_bf16 v[96:99], v[146:149], v[202:205], v[96:99]
	v_mfma_f32_16x16x32_bf16 v[84:87], v[138:141], v[210:213], v[84:87]
	v_mfma_f32_16x16x32_bf16 v[80:83], v[146:149], v[210:213], v[80:83]
	v_mfma_f32_16x16x32_bf16 v[124:127], v[142:145], v[190:193], v[124:127]
	v_mfma_f32_16x16x32_bf16 v[120:123], v[150:153], v[190:193], v[120:123]
	v_mfma_f32_16x16x32_bf16 v[116:119], v[142:145], v[198:201], v[116:119]
	v_mfma_f32_16x16x32_bf16 v[112:115], v[150:153], v[198:201], v[112:115]
	v_mfma_f32_16x16x32_bf16 v[100:103], v[142:145], v[206:209], v[100:103]
	v_mfma_f32_16x16x32_bf16 v[96:99], v[150:153], v[206:209], v[96:99]
	v_mfma_f32_16x16x32_bf16 v[84:87], v[142:145], v[214:217], v[84:87]
	v_mfma_f32_16x16x32_bf16 v[80:83], v[150:153], v[214:217], v[80:83]
	s_setprio 0
	s_barrier
	s_add_i32 s40, 0, 0x14000
	s_add_i32 s37, s37, s23
	ds_read_b128 v[226:229], v135 offset:16384
	ds_read_b128 v[230:233], v135 offset:17408
	ds_read_b128 v[234:237], v135 offset:18432
	ds_read_b128 v[238:241], v135 offset:19456
	v_lshl_add_u64 v[154:155], s[18:19], 0, v[158:159]
	s_mov_b32 m0, s37
	v_lshl_add_u64 v[218:219], s[18:19], 0, v[128:129]
	global_load_lds_dwordx4 v[154:155], off
	s_add_i32 m0, s37, 0x2000
	s_nop 0
	global_load_lds_dwordx4 v[218:219], off
	s_waitcnt lgkmcnt(0)
	s_setprio 1
	s_barrier
	v_mfma_f32_16x16x32_bf16 v[108:111], v[226:229], v[186:189], v[108:111]
	v_mfma_f32_16x16x32_bf16 v[104:107], v[234:237], v[186:189], v[104:107]
	v_mfma_f32_16x16x32_bf16 v[92:95], v[226:229], v[194:197], v[92:95]
	v_mfma_f32_16x16x32_bf16 v[88:91], v[234:237], v[194:197], v[88:91]
	v_mfma_f32_16x16x32_bf16 v[76:79], v[226:229], v[202:205], v[76:79]
	v_mfma_f32_16x16x32_bf16 v[72:75], v[234:237], v[202:205], v[72:75]
	v_mfma_f32_16x16x32_bf16 v[68:71], v[226:229], v[210:213], v[68:71]
	v_mfma_f32_16x16x32_bf16 v[64:67], v[234:237], v[210:213], v[64:67]
	v_mfma_f32_16x16x32_bf16 v[108:111], v[230:233], v[190:193], v[108:111]
	s_mov_b32 m0, s24
	v_mfma_f32_16x16x32_bf16 v[104:107], v[238:241], v[190:193], v[104:107]
	v_lshl_add_u64 v[242:243], s[20:21], 0, v[158:159]
	v_mfma_f32_16x16x32_bf16 v[92:95], v[230:233], v[198:201], v[92:95]
	v_mfma_f32_16x16x32_bf16 v[88:91], v[238:241], v[198:201], v[88:91]
	v_mfma_f32_16x16x32_bf16 v[76:79], v[230:233], v[206:209], v[76:79]
	v_mfma_f32_16x16x32_bf16 v[72:75], v[238:241], v[206:209], v[72:75]
	v_mfma_f32_16x16x32_bf16 v[68:71], v[230:233], v[214:217], v[68:71]
	v_mfma_f32_16x16x32_bf16 v[64:67], v[238:241], v[214:217], v[64:67]
	s_setprio 0
	s_barrier
	ds_read_b128 v[186:189], v137 offset:16384
	ds_read_b128 v[190:193], v137 offset:17408
	ds_read_b128 v[194:197], v137 offset:18432
	ds_read_b128 v[198:201], v137 offset:19456
	ds_read_b128 v[202:205], v137 offset:20480
	ds_read_b128 v[206:209], v137 offset:21504
	ds_read_b128 v[210:213], v137 offset:22528
	ds_read_b128 v[214:217], v137 offset:23552
	global_load_lds_dwordx4 v[242:243], off
	v_lshl_add_u64 v[244:245], s[20:21], 0, v[128:129]
	s_mov_b32 m0, s25
	s_nop 0
	global_load_lds_dwordx4 v[244:245], off
	s_waitcnt lgkmcnt(0)
	s_setprio 1
	s_barrier
	v_mfma_f32_16x16x32_bf16 v[60:63], v[138:141], v[186:189], v[60:63]
	v_mfma_f32_16x16x32_bf16 v[56:59], v[146:149], v[186:189], v[56:59]
	v_mfma_f32_16x16x32_bf16 v[52:55], v[138:141], v[194:197], v[52:55]
	v_mfma_f32_16x16x32_bf16 v[48:51], v[146:149], v[194:197], v[48:51]
	v_mfma_f32_16x16x32_bf16 v[36:39], v[138:141], v[202:205], v[36:39]
	v_mfma_f32_16x16x32_bf16 v[32:35], v[146:149], v[202:205], v[32:35]
	v_mfma_f32_16x16x32_bf16 v[20:23], v[138:141], v[210:213], v[20:23]
	v_mfma_f32_16x16x32_bf16 v[16:19], v[146:149], v[210:213], v[16:19]
	v_mfma_f32_16x16x32_bf16 v[60:63], v[142:145], v[190:193], v[60:63]
	v_mfma_f32_16x16x32_bf16 v[56:59], v[150:153], v[190:193], v[56:59]
	v_mfma_f32_16x16x32_bf16 v[52:55], v[142:145], v[198:201], v[52:55]
	v_mfma_f32_16x16x32_bf16 v[48:51], v[150:153], v[198:201], v[48:51]
	v_mfma_f32_16x16x32_bf16 v[36:39], v[142:145], v[206:209], v[36:39]
	v_mfma_f32_16x16x32_bf16 v[32:35], v[150:153], v[206:209], v[32:35]
	v_mfma_f32_16x16x32_bf16 v[20:23], v[142:145], v[214:217], v[20:23]
	v_mfma_f32_16x16x32_bf16 v[16:19], v[150:153], v[214:217], v[16:19]
	s_setprio 0
	s_barrier
; #define PG8_STAGE(bufoff, gbase) do { _Pragma("unroll") for (int _i = 0; _i < 2; ++_i) \
;         __builtin_amdgcn_global_load_lds((const unsigned*)((const char*)(gbase) + voff[_i]), (LAS unsigned*)(lds + (bufoff) + ldsw + _i * 8192), 16, 0, 0); } while (0)
; #define PG8_LDA(dst, b, h) do { _Pragma("unroll") for (int m = 0; m < 4; ++m) _Pragma("unroll") for (int k = 0; k < 2; ++k) dst[m][k] = *(const LAS bf16x8*)(lds + PG8_SA(b, h) + aoff + m * 2048 + k * 1024); } while (0)
; #define PG8_LDB(dst, b, h) do { _Pragma("unroll") for (int n = 0; n < 2; ++n) _Pragma("unroll") for (int k = 0; k < 2; ++k) dst[n][k] = *(const LAS bf16x8*)(lds + PG8_SB(b, h) + boff + n * 2048 + k * 1024); } while (0)
; #define PG8_MMA(ai, bj, At, Bt) do { __builtin_amdgcn_s_setprio(1); _Pragma("unroll") for (int m = 0; m < 4; ++m) _Pragma("unroll") for (int n = 0; n < 2; ++n) _Pragma("unroll") for (int k = 0; k < 2; ++k) \
;         acc[ai][bj][m][n] = __builtin_amdgcn_mfma_f32_16x16x32_bf16(Bt[n][k], At[m][k], acc[ai][bj][m][n], 0, 0, 0); __builtin_amdgcn_s_setprio(0); } while (0)
; #define PG8_WAIT_V(n) asm volatile("s_waitcnt vmcnt(" #n ")" ::: "memory")
; #define PG8_WAIT_L(n) asm volatile("s_waitcnt lgkmcnt(" #n ")" ::: "memory")
; #define PG8_BAR __builtin_amdgcn_s_barrier()
; #define PG8_SCHED __builtin_amdgcn_sched_barrier(0)
; template <class Epi>
; DI void gemm_phase(LAS unsigned char* lds, const Gemm g, const StaticOrder& S, const Epi& E) {
;     ...
;             PG8_STAGE(PG8_SB(0, 1), b2 + hstep);
;             PG8_WAIT_V(6); PG8_BAR; PG8_MMA(1, 1, At, B1); PG8_BAR;
;             PG8_LDB(B0, 1, 0); PG8_SCHED; PG8_LDA(At, 1, 0); PG8_STAGE(PG8_SA(0, 1), a2 + hstep);
;             PG8_WAIT_L(8); PG8_BAR; PG8_WAIT_L(0); PG8_MMA(0, 0, At, B0); PG8_BAR; PG8_SCHED;
;             PG8_LDB(B1, 1, 1); PG8_STAGE(PG8_SB(1, 0), b3);
	s_add_u32 s38, s18, 0x80000
	s_addc_u32 s39, s19, 0
	s_add_i32 s37, s40, s23
	v_lshl_add_u64 v[138:139], s[38:39], 0, v[158:159]
	s_mov_b32 m0, s37
	s_nop 0
	global_load_lds_dwordx4 v[138:139], off
	v_lshl_add_u64 v[138:139], s[38:39], 0, v[128:129]
	s_add_i32 m0, s37, 0x2000
	s_nop 0
	global_load_lds_dwordx4 v[138:139], off
	s_waitcnt vmcnt(6)
	s_setprio 1
	s_barrier
	v_mfma_f32_16x16x32_bf16 v[44:47], v[226:229], v[186:189], v[44:47]
	v_mfma_f32_16x16x32_bf16 v[40:43], v[234:237], v[186:189], v[40:43]
	v_mfma_f32_16x16x32_bf16 v[28:31], v[226:229], v[194:197], v[28:31]
	v_mfma_f32_16x16x32_bf16 v[24:27], v[234:237], v[194:197], v[24:27]
	v_mfma_f32_16x16x32_bf16 v[12:15], v[226:229], v[202:205], v[12:15]
	v_mfma_f32_16x16x32_bf16 v[8:11], v[234:237], v[202:205], v[8:11]
	v_mfma_f32_16x16x32_bf16 v[4:7], v[226:229], v[210:213], v[4:7]
	v_mfma_f32_16x16x32_bf16 v[0:3], v[234:237], v[210:213], v[0:3]
	v_mfma_f32_16x16x32_bf16 v[44:47], v[230:233], v[190:193], v[44:47]
	s_add_i32 s37, 0, 0x18000
	v_mfma_f32_16x16x32_bf16 v[40:43], v[238:241], v[190:193], v[40:43]
	v_mfma_f32_16x16x32_bf16 v[28:31], v[230:233], v[198:201], v[28:31]
	v_mfma_f32_16x16x32_bf16 v[24:27], v[238:241], v[198:201], v[24:27]
	v_mfma_f32_16x16x32_bf16 v[12:15], v[230:233], v[206:209], v[12:15]
	v_mfma_f32_16x16x32_bf16 v[8:11], v[238:241], v[206:209], v[8:11]
	v_mfma_f32_16x16x32_bf16 v[4:7], v[230:233], v[214:217], v[4:7]
	v_mfma_f32_16x16x32_bf16 v[0:3], v[238:241], v[214:217], v[0:3]
	s_setprio 0
	s_barrier
	ds_read_b128 v[138:141], v135 offset:32768
	ds_read_b128 v[142:145], v135 offset:33792
	ds_read_b128 v[146:149], v135 offset:34816
	ds_read_b128 v[150:153], v135 offset:35840
	s_add_u32 s20, s20, 0x80000
	s_addc_u32 s21, s21, 0
	s_mov_b32 m0, s26
	v_lshl_add_u64 v[226:227], s[20:21], 0, v[158:159]
	ds_read_b128 v[186:189], v137 offset:32768
	ds_read_b128 v[190:193], v137 offset:33792
	ds_read_b128 v[194:197], v137 offset:34816
	ds_read_b128 v[198:201], v137 offset:35840
	ds_read_b128 v[202:205], v137 offset:36864
	ds_read_b128 v[206:209], v137 offset:37888
	ds_read_b128 v[210:213], v137 offset:38912
	ds_read_b128 v[214:217], v137 offset:39936
	global_load_lds_dwordx4 v[226:227], off
	v_lshl_add_u64 v[226:227], s[20:21], 0, v[128:129]
	s_mov_b32 m0, s27
	s_nop 0
	global_load_lds_dwordx4 v[226:227], off
	s_waitcnt lgkmcnt(8)
	s_setprio 1
	s_barrier
	s_waitcnt lgkmcnt(0)
	v_mfma_f32_16x16x32_bf16 v[124:127], v[138:141], v[186:189], v[124:127]
	v_mfma_f32_16x16x32_bf16 v[120:123], v[146:149], v[186:189], v[120:123]
	v_mfma_f32_16x16x32_bf16 v[116:119], v[138:141], v[194:197], v[116:119]
	v_mfma_f32_16x16x32_bf16 v[112:115], v[146:149], v[194:197], v[112:115]
	v_mfma_f32_16x16x32_bf16 v[100:103], v[138:141], v[202:205], v[100:103]
	v_mfma_f32_16x16x32_bf16 v[96:99], v[146:149], v[202:205], v[96:99]
	v_mfma_f32_16x16x32_bf16 v[84:87], v[138:141], v[210:213], v[84:87]
	v_mfma_f32_16x16x32_bf16 v[80:83], v[146:149], v[210:213], v[80:83]
	v_mfma_f32_16x16x32_bf16 v[124:127], v[142:145], v[190:193], v[124:127]
	v_mfma_f32_16x16x32_bf16 v[120:123], v[150:153], v[190:193], v[120:123]
	v_mfma_f32_16x16x32_bf16 v[116:119], v[142:145], v[198:201], v[116:119]
	v_mfma_f32_16x16x32_bf16 v[112:115], v[150:153], v[198:201], v[112:115]
	v_mfma_f32_16x16x32_bf16 v[100:103], v[142:145], v[206:209], v[100:103]
	v_mfma_f32_16x16x32_bf16 v[96:99], v[150:153], v[206:209], v[96:99]
	v_mfma_f32_16x16x32_bf16 v[84:87], v[142:145], v[214:217], v[84:87]
	v_mfma_f32_16x16x32_bf16 v[80:83], v[150:153], v[214:217], v[80:83]
	s_setprio 0
	s_barrier
	s_add_i32 s20, 0, 0x1c000
	s_add_i32 s21, s37, s23
	v_lshl_add_u64 v[154:155], v[154:155], 0, s[94:95]
	s_mov_b32 m0, s21
	ds_read_b128 v[226:229], v135 offset:49152
	ds_read_b128 v[230:233], v135 offset:50176
	ds_read_b128 v[234:237], v135 offset:51200
	ds_read_b128 v[238:241], v135 offset:52224
	global_load_lds_dwordx4 v[154:155], off
	v_lshl_add_u64 v[154:155], v[218:219], 0, s[94:95]
	s_add_i32 m0, s21, 0x2000
	s_nop 0
	global_load_lds_dwordx4 v[154:155], off
	s_waitcnt lgkmcnt(0)
	s_setprio 1
	s_barrier
	v_mfma_f32_16x16x32_bf16 v[108:111], v[226:229], v[186:189], v[108:111]
	v_mfma_f32_16x16x32_bf16 v[104:107], v[234:237], v[186:189], v[104:107]
	v_mfma_f32_16x16x32_bf16 v[92:95], v[226:229], v[194:197], v[92:95]
	v_mfma_f32_16x16x32_bf16 v[88:91], v[234:237], v[194:197], v[88:91]
	v_mfma_f32_16x16x32_bf16 v[76:79], v[226:229], v[202:205], v[76:79]
	v_mfma_f32_16x16x32_bf16 v[72:75], v[234:237], v[202:205], v[72:75]
	v_mfma_f32_16x16x32_bf16 v[68:71], v[226:229], v[210:213], v[68:71]
	v_mfma_f32_16x16x32_bf16 v[64:67], v[234:237], v[210:213], v[64:67]
	v_mfma_f32_16x16x32_bf16 v[108:111], v[230:233], v[190:193], v[108:111]
	s_mov_b32 m0, s28
	v_mfma_f32_16x16x32_bf16 v[104:107], v[238:241], v[190:193], v[104:107]
	v_lshl_add_u64 v[154:155], v[242:243], 0, s[94:95]
	v_mfma_f32_16x16x32_bf16 v[92:95], v[230:233], v[198:201], v[92:95]
	v_mfma_f32_16x16x32_bf16 v[88:91], v[238:241], v[198:201], v[88:91]
	v_mfma_f32_16x16x32_bf16 v[76:79], v[230:233], v[206:209], v[76:79]
	v_mfma_f32_16x16x32_bf16 v[72:75], v[238:241], v[206:209], v[72:75]
	v_mfma_f32_16x16x32_bf16 v[68:71], v[230:233], v[214:217], v[68:71]
	v_mfma_f32_16x16x32_bf16 v[64:67], v[238:241], v[214:217], v[64:67]
	s_setprio 0
	s_barrier
	ds_read_b128 v[186:189], v137 offset:49152
	ds_read_b128 v[190:193], v137 offset:50176
	ds_read_b128 v[194:197], v137 offset:51200
	ds_read_b128 v[198:201], v137 offset:52224
	ds_read_b128 v[202:205], v137 offset:53248
	ds_read_b128 v[206:209], v137 offset:54272
	ds_read_b128 v[210:213], v137 offset:55296
	ds_read_b128 v[214:217], v137 offset:56320
	global_load_lds_dwordx4 v[154:155], off
	v_lshl_add_u64 v[154:155], v[244:245], 0, s[94:95]
	s_mov_b32 m0, s29
	s_nop 0
	global_load_lds_dwordx4 v[154:155], off
	s_waitcnt lgkmcnt(0)
	s_setprio 1
	s_barrier
; #define PG8_STAGE(bufoff, gbase) do { _Pragma("unroll") for (int _i = 0; _i < 2; ++_i) \
;         __builtin_amdgcn_global_load_lds((const unsigned*)((const char*)(gbase) + voff[_i]), (LAS unsigned*)(lds + (bufoff) + ldsw + _i * 8192), 16, 0, 0); } while (0)
; #define PG8_LDA(dst, b, h) do { _Pragma("unroll") for (int m = 0; m < 4; ++m) _Pragma("unroll") for (int k = 0; k < 2; ++k) dst[m][k] = *(const LAS bf16x8*)(lds + PG8_SA(b, h) + aoff + m * 2048 + k * 1024); } while (0)
; #define PG8_MMA(ai, bj, At, Bt) do { __builtin_amdgcn_s_setprio(1); _Pragma("unroll") for (int m = 0; m < 4; ++m) _Pragma("unroll") for (int n = 0; n < 2; ++n) _Pragma("unroll") for (int k = 0; k < 2; ++k) \
;         acc[ai][bj][m][n] = __builtin_amdgcn_mfma_f32_16x16x32_bf16(Bt[n][k], At[m][k], acc[ai][bj][m][n], 0, 0, 0); __builtin_amdgcn_s_setprio(0); } while (0)
; #define PG8_WAIT_V(n) asm volatile("s_waitcnt vmcnt(" #n ")" ::: "memory")
; #define PG8_WAIT_L(n) asm volatile("s_waitcnt lgkmcnt(" #n ")" ::: "memory")
; #define PG8_BAR __builtin_amdgcn_s_barrier()
; #define PG8_SCHED __builtin_amdgcn_sched_barrier(0)
; template <class Epi>
; DI void gemm_phase(LAS unsigned char* lds, const Gemm g, const StaticOrder& S, const Epi& E) {
;     ...
;             PG8_BAR; PG8_WAIT_L(0); PG8_MMA(0, 1, At, B1); PG8_BAR;
;             PG8_LDA(At, 1, 1); PG8_STAGE(PG8_SA(1, 0), a3);
;             PG8_BAR; PG8_WAIT_L(0); PG8_MMA(1, 0, At, B0); PG8_BAR; PG8_SCHED;
;             PG8_STAGE(PG8_SB(1, 1), b3 + hstep);
;             PG8_WAIT_V(6); PG8_BAR; PG8_MMA(1, 1, At, B1); PG8_BAR;
	v_mfma_f32_16x16x32_bf16 v[60:63], v[138:141], v[186:189], v[60:63]
	v_mfma_f32_16x16x32_bf16 v[56:59], v[146:149], v[186:189], v[56:59]
	v_mfma_f32_16x16x32_bf16 v[52:55], v[138:141], v[194:197], v[52:55]
	v_mfma_f32_16x16x32_bf16 v[48:51], v[146:149], v[194:197], v[48:51]
	v_mfma_f32_16x16x32_bf16 v[36:39], v[138:141], v[202:205], v[36:39]
	v_mfma_f32_16x16x32_bf16 v[32:35], v[146:149], v[202:205], v[32:35]
	v_mfma_f32_16x16x32_bf16 v[20:23], v[138:141], v[210:213], v[20:23]
	v_mfma_f32_16x16x32_bf16 v[16:19], v[146:149], v[210:213], v[16:19]
	v_mfma_f32_16x16x32_bf16 v[60:63], v[142:145], v[190:193], v[60:63]
	v_mfma_f32_16x16x32_bf16 v[56:59], v[150:153], v[190:193], v[56:59]
	v_mfma_f32_16x16x32_bf16 v[52:55], v[142:145], v[198:201], v[52:55]
	v_mfma_f32_16x16x32_bf16 v[48:51], v[150:153], v[198:201], v[48:51]
	v_mfma_f32_16x16x32_bf16 v[36:39], v[142:145], v[206:209], v[36:39]
	v_mfma_f32_16x16x32_bf16 v[32:35], v[150:153], v[206:209], v[32:35]
	v_mfma_f32_16x16x32_bf16 v[20:23], v[142:145], v[214:217], v[20:23]
	v_mfma_f32_16x16x32_bf16 v[16:19], v[150:153], v[214:217], v[16:19]
	s_setprio 0
	s_barrier
	s_add_u32 s18, s18, 0x80080
	s_addc_u32 s19, s19, 0
	s_add_i32 s20, s20, s23
	v_lshl_add_u64 v[138:139], s[18:19], 0, v[158:159]
	s_mov_b32 m0, s20
	s_nop 0
	global_load_lds_dwordx4 v[138:139], off
	v_lshl_add_u64 v[138:139], s[18:19], 0, v[128:129]
	s_add_i32 m0, s20, 0x2000
	s_nop 0
	global_load_lds_dwordx4 v[138:139], off
	s_waitcnt vmcnt(6)
	s_setprio 1
	s_barrier
	v_mfma_f32_16x16x32_bf16 v[44:47], v[226:229], v[186:189], v[44:47]
	v_mfma_f32_16x16x32_bf16 v[40:43], v[234:237], v[186:189], v[40:43]
	v_mfma_f32_16x16x32_bf16 v[28:31], v[226:229], v[194:197], v[28:31]
	v_mfma_f32_16x16x32_bf16 v[24:27], v[234:237], v[194:197], v[24:27]
	v_mfma_f32_16x16x32_bf16 v[12:15], v[226:229], v[202:205], v[12:15]
	v_mfma_f32_16x16x32_bf16 v[8:11], v[234:237], v[202:205], v[8:11]
	v_mfma_f32_16x16x32_bf16 v[4:7], v[226:229], v[210:213], v[4:7]
	v_mfma_f32_16x16x32_bf16 v[0:3], v[234:237], v[210:213], v[0:3]
	v_mfma_f32_16x16x32_bf16 v[44:47], v[230:233], v[190:193], v[44:47]
	s_add_i32 s36, s36, 2
	v_mfma_f32_16x16x32_bf16 v[40:43], v[238:241], v[190:193], v[40:43]
	s_add_u32 s16, s16, 0x100
	v_mfma_f32_16x16x32_bf16 v[28:31], v[230:233], v[198:201], v[28:31]
	s_addc_u32 s17, s17, 0
	v_mfma_f32_16x16x32_bf16 v[24:27], v[238:241], v[198:201], v[24:27]
	s_add_u32 s34, s34, 0x100
	v_mfma_f32_16x16x32_bf16 v[12:15], v[230:233], v[206:209], v[12:15]
	s_addc_u32 s35, s35, 0
	v_mfma_f32_16x16x32_bf16 v[8:11], v[238:241], v[206:209], v[8:11]
	s_cmp_gt_u32 s36, 29
	v_mfma_f32_16x16x32_bf16 v[4:7], v[230:233], v[214:217], v[4:7]
	v_mfma_f32_16x16x32_bf16 v[0:3], v[238:241], v[214:217], v[0:3]
	s_setprio 0
	s_barrier
	s_cbranch_scc0 .LBB0_231
; #define PG8_WAIT_V(n) asm volatile("s_waitcnt vmcnt(" #n ")" ::: "memory")
; #define PG8_BAR __builtin_amdgcn_s_barrier()
; template <class Epi>
; DI void gemm_phase(LAS unsigned char* lds, const Gemm g, const StaticOrder& S, const Epi& E) {
;     ...
;         if (!has_next) break;
; #pragma unroll
;         for (int a = 0; a < 2; ++a)
; #pragma unroll
;             for (int b = 0; b < 2; ++b)
; #pragma unroll
;                 for (int m = 0; m < 4; ++m)
; #pragma unroll
;                     for (int n = 0; n < 2; ++n) acc[a][b][m][n] = (f32x4){0.f, 0.f, 0.f, 0.f};
;         cur = nxt; cA = nA; cB = nB; ++ui;
;     }
;     PG8_WAIT_V(0);
;     if (wr == 0) PG8_BAR;
;     PG8_BAR;
;     DI void operator()(const f32x4 (&acc)[2][2][4][2], const Unit& u, int wr, int wc, int fr, int fq) const {
;         const int row0 = u.pm * BM + wr * 64 + fr, col0 = u.pn * BM + wc * 32 + 8 * fq;
; #pragma unroll
;         for (int ai = 0; ai < 2; ++ai)
; #pragma unroll
;             for (int m = 0; m < 4; ++m) { u16* rowp = O + (size_t)(row0 + ai * HALF + m * 16) * ldc + col0;
; #pragma unroll
;                 for (int bj = 0; bj < 2; ++bj) { const f32x4 v0 = acc[ai][bj][m][0], v1 = acc[ai][bj][m][1];
;                     *(u32x4*)(rowp + bj * HALF) = (u32x4){pk(v0[0], v0[1]), pk(v0[2], v0[3]), pk(v1[0], v1[1]), pk(v1[2], v1[3])}; } }
	v_lshl_add_u32 v144, s33, 8, v134
	v_lshl_or_b32 v138, s31, 8, v136
	v_ashrrev_i32_e32 v139, 31, v138
	v_mov_b64_e32 v[140:141], s[50:51]
	s_movk_i32 s9, 0x3000
	v_cvt_pk_bf16_f32 v68, v68, v69
	v_cvt_pk_bf16_f32 v69, v70, v71
	v_cvt_pk_bf16_f32 v70, v64, v65
	v_add_u32_e32 v64, 0x80, v144
	v_mad_i64_i32 v[142:143], s[4:5], v144, s9, v[140:141]
	v_lshlrev_b64 v[138:139], 1, v[138:139]
	v_cvt_pk_bf16_f32 v108, v108, v109
	v_cvt_pk_bf16_f32 v109, v110, v111
	v_cvt_pk_bf16_f32 v110, v104, v105
	v_or_b32_e32 v104, 16, v144
	v_mad_i64_i32 v[64:65], s[4:5], v64, s9, v[140:141]
	v_cvt_pk_bf16_f32 v44, v44, v45
	v_cvt_pk_bf16_f32 v45, v46, v47
	v_cvt_pk_bf16_f32 v46, v40, v41
	v_add_u32_e32 v40, 0x90, v144
	v_lshl_add_u64 v[142:143], v[142:143], 0, v[138:139]
	v_cvt_pk_bf16_f32 v111, v106, v107
	v_mad_i64_i32 v[104:105], s[4:5], v104, s9, v[140:141]
	v_cvt_pk_bf16_f32 v92, v92, v93
	v_cvt_pk_bf16_f32 v93, v94, v95
	v_cvt_pk_bf16_f32 v94, v88, v89
	v_or_b32_e32 v88, 32, v144
	v_lshl_add_u64 v[64:65], v[64:65], 0, v[138:139]
	v_cvt_pk_bf16_f32 v47, v42, v43
	v_mad_i64_i32 v[40:41], s[4:5], v40, s9, v[140:141]
	v_cvt_pk_bf16_f32 v28, v28, v29
	v_cvt_pk_bf16_f32 v29, v30, v31
	v_cvt_pk_bf16_f32 v30, v24, v25
	v_add_u32_e32 v24, 0xa0, v144
	global_store_dwordx4 v[142:143], v[108:111], off offset:256
	v_cvt_pk_bf16_f32 v95, v90, v91
	v_mad_i64_i32 v[88:89], s[4:5], v88, s9, v[140:141]
	v_lshl_add_u64 v[108:109], v[104:105], 0, v[138:139]
	v_cvt_pk_bf16_f32 v76, v76, v77
	v_cvt_pk_bf16_f32 v77, v78, v79
	v_cvt_pk_bf16_f32 v78, v72, v73
	v_or_b32_e32 v72, 48, v144
	global_store_dwordx4 v[64:65], v[44:47], off offset:256
	v_cvt_pk_bf16_f32 v31, v26, v27
	v_mad_i64_i32 v[24:25], s[4:5], v24, s9, v[140:141]
	v_lshl_add_u64 v[44:45], v[40:41], 0, v[138:139]
	v_cvt_pk_bf16_f32 v12, v12, v13
	v_cvt_pk_bf16_f32 v13, v14, v15
	v_cvt_pk_bf16_f32 v14, v8, v9
	v_add_u32_e32 v8, 0xb0, v144
	global_store_dwordx4 v[108:109], v[92:95], off offset:256
	v_cvt_pk_bf16_f32 v79, v74, v75
	v_mad_i64_i32 v[72:73], s[4:5], v72, s9, v[140:141]
	v_lshl_add_u64 v[92:93], v[88:89], 0, v[138:139]
	global_store_dwordx4 v[44:45], v[28:31], off offset:256
	v_cvt_pk_bf16_f32 v15, v10, v11
	v_mad_i64_i32 v[8:9], s[4:5], v8, s9, v[140:141]
	v_lshl_add_u64 v[28:29], v[24:25], 0, v[138:139]
	v_cvt_pk_bf16_f32 v124, v124, v125
	v_cvt_pk_bf16_f32 v125, v126, v127
	v_cvt_pk_bf16_f32 v126, v120, v121
	v_cvt_pk_bf16_f32 v127, v122, v123
	v_cvt_pk_bf16_f32 v104, v116, v117
	v_cvt_pk_bf16_f32 v105, v118, v119
	v_cvt_pk_bf16_f32 v106, v112, v113
	v_cvt_pk_bf16_f32 v107, v114, v115
	v_cvt_pk_bf16_f32 v88, v100, v101
	v_cvt_pk_bf16_f32 v89, v102, v103
	v_cvt_pk_bf16_f32 v90, v96, v97
	v_cvt_pk_bf16_f32 v91, v98, v99
	global_store_dwordx4 v[92:93], v[76:79], off offset:256
	v_cvt_pk_bf16_f32 v74, v80, v81
	v_cvt_pk_bf16_f32 v75, v82, v83
	v_lshl_add_u64 v[76:77], v[72:73], 0, v[138:139]
	v_cvt_pk_bf16_f32 v72, v84, v85
	v_cvt_pk_bf16_f32 v73, v86, v87
	v_cvt_pk_bf16_f32 v71, v66, v67
	v_cvt_pk_bf16_f32 v60, v60, v61
	v_cvt_pk_bf16_f32 v61, v62, v63
	v_cvt_pk_bf16_f32 v62, v56, v57
	v_cvt_pk_bf16_f32 v63, v58, v59
	v_cvt_pk_bf16_f32 v40, v52, v53
	v_cvt_pk_bf16_f32 v41, v54, v55
	v_cvt_pk_bf16_f32 v42, v48, v49
	v_cvt_pk_bf16_f32 v43, v50, v51
	v_cvt_pk_bf16_f32 v24, v36, v37
	v_cvt_pk_bf16_f32 v25, v38, v39
	v_cvt_pk_bf16_f32 v26, v32, v33
	v_cvt_pk_bf16_f32 v27, v34, v35
	global_store_dwordx4 v[28:29], v[12:15], off offset:256
	v_cvt_pk_bf16_f32 v10, v16, v17
	v_cvt_pk_bf16_f32 v11, v18, v19
	v_lshl_add_u64 v[12:13], v[8:9], 0, v[138:139]
	v_cvt_pk_bf16_f32 v8, v20, v21
	v_cvt_pk_bf16_f32 v9, v22, v23
	v_cvt_pk_bf16_f32 v4, v4, v5
	v_cvt_pk_bf16_f32 v5, v6, v7
	v_cvt_pk_bf16_f32 v6, v0, v1
	v_cvt_pk_bf16_f32 v7, v2, v3
	s_and_b64 vcc, exec, s[6:7]
	s_mov_b32 s31, s8
	s_mov_b32 s33, s10
	s_mov_b64 s[18:19], s[14:15]
	s_mov_b64 s[16:17], s[12:13]
	global_store_dwordx4 v[142:143], v[124:127], off
	global_store_dwordx4 v[108:109], v[104:107], off
	global_store_dwordx4 v[92:93], v[88:91], off
	global_store_dwordx4 v[76:77], v[72:75], off
	global_store_dwordx4 v[76:77], v[68:71], off offset:256
	global_store_dwordx4 v[64:65], v[60:63], off
	global_store_dwordx4 v[44:45], v[40:43], off
	global_store_dwordx4 v[28:29], v[24:27], off
	global_store_dwordx4 v[12:13], v[8:11], off
	global_store_dwordx4 v[12:13], v[4:7], off offset:256
	s_cbranch_vccz .LBB0_228
	s_waitcnt vmcnt(0)
	s_cmpk_gt_u32 s2, 0xff
	s_cbranch_scc1 .LBB0_235
	s_barrier

; __device__ __forceinline__ int opaque_tid() { int t = threadIdx.x; asm volatile("" : "+v"(t)); return t; }
; #define PG8_STAGE(bufoff, gbase) do { _Pragma("unroll") for (int _i = 0; _i < 2; ++_i) \
;         __builtin_amdgcn_global_load_lds((const unsigned*)((const char*)(gbase) + voff[_i]), (LAS unsigned*)(lds + (bufoff) + ldsw + _i * 8192), 16, 0, 0); } while (0)
; #define PG8_WAIT_V(n) asm volatile("s_waitcnt vmcnt(" #n ")" ::: "memory")
; #define PG8_BAR __builtin_amdgcn_s_barrier()
; template <class Epi>
; DI void gemm_phase(LAS unsigned char* lds, const Gemm g, const StaticOrder& S, const Epi& E) {
;     const int tid = opaque_tid(), wid = __builtin_amdgcn_readfirstlane(tid >> 6), lane = tid & 63, wr = wid >> 2, wc = wid & 3, fr = lane & 15, fq = lane >> 4;
;     const int K = g.K, nt = K / BK;
;     unsigned voff[2];
; #pragma unroll
;     for (int i = 0; i < 2; ++i) { int R, C; stage_rc(tid * 16 + i * 8192, R, C); voff[i] = (unsigned)(R * K + C) * 2u; }
;     const size_t kstep = (size_t)(BK * 2);
;     const size_t hstep = (size_t)HALF * K * 2;
;     const size_t tstep = 2 * hstep;
;     const unsigned ldsw = (unsigned)wid * 1024u;
;     const int aoff = lds_byte(wr * 64 + fr, fq * 8), boff = lds_byte(wc * 32 + fr, fq * 8);
;     ...
;     PG8_STAGE(PG8_SB(1, 0), cB + kstep); PG8_STAGE(PG8_SA(1, 0), cA + kstep); PG8_STAGE(PG8_SB(1, 1), cB + hstep + kstep);
;     PG8_WAIT_V(6); PG8_BAR;
.LBB0_311:
	v_mov_b32_e32 v189, v159
	v_lshl_add_u64 v[10:11], s[26:27], 0, v[188:189]
	v_mov_b32_e32 v187, v159
	v_readlane_b32 s24, v254, 27
	s_lshl_b32 s3, s3, 5
	v_lshl_add_u64 v[12:13], s[26:27], 0, v[186:187]
	v_readlane_b32 s25, v254, 28
	s_and_b32 s3, s3, 0x60
	s_add_i32 m0, s38, 0x18000
	v_lshl_add_u64 v[10:11], v[10:11], 0, s[94:95]
	v_lshl_add_u64 v[14:15], s[24:25], 0, v[188:189]
	s_lshl_b32 s6, s2, 13
	s_lshl_b32 s7, s3, 7
	s_waitcnt vmcnt(4)
	s_barrier
	global_load_lds_dwordx4 v[10:11], off
	v_lshl_add_u64 v[10:11], v[12:13], 0, s[94:95]
	s_add_i32 m0, s38, 0x1a000
	s_add_i32 s42, s38, 0x8000
	s_add_i32 s43, s38, 0xa000
	v_lshl_add_u64 v[16:17], s[24:25], 0, v[186:187]
	global_load_lds_dwordx4 v[10:11], off
	v_lshl_add_u64 v[10:11], v[14:15], 0, s[94:95]
	s_mov_b32 m0, s42
	s_add_u32 s4, s26, 0x80080
	global_load_lds_dwordx4 v[10:11], off
	v_lshl_add_u64 v[10:11], v[16:17], 0, s[94:95]
	s_mov_b32 m0, s43
	s_addc_u32 s5, s27, 0
	global_load_lds_dwordx4 v[10:11], off
	s_add_i32 m0, s38, 0x1c000
	v_lshl_add_u64 v[10:11], s[4:5], 0, v[188:189]
	global_load_lds_dwordx4 v[10:11], off
	v_lshl_add_u64 v[10:11], s[4:5], 0, v[186:187]
	s_add_i32 m0, s38, 0x1e000
	v_bfe_u32 v9, v0, 4, 2
	global_load_lds_dwordx4 v[10:11], off
	v_and_b32_e32 v10, 15, v0
	v_lshlrev_b32_e32 v11, 4, v9
	v_lshlrev_b32_e32 v0, 2, v0
	v_lshl_or_b32 v225, s2, 6, v10
	v_lshl_or_b32 v10, v10, 6, v11
	v_and_b32_e32 v0, 32, v0
	v_bitop3_b32 v11, v10, s6, v0 bitop3:0xde
	v_bitop3_b32 v226, v10, s7, v0 bitop3:0xde
	v_add_u32_e32 v226, 0x10000, v226
	v_lshlrev_b32_e32 v0, 14, v6
	v_and_b32_e32 v0, 0x7fff8000, v0
	v_lshl_add_u32 v0, v5, 11, v0
	v_or_b32_e32 v0, v0, v7
	v_add_lshl_u32 v158, v0, v8, 1
	v_lshlrev_b32_e32 v0, 14, v1
	v_and_b32_e32 v0, 0x7fff8000, v0
	v_lshl_add_u32 v0, v2, 11, v0
	s_waitcnt vmcnt(6)
	v_lshl_or_b32 v227, v9, 2, s3
	s_mov_b64 s[2:3], 0x80080
	v_or_b32_e32 v0, v0, v3
	v_lshl_add_u64 v[190:191], v[158:159], 0, s[2:3]
	v_add_lshl_u32 v158, v0, v4, 1
	v_readlane_b32 s4, v254, 50
	v_lshl_add_u64 v[192:193], v[158:159], 0, s[2:3]
	s_mov_b32 s44, 0
	v_add_u32_e32 v228, 0, v11
	v_readlane_b32 s2, v254, 31
	s_mov_b32 s3, s4
	s_barrier
	v_readlane_b32 s5, v254, 51
	s_branch .LBB0_313

; #define PG8_STAGE(bufoff, gbase) do { _Pragma("unroll") for (int _i = 0; _i < 2; ++_i) \
;         __builtin_amdgcn_global_load_lds((const unsigned*)((const char*)(gbase) + voff[_i]), (LAS unsigned*)(lds + (bufoff) + ldsw + _i * 8192), 16, 0, 0); } while (0)
; #define PG8_LDA(dst, b, h) do { _Pragma("unroll") for (int m = 0; m < 4; ++m) _Pragma("unroll") for (int k = 0; k < 2; ++k) dst[m][k] = *(const LAS bf16x8*)(lds + PG8_SA(b, h) + aoff + m * 2048 + k * 1024); } while (0)
; #define PG8_LDB(dst, b, h) do { _Pragma("unroll") for (int n = 0; n < 2; ++n) _Pragma("unroll") for (int k = 0; k < 2; ++k) dst[n][k] = *(const LAS bf16x8*)(lds + PG8_SB(b, h) + boff + n * 2048 + k * 1024); } while (0)
; #define PG8_MMA(ai, bj, At, Bt) do { __builtin_amdgcn_s_setprio(1); _Pragma("unroll") for (int m = 0; m < 4; ++m) _Pragma("unroll") for (int n = 0; n < 2; ++n) _Pragma("unroll") for (int k = 0; k < 2; ++k) \
;         acc[ai][bj][m][n] = __builtin_amdgcn_mfma_f32_16x16x32_bf16(Bt[n][k], At[m][k], acc[ai][bj][m][n], 0, 0, 0); __builtin_amdgcn_s_setprio(0); } while (0)
; #define PG8_WAIT_L(n) asm volatile("s_waitcnt lgkmcnt(" #n ")" ::: "memory")
; #define PG8_BAR __builtin_amdgcn_s_barrier()
; #define PG8_SCHED __builtin_amdgcn_sched_barrier(0)
; template <class Epi>
; DI void gemm_phase(LAS unsigned char* lds, const Gemm g, const StaticOrder& S, const Epi& E) {
;     ...
;         for (int t = 0; t < nt; t += 2) {
;             const bool last = (t == nt - 2);
;             const char* a1 = cA + (size_t)(t + 1) * kstep;
;             const char* a2 = last ? nA : cA + (size_t)(t + 2) * kstep; const char* b2 = last ? nB : cB + (size_t)(t + 2) * kstep;
;             const char* a3 = a2 + kstep; const char* b3 = b2 + kstep;
;             PG8_LDB(B0, 0, 0); PG8_SCHED; PG8_LDA(At, 0, 0); PG8_STAGE(PG8_SA(1, 1), a1 + hstep);
;             PG8_WAIT_L(8); PG8_BAR; PG8_WAIT_L(0); PG8_MMA(0, 0, At, B0); PG8_BAR; PG8_SCHED;
;             PG8_LDB(B1, 0, 1); PG8_STAGE(PG8_SB(0, 0), b2);
;             PG8_BAR; PG8_WAIT_L(0); PG8_MMA(0, 1, At, B1); PG8_BAR;
;             PG8_LDA(At, 0, 1); PG8_STAGE(PG8_SA(0, 0), a2);
;             PG8_BAR; PG8_WAIT_L(0); PG8_MMA(1, 0, At, B0); PG8_BAR; PG8_SCHED;
.LBB0_320:
	s_add_u32 s26, s24, 0x100
	s_addc_u32 s27, s25, 0
	s_add_i32 s47, 0, 0x10000
	ds_read_b128 v[128:131], v226
	ds_read_b128 v[132:135], v226 offset:1024
	ds_read_b128 v[136:139], v226 offset:2048
	ds_read_b128 v[140:143], v226 offset:3072
	s_cmp_eq_u32 s46, 28
	s_cselect_b32 s31, s4, s27
	s_cselect_b32 s30, s5, s26
	s_cselect_b32 s29, s9, s45
	s_cselect_b32 s28, s11, s33
	v_lshl_add_u64 v[214:215], s[24:25], 0, v[190:191]
	s_add_i32 m0, s38, 0xc000
	ds_read_b128 v[144:147], v228
	ds_read_b128 v[148:151], v228 offset:1024
	ds_read_b128 v[152:155], v228 offset:2048
	ds_read_b128 v[194:197], v228 offset:3072
	ds_read_b128 v[198:201], v228 offset:4096
	ds_read_b128 v[202:205], v228 offset:5120
	ds_read_b128 v[206:209], v228 offset:6144
	ds_read_b128 v[210:213], v228 offset:7168
	global_load_lds_dwordx4 v[214:215], off
	v_lshl_add_u64 v[214:215], s[24:25], 0, v[192:193]
	s_add_i32 m0, s38, 0xe000
	s_nop 0
	global_load_lds_dwordx4 v[214:215], off
	s_waitcnt lgkmcnt(8)
	s_setprio 1
	s_barrier
	s_waitcnt lgkmcnt(0)
	v_mfma_f32_16x16x32_bf16 v[124:127], v[128:131], v[144:147], v[124:127]
	v_mfma_f32_16x16x32_bf16 v[120:123], v[136:139], v[144:147], v[120:123]
	v_mfma_f32_16x16x32_bf16 v[116:119], v[128:131], v[152:155], v[116:119]
	v_mfma_f32_16x16x32_bf16 v[112:115], v[136:139], v[152:155], v[112:115]
	v_mfma_f32_16x16x32_bf16 v[108:111], v[128:131], v[198:201], v[108:111]
	v_mfma_f32_16x16x32_bf16 v[104:107], v[136:139], v[198:201], v[104:107]
	v_mfma_f32_16x16x32_bf16 v[100:103], v[128:131], v[206:209], v[100:103]
	v_mfma_f32_16x16x32_bf16 v[96:99], v[136:139], v[206:209], v[96:99]
	v_mfma_f32_16x16x32_bf16 v[124:127], v[132:135], v[148:151], v[124:127]
	v_mfma_f32_16x16x32_bf16 v[120:123], v[140:143], v[148:151], v[120:123]
	v_mfma_f32_16x16x32_bf16 v[116:119], v[132:135], v[194:197], v[116:119]
	v_mfma_f32_16x16x32_bf16 v[112:115], v[140:143], v[194:197], v[112:115]
	v_mfma_f32_16x16x32_bf16 v[108:111], v[132:135], v[202:205], v[108:111]
	v_mfma_f32_16x16x32_bf16 v[104:107], v[140:143], v[202:205], v[104:107]
	v_mfma_f32_16x16x32_bf16 v[100:103], v[132:135], v[210:213], v[100:103]
	v_mfma_f32_16x16x32_bf16 v[96:99], v[140:143], v[210:213], v[96:99]
	s_setprio 0
	s_barrier
	s_add_i32 s48, 0, 0x14000
	s_add_i32 s24, s47, s37
	v_lshl_add_u64 v[218:219], s[28:29], 0, v[188:189]
	s_mov_b32 m0, s24
	ds_read_b128 v[214:217], v226 offset:16384
	ds_read_b128 v[230:233], v226 offset:17408
	ds_read_b128 v[234:237], v226 offset:18432
	ds_read_b128 v[238:241], v226 offset:19456
	global_load_lds_dwordx4 v[218:219], off
	v_lshl_add_u64 v[220:221], s[28:29], 0, v[186:187]
	s_add_i32 m0, s24, 0x2000
	s_nop 0
	global_load_lds_dwordx4 v[220:221], off
	s_waitcnt lgkmcnt(0)
	s_setprio 1
	s_barrier
	v_mfma_f32_16x16x32_bf16 v[60:63], v[214:217], v[144:147], v[60:63]
	v_mfma_f32_16x16x32_bf16 v[56:59], v[234:237], v[144:147], v[56:59]
	v_mfma_f32_16x16x32_bf16 v[52:55], v[214:217], v[152:155], v[52:55]
	v_mfma_f32_16x16x32_bf16 v[48:51], v[234:237], v[152:155], v[48:51]
	v_mfma_f32_16x16x32_bf16 v[44:47], v[214:217], v[198:201], v[44:47]
	v_mfma_f32_16x16x32_bf16 v[40:43], v[234:237], v[198:201], v[40:43]
	v_mfma_f32_16x16x32_bf16 v[36:39], v[214:217], v[206:209], v[36:39]
	v_mfma_f32_16x16x32_bf16 v[32:35], v[234:237], v[206:209], v[32:35]
	v_mfma_f32_16x16x32_bf16 v[60:63], v[230:233], v[148:151], v[60:63]
	s_mov_b32 m0, s38
	v_mfma_f32_16x16x32_bf16 v[56:59], v[238:241], v[148:151], v[56:59]
	v_lshl_add_u64 v[242:243], s[30:31], 0, v[188:189]
	v_mfma_f32_16x16x32_bf16 v[52:55], v[230:233], v[194:197], v[52:55]
	v_mfma_f32_16x16x32_bf16 v[48:51], v[238:241], v[194:197], v[48:51]
	v_mfma_f32_16x16x32_bf16 v[44:47], v[230:233], v[202:205], v[44:47]
	v_mfma_f32_16x16x32_bf16 v[40:43], v[238:241], v[202:205], v[40:43]
	v_mfma_f32_16x16x32_bf16 v[36:39], v[230:233], v[210:213], v[36:39]
	v_mfma_f32_16x16x32_bf16 v[32:35], v[238:241], v[210:213], v[32:35]
	s_setprio 0
	s_barrier
	ds_read_b128 v[144:147], v228 offset:16384
	ds_read_b128 v[148:151], v228 offset:17408
	ds_read_b128 v[152:155], v228 offset:18432
	ds_read_b128 v[194:197], v228 offset:19456
	ds_read_b128 v[198:201], v228 offset:20480
	ds_read_b128 v[202:205], v228 offset:21504
	ds_read_b128 v[206:209], v228 offset:22528
	ds_read_b128 v[210:213], v228 offset:23552
	global_load_lds_dwordx4 v[242:243], off
	v_lshl_add_u64 v[244:245], s[30:31], 0, v[186:187]
	s_mov_b32 m0, s39
	s_nop 0
	global_load_lds_dwordx4 v[244:245], off
	s_waitcnt lgkmcnt(0)
	s_setprio 1
	s_barrier
	v_mfma_f32_16x16x32_bf16 v[92:95], v[128:131], v[144:147], v[92:95]
	v_mfma_f32_16x16x32_bf16 v[88:91], v[136:139], v[144:147], v[88:91]
	v_mfma_f32_16x16x32_bf16 v[84:87], v[128:131], v[152:155], v[84:87]
	v_mfma_f32_16x16x32_bf16 v[80:83], v[136:139], v[152:155], v[80:83]
	v_mfma_f32_16x16x32_bf16 v[76:79], v[128:131], v[198:201], v[76:79]
	v_mfma_f32_16x16x32_bf16 v[72:75], v[136:139], v[198:201], v[72:75]
	v_mfma_f32_16x16x32_bf16 v[68:71], v[128:131], v[206:209], v[68:71]
	v_mfma_f32_16x16x32_bf16 v[64:67], v[136:139], v[206:209], v[64:67]
	v_mfma_f32_16x16x32_bf16 v[92:95], v[132:135], v[148:151], v[92:95]
	v_mfma_f32_16x16x32_bf16 v[88:91], v[140:143], v[148:151], v[88:91]
	v_mfma_f32_16x16x32_bf16 v[84:87], v[132:135], v[194:197], v[84:87]
	v_mfma_f32_16x16x32_bf16 v[80:83], v[140:143], v[194:197], v[80:83]
	v_mfma_f32_16x16x32_bf16 v[76:79], v[132:135], v[202:205], v[76:79]
	v_mfma_f32_16x16x32_bf16 v[72:75], v[140:143], v[202:205], v[72:75]
	v_mfma_f32_16x16x32_bf16 v[68:71], v[132:135], v[210:213], v[68:71]
	v_mfma_f32_16x16x32_bf16 v[64:67], v[140:143], v[210:213], v[64:67]
	s_setprio 0
	s_barrier
; #define PG8_STAGE(bufoff, gbase) do { _Pragma("unroll") for (int _i = 0; _i < 2; ++_i) \
;         __builtin_amdgcn_global_load_lds((const unsigned*)((const char*)(gbase) + voff[_i]), (LAS unsigned*)(lds + (bufoff) + ldsw + _i * 8192), 16, 0, 0); } while (0)
; #define PG8_LDA(dst, b, h) do { _Pragma("unroll") for (int m = 0; m < 4; ++m) _Pragma("unroll") for (int k = 0; k < 2; ++k) dst[m][k] = *(const LAS bf16x8*)(lds + PG8_SA(b, h) + aoff + m * 2048 + k * 1024); } while (0)
; #define PG8_LDB(dst, b, h) do { _Pragma("unroll") for (int n = 0; n < 2; ++n) _Pragma("unroll") for (int k = 0; k < 2; ++k) dst[n][k] = *(const LAS bf16x8*)(lds + PG8_SB(b, h) + boff + n * 2048 + k * 1024); } while (0)
; #define PG8_MMA(ai, bj, At, Bt) do { __builtin_amdgcn_s_setprio(1); _Pragma("unroll") for (int m = 0; m < 4; ++m) _Pragma("unroll") for (int n = 0; n < 2; ++n) _Pragma("unroll") for (int k = 0; k < 2; ++k) \
;         acc[ai][bj][m][n] = __builtin_amdgcn_mfma_f32_16x16x32_bf16(Bt[n][k], At[m][k], acc[ai][bj][m][n], 0, 0, 0); __builtin_amdgcn_s_setprio(0); } while (0)
; #define PG8_WAIT_V(n) asm volatile("s_waitcnt vmcnt(" #n ")" ::: "memory")
; #define PG8_WAIT_L(n) asm volatile("s_waitcnt lgkmcnt(" #n ")" ::: "memory")
; #define PG8_BAR __builtin_amdgcn_s_barrier()
; #define PG8_SCHED __builtin_amdgcn_sched_barrier(0)
; template <class Epi>
; DI void gemm_phase(LAS unsigned char* lds, const Gemm g, const StaticOrder& S, const Epi& E) {
;     ...
;             PG8_STAGE(PG8_SB(0, 1), b2 + hstep);
;             PG8_WAIT_V(6); PG8_BAR; PG8_MMA(1, 1, At, B1); PG8_BAR;
;             PG8_LDB(B0, 1, 0); PG8_SCHED; PG8_LDA(At, 1, 0); PG8_STAGE(PG8_SA(0, 1), a2 + hstep);
;             PG8_WAIT_L(8); PG8_BAR; PG8_WAIT_L(0); PG8_MMA(0, 0, At, B0); PG8_BAR; PG8_SCHED;
;             PG8_LDB(B1, 1, 1); PG8_STAGE(PG8_SB(1, 0), b3);
	s_add_u32 s24, s28, 0x80000
	s_addc_u32 s25, s29, 0
	s_add_i32 s47, s48, s37
	v_lshl_add_u64 v[128:129], s[24:25], 0, v[188:189]
	s_mov_b32 m0, s47
	s_nop 0
	global_load_lds_dwordx4 v[128:129], off
	v_lshl_add_u64 v[128:129], s[24:25], 0, v[186:187]
	s_add_i32 m0, s47, 0x2000
	s_nop 0
	global_load_lds_dwordx4 v[128:129], off
	s_waitcnt vmcnt(6)
	s_setprio 1
	s_barrier
	v_mfma_f32_16x16x32_bf16 v[28:31], v[214:217], v[144:147], v[28:31]
	v_mfma_f32_16x16x32_bf16 v[24:27], v[234:237], v[144:147], v[24:27]
	v_mfma_f32_16x16x32_bf16 v[20:23], v[214:217], v[152:155], v[20:23]
	v_mfma_f32_16x16x32_bf16 v[16:19], v[234:237], v[152:155], v[16:19]
	v_mfma_f32_16x16x32_bf16 v[12:15], v[214:217], v[198:201], v[12:15]
	v_mfma_f32_16x16x32_bf16 v[8:11], v[234:237], v[198:201], v[8:11]
	v_mfma_f32_16x16x32_bf16 v[4:7], v[214:217], v[206:209], v[4:7]
	v_mfma_f32_16x16x32_bf16 v[0:3], v[234:237], v[206:209], v[0:3]
	v_mfma_f32_16x16x32_bf16 v[28:31], v[230:233], v[148:151], v[28:31]
	s_add_i32 s47, 0, 0x18000
	v_mfma_f32_16x16x32_bf16 v[24:27], v[238:241], v[148:151], v[24:27]
	v_mfma_f32_16x16x32_bf16 v[20:23], v[230:233], v[194:197], v[20:23]
	v_mfma_f32_16x16x32_bf16 v[16:19], v[238:241], v[194:197], v[16:19]
	v_mfma_f32_16x16x32_bf16 v[12:15], v[230:233], v[202:205], v[12:15]
	v_mfma_f32_16x16x32_bf16 v[8:11], v[238:241], v[202:205], v[8:11]
	v_mfma_f32_16x16x32_bf16 v[4:7], v[230:233], v[210:213], v[4:7]
	v_mfma_f32_16x16x32_bf16 v[0:3], v[238:241], v[210:213], v[0:3]
	s_setprio 0
	s_barrier
	ds_read_b128 v[128:131], v226 offset:32768
	ds_read_b128 v[132:135], v226 offset:33792
	ds_read_b128 v[136:139], v226 offset:34816
	ds_read_b128 v[140:143], v226 offset:35840
	s_add_u32 s24, s30, 0x80000
	s_addc_u32 s25, s31, 0
	s_mov_b32 m0, s40
	v_lshl_add_u64 v[214:215], s[24:25], 0, v[188:189]
	ds_read_b128 v[144:147], v228 offset:32768
	ds_read_b128 v[148:151], v228 offset:33792
	ds_read_b128 v[152:155], v228 offset:34816
	ds_read_b128 v[194:197], v228 offset:35840
	ds_read_b128 v[198:201], v228 offset:36864
	ds_read_b128 v[202:205], v228 offset:37888
	ds_read_b128 v[206:209], v228 offset:38912
	ds_read_b128 v[210:213], v228 offset:39936
	global_load_lds_dwordx4 v[214:215], off
	v_lshl_add_u64 v[214:215], s[24:25], 0, v[186:187]
	s_mov_b32 m0, s41
	s_nop 0
	global_load_lds_dwordx4 v[214:215], off
	s_waitcnt lgkmcnt(8)
	s_setprio 1
	s_barrier
	s_waitcnt lgkmcnt(0)
	v_mfma_f32_16x16x32_bf16 v[124:127], v[128:131], v[144:147], v[124:127]
	v_mfma_f32_16x16x32_bf16 v[120:123], v[136:139], v[144:147], v[120:123]
	v_mfma_f32_16x16x32_bf16 v[116:119], v[128:131], v[152:155], v[116:119]
	v_mfma_f32_16x16x32_bf16 v[112:115], v[136:139], v[152:155], v[112:115]
	v_mfma_f32_16x16x32_bf16 v[108:111], v[128:131], v[198:201], v[108:111]
	v_mfma_f32_16x16x32_bf16 v[104:107], v[136:139], v[198:201], v[104:107]
	v_mfma_f32_16x16x32_bf16 v[100:103], v[128:131], v[206:209], v[100:103]
	v_mfma_f32_16x16x32_bf16 v[96:99], v[136:139], v[206:209], v[96:99]
	v_mfma_f32_16x16x32_bf16 v[124:127], v[132:135], v[148:151], v[124:127]
	v_mfma_f32_16x16x32_bf16 v[120:123], v[140:143], v[148:151], v[120:123]
	v_mfma_f32_16x16x32_bf16 v[116:119], v[132:135], v[194:197], v[116:119]
	v_mfma_f32_16x16x32_bf16 v[112:115], v[140:143], v[194:197], v[112:115]
	v_mfma_f32_16x16x32_bf16 v[108:111], v[132:135], v[202:205], v[108:111]
	v_mfma_f32_16x16x32_bf16 v[104:107], v[140:143], v[202:205], v[104:107]
	v_mfma_f32_16x16x32_bf16 v[100:103], v[132:135], v[210:213], v[100:103]
	v_mfma_f32_16x16x32_bf16 v[96:99], v[140:143], v[210:213], v[96:99]
	s_setprio 0
	s_barrier
	s_add_i32 s30, 0, 0x1c000
	s_add_i32 s24, s47, s37
	v_lshl_add_u64 v[218:219], v[218:219], 0, s[94:95]
	s_mov_b32 m0, s24
	ds_read_b128 v[214:217], v226 offset:49152
	ds_read_b128 v[230:233], v226 offset:50176
	ds_read_b128 v[234:237], v226 offset:51200
	ds_read_b128 v[238:241], v226 offset:52224
	global_load_lds_dwordx4 v[218:219], off
	v_lshl_add_u64 v[218:219], v[220:221], 0, s[94:95]
	s_add_i32 m0, s24, 0x2000
	s_nop 0
	global_load_lds_dwordx4 v[218:219], off
	s_waitcnt lgkmcnt(0)
	s_setprio 1
	s_barrier
	v_mfma_f32_16x16x32_bf16 v[60:63], v[214:217], v[144:147], v[60:63]
	v_mfma_f32_16x16x32_bf16 v[56:59], v[234:237], v[144:147], v[56:59]
	v_mfma_f32_16x16x32_bf16 v[52:55], v[214:217], v[152:155], v[52:55]
	v_mfma_f32_16x16x32_bf16 v[48:51], v[234:237], v[152:155], v[48:51]
	v_mfma_f32_16x16x32_bf16 v[44:47], v[214:217], v[198:201], v[44:47]
	v_mfma_f32_16x16x32_bf16 v[40:43], v[234:237], v[198:201], v[40:43]
	v_mfma_f32_16x16x32_bf16 v[36:39], v[214:217], v[206:209], v[36:39]
	v_mfma_f32_16x16x32_bf16 v[32:35], v[234:237], v[206:209], v[32:35]
	v_mfma_f32_16x16x32_bf16 v[60:63], v[230:233], v[148:151], v[60:63]
	s_mov_b32 m0, s42
	v_mfma_f32_16x16x32_bf16 v[56:59], v[238:241], v[148:151], v[56:59]
	v_lshl_add_u64 v[218:219], v[242:243], 0, s[94:95]
	v_mfma_f32_16x16x32_bf16 v[52:55], v[230:233], v[194:197], v[52:55]
	v_mfma_f32_16x16x32_bf16 v[48:51], v[238:241], v[194:197], v[48:51]
	v_mfma_f32_16x16x32_bf16 v[44:47], v[230:233], v[202:205], v[44:47]
	v_mfma_f32_16x16x32_bf16 v[40:43], v[238:241], v[202:205], v[40:43]
	v_mfma_f32_16x16x32_bf16 v[36:39], v[230:233], v[210:213], v[36:39]
	v_mfma_f32_16x16x32_bf16 v[32:35], v[238:241], v[210:213], v[32:35]
	s_setprio 0
	s_barrier
	ds_read_b128 v[144:147], v228 offset:49152
	ds_read_b128 v[148:151], v228 offset:50176
	ds_read_b128 v[152:155], v228 offset:51200
	ds_read_b128 v[194:197], v228 offset:52224
	ds_read_b128 v[198:201], v228 offset:53248
	ds_read_b128 v[202:205], v228 offset:54272
	ds_read_b128 v[206:209], v228 offset:55296
	ds_read_b128 v[210:213], v228 offset:56320
	global_load_lds_dwordx4 v[218:219], off
	v_lshl_add_u64 v[218:219], v[244:245], 0, s[94:95]
	s_mov_b32 m0, s43
	s_nop 0
	global_load_lds_dwordx4 v[218:219], off
	s_waitcnt lgkmcnt(0)
	s_setprio 1
	s_barrier
; #define PG8_WAIT_V(n) asm volatile("s_waitcnt vmcnt(" #n ")" ::: "memory")
; #define PG8_WAIT_L(n) asm volatile("s_waitcnt lgkmcnt(" #n ")" ::: "memory")
; #define PG8_BAR __builtin_amdgcn_s_barrier()
; template <class Epi>
; DI void gemm_phase(LAS unsigned char* lds, const Gemm g, const StaticOrder& S, const Epi& E) {
;     ...
;             PG8_BAR; PG8_WAIT_L(0); PG8_MMA(1, 0, At, B0); PG8_BAR; PG8_SCHED;
;             PG8_STAGE(PG8_SB(1, 1), b3 + hstep);
;             PG8_WAIT_V(6); PG8_BAR; PG8_MMA(1, 1, At, B1); PG8_BAR;
;     template <bool LN, int BJ, int LO, int HI> DI void batch(const f32x4 (&acc)[2][2][4][2], unsigned row0, unsigned col0, const f32x4 (&gv)[2], const f32x4 (&bv)[2]) const {
;         f32x4 r[HI - LO]; float mean[(HI - LO) / 2], rstd[(HI - LO) / 2];
; #pragma unroll
;         for (int i = LO; i < HI; ++i) { const int ai = i >> 3, m = (i >> 1) & 3, n = i & 1; const unsigned row = row0 + ai * HALF + m * 16;
;             if (n == 0) { mean[(i - LO) >> 1] = 0.f; rstd[(i - LO) >> 1] = 1.f;
;                 if (LN) { const float2 st = *(const float2*)(stats + row * 2u); mean[(i - LO) >> 1] = st.x; rstd[(i - LO) >> 1] = st.y; } }
;             r[i - LO] = *(const f32x4*)(src + (row * (unsigned)DM + col0 + BJ * HALF + n * 16)); }
; #pragma unroll
;         for (int i = LO; i < HI; ++i) { const int ai = i >> 3, m = (i >> 1) & 3, n = i & 1; const unsigned row = row0 + ai * HALF + m * 16;
;             *(f32x4*)(Y + (row * (unsigned)DM + col0 + BJ * HALF + n * 16)) = acc[ai][BJ][m][n] + ((r[i - LO] - mean[(i - LO) >> 1]) * rstd[(i - LO) >> 1]) * gv[n] + bv[n]; }
;         __builtin_amdgcn_sched_barrier(0);
;     }
;     template <bool LN, int BJ> DI void load_gb(unsigned col0, f32x4 (&gv)[2], f32x4 (&bv)[2]) const {
; #pragma unroll
;         for (int n = 0; n < 2; ++n) {
;             if (LN) { gv[n] = *(const f32x4*)(gam + col0 + BJ * HALF + n * 16) * ALPHA; bv[n] = *(const f32x4*)(bet + col0 + BJ * HALF + n * 16) * ALPHA; }
;             else { gv[n] = (f32x4){ALPHA, ALPHA, ALPHA, ALPHA}; bv[n] = (f32x4){0.f, 0.f, 0.f, 0.f}; }
;         }
;     }
;     template <bool LN> DI void run(const f32x4 (&acc)[2][2][4][2], const Unit& u, int wr, int wc, int fr, int fq) const {
;         const unsigned row0 = u.pm * BM + wr * 64 + fr, col0 = u.pn * BM + wc * 32 + 4 * fq;
;         f32x4 gv[2], bv[2];
;         load_gb<LN, 0>(col0, gv, bv);
	v_mfma_f32_16x16x32_bf16 v[92:95], v[128:131], v[144:147], v[92:95]
	v_mfma_f32_16x16x32_bf16 v[88:91], v[136:139], v[144:147], v[88:91]
	v_mfma_f32_16x16x32_bf16 v[84:87], v[128:131], v[152:155], v[84:87]
	v_mfma_f32_16x16x32_bf16 v[80:83], v[136:139], v[152:155], v[80:83]
	v_mfma_f32_16x16x32_bf16 v[76:79], v[128:131], v[198:201], v[76:79]
	v_mfma_f32_16x16x32_bf16 v[72:75], v[136:139], v[198:201], v[72:75]
	v_mfma_f32_16x16x32_bf16 v[68:71], v[128:131], v[206:209], v[68:71]
	v_mfma_f32_16x16x32_bf16 v[64:67], v[136:139], v[206:209], v[64:67]
	v_mfma_f32_16x16x32_bf16 v[92:95], v[132:135], v[148:151], v[92:95]
	v_mfma_f32_16x16x32_bf16 v[88:91], v[140:143], v[148:151], v[88:91]
	v_mfma_f32_16x16x32_bf16 v[84:87], v[132:135], v[194:197], v[84:87]
	v_mfma_f32_16x16x32_bf16 v[80:83], v[140:143], v[194:197], v[80:83]
	v_mfma_f32_16x16x32_bf16 v[76:79], v[132:135], v[202:205], v[76:79]
	v_mfma_f32_16x16x32_bf16 v[72:75], v[140:143], v[202:205], v[72:75]
	v_mfma_f32_16x16x32_bf16 v[68:71], v[132:135], v[210:213], v[68:71]
	v_mfma_f32_16x16x32_bf16 v[64:67], v[140:143], v[210:213], v[64:67]
	s_setprio 0
	s_barrier
	s_add_u32 s24, s28, 0x80080
	s_addc_u32 s25, s29, 0
	s_add_i32 s28, s30, s37
	v_lshl_add_u64 v[128:129], s[24:25], 0, v[188:189]
	s_mov_b32 m0, s28
	s_nop 0
	global_load_lds_dwordx4 v[128:129], off
	v_lshl_add_u64 v[128:129], s[24:25], 0, v[186:187]
	s_add_i32 m0, s28, 0x2000
	s_nop 0
	global_load_lds_dwordx4 v[128:129], off
	s_waitcnt vmcnt(6)
	s_setprio 1
	s_barrier
	v_mfma_f32_16x16x32_bf16 v[28:31], v[214:217], v[144:147], v[28:31]
	v_mfma_f32_16x16x32_bf16 v[24:27], v[234:237], v[144:147], v[24:27]
	v_mfma_f32_16x16x32_bf16 v[20:23], v[214:217], v[152:155], v[20:23]
	v_mfma_f32_16x16x32_bf16 v[16:19], v[234:237], v[152:155], v[16:19]
	v_mfma_f32_16x16x32_bf16 v[12:15], v[214:217], v[198:201], v[12:15]
	v_mfma_f32_16x16x32_bf16 v[8:11], v[234:237], v[198:201], v[8:11]
	v_mfma_f32_16x16x32_bf16 v[4:7], v[214:217], v[206:209], v[4:7]
	v_mfma_f32_16x16x32_bf16 v[0:3], v[234:237], v[206:209], v[0:3]
	v_mfma_f32_16x16x32_bf16 v[28:31], v[230:233], v[148:151], v[28:31]
	s_add_i32 s46, s46, 2
	v_mfma_f32_16x16x32_bf16 v[24:27], v[238:241], v[148:151], v[24:27]
	s_add_u32 s33, s33, 0x100
	v_mfma_f32_16x16x32_bf16 v[20:23], v[230:233], v[194:197], v[20:23]
	s_addc_u32 s45, s45, 0
	v_mfma_f32_16x16x32_bf16 v[16:19], v[238:241], v[194:197], v[16:19]
	s_cmp_gt_u32 s46, 29
	v_mfma_f32_16x16x32_bf16 v[12:15], v[230:233], v[202:205], v[12:15]
	s_mov_b64 s[24:25], s[26:27]
	v_mfma_f32_16x16x32_bf16 v[8:11], v[238:241], v[202:205], v[8:11]
	v_mfma_f32_16x16x32_bf16 v[4:7], v[230:233], v[210:213], v[4:7]
	v_mfma_f32_16x16x32_bf16 v[0:3], v[238:241], v[210:213], v[0:3]
	s_setprio 0
	s_barrier
	s_cbranch_scc0 .LBB0_320
	v_lshl_add_u32 v206, s3, 8, v225
	v_lshl_or_b32 v158, s2, 8, v227
	v_lshlrev_b32_e32 v232, 11, v206
	s_andn2_b64 vcc, exec, s[14:15]
	v_or_b32_e32 v231, 16, v158
	v_add_u32_e32 v194, v232, v158
	v_or_b32_e32 v230, 0x80, v158
	v_or_b32_e32 v229, 0x90, v158
	s_cbranch_vccnz .LBB0_323
	v_lshlrev_b64 v[132:133], 2, v[158:159]
	v_lshl_add_u64 v[140:141], s[16:17], 0, v[132:133]
	global_load_dwordx4 v[128:131], v[140:141], off
	v_lshl_add_u64 v[142:143], s[18:19], 0, v[132:133]
	v_readlane_b32 s2, v253, 8
	v_mov_b32_e32 v195, v159
	v_lshlrev_b32_e32 v136, 1, v206
	v_mov_b32_e32 v137, v159
	v_readlane_b32 s3, v253, 9
	v_lshlrev_b64 v[212:213], 2, v[194:195]
	v_add_u32_e32 v146, v232, v231
	v_lshl_add_u64 v[144:145], v[136:137], 2, s[2:3]
	v_lshl_add_u64 v[136:137], s[88:89], 0, v[212:213]
	v_mov_b32_e32 v147, v159
	v_lshl_add_u64 v[146:147], v[146:147], 2, s[88:89]
	v_or_b32_e32 v195, 16, v206
	v_mov_b32_e32 v201, v159
	v_mov_b32_e32 v209, v159
	v_lshl_add_u64 v[212:213], s[90:91], 0, v[212:213]
	s_waitcnt vmcnt(0)
	v_pk_mul_f32 v[152:153], v[130:131], s[78:79] op_sel_hi:[1,0]
	v_pk_mul_f32 v[154:155], v[128:129], s[78:79] op_sel_hi:[1,0]
	global_load_dwordx4 v[132:135], v[142:143], off
	global_load_dwordx4 v[128:131], v[140:141], off offset:64
	global_load_dwordx2 v[204:205], v[144:145], off
	global_load_dwordx4 v[196:199], v[146:147], off
	v_lshlrev_b32_e32 v146, 1, v195
	global_load_dwordx4 v[136:139], v[136:137], off
	v_lshlrev_b32_e32 v195, 11, v195
	v_mov_b32_e32 v147, v159
	v_add_u32_e32 v200, v195, v158
	v_lshl_add_u64 v[146:147], v[146:147], 2, s[2:3]
	v_lshl_add_u64 v[200:201], v[200:201], 2, s[88:89]
	global_load_dwordx2 v[214:215], v[146:147], off
	v_add_u32_e32 v208, v195, v231
	global_load_dwordx4 v[200:203], v[200:201], off
	v_lshl_add_u64 v[208:209], v[208:209], 2, s[88:89]
	global_load_dwordx4 v[208:211], v[208:209], off
	s_waitcnt vmcnt(0)
	v_pk_mul_f32 v[148:149], v[130:131], s[78:79] op_sel_hi:[1,0]
	v_pk_mul_f32 v[150:151], v[128:129], s[78:79] op_sel_hi:[1,0]
	global_load_dwordx4 v[128:131], v[142:143], off offset:64
	v_sub_f32_e32 v137, v137, v204
	v_sub_f32_e32 v136, v136, v204
	v_sub_f32_e32 v139, v139, v204
	v_sub_f32_e32 v138, v138, v204
	v_pk_mul_f32 v[138:139], v[204:205], v[138:139] op_sel:[1,0]
	v_pk_mul_f32 v[136:137], v[204:205], v[136:137] op_sel:[1,0]
	v_pk_fma_f32 v[138:139], v[152:153], v[138:139], v[126:127]
	v_pk_fma_f32 v[136:137], v[154:155], v[136:137], v[124:125]
	v_pk_fma_f32 v[138:139], v[134:135], s[78:79], v[138:139] op_sel_hi:[1,0,1]
	v_pk_fma_f32 v[136:137], v[132:133], s[78:79], v[136:137] op_sel_hi:[1,0,1]
	global_store_dwordx4 v[212:213], v[136:139], off
	s_nop 1
	v_sub_f32_e32 v137, v197, v204
	v_sub_f32_e32 v136, v196, v204
	v_sub_f32_e32 v139, v199, v204
	v_sub_f32_e32 v138, v198, v204
	v_pk_mul_f32 v[138:139], v[204:205], v[138:139] op_sel:[1,0]
	v_pk_mul_f32 v[136:137], v[204:205], v[136:137] op_sel:[1,0]
	v_pk_fma_f32 v[138:139], v[148:149], v[138:139], v[122:123]
	v_pk_fma_f32 v[136:137], v[150:151], v[136:137], v[120:121]
	v_or_b32_e32 v196, 16, v194
	v_mov_b32_e32 v197, v159
	v_lshl_add_u64 v[196:197], v[196:197], 2, s[90:91]
	s_waitcnt vmcnt(0)
;     template <bool LN, int BJ, int LO, int HI> DI void batch(const f32x4 (&acc)[2][2][4][2], unsigned row0, unsigned col0, const f32x4 (&gv)[2], const f32x4 (&bv)[2]) const {
;         f32x4 r[HI - LO]; float mean[(HI - LO) / 2], rstd[(HI - LO) / 2];
; #pragma unroll
;         for (int i = LO; i < HI; ++i) { const int ai = i >> 3, m = (i >> 1) & 3, n = i & 1; const unsigned row = row0 + ai * HALF + m * 16;
;             if (n == 0) { mean[(i - LO) >> 1] = 0.f; rstd[(i - LO) >> 1] = 1.f;
;                 if (LN) { const float2 st = *(const float2*)(stats + row * 2u); mean[(i - LO) >> 1] = st.x; rstd[(i - LO) >> 1] = st.y; } }
;             r[i - LO] = *(const f32x4*)(src + (row * (unsigned)DM + col0 + BJ * HALF + n * 16)); }
; #pragma unroll
;         for (int i = LO; i < HI; ++i) { const int ai = i >> 3, m = (i >> 1) & 3, n = i & 1; const unsigned row = row0 + ai * HALF + m * 16;
;             *(f32x4*)(Y + (row * (unsigned)DM + col0 + BJ * HALF + n * 16)) = acc[ai][BJ][m][n] + ((r[i - LO] - mean[(i - LO) >> 1]) * rstd[(i - LO) >> 1]) * gv[n] + bv[n]; }
	v_pk_fma_f32 v[138:139], v[130:131], s[78:79], v[138:139] op_sel_hi:[1,0,1]
	v_pk_fma_f32 v[136:137], v[128:129], s[78:79], v[136:137] op_sel_hi:[1,0,1]
	global_store_dwordx4 v[196:197], v[136:139], off
	v_add_u32_e32 v196, 0x8000, v194
	v_mov_b32_e32 v197, v159
	v_sub_f32_e32 v137, v201, v214
	v_sub_f32_e32 v136, v200, v214
	v_sub_f32_e32 v139, v203, v214
	v_sub_f32_e32 v138, v202, v214
	v_pk_mul_f32 v[138:139], v[214:215], v[138:139] op_sel:[1,0]
	v_pk_mul_f32 v[136:137], v[214:215], v[136:137] op_sel:[1,0]
	v_pk_fma_f32 v[138:139], v[152:153], v[138:139], v[118:119]
	v_pk_fma_f32 v[136:137], v[154:155], v[136:137], v[116:117]
	v_pk_fma_f32 v[138:139], v[134:135], s[78:79], v[138:139] op_sel_hi:[1,0,1]
	v_pk_fma_f32 v[136:137], v[132:133], s[78:79], v[136:137] op_sel_hi:[1,0,1]
	v_lshl_add_u64 v[196:197], v[196:197], 2, s[90:91]
	global_store_dwordx4 v[196:197], v[136:139], off
	v_add_u32_e32 v196, 0x8010, v194
	v_mov_b32_e32 v197, v159
	v_sub_f32_e32 v137, v209, v214
	v_sub_f32_e32 v136, v208, v214
	v_sub_f32_e32 v139, v211, v214
	v_sub_f32_e32 v138, v210, v214
	v_pk_mul_f32 v[138:139], v[214:215], v[138:139] op_sel:[1,0]
	v_pk_mul_f32 v[136:137], v[214:215], v[136:137] op_sel:[1,0]
	v_pk_fma_f32 v[138:139], v[148:149], v[138:139], v[114:115]
	v_pk_fma_f32 v[136:137], v[150:151], v[136:137], v[112:113]
	v_pk_fma_f32 v[138:139], v[130:131], s[78:79], v[138:139] op_sel_hi:[1,0,1]
	v_pk_fma_f32 v[136:137], v[128:129], s[78:79], v[136:137] op_sel_hi:[1,0,1]
	v_lshl_add_u64 v[196:197], v[196:197], 2, s[90:91]
	global_store_dwordx4 v[196:197], v[136:139], off
	s_nop 1
	v_or_b32_e32 v138, 32, v206
	v_lshlrev_b32_e32 v136, 1, v138
	v_mov_b32_e32 v137, v159
	v_lshlrev_b32_e32 v236, 11, v138
	v_lshl_add_u64 v[200:201], v[136:137], 2, s[2:3]
	v_add_u32_e32 v136, v236, v158
	v_lshl_add_u64 v[136:137], v[136:137], 2, s[88:89]
	global_load_dwordx2 v[204:205], v[200:201], off
	v_add_u32_e32 v196, v236, v231
	global_load_dwordx4 v[136:139], v[136:137], off
	v_mov_b32_e32 v197, v159
	v_lshl_add_u64 v[196:197], v[196:197], 2, s[88:89]
	global_load_dwordx4 v[196:199], v[196:197], off
	v_or_b32_e32 v207, 48, v206
	v_lshlrev_b32_e32 v235, 11, v207
	v_lshlrev_b32_e32 v202, 1, v207
	v_mov_b32_e32 v203, v159
	v_add_u32_e32 v208, v235, v158
	v_mov_b32_e32 v209, v159
	v_lshl_add_u64 v[202:203], v[202:203], 2, s[2:3]
	v_lshl_add_u64 v[208:209], v[208:209], 2, s[88:89]
	global_load_dwordx2 v[216:217], v[202:203], off
	v_add_u32_e32 v212, v235, v231
	global_load_dwordx4 v[208:211], v[208:209], off
	v_mov_b32_e32 v213, v159
	v_lshl_add_u64 v[212:213], v[212:213], 2, s[88:89]
	global_load_dwordx4 v[212:215], v[212:213], off
	v_add_u32_e32 v218, 0x10000, v194
	v_mov_b32_e32 v219, v159
	v_lshl_add_u64 v[218:219], v[218:219], 2, s[90:91]
	s_waitcnt vmcnt(0)
	v_sub_f32_e32 v137, v137, v204
	v_sub_f32_e32 v136, v136, v204
	v_sub_f32_e32 v139, v139, v204
	v_sub_f32_e32 v138, v138, v204
	v_pk_mul_f32 v[138:139], v[204:205], v[138:139] op_sel:[1,0]
	v_pk_mul_f32 v[136:137], v[204:205], v[136:137] op_sel:[1,0]
	v_pk_fma_f32 v[138:139], v[152:153], v[138:139], v[110:111]
	v_pk_fma_f32 v[136:137], v[154:155], v[136:137], v[108:109]
	v_pk_fma_f32 v[138:139], v[134:135], s[78:79], v[138:139] op_sel_hi:[1,0,1]
	v_pk_fma_f32 v[136:137], v[132:133], s[78:79], v[136:137] op_sel_hi:[1,0,1]
	global_store_dwordx4 v[218:219], v[136:139], off
	s_nop 1
	v_sub_f32_e32 v137, v197, v204
	v_sub_f32_e32 v136, v196, v204
	v_sub_f32_e32 v139, v199, v204
	v_sub_f32_e32 v138, v198, v204
	v_pk_mul_f32 v[138:139], v[204:205], v[138:139] op_sel:[1,0]
	v_pk_mul_f32 v[136:137], v[204:205], v[136:137] op_sel:[1,0]
	v_pk_fma_f32 v[138:139], v[148:149], v[138:139], v[106:107]
	v_pk_fma_f32 v[136:137], v[150:151], v[136:137], v[104:105]
	v_add_u32_e32 v196, 0x10010, v194
	v_mov_b32_e32 v197, v159
	v_pk_fma_f32 v[138:139], v[130:131], s[78:79], v[138:139] op_sel_hi:[1,0,1]
	v_pk_fma_f32 v[136:137], v[128:129], s[78:79], v[136:137] op_sel_hi:[1,0,1]
	v_lshl_add_u64 v[196:197], v[196:197], 2, s[90:91]
	global_store_dwordx4 v[196:197], v[136:139], off
	v_add_u32_e32 v196, 0x18000, v194
	v_mov_b32_e32 v197, v159
	v_sub_f32_e32 v137, v209, v216
	v_sub_f32_e32 v136, v208, v216
	v_sub_f32_e32 v139, v211, v216
	v_sub_f32_e32 v138, v210, v216
	v_pk_mul_f32 v[138:139], v[216:217], v[138:139] op_sel:[1,0]
	v_pk_mul_f32 v[136:137], v[216:217], v[136:137] op_sel:[1,0]
	v_pk_fma_f32 v[138:139], v[152:153], v[138:139], v[102:103]
	v_pk_fma_f32 v[136:137], v[154:155], v[136:137], v[100:101]
	v_pk_fma_f32 v[138:139], v[134:135], s[78:79], v[138:139] op_sel_hi:[1,0,1]
	v_pk_fma_f32 v[136:137], v[132:133], s[78:79], v[136:137] op_sel_hi:[1,0,1]
	v_lshl_add_u64 v[196:197], v[196:197], 2, s[90:91]
	global_store_dwordx4 v[196:197], v[136:139], off
	v_add_u32_e32 v196, 0x18010, v194
	v_mov_b32_e32 v197, v159
	v_sub_f32_e32 v137, v213, v216
	v_sub_f32_e32 v136, v212, v216
	v_sub_f32_e32 v139, v215, v216
	v_sub_f32_e32 v138, v214, v216
	v_pk_mul_f32 v[138:139], v[216:217], v[138:139] op_sel:[1,0]
	v_pk_mul_f32 v[136:137], v[216:217], v[136:137] op_sel:[1,0]
	v_pk_fma_f32 v[138:139], v[148:149], v[138:139], v[98:99]
	v_pk_fma_f32 v[136:137], v[150:151], v[136:137], v[96:97]
	v_pk_fma_f32 v[138:139], v[130:131], s[78:79], v[138:139] op_sel_hi:[1,0,1]
	v_pk_fma_f32 v[136:137], v[128:129], s[78:79], v[136:137] op_sel_hi:[1,0,1]
	v_lshl_add_u64 v[196:197], v[196:197], 2, s[90:91]
	global_store_dwordx4 v[196:197], v[136:139], off
	s_nop 1
	v_add_u32_e32 v138, 0x80, v206
	v_lshlrev_b32_e32 v136, 1, v138
	v_mov_b32_e32 v137, v159
	v_lshlrev_b32_e32 v233, 11, v138
	v_lshl_add_u64 v[196:197], v[136:137], 2, s[2:3]
	v_add_u32_e32 v136, v233, v158
	v_lshl_add_u64 v[136:137], v[136:137], 2, s[88:89]
	global_load_dwordx2 v[204:205], v[196:197], off
	v_add_u32_e32 v198, v233, v231
	global_load_dwordx4 v[136:139], v[136:137], off
	v_mov_b32_e32 v199, v159
	v_add_u32_e32 v207, 0x90, v206
	v_lshl_add_u64 v[198:199], v[198:199], 2, s[88:89]
	v_lshlrev_b32_e32 v234, 11, v207
	global_load_dwordx4 v[208:211], v[198:199], off
	v_add_u32_e32 v212, v234, v158
	v_mov_b32_e32 v213, v159
	v_lshl_add_u64 v[212:213], v[212:213], 2, s[88:89]
	global_load_dwordx4 v[212:215], v[212:213], off
	v_lshlrev_b32_e32 v198, 1, v207
	v_mov_b32_e32 v199, v159
	v_lshl_add_u64 v[198:199], v[198:199], 2, s[2:3]
	global_load_dwordx2 v[238:239], v[198:199], off
	v_add_u32_e32 v216, v234, v231
	v_mov_b32_e32 v217, v159
	v_lshl_add_u64 v[216:217], v[216:217], 2, s[88:89]
	global_load_dwordx4 v[216:219], v[216:217], off
	v_add_u32_e32 v240, 0x40000, v194
	v_mov_b32_e32 v241, v159
	v_lshl_add_u64 v[240:241], v[240:241], 2, s[90:91]
	s_waitcnt vmcnt(0)
;     template <bool LN, int BJ, int LO, int HI> DI void batch(const f32x4 (&acc)[2][2][4][2], unsigned row0, unsigned col0, const f32x4 (&gv)[2], const f32x4 (&bv)[2]) const {
;         f32x4 r[HI - LO]; float mean[(HI - LO) / 2], rstd[(HI - LO) / 2];
; #pragma unroll
;         for (int i = LO; i < HI; ++i) { const int ai = i >> 3, m = (i >> 1) & 3, n = i & 1; const unsigned row = row0 + ai * HALF + m * 16;
;             if (n == 0) { mean[(i - LO) >> 1] = 0.f; rstd[(i - LO) >> 1] = 1.f;
;                 if (LN) { const float2 st = *(const float2*)(stats + row * 2u); mean[(i - LO) >> 1] = st.x; rstd[(i - LO) >> 1] = st.y; } }
;             r[i - LO] = *(const f32x4*)(src + (row * (unsigned)DM + col0 + BJ * HALF + n * 16)); }
; #pragma unroll
;         for (int i = LO; i < HI; ++i) { const int ai = i >> 3, m = (i >> 1) & 3, n = i & 1; const unsigned row = row0 + ai * HALF + m * 16;
;             *(f32x4*)(Y + (row * (unsigned)DM + col0 + BJ * HALF + n * 16)) = acc[ai][BJ][m][n] + ((r[i - LO] - mean[(i - LO) >> 1]) * rstd[(i - LO) >> 1]) * gv[n] + bv[n]; }
	v_sub_f32_e32 v137, v137, v204
	v_sub_f32_e32 v136, v136, v204
	v_sub_f32_e32 v139, v139, v204
	v_sub_f32_e32 v138, v138, v204
	v_pk_mul_f32 v[138:139], v[204:205], v[138:139] op_sel:[1,0]
	v_pk_mul_f32 v[136:137], v[204:205], v[136:137] op_sel:[1,0]
	v_pk_fma_f32 v[138:139], v[152:153], v[138:139], v[94:95]
	v_pk_fma_f32 v[136:137], v[154:155], v[136:137], v[92:93]
	v_pk_fma_f32 v[138:139], v[134:135], s[78:79], v[138:139] op_sel_hi:[1,0,1]
	v_pk_fma_f32 v[136:137], v[132:133], s[78:79], v[136:137] op_sel_hi:[1,0,1]
	global_store_dwordx4 v[240:241], v[136:139], off
	s_nop 1
	v_sub_f32_e32 v137, v209, v204
	v_sub_f32_e32 v136, v208, v204
	v_sub_f32_e32 v139, v211, v204
	v_sub_f32_e32 v138, v210, v204
	v_pk_mul_f32 v[138:139], v[204:205], v[138:139] op_sel:[1,0]
	v_pk_mul_f32 v[136:137], v[204:205], v[136:137] op_sel:[1,0]
	v_pk_fma_f32 v[138:139], v[148:149], v[138:139], v[90:91]
	v_pk_fma_f32 v[136:137], v[150:151], v[136:137], v[88:89]
	v_add_u32_e32 v204, 0x40010, v194
	v_mov_b32_e32 v205, v159
	v_pk_fma_f32 v[138:139], v[130:131], s[78:79], v[138:139] op_sel_hi:[1,0,1]
	v_pk_fma_f32 v[136:137], v[128:129], s[78:79], v[136:137] op_sel_hi:[1,0,1]
	v_lshl_add_u64 v[204:205], v[204:205], 2, s[90:91]
	global_store_dwordx4 v[204:205], v[136:139], off
	v_add_u32_e32 v204, 0x48000, v194
	v_mov_b32_e32 v205, v159
	v_sub_f32_e32 v137, v213, v238
	v_sub_f32_e32 v136, v212, v238
	v_sub_f32_e32 v139, v215, v238
	v_sub_f32_e32 v138, v214, v238
	v_pk_mul_f32 v[138:139], v[238:239], v[138:139] op_sel:[1,0]
	v_pk_mul_f32 v[136:137], v[238:239], v[136:137] op_sel:[1,0]
	v_pk_fma_f32 v[138:139], v[152:153], v[138:139], v[86:87]
	v_pk_fma_f32 v[136:137], v[154:155], v[136:137], v[84:85]
	v_pk_fma_f32 v[138:139], v[134:135], s[78:79], v[138:139] op_sel_hi:[1,0,1]
	v_pk_fma_f32 v[136:137], v[132:133], s[78:79], v[136:137] op_sel_hi:[1,0,1]
	v_lshl_add_u64 v[204:205], v[204:205], 2, s[90:91]
	global_store_dwordx4 v[204:205], v[136:139], off
	v_add_u32_e32 v204, 0x48010, v194
	v_mov_b32_e32 v205, v159
	v_sub_f32_e32 v137, v217, v238
	v_sub_f32_e32 v136, v216, v238
	v_sub_f32_e32 v139, v219, v238
	v_sub_f32_e32 v138, v218, v238
	v_pk_mul_f32 v[138:139], v[238:239], v[138:139] op_sel:[1,0]
	v_pk_mul_f32 v[136:137], v[238:239], v[136:137] op_sel:[1,0]
	v_pk_fma_f32 v[138:139], v[148:149], v[138:139], v[82:83]
	v_pk_fma_f32 v[136:137], v[150:151], v[136:137], v[80:81]
	v_pk_fma_f32 v[138:139], v[130:131], s[78:79], v[138:139] op_sel_hi:[1,0,1]
	v_pk_fma_f32 v[136:137], v[128:129], s[78:79], v[136:137] op_sel_hi:[1,0,1]
	v_lshl_add_u64 v[204:205], v[204:205], 2, s[90:91]
	global_store_dwordx4 v[204:205], v[136:139], off
	s_nop 1
	v_add_u32_e32 v138, 0xa0, v206
	v_lshlrev_b32_e32 v136, 1, v138
	v_mov_b32_e32 v137, v159
	v_lshlrev_b32_e32 v237, 11, v138
	v_lshl_add_u64 v[204:205], v[136:137], 2, s[2:3]
	v_add_u32_e32 v136, v237, v158
	v_lshl_add_u64 v[136:137], v[136:137], 2, s[88:89]
	global_load_dwordx2 v[240:241], v[204:205], off
	v_add_u32_e32 v208, v237, v231
	global_load_dwordx4 v[136:139], v[136:137], off
	v_mov_b32_e32 v209, v159
	v_lshl_add_u64 v[208:209], v[208:209], 2, s[88:89]
	global_load_dwordx4 v[212:215], v[208:209], off
	v_add_u32_e32 v208, 0xb0, v206
	v_lshlrev_b32_e32 v206, 1, v208
	v_mov_b32_e32 v207, v159
	v_lshlrev_b32_e32 v238, 11, v208
	v_lshl_add_u64 v[210:211], v[206:207], 2, s[2:3]
	v_add_u32_e32 v206, v238, v158
	v_lshl_add_u64 v[206:207], v[206:207], 2, s[88:89]
	global_load_dwordx2 v[242:243], v[210:211], off
	v_add_u32_e32 v216, v238, v231
	global_load_dwordx4 v[206:209], v[206:207], off
	v_mov_b32_e32 v217, v159
	v_lshl_add_u64 v[216:217], v[216:217], 2, s[88:89]
	global_load_dwordx4 v[216:219], v[216:217], off
	v_add_u32_e32 v244, 0x50000, v194
	v_mov_b32_e32 v245, v159
	v_lshl_add_u64 v[244:245], v[244:245], 2, s[90:91]
	s_waitcnt vmcnt(0)
	v_sub_f32_e32 v137, v137, v240
	v_sub_f32_e32 v136, v136, v240
	v_sub_f32_e32 v139, v139, v240
	v_sub_f32_e32 v138, v138, v240
	v_pk_mul_f32 v[138:139], v[240:241], v[138:139] op_sel:[1,0]
	v_pk_mul_f32 v[136:137], v[240:241], v[136:137] op_sel:[1,0]
	v_pk_fma_f32 v[138:139], v[152:153], v[138:139], v[78:79]
	v_pk_fma_f32 v[136:137], v[154:155], v[136:137], v[76:77]
	v_pk_fma_f32 v[138:139], v[134:135], s[78:79], v[138:139] op_sel_hi:[1,0,1]
	v_pk_fma_f32 v[136:137], v[132:133], s[78:79], v[136:137] op_sel_hi:[1,0,1]
	global_store_dwordx4 v[244:245], v[136:139], off
	s_nop 1
	v_sub_f32_e32 v137, v213, v240
	v_sub_f32_e32 v136, v212, v240
	v_sub_f32_e32 v139, v215, v240
	v_sub_f32_e32 v138, v214, v240
	v_pk_mul_f32 v[138:139], v[240:241], v[138:139] op_sel:[1,0]
	v_pk_mul_f32 v[136:137], v[240:241], v[136:137] op_sel:[1,0]
	v_pk_fma_f32 v[138:139], v[148:149], v[138:139], v[74:75]
	v_pk_fma_f32 v[136:137], v[150:151], v[136:137], v[72:73]
	v_add_u32_e32 v212, 0x50010, v194
	v_mov_b32_e32 v213, v159
	v_pk_fma_f32 v[138:139], v[130:131], s[78:79], v[138:139] op_sel_hi:[1,0,1]
	v_pk_fma_f32 v[136:137], v[128:129], s[78:79], v[136:137] op_sel_hi:[1,0,1]
	v_lshl_add_u64 v[212:213], v[212:213], 2, s[90:91]
	global_store_dwordx4 v[212:213], v[136:139], off
	s_nop 1
	v_sub_f32_e32 v137, v207, v242
	v_sub_f32_e32 v136, v206, v242
	v_sub_f32_e32 v139, v209, v242
	v_sub_f32_e32 v138, v208, v242
	v_pk_mul_f32 v[136:137], v[242:243], v[136:137] op_sel:[1,0]
	v_pk_mul_f32 v[138:139], v[242:243], v[138:139] op_sel:[1,0]
	v_pk_fma_f32 v[136:137], v[154:155], v[136:137], v[68:69]
	v_pk_fma_f32 v[138:139], v[152:153], v[138:139], v[70:71]
	v_pk_fma_f32 v[132:133], v[132:133], s[78:79], v[136:137] op_sel_hi:[1,0,1]
	v_add_u32_e32 v136, 0x58000, v194
	v_mov_b32_e32 v137, v159
	v_pk_fma_f32 v[134:135], v[134:135], s[78:79], v[138:139] op_sel_hi:[1,0,1]
	v_lshl_add_u64 v[136:137], v[136:137], 2, s[90:91]
	global_store_dwordx4 v[136:137], v[132:135], off
	s_nop 1
	v_sub_f32_e32 v133, v217, v242
	v_sub_f32_e32 v132, v216, v242
	v_sub_f32_e32 v135, v219, v242
	v_sub_f32_e32 v134, v218, v242
	v_pk_mul_f32 v[132:133], v[242:243], v[132:133] op_sel:[1,0]
	v_pk_mul_f32 v[134:135], v[242:243], v[134:135] op_sel:[1,0]
	v_pk_fma_f32 v[132:133], v[150:151], v[132:133], v[64:65]
	v_pk_fma_f32 v[134:135], v[148:149], v[134:135], v[66:67]
	v_pk_fma_f32 v[128:129], v[128:129], s[78:79], v[132:133] op_sel_hi:[1,0,1]
	v_add_u32_e32 v132, 0x58010, v194
	v_mov_b32_e32 v133, v159
	v_pk_fma_f32 v[130:131], v[130:131], s[78:79], v[134:135] op_sel_hi:[1,0,1]
	v_lshl_add_u64 v[132:133], v[132:133], 2, s[90:91]
	global_store_dwordx4 v[132:133], v[128:131], off
	global_load_dwordx4 v[128:131], v[140:141], off offset:512
	v_add_u32_e32 v136, v232, v230
	v_mov_b32_e32 v137, v159
	v_lshl_add_u64 v[136:137], v[136:137], 2, s[88:89]
	s_waitcnt vmcnt(0)
;     template <bool LN, int BJ, int LO, int HI> DI void batch(const f32x4 (&acc)[2][2][4][2], unsigned row0, unsigned col0, const f32x4 (&gv)[2], const f32x4 (&bv)[2]) const {
;         f32x4 r[HI - LO]; float mean[(HI - LO) / 2], rstd[(HI - LO) / 2];
; #pragma unroll
;         for (int i = LO; i < HI; ++i) { const int ai = i >> 3, m = (i >> 1) & 3, n = i & 1; const unsigned row = row0 + ai * HALF + m * 16;
;             if (n == 0) { mean[(i - LO) >> 1] = 0.f; rstd[(i - LO) >> 1] = 1.f;
;                 if (LN) { const float2 st = *(const float2*)(stats + row * 2u); mean[(i - LO) >> 1] = st.x; rstd[(i - LO) >> 1] = st.y; } }
;             r[i - LO] = *(const f32x4*)(src + (row * (unsigned)DM + col0 + BJ * HALF + n * 16)); }
; #pragma unroll
;         for (int i = LO; i < HI; ++i) { const int ai = i >> 3, m = (i >> 1) & 3, n = i & 1; const unsigned row = row0 + ai * HALF + m * 16;
;             *(f32x4*)(Y + (row * (unsigned)DM + col0 + BJ * HALF + n * 16)) = acc[ai][BJ][m][n] + ((r[i - LO] - mean[(i - LO) >> 1]) * rstd[(i - LO) >> 1]) * gv[n] + bv[n]; }
	v_pk_mul_f32 v[212:213], v[130:131], s[78:79] op_sel_hi:[1,0]
	v_pk_mul_f32 v[214:215], v[128:129], s[78:79] op_sel_hi:[1,0]
	global_load_dwordx4 v[132:135], v[142:143], off offset:512
	global_load_dwordx4 v[128:131], v[140:141], off offset:576
	s_waitcnt vmcnt(0)
	v_pk_mul_f32 v[206:207], v[130:131], s[78:79] op_sel_hi:[1,0]
	v_pk_mul_f32 v[208:209], v[128:129], s[78:79] op_sel_hi:[1,0]
	global_load_dwordx4 v[128:131], v[142:143], off offset:576
	global_load_dwordx2 v[220:221], v[144:145], off
	global_load_dwordx4 v[240:243], v[136:137], off
	v_add_u32_e32 v136, v232, v229
	v_mov_b32_e32 v137, v159
	v_lshl_add_u64 v[136:137], v[136:137], 2, s[88:89]
	global_load_dwordx4 v[244:247], v[136:137], off
	global_load_dwordx2 v[218:219], v[146:147], off
	v_add_u32_e32 v136, v195, v230
	v_mov_b32_e32 v137, v159
	v_lshl_add_u64 v[136:137], v[136:137], 2, s[88:89]
	global_load_dwordx4 v[248:251], v[136:137], off
	v_add_u32_e32 v136, v195, v229
	v_mov_b32_e32 v137, v159
	v_lshl_add_u64 v[136:137], v[136:137], 2, s[88:89]
	global_load_dwordx4 v[152:155], v[136:137], off
	global_load_dwordx2 v[216:217], v[200:201], off
	v_add_u32_e32 v136, v236, v230
	v_mov_b32_e32 v137, v159
	v_lshl_add_u64 v[136:137], v[136:137], 2, s[88:89]
	global_load_dwordx4 v[148:151], v[136:137], off
	v_add_u32_e32 v136, v236, v229
	v_mov_b32_e32 v137, v159
	v_lshl_add_u64 v[136:137], v[136:137], 2, s[88:89]
	global_load_dwordx4 v[144:147], v[136:137], off
	global_load_dwordx2 v[200:201], v[202:203], off
	v_add_u32_e32 v136, v235, v230
	v_mov_b32_e32 v137, v159
	v_lshl_add_u64 v[136:137], v[136:137], 2, s[88:89]
	global_load_dwordx4 v[140:143], v[136:137], off
	v_add_u32_e32 v136, v235, v229
	v_mov_b32_e32 v137, v159
	v_lshl_add_u64 v[136:137], v[136:137], 2, s[88:89]
	global_load_dwordx4 v[136:139], v[136:137], off
	v_add_u32_e32 v202, 0x80, v194
	v_mov_b32_e32 v203, v159
	v_lshl_add_u64 v[202:203], v[202:203], 2, s[90:91]
	s_waitcnt vmcnt(0)
	v_sub_f32_e32 v241, v241, v220
	v_sub_f32_e32 v240, v240, v220
	v_sub_f32_e32 v243, v243, v220
	v_sub_f32_e32 v242, v242, v220
	v_pk_mul_f32 v[242:243], v[220:221], v[242:243] op_sel:[1,0]
	v_pk_mul_f32 v[240:241], v[220:221], v[240:241] op_sel:[1,0]
	v_pk_fma_f32 v[242:243], v[212:213], v[242:243], v[62:63]
	v_pk_fma_f32 v[240:241], v[214:215], v[240:241], v[60:61]
	v_pk_fma_f32 v[242:243], v[134:135], s[78:79], v[242:243] op_sel_hi:[1,0,1]
	v_pk_fma_f32 v[240:241], v[132:133], s[78:79], v[240:241] op_sel_hi:[1,0,1]
	global_store_dwordx4 v[202:203], v[240:243], off
	v_sub_f32_e32 v203, v245, v220
	v_sub_f32_e32 v202, v244, v220
	v_sub_f32_e32 v241, v247, v220
	v_sub_f32_e32 v240, v246, v220
	v_pk_mul_f32 v[202:203], v[220:221], v[202:203] op_sel:[1,0]
	v_pk_mul_f32 v[240:241], v[220:221], v[240:241] op_sel:[1,0]
	v_pk_fma_f32 v[202:203], v[208:209], v[202:203], v[56:57]
	v_pk_fma_f32 v[220:221], v[206:207], v[240:241], v[58:59]
	v_pk_fma_f32 v[240:241], v[128:129], s[78:79], v[202:203] op_sel_hi:[1,0,1]
	v_add_u32_e32 v202, 0x90, v194
	v_mov_b32_e32 v203, v159
	v_pk_fma_f32 v[242:243], v[130:131], s[78:79], v[220:221] op_sel_hi:[1,0,1]
	v_lshl_add_u64 v[202:203], v[202:203], 2, s[90:91]
	global_store_dwordx4 v[202:203], v[240:243], off
	v_sub_f32_e32 v203, v249, v218
	v_sub_f32_e32 v202, v248, v218
	v_sub_f32_e32 v221, v251, v218
	v_sub_f32_e32 v220, v250, v218
	v_pk_mul_f32 v[202:203], v[218:219], v[202:203] op_sel:[1,0]
	v_pk_mul_f32 v[220:221], v[218:219], v[220:221] op_sel:[1,0]
	v_pk_fma_f32 v[202:203], v[214:215], v[202:203], v[52:53]
	v_pk_fma_f32 v[220:221], v[212:213], v[220:221], v[54:55]
	v_pk_fma_f32 v[240:241], v[132:133], s[78:79], v[202:203] op_sel_hi:[1,0,1]
	v_add_u32_e32 v202, 0x8080, v194
	v_mov_b32_e32 v203, v159
	v_sub_f32_e32 v153, v153, v218
	v_sub_f32_e32 v152, v152, v218
	v_sub_f32_e32 v155, v155, v218
	v_sub_f32_e32 v154, v154, v218
	v_pk_fma_f32 v[242:243], v[134:135], s[78:79], v[220:221] op_sel_hi:[1,0,1]
	v_lshl_add_u64 v[202:203], v[202:203], 2, s[90:91]
	v_pk_mul_f32 v[154:155], v[218:219], v[154:155] op_sel:[1,0]
	v_pk_mul_f32 v[152:153], v[218:219], v[152:153] op_sel:[1,0]
	global_store_dwordx4 v[202:203], v[240:243], off
	v_pk_fma_f32 v[152:153], v[208:209], v[152:153], v[48:49]
	v_pk_fma_f32 v[154:155], v[206:207], v[154:155], v[50:51]
	v_add_u32_e32 v202, 0x8090, v194
	v_mov_b32_e32 v203, v159
	v_sub_f32_e32 v149, v149, v216
	v_sub_f32_e32 v148, v148, v216
	v_sub_f32_e32 v151, v151, v216
	v_sub_f32_e32 v150, v150, v216
	v_pk_fma_f32 v[154:155], v[130:131], s[78:79], v[154:155] op_sel_hi:[1,0,1]
	v_pk_fma_f32 v[152:153], v[128:129], s[78:79], v[152:153] op_sel_hi:[1,0,1]
	v_lshl_add_u64 v[202:203], v[202:203], 2, s[90:91]
	v_pk_mul_f32 v[150:151], v[216:217], v[150:151] op_sel:[1,0]
	v_pk_mul_f32 v[148:149], v[216:217], v[148:149] op_sel:[1,0]
	global_store_dwordx4 v[202:203], v[152:155], off
	v_pk_fma_f32 v[148:149], v[214:215], v[148:149], v[44:45]
	v_pk_fma_f32 v[150:151], v[212:213], v[150:151], v[46:47]
	v_add_u32_e32 v152, 0x10080, v194
	v_mov_b32_e32 v153, v159
	v_sub_f32_e32 v145, v145, v216
	v_sub_f32_e32 v144, v144, v216
	v_sub_f32_e32 v147, v147, v216
	v_sub_f32_e32 v146, v146, v216
	v_pk_fma_f32 v[150:151], v[134:135], s[78:79], v[150:151] op_sel_hi:[1,0,1]
	v_pk_fma_f32 v[148:149], v[132:133], s[78:79], v[148:149] op_sel_hi:[1,0,1]
	v_lshl_add_u64 v[152:153], v[152:153], 2, s[90:91]
	v_pk_mul_f32 v[146:147], v[216:217], v[146:147] op_sel:[1,0]
	v_pk_mul_f32 v[144:145], v[216:217], v[144:145] op_sel:[1,0]
	global_store_dwordx4 v[152:153], v[148:151], off
	v_pk_fma_f32 v[144:145], v[208:209], v[144:145], v[40:41]
	v_pk_fma_f32 v[146:147], v[206:207], v[146:147], v[42:43]
;     template <bool LN, int BJ, int LO, int HI> DI void batch(const f32x4 (&acc)[2][2][4][2], unsigned row0, unsigned col0, const f32x4 (&gv)[2], const f32x4 (&bv)[2]) const {
;         f32x4 r[HI - LO]; float mean[(HI - LO) / 2], rstd[(HI - LO) / 2];
; #pragma unroll
;         for (int i = LO; i < HI; ++i) { const int ai = i >> 3, m = (i >> 1) & 3, n = i & 1; const unsigned row = row0 + ai * HALF + m * 16;
;             if (n == 0) { mean[(i - LO) >> 1] = 0.f; rstd[(i - LO) >> 1] = 1.f;
;                 if (LN) { const float2 st = *(const float2*)(stats + row * 2u); mean[(i - LO) >> 1] = st.x; rstd[(i - LO) >> 1] = st.y; } }
;             r[i - LO] = *(const f32x4*)(src + (row * (unsigned)DM + col0 + BJ * HALF + n * 16)); }
; #pragma unroll
;         for (int i = LO; i < HI; ++i) { const int ai = i >> 3, m = (i >> 1) & 3, n = i & 1; const unsigned row = row0 + ai * HALF + m * 16;
;             *(f32x4*)(Y + (row * (unsigned)DM + col0 + BJ * HALF + n * 16)) = acc[ai][BJ][m][n] + ((r[i - LO] - mean[(i - LO) >> 1]) * rstd[(i - LO) >> 1]) * gv[n] + bv[n]; }
	v_add_u32_e32 v148, 0x10090, v194
	v_mov_b32_e32 v149, v159
	v_sub_f32_e32 v141, v141, v200
	v_sub_f32_e32 v140, v140, v200
	v_sub_f32_e32 v143, v143, v200
	v_sub_f32_e32 v142, v142, v200
	v_pk_fma_f32 v[146:147], v[130:131], s[78:79], v[146:147] op_sel_hi:[1,0,1]
	v_pk_fma_f32 v[144:145], v[128:129], s[78:79], v[144:145] op_sel_hi:[1,0,1]
	v_lshl_add_u64 v[148:149], v[148:149], 2, s[90:91]
	v_pk_mul_f32 v[142:143], v[200:201], v[142:143] op_sel:[1,0]
	v_pk_mul_f32 v[140:141], v[200:201], v[140:141] op_sel:[1,0]
	global_store_dwordx4 v[148:149], v[144:147], off
	v_pk_fma_f32 v[140:141], v[214:215], v[140:141], v[36:37]
	v_pk_fma_f32 v[142:143], v[212:213], v[142:143], v[38:39]
	v_add_u32_e32 v144, 0x18080, v194
	v_mov_b32_e32 v145, v159
	v_sub_f32_e32 v137, v137, v200
	v_sub_f32_e32 v136, v136, v200
	v_sub_f32_e32 v139, v139, v200
	v_sub_f32_e32 v138, v138, v200
	v_pk_fma_f32 v[142:143], v[134:135], s[78:79], v[142:143] op_sel_hi:[1,0,1]
	v_pk_fma_f32 v[140:141], v[132:133], s[78:79], v[140:141] op_sel_hi:[1,0,1]
	v_lshl_add_u64 v[144:145], v[144:145], 2, s[90:91]
	v_pk_mul_f32 v[138:139], v[200:201], v[138:139] op_sel:[1,0]
	v_pk_mul_f32 v[136:137], v[200:201], v[136:137] op_sel:[1,0]
	global_store_dwordx4 v[144:145], v[140:143], off
	v_pk_fma_f32 v[136:137], v[208:209], v[136:137], v[32:33]
	v_pk_fma_f32 v[138:139], v[206:207], v[138:139], v[34:35]
	v_add_u32_e32 v140, 0x18090, v194
	v_mov_b32_e32 v141, v159
	v_pk_fma_f32 v[138:139], v[130:131], s[78:79], v[138:139] op_sel_hi:[1,0,1]
	v_pk_fma_f32 v[136:137], v[128:129], s[78:79], v[136:137] op_sel_hi:[1,0,1]
	v_lshl_add_u64 v[140:141], v[140:141], 2, s[90:91]
	global_store_dwordx4 v[140:141], v[136:139], off
	s_nop 1
	v_add_u32_e32 v136, v233, v230
	v_mov_b32_e32 v137, v159
	v_lshl_add_u64 v[136:137], v[136:137], 2, s[88:89]
	global_load_dwordx2 v[220:221], v[196:197], off
	global_load_dwordx4 v[216:219], v[136:137], off
	v_add_u32_e32 v136, v233, v229
	v_mov_b32_e32 v137, v159
	v_lshl_add_u64 v[136:137], v[136:137], 2, s[88:89]
	global_load_dwordx4 v[240:243], v[136:137], off
	global_load_dwordx2 v[200:201], v[198:199], off
	v_add_u32_e32 v136, v234, v230
	v_mov_b32_e32 v137, v159
	v_lshl_add_u64 v[136:137], v[136:137], 2, s[88:89]
	global_load_dwordx4 v[244:247], v[136:137], off
	v_add_u32_e32 v136, v234, v229
	v_mov_b32_e32 v137, v159
	v_lshl_add_u64 v[136:137], v[136:137], 2, s[88:89]
	global_load_dwordx4 v[152:155], v[136:137], off
	global_load_dwordx2 v[198:199], v[204:205], off
	v_add_u32_e32 v136, v237, v230
	v_mov_b32_e32 v137, v159
	v_lshl_add_u64 v[136:137], v[136:137], 2, s[88:89]
	global_load_dwordx4 v[148:151], v[136:137], off
	v_add_u32_e32 v136, v237, v229
	v_mov_b32_e32 v137, v159
	v_lshl_add_u64 v[136:137], v[136:137], 2, s[88:89]
	global_load_dwordx4 v[144:147], v[136:137], off
	global_load_dwordx2 v[196:197], v[210:211], off
	v_add_u32_e32 v136, v238, v230
	v_mov_b32_e32 v137, v159
	v_lshl_add_u64 v[136:137], v[136:137], 2, s[88:89]
	global_load_dwordx4 v[140:143], v[136:137], off
	v_add_u32_e32 v136, v238, v229
	v_mov_b32_e32 v137, v159
	v_lshl_add_u64 v[136:137], v[136:137], 2, s[88:89]
	global_load_dwordx4 v[136:139], v[136:137], off
	v_add_u32_e32 v210, 0x40080, v194
	v_mov_b32_e32 v211, v159
	v_lshl_add_u64 v[210:211], v[210:211], 2, s[90:91]
	s_waitcnt vmcnt(0)
;     template <bool LN, int BJ, int LO, int HI> DI void batch(const f32x4 (&acc)[2][2][4][2], unsigned row0, unsigned col0, const f32x4 (&gv)[2], const f32x4 (&bv)[2]) const {
;     ...
;         for (int i = LO; i < HI; ++i) { const int ai = i >> 3, m = (i >> 1) & 3, n = i & 1; const unsigned row = row0 + ai * HALF + m * 16;
;             *(f32x4*)(Y + (row * (unsigned)DM + col0 + BJ * HALF + n * 16)) = acc[ai][BJ][m][n] + ((r[i - LO] - mean[(i - LO) >> 1]) * rstd[(i - LO) >> 1]) * gv[n] + bv[n]; }
	v_sub_f32_e32 v203, v217, v220
	v_sub_f32_e32 v202, v216, v220
	v_sub_f32_e32 v205, v219, v220
	v_sub_f32_e32 v204, v218, v220
	v_pk_mul_f32 v[204:205], v[220:221], v[204:205] op_sel:[1,0]
	v_pk_mul_f32 v[202:203], v[220:221], v[202:203] op_sel:[1,0]
	v_pk_fma_f32 v[204:205], v[212:213], v[204:205], v[30:31]
	v_pk_fma_f32 v[202:203], v[214:215], v[202:203], v[28:29]
	v_pk_fma_f32 v[204:205], v[134:135], s[78:79], v[204:205] op_sel_hi:[1,0,1]
	v_pk_fma_f32 v[202:203], v[132:133], s[78:79], v[202:203] op_sel_hi:[1,0,1]
	global_store_dwordx4 v[210:211], v[202:205], off
	v_add_u32_e32 v210, 0x40090, v194
	v_mov_b32_e32 v211, v159
	v_sub_f32_e32 v203, v241, v220
	v_sub_f32_e32 v202, v240, v220
	v_sub_f32_e32 v205, v243, v220
	v_sub_f32_e32 v204, v242, v220
	v_pk_mul_f32 v[204:205], v[220:221], v[204:205] op_sel:[1,0]
	v_pk_mul_f32 v[202:203], v[220:221], v[202:203] op_sel:[1,0]
	v_pk_fma_f32 v[204:205], v[206:207], v[204:205], v[26:27]
	v_pk_fma_f32 v[202:203], v[208:209], v[202:203], v[24:25]
	v_pk_fma_f32 v[204:205], v[130:131], s[78:79], v[204:205] op_sel_hi:[1,0,1]
	v_pk_fma_f32 v[202:203], v[128:129], s[78:79], v[202:203] op_sel_hi:[1,0,1]
	v_lshl_add_u64 v[210:211], v[210:211], 2, s[90:91]
	global_store_dwordx4 v[210:211], v[202:205], off
	v_sub_f32_e32 v149, v149, v198
	v_sub_f32_e32 v148, v148, v198
	v_sub_f32_e32 v203, v245, v200
	v_sub_f32_e32 v202, v244, v200
	v_sub_f32_e32 v141, v141, v196
	v_sub_f32_e32 v140, v140, v196
	v_sub_f32_e32 v205, v247, v200
	v_sub_f32_e32 v204, v246, v200
	v_pk_mul_f32 v[202:203], v[200:201], v[202:203] op_sel:[1,0]
	v_sub_f32_e32 v151, v151, v198
	v_sub_f32_e32 v150, v150, v198
	v_pk_mul_f32 v[148:149], v[198:199], v[148:149] op_sel:[1,0]
	v_sub_f32_e32 v143, v143, v196
	v_sub_f32_e32 v142, v142, v196
	v_pk_mul_f32 v[140:141], v[196:197], v[140:141] op_sel:[1,0]
	v_pk_mul_f32 v[204:205], v[200:201], v[204:205] op_sel:[1,0]
	v_pk_fma_f32 v[202:203], v[214:215], v[202:203], v[20:21]
	v_sub_f32_e32 v153, v153, v200
	v_sub_f32_e32 v152, v152, v200
	v_sub_f32_e32 v155, v155, v200
	v_sub_f32_e32 v154, v154, v200
	v_pk_mul_f32 v[150:151], v[198:199], v[150:151] op_sel:[1,0]
	v_pk_fma_f32 v[148:149], v[214:215], v[148:149], v[12:13]
	v_pk_mul_f32 v[142:143], v[196:197], v[142:143] op_sel:[1,0]
	v_pk_fma_f32 v[140:141], v[214:215], v[140:141], v[4:5]
	v_pk_fma_f32 v[204:205], v[212:213], v[204:205], v[22:23]
	v_pk_fma_f32 v[202:203], v[132:133], s[78:79], v[202:203] op_sel_hi:[1,0,1]
	v_pk_mul_f32 v[154:155], v[200:201], v[154:155] op_sel:[1,0]
	v_pk_mul_f32 v[152:153], v[200:201], v[152:153] op_sel:[1,0]
	v_pk_fma_f32 v[150:151], v[212:213], v[150:151], v[14:15]
	v_pk_fma_f32 v[148:149], v[132:133], s[78:79], v[148:149] op_sel_hi:[1,0,1]
	v_pk_fma_f32 v[142:143], v[212:213], v[142:143], v[6:7]
	v_pk_fma_f32 v[132:133], v[132:133], s[78:79], v[140:141] op_sel_hi:[1,0,1]
	v_add_u32_e32 v140, 0x58080, v194
	v_mov_b32_e32 v141, v159
	v_pk_fma_f32 v[204:205], v[134:135], s[78:79], v[204:205] op_sel_hi:[1,0,1]
	v_pk_fma_f32 v[152:153], v[208:209], v[152:153], v[16:17]
	v_pk_fma_f32 v[154:155], v[206:207], v[154:155], v[18:19]
	v_add_u32_e32 v200, 0x48090, v194
	v_mov_b32_e32 v201, v159
	v_pk_fma_f32 v[150:151], v[134:135], s[78:79], v[150:151] op_sel_hi:[1,0,1]
	v_pk_fma_f32 v[134:135], v[134:135], s[78:79], v[142:143] op_sel_hi:[1,0,1]
	v_lshl_add_u64 v[140:141], v[140:141], 2, s[90:91]
	v_pk_fma_f32 v[154:155], v[130:131], s[78:79], v[154:155] op_sel_hi:[1,0,1]
	v_pk_fma_f32 v[152:153], v[128:129], s[78:79], v[152:153] op_sel_hi:[1,0,1]
	v_lshl_add_u64 v[200:201], v[200:201], 2, s[90:91]
	v_sub_f32_e32 v145, v145, v198
	v_sub_f32_e32 v144, v144, v198
	global_store_dwordx4 v[140:141], v[132:135], off
	global_store_dwordx4 v[200:201], v[152:155], off
	v_sub_f32_e32 v147, v147, v198
	v_sub_f32_e32 v133, v137, v196
	v_sub_f32_e32 v132, v136, v196
	v_add_u32_e32 v152, 0x50080, v194
	v_mov_b32_e32 v153, v159
	v_sub_f32_e32 v146, v146, v198
	v_pk_mul_f32 v[144:145], v[198:199], v[144:145] op_sel:[1,0]
	v_sub_f32_e32 v135, v139, v196
	v_sub_f32_e32 v134, v138, v196
	v_pk_mul_f32 v[132:133], v[196:197], v[132:133] op_sel:[1,0]
	v_lshl_add_u64 v[152:153], v[152:153], 2, s[90:91]
	v_pk_mul_f32 v[146:147], v[198:199], v[146:147] op_sel:[1,0]
	v_pk_fma_f32 v[144:145], v[208:209], v[144:145], v[8:9]
	v_pk_mul_f32 v[134:135], v[196:197], v[134:135] op_sel:[1,0]
	v_pk_fma_f32 v[132:133], v[208:209], v[132:133], v[0:1]
	v_add_u32_e32 v210, 0x48080, v194
	v_mov_b32_e32 v211, v159
	global_store_dwordx4 v[152:153], v[148:151], off
	v_pk_fma_f32 v[146:147], v[206:207], v[146:147], v[10:11]
	v_pk_fma_f32 v[144:145], v[128:129], s[78:79], v[144:145] op_sel_hi:[1,0,1]
	v_add_u32_e32 v148, 0x50090, v194
	v_mov_b32_e32 v149, v159
	v_pk_fma_f32 v[134:135], v[206:207], v[134:135], v[2:3]
	v_pk_fma_f32 v[128:129], v[128:129], s[78:79], v[132:133] op_sel_hi:[1,0,1]
	v_add_u32_e32 v132, 0x58090, v194
	v_mov_b32_e32 v133, v159
	v_lshl_add_u64 v[210:211], v[210:211], 2, s[90:91]
	v_pk_fma_f32 v[146:147], v[130:131], s[78:79], v[146:147] op_sel_hi:[1,0,1]
	v_lshl_add_u64 v[148:149], v[148:149], 2, s[90:91]
	v_pk_fma_f32 v[130:131], v[130:131], s[78:79], v[134:135] op_sel_hi:[1,0,1]
	v_lshl_add_u64 v[132:133], v[132:133], 2, s[90:91]
	global_store_dwordx4 v[210:211], v[202:205], off
	global_store_dwordx4 v[148:149], v[144:147], off
	global_store_dwordx4 v[132:133], v[128:131], off
	s_mov_b64 s[24:25], 0
	s_branch .LBB0_324
